# every K-loop MFMA segment pinned to an 8-byte boundary (pad in the load segment before the opening barrier)
# speedup vs baseline: 1.0095x; 1.0095x over previous
.LBB0_74:
	s_ashr_i32 s27, s26, 31
	s_lshl_b64 s[28:29], s[26:27], 19
	s_add_u32 s28, s3, s28
	s_addc_u32 s29, s35, s29
	s_and_b64 s[30:31], s[4:5], exec
	s_cselect_b32 s27, s29, s49
	s_cselect_b32 s68, s28, s48
	s_ashr_i32 s23, s22, 31
	s_lshl_b64 s[30:31], s[22:23], 19
	s_add_u32 s30, s50, s30
	s_addc_u32 s31, s51, s31
	s_and_b64 s[70:71], s[4:5], exec
	s_cselect_b32 s69, s31, s47
	s_cselect_b32 s70, s30, s46
	s_lshl_b32 s23, s44, 8
	v_add_u32_e32 v0, s23, v148
	s_add_u32 s71, s46, 0x100
	v_ashrrev_i32_e32 v1, 31, v0
	s_addc_u32 s74, s47, 0
	v_lshl_add_u64 v[144:145], v[0:1], 4, s[12:13]
	s_add_u32 s44, s48, 0x40080
	s_addc_u32 s45, s49, 0
	s_mov_b32 s75, -2
	s_mov_b64 s[46:47], 0
	s_cmp_eq_u32 s59, 1
	s_cbranch_scc1 .Lfa_0
	v_add_u32_e32 v153, s64, v147
	ds_read_b128 v[160:163], v153
	v_xor_b32_e32 v253, 64, v153
	ds_read_b128 v[164:167], v253
	ds_read_b128 v[168:171], v153 offset:2048
	ds_read_b128 v[172:175], v253 offset:2048
	v_add_u32_e32 v153, s65, v147
	ds_read_b128 v[176:179], v153
	v_xor_b32_e32 v253, 64, v153
	ds_read_b128 v[180:183], v253
	ds_read_b128 v[186:189], v153 offset:2048
	ds_read_b128 v[190:193], v253 offset:2048
	s_add_u32 s48, s44, 0xfffc0080
	s_addc_u32 s49, s45, -1
	s_and_b64 s[46:47], s[46:47], exec
	s_cselect_b32 s49, s27, s49
	s_cselect_b32 s48, s68, s48
	s_cselect_b32 s47, s69, s74
	s_cselect_b32 s46, s70, s71
	v_lshl_add_u64 v[154:155], s[44:45], 0, v[138:139]
	s_add_i32 m0, s55, 0xc000
	ds_read_b128 v[194:197], v150
	v_xor_b32_e32 v253, 64, v150
	ds_read_b128 v[198:201], v253
	ds_read_b128 v[202:205], v150 offset:2048
	ds_read_b128 v[206:209], v253 offset:2048
	ds_read_b128 v[210:213], v150 offset:4096
	ds_read_b128 v[214:217], v253 offset:4096
	ds_read_b128 v[218:221], v150 offset:6144
	ds_read_b128 v[222:225], v253 offset:6144
	global_load_lds_dwordx4 v[154:155], off
	v_lshl_add_u64 v[154:155], s[44:45], 0, v[136:137]
	s_add_i32 m0, s55, 0xe000
	s_nop 0
	global_load_lds_dwordx4 v[154:155], off
	s_waitcnt vmcnt(16)
	s_waitcnt lgkmcnt(0)
	.p2align 3
	s_setprio 1
	s_barrier
	v_mfma_f32_16x16x32_bf16 v[124:127], v[160:163], v[194:197], 0
	v_mfma_f32_16x16x32_bf16 v[116:119], v[168:171], v[194:197], 0
	v_mfma_f32_16x16x32_bf16 v[108:111], v[160:163], v[202:205], 0
	v_mfma_f32_16x16x32_bf16 v[100:103], v[168:171], v[202:205], 0
	v_mfma_f32_16x16x32_bf16 v[92:95], v[160:163], v[210:213], 0
	v_mfma_f32_16x16x32_bf16 v[84:87], v[168:171], v[210:213], 0
	v_mfma_f32_16x16x32_bf16 v[76:79], v[160:163], v[218:221], 0
	v_mfma_f32_16x16x32_bf16 v[68:71], v[168:171], v[218:221], 0
	v_mfma_f32_16x16x32_bf16 v[124:127], v[164:167], v[198:201], v[124:127]
	v_mfma_f32_16x16x32_bf16 v[116:119], v[172:175], v[198:201], v[116:119]
	v_mfma_f32_16x16x32_bf16 v[108:111], v[164:167], v[206:209], v[108:111]
	v_mfma_f32_16x16x32_bf16 v[100:103], v[172:175], v[206:209], v[100:103]
	v_mfma_f32_16x16x32_bf16 v[92:95], v[164:167], v[214:217], v[92:95]
	v_mfma_f32_16x16x32_bf16 v[84:87], v[172:175], v[214:217], v[84:87]
	v_mfma_f32_16x16x32_bf16 v[76:79], v[164:167], v[222:225], v[76:79]
	v_mfma_f32_16x16x32_bf16 v[68:71], v[172:175], v[222:225], v[68:71]
	s_setprio 0
	s_setprio 1
	v_mfma_f32_16x16x32_bf16 v[120:123], v[176:179], v[194:197], 0
	v_mfma_f32_16x16x32_bf16 v[112:115], v[186:189], v[194:197], 0
	v_mfma_f32_16x16x32_bf16 v[104:107], v[176:179], v[202:205], 0
	v_mfma_f32_16x16x32_bf16 v[96:99], v[186:189], v[202:205], 0
	v_mfma_f32_16x16x32_bf16 v[88:91], v[176:179], v[210:213], 0
	v_mfma_f32_16x16x32_bf16 v[80:83], v[186:189], v[210:213], 0
	v_mfma_f32_16x16x32_bf16 v[72:75], v[176:179], v[218:221], 0
	v_mfma_f32_16x16x32_bf16 v[64:67], v[186:189], v[218:221], 0
	v_mfma_f32_16x16x32_bf16 v[120:123], v[180:183], v[198:201], v[120:123]
	v_mfma_f32_16x16x32_bf16 v[112:115], v[190:193], v[198:201], v[112:115]
	v_mfma_f32_16x16x32_bf16 v[104:107], v[180:183], v[206:209], v[104:107]
	v_mfma_f32_16x16x32_bf16 v[96:99], v[190:193], v[206:209], v[96:99]
	v_mfma_f32_16x16x32_bf16 v[88:91], v[180:183], v[214:217], v[88:91]
	v_mfma_f32_16x16x32_bf16 v[80:83], v[190:193], v[214:217], v[80:83]
	v_mfma_f32_16x16x32_bf16 v[72:75], v[180:183], v[222:225], v[72:75]
	v_mfma_f32_16x16x32_bf16 v[64:67], v[190:193], v[222:225], v[64:67]
	s_barrier
	s_setprio 0
	s_add_i32 s76, s64, s52
	v_lshl_add_u64 v[154:155], s[46:47], 0, v[132:133]
	s_mov_b32 m0, s76
	ds_read_b128 v[194:197], v150 offset:16384
	v_xor_b32_e32 v253, 64, v150
	ds_read_b128 v[198:201], v253 offset:16384
	ds_read_b128 v[202:205], v150 offset:18432
	ds_read_b128 v[206:209], v253 offset:18432
	ds_read_b128 v[210:213], v150 offset:20480
	ds_read_b128 v[214:217], v253 offset:20480
	ds_read_b128 v[218:221], v150 offset:22528
	ds_read_b128 v[222:225], v253 offset:22528
	global_load_lds_dwordx4 v[154:155], off
	s_add_i32 m0, s76, 0x2000
	s_add_u32 s76, s46, 0x40000
	v_lshl_add_u64 v[226:227], s[46:47], 0, v[128:129]
	s_addc_u32 s77, s47, 0
	s_add_i32 s78, s65, s52
	global_load_lds_dwordx4 v[226:227], off
	v_lshl_add_u64 v[228:229], s[76:77], 0, v[132:133]
	s_mov_b32 m0, s78
	v_lshl_add_u64 v[230:231], s[48:49], 0, v[130:131]
	global_load_lds_dwordx4 v[228:229], off
	v_lshl_add_u64 v[228:229], s[76:77], 0, v[128:129]
	s_add_i32 m0, s78, 0x2000
	s_nop 0
	global_load_lds_dwordx4 v[228:229], off
	v_lshl_add_u64 v[228:229], s[48:49], 0, v[134:135]
	s_mov_b32 m0, s55
	s_nop 0
	global_load_lds_dwordx4 v[228:229], off
	s_mov_b32 m0, s56
	s_nop 0
	global_load_lds_dwordx4 v[230:231], off
	s_waitcnt vmcnt(16)
	s_waitcnt lgkmcnt(0)
	.p2align 3
	s_setprio 1
	s_barrier
	v_mfma_f32_16x16x32_bf16 v[60:63], v[160:163], v[194:197], 0
	v_mfma_f32_16x16x32_bf16 v[52:55], v[168:171], v[194:197], 0
	v_mfma_f32_16x16x32_bf16 v[44:47], v[160:163], v[202:205], 0
	v_mfma_f32_16x16x32_bf16 v[36:39], v[168:171], v[202:205], 0
	v_mfma_f32_16x16x32_bf16 v[28:31], v[160:163], v[210:213], 0
	v_mfma_f32_16x16x32_bf16 v[20:23], v[168:171], v[210:213], 0
	v_mfma_f32_16x16x32_bf16 v[12:15], v[160:163], v[218:221], 0
	v_mfma_f32_16x16x32_bf16 v[4:7], v[168:171], v[218:221], 0
	v_mfma_f32_16x16x32_bf16 v[60:63], v[164:167], v[198:201], v[60:63]
	v_mfma_f32_16x16x32_bf16 v[52:55], v[172:175], v[198:201], v[52:55]
	v_mfma_f32_16x16x32_bf16 v[44:47], v[164:167], v[206:209], v[44:47]
	v_mfma_f32_16x16x32_bf16 v[36:39], v[172:175], v[206:209], v[36:39]
	v_mfma_f32_16x16x32_bf16 v[28:31], v[164:167], v[214:217], v[28:31]
	v_mfma_f32_16x16x32_bf16 v[20:23], v[172:175], v[214:217], v[20:23]
	v_mfma_f32_16x16x32_bf16 v[12:15], v[164:167], v[222:225], v[12:15]
	v_mfma_f32_16x16x32_bf16 v[4:7], v[172:175], v[222:225], v[4:7]
	s_setprio 0
	s_setprio 1
	v_mfma_f32_16x16x32_bf16 v[56:59], v[176:179], v[194:197], 0
	v_mfma_f32_16x16x32_bf16 v[48:51], v[186:189], v[194:197], 0
	v_mfma_f32_16x16x32_bf16 v[40:43], v[176:179], v[202:205], 0
	v_mfma_f32_16x16x32_bf16 v[32:35], v[186:189], v[202:205], 0
	v_mfma_f32_16x16x32_bf16 v[24:27], v[176:179], v[210:213], 0
	v_mfma_f32_16x16x32_bf16 v[16:19], v[186:189], v[210:213], 0
	v_mfma_f32_16x16x32_bf16 v[8:11], v[176:179], v[218:221], 0
	v_mfma_f32_16x16x32_bf16 v[0:3], v[186:189], v[218:221], 0
	v_mfma_f32_16x16x32_bf16 v[56:59], v[180:183], v[198:201], v[56:59]
	v_mfma_f32_16x16x32_bf16 v[48:51], v[190:193], v[198:201], v[48:51]
	v_mfma_f32_16x16x32_bf16 v[40:43], v[180:183], v[206:209], v[40:43]
	v_mfma_f32_16x16x32_bf16 v[32:35], v[190:193], v[206:209], v[32:35]
	v_mfma_f32_16x16x32_bf16 v[24:27], v[180:183], v[214:217], v[24:27]
	v_mfma_f32_16x16x32_bf16 v[16:19], v[190:193], v[214:217], v[16:19]
	v_mfma_f32_16x16x32_bf16 v[8:11], v[180:183], v[222:225], v[8:11]
	v_mfma_f32_16x16x32_bf16 v[0:3], v[190:193], v[222:225], v[0:3]
	s_barrier
	s_setprio 0
	s_add_i32 s76, 0, 0x18000
	v_add_u32_e32 v153, s76, v147
	s_add_i32 s77, 0, 0x1c000
	ds_read_b128 v[160:163], v153
	v_xor_b32_e32 v253, 64, v153
	ds_read_b128 v[164:167], v253
	ds_read_b128 v[168:171], v153 offset:2048
	ds_read_b128 v[172:175], v253 offset:2048
	v_add_u32_e32 v153, s77, v147
	ds_read_b128 v[176:179], v153
	v_xor_b32_e32 v253, 64, v153
	ds_read_b128 v[180:183], v253
	ds_read_b128 v[186:189], v153 offset:2048
	ds_read_b128 v[190:193], v253 offset:2048
	s_add_u32 s48, s48, 0x40000
	s_addc_u32 s49, s49, 0
	s_mov_b32 m0, s57
	v_lshl_add_u64 v[232:233], s[48:49], 0, v[134:135]
	ds_read_b128 v[194:197], v150 offset:32768
	v_xor_b32_e32 v253, 64, v150
	ds_read_b128 v[198:201], v253 offset:32768
	ds_read_b128 v[202:205], v150 offset:34816
	ds_read_b128 v[206:209], v253 offset:34816
	ds_read_b128 v[210:213], v150 offset:36864
	ds_read_b128 v[214:217], v253 offset:36864
	ds_read_b128 v[218:221], v150 offset:38912
	ds_read_b128 v[222:225], v253 offset:38912
	global_load_lds_dwordx4 v[232:233], off
	v_lshl_add_u64 v[232:233], s[48:49], 0, v[130:131]
	s_mov_b32 m0, s58
	s_nop 0
	global_load_lds_dwordx4 v[232:233], off
	s_waitcnt vmcnt(8)
	s_waitcnt lgkmcnt(0)
	.p2align 3
	s_setprio 1
	s_barrier
	v_mfma_f32_16x16x32_bf16 v[124:127], v[160:163], v[194:197], v[124:127]
	v_mfma_f32_16x16x32_bf16 v[124:127], v[164:167], v[198:201], v[124:127]
	v_mfma_f32_16x16x32_bf16 v[116:119], v[172:175], v[198:201], v[116:119]
	v_mfma_f32_16x16x32_bf16 v[116:119], v[168:171], v[194:197], v[116:119]
	v_mfma_f32_16x16x32_bf16 v[100:103], v[168:171], v[202:205], v[100:103]
	v_mfma_f32_16x16x32_bf16 v[100:103], v[172:175], v[206:209], v[100:103]
	v_mfma_f32_16x16x32_bf16 v[108:111], v[164:167], v[206:209], v[108:111]
	v_mfma_f32_16x16x32_bf16 v[108:111], v[160:163], v[202:205], v[108:111]
	v_mfma_f32_16x16x32_bf16 v[92:95], v[160:163], v[210:213], v[92:95]
	v_mfma_f32_16x16x32_bf16 v[92:95], v[164:167], v[214:217], v[92:95]
	v_mfma_f32_16x16x32_bf16 v[84:87], v[172:175], v[214:217], v[84:87]
	v_mfma_f32_16x16x32_bf16 v[84:87], v[168:171], v[210:213], v[84:87]
	v_mfma_f32_16x16x32_bf16 v[68:71], v[168:171], v[218:221], v[68:71]
	v_mfma_f32_16x16x32_bf16 v[68:71], v[172:175], v[222:225], v[68:71]
	v_mfma_f32_16x16x32_bf16 v[76:79], v[164:167], v[222:225], v[76:79]
	v_mfma_f32_16x16x32_bf16 v[76:79], v[160:163], v[218:221], v[76:79]
	s_setprio 0
	s_setprio 1
	v_mfma_f32_16x16x32_bf16 v[120:123], v[176:179], v[194:197], v[120:123]
	v_mfma_f32_16x16x32_bf16 v[120:123], v[180:183], v[198:201], v[120:123]
	v_mfma_f32_16x16x32_bf16 v[112:115], v[190:193], v[198:201], v[112:115]
	v_mfma_f32_16x16x32_bf16 v[112:115], v[186:189], v[194:197], v[112:115]
	v_mfma_f32_16x16x32_bf16 v[96:99], v[186:189], v[202:205], v[96:99]
	v_mfma_f32_16x16x32_bf16 v[96:99], v[190:193], v[206:209], v[96:99]
	v_mfma_f32_16x16x32_bf16 v[104:107], v[180:183], v[206:209], v[104:107]
	v_mfma_f32_16x16x32_bf16 v[104:107], v[176:179], v[202:205], v[104:107]
	v_mfma_f32_16x16x32_bf16 v[88:91], v[176:179], v[210:213], v[88:91]
	v_mfma_f32_16x16x32_bf16 v[88:91], v[180:183], v[214:217], v[88:91]
	v_mfma_f32_16x16x32_bf16 v[80:83], v[190:193], v[214:217], v[80:83]
	v_mfma_f32_16x16x32_bf16 v[80:83], v[186:189], v[210:213], v[80:83]
	v_mfma_f32_16x16x32_bf16 v[64:67], v[186:189], v[218:221], v[64:67]
	v_mfma_f32_16x16x32_bf16 v[64:67], v[190:193], v[222:225], v[64:67]
	v_mfma_f32_16x16x32_bf16 v[72:75], v[180:183], v[222:225], v[72:75]
	v_mfma_f32_16x16x32_bf16 v[72:75], v[176:179], v[218:221], v[72:75]
	s_barrier
	s_setprio 0
	s_add_i32 s48, s76, s52
	v_lshl_add_u64 v[154:155], v[154:155], 0, s[14:15]
	s_mov_b32 m0, s48
	ds_read_b128 v[194:197], v150 offset:49152
	v_xor_b32_e32 v253, 64, v150
	ds_read_b128 v[198:201], v253 offset:49152
	ds_read_b128 v[202:205], v150 offset:51200
	ds_read_b128 v[206:209], v253 offset:51200
	ds_read_b128 v[210:213], v150 offset:53248
	ds_read_b128 v[214:217], v253 offset:53248
	ds_read_b128 v[218:221], v150 offset:55296
	ds_read_b128 v[222:225], v253 offset:55296
	global_load_lds_dwordx4 v[154:155], off
	s_add_i32 m0, s48, 0x2000
	s_add_u32 s46, s46, 0x40080
	v_lshl_add_u64 v[154:155], v[226:227], 0, s[14:15]
	s_addc_u32 s47, s47, 0
	s_add_i32 s48, s77, s52
	global_load_lds_dwordx4 v[154:155], off
	v_lshl_add_u64 v[154:155], s[46:47], 0, v[132:133]
	s_mov_b32 m0, s48
	s_nop 0
	global_load_lds_dwordx4 v[154:155], off
	v_lshl_add_u64 v[154:155], s[46:47], 0, v[128:129]
	s_add_i32 m0, s48, 0x2000
	s_nop 0
	global_load_lds_dwordx4 v[154:155], off
	v_lshl_add_u64 v[154:155], v[228:229], 0, s[14:15]
	s_mov_b32 m0, s60
	s_nop 0
	global_load_lds_dwordx4 v[154:155], off
	v_lshl_add_u64 v[154:155], v[230:231], 0, s[14:15]
	s_mov_b32 m0, s61
	s_nop 0
	global_load_lds_dwordx4 v[154:155], off
	s_waitcnt vmcnt(8)
	s_waitcnt lgkmcnt(0)
	.p2align 3
	s_setprio 1
	s_barrier
	v_mfma_f32_16x16x32_bf16 v[60:63], v[160:163], v[194:197], v[60:63]
	v_mfma_f32_16x16x32_bf16 v[60:63], v[164:167], v[198:201], v[60:63]
	v_mfma_f32_16x16x32_bf16 v[52:55], v[172:175], v[198:201], v[52:55]
	v_mfma_f32_16x16x32_bf16 v[52:55], v[168:171], v[194:197], v[52:55]
	v_mfma_f32_16x16x32_bf16 v[36:39], v[168:171], v[202:205], v[36:39]
	v_mfma_f32_16x16x32_bf16 v[36:39], v[172:175], v[206:209], v[36:39]
	v_mfma_f32_16x16x32_bf16 v[44:47], v[164:167], v[206:209], v[44:47]
	v_mfma_f32_16x16x32_bf16 v[44:47], v[160:163], v[202:205], v[44:47]
	v_mfma_f32_16x16x32_bf16 v[28:31], v[160:163], v[210:213], v[28:31]
	v_mfma_f32_16x16x32_bf16 v[28:31], v[164:167], v[214:217], v[28:31]
	v_mfma_f32_16x16x32_bf16 v[20:23], v[172:175], v[214:217], v[20:23]
	v_mfma_f32_16x16x32_bf16 v[20:23], v[168:171], v[210:213], v[20:23]
	v_mfma_f32_16x16x32_bf16 v[4:7], v[168:171], v[218:221], v[4:7]
	v_mfma_f32_16x16x32_bf16 v[4:7], v[172:175], v[222:225], v[4:7]
	v_mfma_f32_16x16x32_bf16 v[12:15], v[164:167], v[222:225], v[12:15]
	v_mfma_f32_16x16x32_bf16 v[12:15], v[160:163], v[218:221], v[12:15]
	s_setprio 0
	s_setprio 1
	v_mfma_f32_16x16x32_bf16 v[56:59], v[176:179], v[194:197], v[56:59]
	v_mfma_f32_16x16x32_bf16 v[56:59], v[180:183], v[198:201], v[56:59]
	v_mfma_f32_16x16x32_bf16 v[48:51], v[190:193], v[198:201], v[48:51]
	v_mfma_f32_16x16x32_bf16 v[48:51], v[186:189], v[194:197], v[48:51]
	v_mfma_f32_16x16x32_bf16 v[32:35], v[186:189], v[202:205], v[32:35]
	v_mfma_f32_16x16x32_bf16 v[32:35], v[190:193], v[206:209], v[32:35]
	v_mfma_f32_16x16x32_bf16 v[40:43], v[180:183], v[206:209], v[40:43]
	v_mfma_f32_16x16x32_bf16 v[40:43], v[176:179], v[202:205], v[40:43]
	v_mfma_f32_16x16x32_bf16 v[24:27], v[176:179], v[210:213], v[24:27]
	v_mfma_f32_16x16x32_bf16 v[24:27], v[180:183], v[214:217], v[24:27]
	v_mfma_f32_16x16x32_bf16 v[16:19], v[190:193], v[214:217], v[16:19]
	v_mfma_f32_16x16x32_bf16 v[16:19], v[186:189], v[210:213], v[16:19]
	v_mfma_f32_16x16x32_bf16 v[0:3], v[186:189], v[218:221], v[0:3]
	v_mfma_f32_16x16x32_bf16 v[0:3], v[190:193], v[222:225], v[0:3]
	v_mfma_f32_16x16x32_bf16 v[8:11], v[180:183], v[222:225], v[8:11]
	v_mfma_f32_16x16x32_bf16 v[8:11], v[176:179], v[218:221], v[8:11]
	s_barrier
	s_setprio 0
	s_add_i32 s75, s75, 2
	s_add_u32 s71, s71, 0x100
	s_addc_u32 s74, s74, 0
	s_add_u32 s44, s44, 0x100
	s_addc_u32 s45, s45, 0
	s_branch .LBB0_76
.Lfa_0:
	v_add_u32_e32 v153, s64, v147
	ds_read_b128 v[160:163], v153
	v_xor_b32_e32 v253, 64, v153
	ds_read_b128 v[164:167], v253
	ds_read_b128 v[168:171], v153 offset:2048
	ds_read_b128 v[172:175], v253 offset:2048
	v_add_u32_e32 v153, s65, v147
	ds_read_b128 v[176:179], v153
	v_xor_b32_e32 v253, 64, v153
	ds_read_b128 v[180:183], v253
	ds_read_b128 v[186:189], v153 offset:2048
	ds_read_b128 v[190:193], v253 offset:2048
	s_add_u32 s48, s44, 0xfffc0080
	s_addc_u32 s49, s45, -1
	s_and_b64 s[46:47], s[46:47], exec
	s_cselect_b32 s49, s27, s49
	s_cselect_b32 s48, s68, s48
	s_cselect_b32 s47, s69, s74
	s_cselect_b32 s46, s70, s71
	v_lshl_add_u64 v[154:155], s[44:45], 0, v[138:139]
	s_add_i32 m0, s55, 0xc000
	ds_read_b128 v[194:197], v150
	v_xor_b32_e32 v253, 64, v150
	ds_read_b128 v[198:201], v253
	ds_read_b128 v[202:205], v150 offset:2048
	ds_read_b128 v[206:209], v253 offset:2048
	ds_read_b128 v[210:213], v150 offset:4096
	ds_read_b128 v[214:217], v253 offset:4096
	ds_read_b128 v[218:221], v150 offset:6144
	ds_read_b128 v[222:225], v253 offset:6144
	global_load_lds_dwordx4 v[154:155], off
	v_lshl_add_u64 v[154:155], s[44:45], 0, v[136:137]
	s_add_i32 m0, s55, 0xe000
	s_nop 0
	global_load_lds_dwordx4 v[154:155], off
	s_waitcnt vmcnt(8)
	s_waitcnt lgkmcnt(0)
	.p2align 3
	s_setprio 1
	s_barrier
	v_mfma_f32_16x16x32_bf16 v[124:127], v[160:163], v[194:197], 0
	v_mfma_f32_16x16x32_bf16 v[116:119], v[168:171], v[194:197], 0
	v_mfma_f32_16x16x32_bf16 v[108:111], v[160:163], v[202:205], 0
	v_mfma_f32_16x16x32_bf16 v[100:103], v[168:171], v[202:205], 0
	v_mfma_f32_16x16x32_bf16 v[92:95], v[160:163], v[210:213], 0
	v_mfma_f32_16x16x32_bf16 v[84:87], v[168:171], v[210:213], 0
	v_mfma_f32_16x16x32_bf16 v[76:79], v[160:163], v[218:221], 0
	v_mfma_f32_16x16x32_bf16 v[68:71], v[168:171], v[218:221], 0
	v_mfma_f32_16x16x32_bf16 v[124:127], v[164:167], v[198:201], v[124:127]
	v_mfma_f32_16x16x32_bf16 v[116:119], v[172:175], v[198:201], v[116:119]
	v_mfma_f32_16x16x32_bf16 v[108:111], v[164:167], v[206:209], v[108:111]
	v_mfma_f32_16x16x32_bf16 v[100:103], v[172:175], v[206:209], v[100:103]
	v_mfma_f32_16x16x32_bf16 v[92:95], v[164:167], v[214:217], v[92:95]
	v_mfma_f32_16x16x32_bf16 v[84:87], v[172:175], v[214:217], v[84:87]
	v_mfma_f32_16x16x32_bf16 v[76:79], v[164:167], v[222:225], v[76:79]
	v_mfma_f32_16x16x32_bf16 v[68:71], v[172:175], v[222:225], v[68:71]
	s_setprio 0
	s_setprio 1
	v_mfma_f32_16x16x32_bf16 v[120:123], v[176:179], v[194:197], 0
	v_mfma_f32_16x16x32_bf16 v[112:115], v[186:189], v[194:197], 0
	v_mfma_f32_16x16x32_bf16 v[104:107], v[176:179], v[202:205], 0
	v_mfma_f32_16x16x32_bf16 v[96:99], v[186:189], v[202:205], 0
	v_mfma_f32_16x16x32_bf16 v[88:91], v[176:179], v[210:213], 0
	v_mfma_f32_16x16x32_bf16 v[80:83], v[186:189], v[210:213], 0
	v_mfma_f32_16x16x32_bf16 v[72:75], v[176:179], v[218:221], 0
	v_mfma_f32_16x16x32_bf16 v[64:67], v[186:189], v[218:221], 0
	v_mfma_f32_16x16x32_bf16 v[120:123], v[180:183], v[198:201], v[120:123]
	v_mfma_f32_16x16x32_bf16 v[112:115], v[190:193], v[198:201], v[112:115]
	v_mfma_f32_16x16x32_bf16 v[104:107], v[180:183], v[206:209], v[104:107]
	v_mfma_f32_16x16x32_bf16 v[96:99], v[190:193], v[206:209], v[96:99]
	v_mfma_f32_16x16x32_bf16 v[88:91], v[180:183], v[214:217], v[88:91]
	v_mfma_f32_16x16x32_bf16 v[80:83], v[190:193], v[214:217], v[80:83]
	v_mfma_f32_16x16x32_bf16 v[72:75], v[180:183], v[222:225], v[72:75]
	v_mfma_f32_16x16x32_bf16 v[64:67], v[190:193], v[222:225], v[64:67]
	s_barrier
	s_setprio 0
	s_add_i32 s76, s64, s52
	v_lshl_add_u64 v[154:155], s[46:47], 0, v[132:133]
	s_mov_b32 m0, s76
	ds_read_b128 v[194:197], v150 offset:16384
	v_xor_b32_e32 v253, 64, v150
	ds_read_b128 v[198:201], v253 offset:16384
	ds_read_b128 v[202:205], v150 offset:18432
	ds_read_b128 v[206:209], v253 offset:18432
	ds_read_b128 v[210:213], v150 offset:20480
	ds_read_b128 v[214:217], v253 offset:20480
	ds_read_b128 v[218:221], v150 offset:22528
	ds_read_b128 v[222:225], v253 offset:22528
	global_load_lds_dwordx4 v[154:155], off
	s_add_i32 m0, s76, 0x2000
	s_add_u32 s76, s46, 0x40000
	v_lshl_add_u64 v[226:227], s[46:47], 0, v[128:129]
	s_addc_u32 s77, s47, 0
	s_add_i32 s78, s65, s52
	global_load_lds_dwordx4 v[226:227], off
	v_lshl_add_u64 v[228:229], s[76:77], 0, v[132:133]
	s_mov_b32 m0, s78
	v_lshl_add_u64 v[230:231], s[48:49], 0, v[130:131]
	global_load_lds_dwordx4 v[228:229], off
	v_lshl_add_u64 v[228:229], s[76:77], 0, v[128:129]
	s_add_i32 m0, s78, 0x2000
	s_nop 0
	global_load_lds_dwordx4 v[228:229], off
	v_lshl_add_u64 v[228:229], s[48:49], 0, v[134:135]
	s_mov_b32 m0, s55
	s_nop 0
	global_load_lds_dwordx4 v[228:229], off
	s_mov_b32 m0, s56
	s_nop 0
	global_load_lds_dwordx4 v[230:231], off
	s_waitcnt vmcnt(8)
	s_waitcnt lgkmcnt(0)
	.p2align 3
	s_setprio 1
	s_barrier
	v_mfma_f32_16x16x32_bf16 v[60:63], v[160:163], v[194:197], 0
	v_mfma_f32_16x16x32_bf16 v[52:55], v[168:171], v[194:197], 0
	v_mfma_f32_16x16x32_bf16 v[44:47], v[160:163], v[202:205], 0
	v_mfma_f32_16x16x32_bf16 v[36:39], v[168:171], v[202:205], 0
	v_mfma_f32_16x16x32_bf16 v[28:31], v[160:163], v[210:213], 0
	v_mfma_f32_16x16x32_bf16 v[20:23], v[168:171], v[210:213], 0
	v_mfma_f32_16x16x32_bf16 v[12:15], v[160:163], v[218:221], 0
	v_mfma_f32_16x16x32_bf16 v[4:7], v[168:171], v[218:221], 0
	v_mfma_f32_16x16x32_bf16 v[60:63], v[164:167], v[198:201], v[60:63]
	v_mfma_f32_16x16x32_bf16 v[52:55], v[172:175], v[198:201], v[52:55]
	v_mfma_f32_16x16x32_bf16 v[44:47], v[164:167], v[206:209], v[44:47]
	v_mfma_f32_16x16x32_bf16 v[36:39], v[172:175], v[206:209], v[36:39]
	v_mfma_f32_16x16x32_bf16 v[28:31], v[164:167], v[214:217], v[28:31]
	v_mfma_f32_16x16x32_bf16 v[20:23], v[172:175], v[214:217], v[20:23]
	v_mfma_f32_16x16x32_bf16 v[12:15], v[164:167], v[222:225], v[12:15]
	v_mfma_f32_16x16x32_bf16 v[4:7], v[172:175], v[222:225], v[4:7]
	s_setprio 0
	s_setprio 1
	v_mfma_f32_16x16x32_bf16 v[56:59], v[176:179], v[194:197], 0
	v_mfma_f32_16x16x32_bf16 v[48:51], v[186:189], v[194:197], 0
	v_mfma_f32_16x16x32_bf16 v[40:43], v[176:179], v[202:205], 0
	v_mfma_f32_16x16x32_bf16 v[32:35], v[186:189], v[202:205], 0
	v_mfma_f32_16x16x32_bf16 v[24:27], v[176:179], v[210:213], 0
	v_mfma_f32_16x16x32_bf16 v[16:19], v[186:189], v[210:213], 0
	v_mfma_f32_16x16x32_bf16 v[8:11], v[176:179], v[218:221], 0
	v_mfma_f32_16x16x32_bf16 v[0:3], v[186:189], v[218:221], 0
	v_mfma_f32_16x16x32_bf16 v[56:59], v[180:183], v[198:201], v[56:59]
	v_mfma_f32_16x16x32_bf16 v[48:51], v[190:193], v[198:201], v[48:51]
	v_mfma_f32_16x16x32_bf16 v[40:43], v[180:183], v[206:209], v[40:43]
	v_mfma_f32_16x16x32_bf16 v[32:35], v[190:193], v[206:209], v[32:35]
	v_mfma_f32_16x16x32_bf16 v[24:27], v[180:183], v[214:217], v[24:27]
	v_mfma_f32_16x16x32_bf16 v[16:19], v[190:193], v[214:217], v[16:19]
	v_mfma_f32_16x16x32_bf16 v[8:11], v[180:183], v[222:225], v[8:11]
	v_mfma_f32_16x16x32_bf16 v[0:3], v[190:193], v[222:225], v[0:3]
	s_barrier
	s_setprio 0
	s_add_i32 s76, 0, 0x18000
	v_add_u32_e32 v153, s76, v147
	s_add_i32 s77, 0, 0x1c000
	ds_read_b128 v[160:163], v153
	v_xor_b32_e32 v253, 64, v153
	ds_read_b128 v[164:167], v253
	ds_read_b128 v[168:171], v153 offset:2048
	ds_read_b128 v[172:175], v253 offset:2048
	v_add_u32_e32 v153, s77, v147
	ds_read_b128 v[176:179], v153
	v_xor_b32_e32 v253, 64, v153
	ds_read_b128 v[180:183], v253
	ds_read_b128 v[186:189], v153 offset:2048
	ds_read_b128 v[190:193], v253 offset:2048
	s_add_u32 s48, s48, 0x40000
	s_addc_u32 s49, s49, 0
	s_mov_b32 m0, s57
	v_lshl_add_u64 v[232:233], s[48:49], 0, v[134:135]
	ds_read_b128 v[194:197], v150 offset:32768
	v_xor_b32_e32 v253, 64, v150
	ds_read_b128 v[198:201], v253 offset:32768
	ds_read_b128 v[202:205], v150 offset:34816
	ds_read_b128 v[206:209], v253 offset:34816
	ds_read_b128 v[210:213], v150 offset:36864
	ds_read_b128 v[214:217], v253 offset:36864
	ds_read_b128 v[218:221], v150 offset:38912
	ds_read_b128 v[222:225], v253 offset:38912
	global_load_lds_dwordx4 v[232:233], off
	v_lshl_add_u64 v[232:233], s[48:49], 0, v[130:131]
	s_mov_b32 m0, s58
	s_nop 0
	global_load_lds_dwordx4 v[232:233], off
	s_waitcnt vmcnt(8)
	s_waitcnt lgkmcnt(0)
	.p2align 3
	s_setprio 1
	s_barrier
	v_mfma_f32_16x16x32_bf16 v[124:127], v[160:163], v[194:197], v[124:127]
	v_mfma_f32_16x16x32_bf16 v[124:127], v[164:167], v[198:201], v[124:127]
	v_mfma_f32_16x16x32_bf16 v[116:119], v[172:175], v[198:201], v[116:119]
	v_mfma_f32_16x16x32_bf16 v[116:119], v[168:171], v[194:197], v[116:119]
	v_mfma_f32_16x16x32_bf16 v[100:103], v[168:171], v[202:205], v[100:103]
	v_mfma_f32_16x16x32_bf16 v[100:103], v[172:175], v[206:209], v[100:103]
	v_mfma_f32_16x16x32_bf16 v[108:111], v[164:167], v[206:209], v[108:111]
	v_mfma_f32_16x16x32_bf16 v[108:111], v[160:163], v[202:205], v[108:111]
	v_mfma_f32_16x16x32_bf16 v[92:95], v[160:163], v[210:213], v[92:95]
	v_mfma_f32_16x16x32_bf16 v[92:95], v[164:167], v[214:217], v[92:95]
	v_mfma_f32_16x16x32_bf16 v[84:87], v[172:175], v[214:217], v[84:87]
	v_mfma_f32_16x16x32_bf16 v[84:87], v[168:171], v[210:213], v[84:87]
	v_mfma_f32_16x16x32_bf16 v[68:71], v[168:171], v[218:221], v[68:71]
	v_mfma_f32_16x16x32_bf16 v[68:71], v[172:175], v[222:225], v[68:71]
	v_mfma_f32_16x16x32_bf16 v[76:79], v[164:167], v[222:225], v[76:79]
	v_mfma_f32_16x16x32_bf16 v[76:79], v[160:163], v[218:221], v[76:79]
	s_setprio 0
	s_setprio 1
	v_mfma_f32_16x16x32_bf16 v[120:123], v[176:179], v[194:197], v[120:123]
	v_mfma_f32_16x16x32_bf16 v[120:123], v[180:183], v[198:201], v[120:123]
	v_mfma_f32_16x16x32_bf16 v[112:115], v[190:193], v[198:201], v[112:115]
	v_mfma_f32_16x16x32_bf16 v[112:115], v[186:189], v[194:197], v[112:115]
	v_mfma_f32_16x16x32_bf16 v[96:99], v[186:189], v[202:205], v[96:99]
	v_mfma_f32_16x16x32_bf16 v[96:99], v[190:193], v[206:209], v[96:99]
	v_mfma_f32_16x16x32_bf16 v[104:107], v[180:183], v[206:209], v[104:107]
	v_mfma_f32_16x16x32_bf16 v[104:107], v[176:179], v[202:205], v[104:107]
	v_mfma_f32_16x16x32_bf16 v[88:91], v[176:179], v[210:213], v[88:91]
	v_mfma_f32_16x16x32_bf16 v[88:91], v[180:183], v[214:217], v[88:91]
	v_mfma_f32_16x16x32_bf16 v[80:83], v[190:193], v[214:217], v[80:83]
	v_mfma_f32_16x16x32_bf16 v[80:83], v[186:189], v[210:213], v[80:83]
	v_mfma_f32_16x16x32_bf16 v[64:67], v[186:189], v[218:221], v[64:67]
	v_mfma_f32_16x16x32_bf16 v[64:67], v[190:193], v[222:225], v[64:67]
	v_mfma_f32_16x16x32_bf16 v[72:75], v[180:183], v[222:225], v[72:75]
	v_mfma_f32_16x16x32_bf16 v[72:75], v[176:179], v[218:221], v[72:75]
	s_barrier
	s_setprio 0
	s_add_i32 s48, s76, s52
	v_lshl_add_u64 v[154:155], v[154:155], 0, s[14:15]
	s_mov_b32 m0, s48
	ds_read_b128 v[194:197], v150 offset:49152
	v_xor_b32_e32 v253, 64, v150
	ds_read_b128 v[198:201], v253 offset:49152
	ds_read_b128 v[202:205], v150 offset:51200
	ds_read_b128 v[206:209], v253 offset:51200
	ds_read_b128 v[210:213], v150 offset:53248
	ds_read_b128 v[214:217], v253 offset:53248
	ds_read_b128 v[218:221], v150 offset:55296
	ds_read_b128 v[222:225], v253 offset:55296
	global_load_lds_dwordx4 v[154:155], off
	s_add_i32 m0, s48, 0x2000
	s_add_u32 s46, s46, 0x40080
	v_lshl_add_u64 v[154:155], v[226:227], 0, s[14:15]
	s_addc_u32 s47, s47, 0
	s_add_i32 s48, s77, s52
	global_load_lds_dwordx4 v[154:155], off
	v_lshl_add_u64 v[154:155], s[46:47], 0, v[132:133]
	s_mov_b32 m0, s48
	s_nop 0
	global_load_lds_dwordx4 v[154:155], off
	v_lshl_add_u64 v[154:155], s[46:47], 0, v[128:129]
	s_add_i32 m0, s48, 0x2000
	s_nop 0
	global_load_lds_dwordx4 v[154:155], off
	v_lshl_add_u64 v[154:155], v[228:229], 0, s[14:15]
	s_mov_b32 m0, s60
	s_nop 0
	global_load_lds_dwordx4 v[154:155], off
	v_lshl_add_u64 v[154:155], v[230:231], 0, s[14:15]
	s_mov_b32 m0, s61
	s_nop 0
	global_load_lds_dwordx4 v[154:155], off
	s_waitcnt vmcnt(8)
	s_waitcnt lgkmcnt(0)
	.p2align 3
	s_setprio 1
	s_barrier
	v_mfma_f32_16x16x32_bf16 v[60:63], v[160:163], v[194:197], v[60:63]
	v_mfma_f32_16x16x32_bf16 v[60:63], v[164:167], v[198:201], v[60:63]
	v_mfma_f32_16x16x32_bf16 v[52:55], v[172:175], v[198:201], v[52:55]
	v_mfma_f32_16x16x32_bf16 v[52:55], v[168:171], v[194:197], v[52:55]
	v_mfma_f32_16x16x32_bf16 v[36:39], v[168:171], v[202:205], v[36:39]
	v_mfma_f32_16x16x32_bf16 v[36:39], v[172:175], v[206:209], v[36:39]
	v_mfma_f32_16x16x32_bf16 v[44:47], v[164:167], v[206:209], v[44:47]
	v_mfma_f32_16x16x32_bf16 v[44:47], v[160:163], v[202:205], v[44:47]
	v_mfma_f32_16x16x32_bf16 v[28:31], v[160:163], v[210:213], v[28:31]
	v_mfma_f32_16x16x32_bf16 v[28:31], v[164:167], v[214:217], v[28:31]
	v_mfma_f32_16x16x32_bf16 v[20:23], v[172:175], v[214:217], v[20:23]
	v_mfma_f32_16x16x32_bf16 v[20:23], v[168:171], v[210:213], v[20:23]
	v_mfma_f32_16x16x32_bf16 v[4:7], v[168:171], v[218:221], v[4:7]
	v_mfma_f32_16x16x32_bf16 v[4:7], v[172:175], v[222:225], v[4:7]
	v_mfma_f32_16x16x32_bf16 v[12:15], v[164:167], v[222:225], v[12:15]
	v_mfma_f32_16x16x32_bf16 v[12:15], v[160:163], v[218:221], v[12:15]
	s_setprio 0
	s_setprio 1
	v_mfma_f32_16x16x32_bf16 v[56:59], v[176:179], v[194:197], v[56:59]
	v_mfma_f32_16x16x32_bf16 v[56:59], v[180:183], v[198:201], v[56:59]
	v_mfma_f32_16x16x32_bf16 v[48:51], v[190:193], v[198:201], v[48:51]
	v_mfma_f32_16x16x32_bf16 v[48:51], v[186:189], v[194:197], v[48:51]
	v_mfma_f32_16x16x32_bf16 v[32:35], v[186:189], v[202:205], v[32:35]
	v_mfma_f32_16x16x32_bf16 v[32:35], v[190:193], v[206:209], v[32:35]
	v_mfma_f32_16x16x32_bf16 v[40:43], v[180:183], v[206:209], v[40:43]
	v_mfma_f32_16x16x32_bf16 v[40:43], v[176:179], v[202:205], v[40:43]
	v_mfma_f32_16x16x32_bf16 v[24:27], v[176:179], v[210:213], v[24:27]
	v_mfma_f32_16x16x32_bf16 v[24:27], v[180:183], v[214:217], v[24:27]
	v_mfma_f32_16x16x32_bf16 v[16:19], v[190:193], v[214:217], v[16:19]
	v_mfma_f32_16x16x32_bf16 v[16:19], v[186:189], v[210:213], v[16:19]
	v_mfma_f32_16x16x32_bf16 v[0:3], v[186:189], v[218:221], v[0:3]
	v_mfma_f32_16x16x32_bf16 v[0:3], v[190:193], v[222:225], v[0:3]
	v_mfma_f32_16x16x32_bf16 v[8:11], v[180:183], v[222:225], v[8:11]
	v_mfma_f32_16x16x32_bf16 v[8:11], v[176:179], v[218:221], v[8:11]
	s_barrier
	s_setprio 0
	s_add_i32 s75, s75, 2
	s_add_u32 s71, s71, 0x100
	s_addc_u32 s74, s74, 0
	s_add_u32 s44, s44, 0x100
	s_addc_u32 s45, s45, 0
	s_branch .LBB0_76
.LBB0_75:
	v_add_u32_e32 v153, s64, v147
	ds_read_b128 v[160:163], v153
	v_xor_b32_e32 v253, 64, v153
	ds_read_b128 v[164:167], v253
	ds_read_b128 v[168:171], v153 offset:2048
	ds_read_b128 v[172:175], v253 offset:2048
	v_add_u32_e32 v153, s65, v147
	ds_read_b128 v[176:179], v153
	v_xor_b32_e32 v253, 64, v153
	ds_read_b128 v[180:183], v253
	ds_read_b128 v[186:189], v153 offset:2048
	ds_read_b128 v[190:193], v253 offset:2048
	s_add_u32 s48, s44, 0xfffc0080
	s_addc_u32 s49, s45, -1
	s_and_b64 s[46:47], s[46:47], exec
	s_cselect_b32 s49, s27, s49
	s_cselect_b32 s48, s68, s48
	s_cselect_b32 s47, s69, s74
	s_cselect_b32 s46, s70, s71
	v_lshl_add_u64 v[154:155], s[44:45], 0, v[138:139]
	s_add_i32 m0, s55, 0xc000
	ds_read_b128 v[194:197], v150
	v_xor_b32_e32 v253, 64, v150
	ds_read_b128 v[198:201], v253
	ds_read_b128 v[202:205], v150 offset:2048
	ds_read_b128 v[206:209], v253 offset:2048
	ds_read_b128 v[210:213], v150 offset:4096
	ds_read_b128 v[214:217], v253 offset:4096
	ds_read_b128 v[218:221], v150 offset:6144
	ds_read_b128 v[222:225], v253 offset:6144
	global_load_lds_dwordx4 v[154:155], off
	v_lshl_add_u64 v[154:155], s[44:45], 0, v[136:137]
	s_add_i32 m0, s55, 0xe000
	s_nop 0
	global_load_lds_dwordx4 v[154:155], off
	s_waitcnt vmcnt(8)
	s_waitcnt lgkmcnt(0)
	.p2align 3
	s_setprio 1
	s_barrier
	v_mfma_f32_16x16x32_bf16 v[124:127], v[160:163], v[194:197], v[124:127]
	v_mfma_f32_16x16x32_bf16 v[124:127], v[164:167], v[198:201], v[124:127]
	v_mfma_f32_16x16x32_bf16 v[116:119], v[172:175], v[198:201], v[116:119]
	v_mfma_f32_16x16x32_bf16 v[116:119], v[168:171], v[194:197], v[116:119]
	v_mfma_f32_16x16x32_bf16 v[100:103], v[168:171], v[202:205], v[100:103]
	v_mfma_f32_16x16x32_bf16 v[100:103], v[172:175], v[206:209], v[100:103]
	v_mfma_f32_16x16x32_bf16 v[108:111], v[164:167], v[206:209], v[108:111]
	v_mfma_f32_16x16x32_bf16 v[108:111], v[160:163], v[202:205], v[108:111]
	v_mfma_f32_16x16x32_bf16 v[92:95], v[160:163], v[210:213], v[92:95]
	v_mfma_f32_16x16x32_bf16 v[92:95], v[164:167], v[214:217], v[92:95]
	v_mfma_f32_16x16x32_bf16 v[84:87], v[172:175], v[214:217], v[84:87]
	v_mfma_f32_16x16x32_bf16 v[84:87], v[168:171], v[210:213], v[84:87]
	v_mfma_f32_16x16x32_bf16 v[68:71], v[168:171], v[218:221], v[68:71]
	v_mfma_f32_16x16x32_bf16 v[68:71], v[172:175], v[222:225], v[68:71]
	v_mfma_f32_16x16x32_bf16 v[76:79], v[164:167], v[222:225], v[76:79]
	v_mfma_f32_16x16x32_bf16 v[76:79], v[160:163], v[218:221], v[76:79]
	s_setprio 0
	s_setprio 1
	v_mfma_f32_16x16x32_bf16 v[120:123], v[176:179], v[194:197], v[120:123]
	v_mfma_f32_16x16x32_bf16 v[120:123], v[180:183], v[198:201], v[120:123]
	v_mfma_f32_16x16x32_bf16 v[112:115], v[190:193], v[198:201], v[112:115]
	v_mfma_f32_16x16x32_bf16 v[112:115], v[186:189], v[194:197], v[112:115]
	v_mfma_f32_16x16x32_bf16 v[96:99], v[186:189], v[202:205], v[96:99]
	v_mfma_f32_16x16x32_bf16 v[96:99], v[190:193], v[206:209], v[96:99]
	v_mfma_f32_16x16x32_bf16 v[104:107], v[180:183], v[206:209], v[104:107]
	v_mfma_f32_16x16x32_bf16 v[104:107], v[176:179], v[202:205], v[104:107]
	v_mfma_f32_16x16x32_bf16 v[88:91], v[176:179], v[210:213], v[88:91]
	v_mfma_f32_16x16x32_bf16 v[88:91], v[180:183], v[214:217], v[88:91]
	v_mfma_f32_16x16x32_bf16 v[80:83], v[190:193], v[214:217], v[80:83]
	v_mfma_f32_16x16x32_bf16 v[80:83], v[186:189], v[210:213], v[80:83]
	v_mfma_f32_16x16x32_bf16 v[64:67], v[186:189], v[218:221], v[64:67]
	v_mfma_f32_16x16x32_bf16 v[64:67], v[190:193], v[222:225], v[64:67]
	v_mfma_f32_16x16x32_bf16 v[72:75], v[180:183], v[222:225], v[72:75]
	v_mfma_f32_16x16x32_bf16 v[72:75], v[176:179], v[218:221], v[72:75]
	s_barrier
	s_setprio 0
	s_add_i32 s76, s64, s52
	v_lshl_add_u64 v[154:155], s[46:47], 0, v[132:133]
	s_mov_b32 m0, s76
	ds_read_b128 v[194:197], v150 offset:16384
	v_xor_b32_e32 v253, 64, v150
	ds_read_b128 v[198:201], v253 offset:16384
	ds_read_b128 v[202:205], v150 offset:18432
	ds_read_b128 v[206:209], v253 offset:18432
	ds_read_b128 v[210:213], v150 offset:20480
	ds_read_b128 v[214:217], v253 offset:20480
	ds_read_b128 v[218:221], v150 offset:22528
	ds_read_b128 v[222:225], v253 offset:22528
	global_load_lds_dwordx4 v[154:155], off
	s_add_i32 m0, s76, 0x2000
	s_add_u32 s76, s46, 0x40000
	v_lshl_add_u64 v[226:227], s[46:47], 0, v[128:129]
	s_addc_u32 s77, s47, 0
	s_add_i32 s78, s65, s52
	global_load_lds_dwordx4 v[226:227], off
	v_lshl_add_u64 v[228:229], s[76:77], 0, v[132:133]
	s_mov_b32 m0, s78
	v_lshl_add_u64 v[230:231], s[48:49], 0, v[130:131]
	global_load_lds_dwordx4 v[228:229], off
	v_lshl_add_u64 v[228:229], s[76:77], 0, v[128:129]
	s_add_i32 m0, s78, 0x2000
	s_nop 0
	global_load_lds_dwordx4 v[228:229], off
	v_lshl_add_u64 v[228:229], s[48:49], 0, v[134:135]
	s_mov_b32 m0, s55
	s_nop 0
	global_load_lds_dwordx4 v[228:229], off
	s_mov_b32 m0, s56
	s_nop 0
	global_load_lds_dwordx4 v[230:231], off
	s_waitcnt vmcnt(8)
	s_waitcnt lgkmcnt(0)
	.p2align 3
	s_setprio 1
	s_barrier
	v_mfma_f32_16x16x32_bf16 v[60:63], v[160:163], v[194:197], v[60:63]
	v_mfma_f32_16x16x32_bf16 v[60:63], v[164:167], v[198:201], v[60:63]
	v_mfma_f32_16x16x32_bf16 v[52:55], v[172:175], v[198:201], v[52:55]
	v_mfma_f32_16x16x32_bf16 v[52:55], v[168:171], v[194:197], v[52:55]
	v_mfma_f32_16x16x32_bf16 v[36:39], v[168:171], v[202:205], v[36:39]
	v_mfma_f32_16x16x32_bf16 v[36:39], v[172:175], v[206:209], v[36:39]
	v_mfma_f32_16x16x32_bf16 v[44:47], v[164:167], v[206:209], v[44:47]
	v_mfma_f32_16x16x32_bf16 v[44:47], v[160:163], v[202:205], v[44:47]
	v_mfma_f32_16x16x32_bf16 v[28:31], v[160:163], v[210:213], v[28:31]
	v_mfma_f32_16x16x32_bf16 v[28:31], v[164:167], v[214:217], v[28:31]
	v_mfma_f32_16x16x32_bf16 v[20:23], v[172:175], v[214:217], v[20:23]
	v_mfma_f32_16x16x32_bf16 v[20:23], v[168:171], v[210:213], v[20:23]
	v_mfma_f32_16x16x32_bf16 v[4:7], v[168:171], v[218:221], v[4:7]
	v_mfma_f32_16x16x32_bf16 v[4:7], v[172:175], v[222:225], v[4:7]
	v_mfma_f32_16x16x32_bf16 v[12:15], v[164:167], v[222:225], v[12:15]
	v_mfma_f32_16x16x32_bf16 v[12:15], v[160:163], v[218:221], v[12:15]
	s_setprio 0
	s_setprio 1
	v_mfma_f32_16x16x32_bf16 v[56:59], v[176:179], v[194:197], v[56:59]
	v_mfma_f32_16x16x32_bf16 v[56:59], v[180:183], v[198:201], v[56:59]
	v_mfma_f32_16x16x32_bf16 v[48:51], v[190:193], v[198:201], v[48:51]
	v_mfma_f32_16x16x32_bf16 v[48:51], v[186:189], v[194:197], v[48:51]
	v_mfma_f32_16x16x32_bf16 v[32:35], v[186:189], v[202:205], v[32:35]
	v_mfma_f32_16x16x32_bf16 v[32:35], v[190:193], v[206:209], v[32:35]
	v_mfma_f32_16x16x32_bf16 v[40:43], v[180:183], v[206:209], v[40:43]
	v_mfma_f32_16x16x32_bf16 v[40:43], v[176:179], v[202:205], v[40:43]
	v_mfma_f32_16x16x32_bf16 v[24:27], v[176:179], v[210:213], v[24:27]
	v_mfma_f32_16x16x32_bf16 v[24:27], v[180:183], v[214:217], v[24:27]
	v_mfma_f32_16x16x32_bf16 v[16:19], v[190:193], v[214:217], v[16:19]
	v_mfma_f32_16x16x32_bf16 v[16:19], v[186:189], v[210:213], v[16:19]
	v_mfma_f32_16x16x32_bf16 v[0:3], v[186:189], v[218:221], v[0:3]
	v_mfma_f32_16x16x32_bf16 v[0:3], v[190:193], v[222:225], v[0:3]
	v_mfma_f32_16x16x32_bf16 v[8:11], v[180:183], v[222:225], v[8:11]
	v_mfma_f32_16x16x32_bf16 v[8:11], v[176:179], v[218:221], v[8:11]
	s_barrier
	s_setprio 0
	s_add_i32 s76, 0, 0x18000
	v_add_u32_e32 v153, s76, v147
	s_add_i32 s77, 0, 0x1c000
	ds_read_b128 v[160:163], v153
	v_xor_b32_e32 v253, 64, v153
	ds_read_b128 v[164:167], v253
	ds_read_b128 v[168:171], v153 offset:2048
	ds_read_b128 v[172:175], v253 offset:2048
	v_add_u32_e32 v153, s77, v147
	ds_read_b128 v[176:179], v153
	v_xor_b32_e32 v253, 64, v153
	ds_read_b128 v[180:183], v253
	ds_read_b128 v[186:189], v153 offset:2048
	ds_read_b128 v[190:193], v253 offset:2048
	s_add_u32 s48, s48, 0x40000
	s_addc_u32 s49, s49, 0
	s_mov_b32 m0, s57
	v_lshl_add_u64 v[232:233], s[48:49], 0, v[134:135]
	ds_read_b128 v[194:197], v150 offset:32768
	v_xor_b32_e32 v253, 64, v150
	ds_read_b128 v[198:201], v253 offset:32768
	ds_read_b128 v[202:205], v150 offset:34816
	ds_read_b128 v[206:209], v253 offset:34816
	ds_read_b128 v[210:213], v150 offset:36864
	ds_read_b128 v[214:217], v253 offset:36864
	ds_read_b128 v[218:221], v150 offset:38912
	ds_read_b128 v[222:225], v253 offset:38912
	global_load_lds_dwordx4 v[232:233], off
	v_lshl_add_u64 v[232:233], s[48:49], 0, v[130:131]
	s_mov_b32 m0, s58
	s_nop 0
	global_load_lds_dwordx4 v[232:233], off
	s_waitcnt vmcnt(8)
	s_waitcnt lgkmcnt(0)
	.p2align 3
	s_setprio 1
	s_barrier
	v_mfma_f32_16x16x32_bf16 v[124:127], v[160:163], v[194:197], v[124:127]
	v_mfma_f32_16x16x32_bf16 v[124:127], v[164:167], v[198:201], v[124:127]
	v_mfma_f32_16x16x32_bf16 v[116:119], v[172:175], v[198:201], v[116:119]
	v_mfma_f32_16x16x32_bf16 v[116:119], v[168:171], v[194:197], v[116:119]
	v_mfma_f32_16x16x32_bf16 v[100:103], v[168:171], v[202:205], v[100:103]
	v_mfma_f32_16x16x32_bf16 v[100:103], v[172:175], v[206:209], v[100:103]
	v_mfma_f32_16x16x32_bf16 v[108:111], v[164:167], v[206:209], v[108:111]
	v_mfma_f32_16x16x32_bf16 v[108:111], v[160:163], v[202:205], v[108:111]
	v_mfma_f32_16x16x32_bf16 v[92:95], v[160:163], v[210:213], v[92:95]
	v_mfma_f32_16x16x32_bf16 v[92:95], v[164:167], v[214:217], v[92:95]
	v_mfma_f32_16x16x32_bf16 v[84:87], v[172:175], v[214:217], v[84:87]
	v_mfma_f32_16x16x32_bf16 v[84:87], v[168:171], v[210:213], v[84:87]
	v_mfma_f32_16x16x32_bf16 v[68:71], v[168:171], v[218:221], v[68:71]
	v_mfma_f32_16x16x32_bf16 v[68:71], v[172:175], v[222:225], v[68:71]
	v_mfma_f32_16x16x32_bf16 v[76:79], v[164:167], v[222:225], v[76:79]
	v_mfma_f32_16x16x32_bf16 v[76:79], v[160:163], v[218:221], v[76:79]
	s_setprio 0
	s_setprio 1
	v_mfma_f32_16x16x32_bf16 v[120:123], v[176:179], v[194:197], v[120:123]
	v_mfma_f32_16x16x32_bf16 v[120:123], v[180:183], v[198:201], v[120:123]
	v_mfma_f32_16x16x32_bf16 v[112:115], v[190:193], v[198:201], v[112:115]
	v_mfma_f32_16x16x32_bf16 v[112:115], v[186:189], v[194:197], v[112:115]
	v_mfma_f32_16x16x32_bf16 v[96:99], v[186:189], v[202:205], v[96:99]
	v_mfma_f32_16x16x32_bf16 v[96:99], v[190:193], v[206:209], v[96:99]
	v_mfma_f32_16x16x32_bf16 v[104:107], v[180:183], v[206:209], v[104:107]
	v_mfma_f32_16x16x32_bf16 v[104:107], v[176:179], v[202:205], v[104:107]
	v_mfma_f32_16x16x32_bf16 v[88:91], v[176:179], v[210:213], v[88:91]
	v_mfma_f32_16x16x32_bf16 v[88:91], v[180:183], v[214:217], v[88:91]
	v_mfma_f32_16x16x32_bf16 v[80:83], v[190:193], v[214:217], v[80:83]
	v_mfma_f32_16x16x32_bf16 v[80:83], v[186:189], v[210:213], v[80:83]
	v_mfma_f32_16x16x32_bf16 v[64:67], v[186:189], v[218:221], v[64:67]
	v_mfma_f32_16x16x32_bf16 v[64:67], v[190:193], v[222:225], v[64:67]
	v_mfma_f32_16x16x32_bf16 v[72:75], v[180:183], v[222:225], v[72:75]
	v_mfma_f32_16x16x32_bf16 v[72:75], v[176:179], v[218:221], v[72:75]
	s_barrier
	s_setprio 0
	s_add_i32 s48, s76, s52
	v_lshl_add_u64 v[154:155], v[154:155], 0, s[14:15]
	s_mov_b32 m0, s48
	ds_read_b128 v[194:197], v150 offset:49152
	v_xor_b32_e32 v253, 64, v150
	ds_read_b128 v[198:201], v253 offset:49152
	ds_read_b128 v[202:205], v150 offset:51200
	ds_read_b128 v[206:209], v253 offset:51200
	ds_read_b128 v[210:213], v150 offset:53248
	ds_read_b128 v[214:217], v253 offset:53248
	ds_read_b128 v[218:221], v150 offset:55296
	ds_read_b128 v[222:225], v253 offset:55296
	global_load_lds_dwordx4 v[154:155], off
	s_add_i32 m0, s48, 0x2000
	s_add_u32 s46, s46, 0x40080
	v_lshl_add_u64 v[154:155], v[226:227], 0, s[14:15]
	s_addc_u32 s47, s47, 0
	s_add_i32 s48, s77, s52
	global_load_lds_dwordx4 v[154:155], off
	v_lshl_add_u64 v[154:155], s[46:47], 0, v[132:133]
	s_mov_b32 m0, s48
	s_nop 0
	global_load_lds_dwordx4 v[154:155], off
	v_lshl_add_u64 v[154:155], s[46:47], 0, v[128:129]
	s_add_i32 m0, s48, 0x2000
	s_nop 0
	global_load_lds_dwordx4 v[154:155], off
	v_lshl_add_u64 v[154:155], v[228:229], 0, s[14:15]
	s_mov_b32 m0, s60
	s_nop 0
	global_load_lds_dwordx4 v[154:155], off
	v_lshl_add_u64 v[154:155], v[230:231], 0, s[14:15]
	s_mov_b32 m0, s61
	s_nop 0
	global_load_lds_dwordx4 v[154:155], off
	s_waitcnt vmcnt(8)
	s_waitcnt lgkmcnt(0)
	.p2align 3
	s_setprio 1
	s_barrier
	v_mfma_f32_16x16x32_bf16 v[60:63], v[160:163], v[194:197], v[60:63]
	v_mfma_f32_16x16x32_bf16 v[60:63], v[164:167], v[198:201], v[60:63]
	v_mfma_f32_16x16x32_bf16 v[52:55], v[172:175], v[198:201], v[52:55]
	v_mfma_f32_16x16x32_bf16 v[52:55], v[168:171], v[194:197], v[52:55]
	v_mfma_f32_16x16x32_bf16 v[36:39], v[168:171], v[202:205], v[36:39]
	v_mfma_f32_16x16x32_bf16 v[36:39], v[172:175], v[206:209], v[36:39]
	v_mfma_f32_16x16x32_bf16 v[44:47], v[164:167], v[206:209], v[44:47]
	v_mfma_f32_16x16x32_bf16 v[44:47], v[160:163], v[202:205], v[44:47]
	v_mfma_f32_16x16x32_bf16 v[28:31], v[160:163], v[210:213], v[28:31]
	v_mfma_f32_16x16x32_bf16 v[28:31], v[164:167], v[214:217], v[28:31]
	v_mfma_f32_16x16x32_bf16 v[20:23], v[172:175], v[214:217], v[20:23]
	v_mfma_f32_16x16x32_bf16 v[20:23], v[168:171], v[210:213], v[20:23]
	v_mfma_f32_16x16x32_bf16 v[4:7], v[168:171], v[218:221], v[4:7]
	v_mfma_f32_16x16x32_bf16 v[4:7], v[172:175], v[222:225], v[4:7]
	v_mfma_f32_16x16x32_bf16 v[12:15], v[164:167], v[222:225], v[12:15]
	v_mfma_f32_16x16x32_bf16 v[12:15], v[160:163], v[218:221], v[12:15]
	s_setprio 0
	s_setprio 1
	v_mfma_f32_16x16x32_bf16 v[56:59], v[176:179], v[194:197], v[56:59]
	v_mfma_f32_16x16x32_bf16 v[56:59], v[180:183], v[198:201], v[56:59]
	v_mfma_f32_16x16x32_bf16 v[48:51], v[190:193], v[198:201], v[48:51]
	v_mfma_f32_16x16x32_bf16 v[48:51], v[186:189], v[194:197], v[48:51]
	v_mfma_f32_16x16x32_bf16 v[32:35], v[186:189], v[202:205], v[32:35]
	v_mfma_f32_16x16x32_bf16 v[32:35], v[190:193], v[206:209], v[32:35]
	v_mfma_f32_16x16x32_bf16 v[40:43], v[180:183], v[206:209], v[40:43]
	v_mfma_f32_16x16x32_bf16 v[40:43], v[176:179], v[202:205], v[40:43]
	v_mfma_f32_16x16x32_bf16 v[24:27], v[176:179], v[210:213], v[24:27]
	v_mfma_f32_16x16x32_bf16 v[24:27], v[180:183], v[214:217], v[24:27]
	v_mfma_f32_16x16x32_bf16 v[16:19], v[190:193], v[214:217], v[16:19]
	v_mfma_f32_16x16x32_bf16 v[16:19], v[186:189], v[210:213], v[16:19]
	v_mfma_f32_16x16x32_bf16 v[0:3], v[186:189], v[218:221], v[0:3]
	v_mfma_f32_16x16x32_bf16 v[0:3], v[190:193], v[222:225], v[0:3]
	v_mfma_f32_16x16x32_bf16 v[8:11], v[180:183], v[222:225], v[8:11]
	v_mfma_f32_16x16x32_bf16 v[8:11], v[176:179], v[218:221], v[8:11]
	s_barrier
	s_setprio 0
	s_add_i32 s75, s75, 2
	s_add_u32 s71, s71, 0x100
	s_addc_u32 s74, s74, 0
	s_add_u32 s44, s44, 0x100
	s_addc_u32 s45, s45, 0
	s_cmp_gt_u32 s75, 13
	s_cbranch_scc1 .LBB0_78

.Llast_0:
	v_add_u32_e32 v153, s64, v147
	ds_read_b128 v[160:163], v153
	v_xor_b32_e32 v253, 64, v153
	ds_read_b128 v[164:167], v253
	ds_read_b128 v[168:171], v153 offset:2048
	ds_read_b128 v[172:175], v253 offset:2048
	v_add_u32_e32 v153, s65, v147
	ds_read_b128 v[176:179], v153
	v_xor_b32_e32 v253, 64, v153
	ds_read_b128 v[180:183], v253
	ds_read_b128 v[186:189], v153 offset:2048
	ds_read_b128 v[190:193], v253 offset:2048
	s_add_u32 s48, s44, 0xfffc0080
	s_addc_u32 s49, s45, -1
	s_and_b64 s[46:47], s[46:47], exec
	s_cselect_b32 s49, s27, s49
	s_cselect_b32 s48, s68, s48
	s_cselect_b32 s47, s69, s74
	s_cselect_b32 s46, s70, s71
	v_lshl_add_u64 v[154:155], s[44:45], 0, v[138:139]
	s_add_i32 m0, s55, 0xc000
	ds_read_b128 v[194:197], v150
	v_xor_b32_e32 v253, 64, v150
	ds_read_b128 v[198:201], v253
	ds_read_b128 v[202:205], v150 offset:2048
	ds_read_b128 v[206:209], v253 offset:2048
	ds_read_b128 v[210:213], v150 offset:4096
	ds_read_b128 v[214:217], v253 offset:4096
	ds_read_b128 v[218:221], v150 offset:6144
	ds_read_b128 v[222:225], v253 offset:6144
	global_load_lds_dwordx4 v[154:155], off
	v_lshl_add_u64 v[154:155], s[44:45], 0, v[136:137]
	s_add_i32 m0, s55, 0xe000
	s_nop 0
	global_load_lds_dwordx4 v[154:155], off
	s_waitcnt vmcnt(8)
	s_waitcnt lgkmcnt(0)
	.p2align 3
	s_setprio 1
	s_barrier
	v_mfma_f32_16x16x32_bf16 v[124:127], v[160:163], v[194:197], v[124:127]
	v_mfma_f32_16x16x32_bf16 v[124:127], v[164:167], v[198:201], v[124:127]
	v_mfma_f32_16x16x32_bf16 v[116:119], v[172:175], v[198:201], v[116:119]
	v_mfma_f32_16x16x32_bf16 v[116:119], v[168:171], v[194:197], v[116:119]
	v_mfma_f32_16x16x32_bf16 v[100:103], v[168:171], v[202:205], v[100:103]
	v_mfma_f32_16x16x32_bf16 v[100:103], v[172:175], v[206:209], v[100:103]
	v_mfma_f32_16x16x32_bf16 v[108:111], v[164:167], v[206:209], v[108:111]
	v_mfma_f32_16x16x32_bf16 v[108:111], v[160:163], v[202:205], v[108:111]
	v_mfma_f32_16x16x32_bf16 v[92:95], v[160:163], v[210:213], v[92:95]
	v_mfma_f32_16x16x32_bf16 v[92:95], v[164:167], v[214:217], v[92:95]
	v_mfma_f32_16x16x32_bf16 v[84:87], v[172:175], v[214:217], v[84:87]
	v_mfma_f32_16x16x32_bf16 v[84:87], v[168:171], v[210:213], v[84:87]
	v_mfma_f32_16x16x32_bf16 v[68:71], v[168:171], v[218:221], v[68:71]
	v_mfma_f32_16x16x32_bf16 v[68:71], v[172:175], v[222:225], v[68:71]
	v_mfma_f32_16x16x32_bf16 v[76:79], v[164:167], v[222:225], v[76:79]
	v_mfma_f32_16x16x32_bf16 v[76:79], v[160:163], v[218:221], v[76:79]
	s_setprio 0
	s_setprio 1
	v_mfma_f32_16x16x32_bf16 v[120:123], v[176:179], v[194:197], v[120:123]
	v_mfma_f32_16x16x32_bf16 v[120:123], v[180:183], v[198:201], v[120:123]
	v_mfma_f32_16x16x32_bf16 v[112:115], v[190:193], v[198:201], v[112:115]
	v_mfma_f32_16x16x32_bf16 v[112:115], v[186:189], v[194:197], v[112:115]
	v_mfma_f32_16x16x32_bf16 v[96:99], v[186:189], v[202:205], v[96:99]
	v_mfma_f32_16x16x32_bf16 v[96:99], v[190:193], v[206:209], v[96:99]
	v_mfma_f32_16x16x32_bf16 v[104:107], v[180:183], v[206:209], v[104:107]
	v_mfma_f32_16x16x32_bf16 v[104:107], v[176:179], v[202:205], v[104:107]
	v_mfma_f32_16x16x32_bf16 v[88:91], v[176:179], v[210:213], v[88:91]
	v_mfma_f32_16x16x32_bf16 v[88:91], v[180:183], v[214:217], v[88:91]
	v_mfma_f32_16x16x32_bf16 v[80:83], v[190:193], v[214:217], v[80:83]
	v_mfma_f32_16x16x32_bf16 v[80:83], v[186:189], v[210:213], v[80:83]
	v_mfma_f32_16x16x32_bf16 v[64:67], v[186:189], v[218:221], v[64:67]
	v_mfma_f32_16x16x32_bf16 v[64:67], v[190:193], v[222:225], v[64:67]
	v_mfma_f32_16x16x32_bf16 v[72:75], v[180:183], v[222:225], v[72:75]
	v_mfma_f32_16x16x32_bf16 v[72:75], v[176:179], v[218:221], v[72:75]
	s_barrier
	s_setprio 0
	s_add_i32 s76, s64, s52
	v_lshl_add_u64 v[154:155], s[46:47], 0, v[132:133]
	s_mov_b32 m0, s76
	ds_read_b128 v[194:197], v150 offset:16384
	v_xor_b32_e32 v253, 64, v150
	ds_read_b128 v[198:201], v253 offset:16384
	ds_read_b128 v[202:205], v150 offset:18432
	ds_read_b128 v[206:209], v253 offset:18432
	ds_read_b128 v[210:213], v150 offset:20480
	ds_read_b128 v[214:217], v253 offset:20480
	ds_read_b128 v[218:221], v150 offset:22528
	ds_read_b128 v[222:225], v253 offset:22528
	global_load_lds_dwordx4 v[154:155], off
	s_add_i32 m0, s76, 0x2000
	s_add_u32 s76, s46, 0x40000
	v_lshl_add_u64 v[226:227], s[46:47], 0, v[128:129]
	s_addc_u32 s77, s47, 0
	s_add_i32 s78, s65, s52
	global_load_lds_dwordx4 v[226:227], off
	v_lshl_add_u64 v[228:229], s[76:77], 0, v[132:133]
	s_mov_b32 m0, s78
	v_lshl_add_u64 v[230:231], s[48:49], 0, v[130:131]
	global_load_lds_dwordx4 v[228:229], off
	v_lshl_add_u64 v[228:229], s[76:77], 0, v[128:129]
	s_add_i32 m0, s78, 0x2000
	s_nop 0
	global_load_lds_dwordx4 v[228:229], off
	v_lshl_add_u64 v[228:229], s[48:49], 0, v[134:135]
	s_mov_b32 m0, s55
	s_nop 0
	global_load_lds_dwordx4 v[228:229], off
	s_mov_b32 m0, s56
	s_nop 0
	global_load_lds_dwordx4 v[230:231], off
	s_waitcnt vmcnt(8)
	s_waitcnt lgkmcnt(0)
	.p2align 3
	s_setprio 1
	s_barrier
	v_mfma_f32_16x16x32_bf16 v[60:63], v[160:163], v[194:197], v[60:63]
	v_mfma_f32_16x16x32_bf16 v[60:63], v[164:167], v[198:201], v[60:63]
	v_mfma_f32_16x16x32_bf16 v[52:55], v[172:175], v[198:201], v[52:55]
	v_mfma_f32_16x16x32_bf16 v[52:55], v[168:171], v[194:197], v[52:55]
	v_mfma_f32_16x16x32_bf16 v[36:39], v[168:171], v[202:205], v[36:39]
	v_mfma_f32_16x16x32_bf16 v[36:39], v[172:175], v[206:209], v[36:39]
	v_mfma_f32_16x16x32_bf16 v[44:47], v[164:167], v[206:209], v[44:47]
	v_mfma_f32_16x16x32_bf16 v[44:47], v[160:163], v[202:205], v[44:47]
	v_mfma_f32_16x16x32_bf16 v[28:31], v[160:163], v[210:213], v[28:31]
	v_mfma_f32_16x16x32_bf16 v[28:31], v[164:167], v[214:217], v[28:31]
	v_mfma_f32_16x16x32_bf16 v[20:23], v[172:175], v[214:217], v[20:23]
	v_mfma_f32_16x16x32_bf16 v[20:23], v[168:171], v[210:213], v[20:23]
	v_mfma_f32_16x16x32_bf16 v[4:7], v[168:171], v[218:221], v[4:7]
	v_mfma_f32_16x16x32_bf16 v[4:7], v[172:175], v[222:225], v[4:7]
	v_mfma_f32_16x16x32_bf16 v[12:15], v[164:167], v[222:225], v[12:15]
	v_mfma_f32_16x16x32_bf16 v[12:15], v[160:163], v[218:221], v[12:15]
	s_setprio 0
	s_setprio 1
	v_mfma_f32_16x16x32_bf16 v[56:59], v[176:179], v[194:197], v[56:59]
	v_mfma_f32_16x16x32_bf16 v[56:59], v[180:183], v[198:201], v[56:59]
	v_mfma_f32_16x16x32_bf16 v[48:51], v[190:193], v[198:201], v[48:51]
	v_mfma_f32_16x16x32_bf16 v[48:51], v[186:189], v[194:197], v[48:51]
	v_mfma_f32_16x16x32_bf16 v[32:35], v[186:189], v[202:205], v[32:35]
	v_mfma_f32_16x16x32_bf16 v[32:35], v[190:193], v[206:209], v[32:35]
	v_mfma_f32_16x16x32_bf16 v[40:43], v[180:183], v[206:209], v[40:43]
	v_mfma_f32_16x16x32_bf16 v[40:43], v[176:179], v[202:205], v[40:43]
	v_mfma_f32_16x16x32_bf16 v[24:27], v[176:179], v[210:213], v[24:27]
	v_mfma_f32_16x16x32_bf16 v[24:27], v[180:183], v[214:217], v[24:27]
	v_mfma_f32_16x16x32_bf16 v[16:19], v[190:193], v[214:217], v[16:19]
	v_mfma_f32_16x16x32_bf16 v[16:19], v[186:189], v[210:213], v[16:19]
	v_mfma_f32_16x16x32_bf16 v[0:3], v[186:189], v[218:221], v[0:3]
	v_mfma_f32_16x16x32_bf16 v[0:3], v[190:193], v[222:225], v[0:3]
	v_mfma_f32_16x16x32_bf16 v[8:11], v[180:183], v[222:225], v[8:11]
	v_mfma_f32_16x16x32_bf16 v[8:11], v[176:179], v[218:221], v[8:11]
	s_barrier
	s_setprio 0
	s_add_i32 s76, 0, 0x18000
	v_add_u32_e32 v153, s76, v147
	s_add_i32 s77, 0, 0x1c000
	ds_read_b128 v[160:163], v153
	v_xor_b32_e32 v253, 64, v153
	ds_read_b128 v[164:167], v253
	ds_read_b128 v[168:171], v153 offset:2048
	ds_read_b128 v[172:175], v253 offset:2048
	v_add_u32_e32 v153, s77, v147
	ds_read_b128 v[176:179], v153
	v_xor_b32_e32 v253, 64, v153
	ds_read_b128 v[180:183], v253
	ds_read_b128 v[186:189], v153 offset:2048
	ds_read_b128 v[190:193], v253 offset:2048
	s_add_u32 s48, s48, 0x40000
	s_addc_u32 s49, s49, 0
	s_mov_b32 m0, s57
	v_lshl_add_u64 v[232:233], s[48:49], 0, v[134:135]
	ds_read_b128 v[194:197], v150 offset:32768
	v_xor_b32_e32 v253, 64, v150
	ds_read_b128 v[198:201], v253 offset:32768
	ds_read_b128 v[202:205], v150 offset:34816
	ds_read_b128 v[206:209], v253 offset:34816
	ds_read_b128 v[210:213], v150 offset:36864
	ds_read_b128 v[214:217], v253 offset:36864
	ds_read_b128 v[218:221], v150 offset:38912
	ds_read_b128 v[222:225], v253 offset:38912
	global_load_lds_dwordx4 v[232:233], off
	v_lshl_add_u64 v[232:233], s[48:49], 0, v[130:131]
	s_mov_b32 m0, s58
	s_nop 0
	global_load_lds_dwordx4 v[232:233], off
	s_waitcnt vmcnt(8)
	s_waitcnt lgkmcnt(0)
	.p2align 3
	s_setprio 1
	s_barrier
	v_mfma_f32_16x16x32_bf16 v[124:127], v[160:163], v[194:197], v[124:127]
	v_mfma_f32_16x16x32_bf16 v[124:127], v[164:167], v[198:201], v[124:127]
	v_mfma_f32_16x16x32_bf16 v[116:119], v[172:175], v[198:201], v[116:119]
	v_mfma_f32_16x16x32_bf16 v[116:119], v[168:171], v[194:197], v[116:119]
	v_mfma_f32_16x16x32_bf16 v[100:103], v[168:171], v[202:205], v[100:103]
	v_mfma_f32_16x16x32_bf16 v[100:103], v[172:175], v[206:209], v[100:103]
	v_mfma_f32_16x16x32_bf16 v[108:111], v[164:167], v[206:209], v[108:111]
	v_mfma_f32_16x16x32_bf16 v[108:111], v[160:163], v[202:205], v[108:111]
	v_mfma_f32_16x16x32_bf16 v[92:95], v[160:163], v[210:213], v[92:95]
	v_mfma_f32_16x16x32_bf16 v[92:95], v[164:167], v[214:217], v[92:95]
	v_mfma_f32_16x16x32_bf16 v[84:87], v[172:175], v[214:217], v[84:87]
	v_mfma_f32_16x16x32_bf16 v[84:87], v[168:171], v[210:213], v[84:87]
	v_mfma_f32_16x16x32_bf16 v[68:71], v[168:171], v[218:221], v[68:71]
	v_mfma_f32_16x16x32_bf16 v[68:71], v[172:175], v[222:225], v[68:71]
	v_mfma_f32_16x16x32_bf16 v[76:79], v[164:167], v[222:225], v[76:79]
	v_mfma_f32_16x16x32_bf16 v[76:79], v[160:163], v[218:221], v[76:79]
	s_setprio 0
	s_setprio 1
	v_mfma_f32_16x16x32_bf16 v[120:123], v[176:179], v[194:197], v[120:123]
	v_mfma_f32_16x16x32_bf16 v[120:123], v[180:183], v[198:201], v[120:123]
	v_mfma_f32_16x16x32_bf16 v[112:115], v[190:193], v[198:201], v[112:115]
	v_mfma_f32_16x16x32_bf16 v[112:115], v[186:189], v[194:197], v[112:115]
	v_mfma_f32_16x16x32_bf16 v[96:99], v[186:189], v[202:205], v[96:99]
	v_mfma_f32_16x16x32_bf16 v[96:99], v[190:193], v[206:209], v[96:99]
	v_mfma_f32_16x16x32_bf16 v[104:107], v[180:183], v[206:209], v[104:107]
	v_mfma_f32_16x16x32_bf16 v[104:107], v[176:179], v[202:205], v[104:107]
	v_mfma_f32_16x16x32_bf16 v[88:91], v[176:179], v[210:213], v[88:91]
	v_mfma_f32_16x16x32_bf16 v[88:91], v[180:183], v[214:217], v[88:91]
	v_mfma_f32_16x16x32_bf16 v[80:83], v[190:193], v[214:217], v[80:83]
	v_mfma_f32_16x16x32_bf16 v[80:83], v[186:189], v[210:213], v[80:83]
	v_mfma_f32_16x16x32_bf16 v[64:67], v[186:189], v[218:221], v[64:67]
	v_mfma_f32_16x16x32_bf16 v[64:67], v[190:193], v[222:225], v[64:67]
	v_mfma_f32_16x16x32_bf16 v[72:75], v[180:183], v[222:225], v[72:75]
	v_mfma_f32_16x16x32_bf16 v[72:75], v[176:179], v[218:221], v[72:75]
	s_barrier
	s_setprio 0
	v_add_u32_e32 v234, 0x21000, v151
	ds_read_b128 v[236:239], v234
	ds_read_b128 v[240:243], v234 offset:256
	ds_read_b128 v[244:247], v234 offset:512
	ds_read_b128 v[248:251], v234 offset:768
	v_add_u32_e32 v235, s23, v146
	v_mul_u32_u24_e32 v235, 0x1600, v235
	v_lshl_or_b32 v234, s67, 7, v149
	v_lshl_add_u32 v235, v234, 1, v235
	s_add_i32 s48, s76, s52
	v_lshl_add_u64 v[154:155], v[154:155], 0, s[14:15]
	s_mov_b32 m0, s48
	ds_read_b128 v[194:197], v150 offset:49152
	v_xor_b32_e32 v253, 64, v150
	ds_read_b128 v[198:201], v253 offset:49152
	ds_read_b128 v[202:205], v150 offset:51200
	ds_read_b128 v[206:209], v253 offset:51200
	ds_read_b128 v[210:213], v150 offset:53248
	ds_read_b128 v[214:217], v253 offset:53248
	ds_read_b128 v[218:221], v150 offset:55296
	ds_read_b128 v[222:225], v253 offset:55296
	global_load_lds_dwordx4 v[154:155], off
	s_add_i32 m0, s48, 0x2000
	s_add_u32 s46, s46, 0x40080
	v_lshl_add_u64 v[154:155], v[226:227], 0, s[14:15]
	s_addc_u32 s47, s47, 0
	s_add_i32 s48, s77, s52
	global_load_lds_dwordx4 v[154:155], off
	v_lshl_add_u64 v[154:155], s[46:47], 0, v[132:133]
	s_mov_b32 m0, s48
	s_nop 0
	global_load_lds_dwordx4 v[154:155], off
	v_lshl_add_u64 v[154:155], s[46:47], 0, v[128:129]
	s_add_i32 m0, s48, 0x2000
	s_nop 0
	global_load_lds_dwordx4 v[154:155], off
	v_lshl_add_u64 v[154:155], v[228:229], 0, s[14:15]
	s_mov_b32 m0, s60
	s_nop 0
	global_load_lds_dwordx4 v[154:155], off
	v_lshl_add_u64 v[154:155], v[230:231], 0, s[14:15]
	s_mov_b32 m0, s61
	s_nop 0
	global_load_lds_dwordx4 v[154:155], off
	s_waitcnt lgkmcnt(8)
	v_add_f32_e32 v236, v236, v237
	v_add_f32_e32 v238, v238, v239
	v_add_f32_e32 v240, v240, v241
	v_add_f32_e32 v242, v242, v243
	v_add_f32_e32 v244, v244, v245
	v_add_f32_e32 v246, v246, v247
	v_add_f32_e32 v248, v248, v249
	v_add_f32_e32 v250, v250, v251
	v_add_f32_e32 v236, v236, v238
	v_add_f32_e32 v240, v240, v242
	v_add_f32_e32 v244, v244, v246
	v_add_f32_e32 v248, v248, v250
	v_fmamk_f32 v236, v236, 0x3a800000, v152
	v_fmamk_f32 v240, v240, 0x3a800000, v152
	v_fmamk_f32 v244, v244, 0x3a800000, v152
	v_fmamk_f32 v248, v248, 0x3a800000, v152
	v_rsq_f32_e32 v236, v236
	v_rsq_f32_e32 v240, v240
	v_rsq_f32_e32 v244, v244
	v_rsq_f32_e32 v248, v248
	v_mul_f32_e32 v252, 0xbfb8aa3b, v236
	v_mul_f32_e32 v254, v236, v236
	v_rcp_f32_e32 v254, v254
	v_pk_mul_f32 v[120:121], v[124:125], v[120:121]
	v_pk_mul_f32 v[122:123], v[126:127], v[122:123]
	v_pk_mul_f32 v[112:113], v[116:117], v[112:113]
	v_pk_mul_f32 v[114:115], v[118:119], v[114:115]
	v_pk_mul_f32 v[124:125], v[124:125], v[252:253] op_sel_hi:[1,0]
	v_pk_mul_f32 v[126:127], v[126:127], v[252:253] op_sel_hi:[1,0]
	v_pk_mul_f32 v[116:117], v[116:117], v[252:253] op_sel_hi:[1,0]
	v_pk_mul_f32 v[118:119], v[118:119], v[252:253] op_sel_hi:[1,0]
	v_exp_f32_e32 v124, v124
	v_exp_f32_e32 v125, v125
	v_exp_f32_e32 v126, v126
	v_exp_f32_e32 v127, v127
	v_exp_f32_e32 v116, v116
	v_exp_f32_e32 v117, v117
	v_exp_f32_e32 v118, v118
	v_exp_f32_e32 v119, v119
	v_pk_fma_f32 v[124:125], v[124:125], v[254:255], v[254:255] op_sel_hi:[1,0,0]
	v_pk_fma_f32 v[126:127], v[126:127], v[254:255], v[254:255] op_sel_hi:[1,0,0]
	v_pk_fma_f32 v[116:117], v[116:117], v[254:255], v[254:255] op_sel_hi:[1,0,0]
	v_pk_fma_f32 v[118:119], v[118:119], v[254:255], v[254:255] op_sel_hi:[1,0,0]
	v_rcp_f32_e32 v124, v124
	v_rcp_f32_e32 v125, v125
	v_rcp_f32_e32 v126, v126
	v_rcp_f32_e32 v127, v127
	v_rcp_f32_e32 v116, v116
	v_rcp_f32_e32 v117, v117
	v_rcp_f32_e32 v118, v118
	v_rcp_f32_e32 v119, v119
	v_pk_mul_f32 v[120:121], v[120:121], v[124:125]
	v_pk_mul_f32 v[122:123], v[122:123], v[126:127]
	v_pk_mul_f32 v[112:113], v[112:113], v[116:117]
	v_pk_mul_f32 v[114:115], v[114:115], v[118:119]
	v_cvt_pk_bf16_f32 v120, v120, v121
	v_cvt_pk_bf16_f32 v121, v122, v123
	v_cvt_pk_bf16_f32 v122, v112, v113
	v_cvt_pk_bf16_f32 v123, v114, v115
	global_store_dwordx4 v235, v[120:123], s[10:11]
	v_add_u32_e32 v234, 0x16000, v235
	v_mul_f32_e32 v252, 0xbfb8aa3b, v240
	v_mul_f32_e32 v254, v240, v240
	v_rcp_f32_e32 v254, v254
	v_pk_mul_f32 v[104:105], v[108:109], v[104:105]
	v_pk_mul_f32 v[106:107], v[110:111], v[106:107]
	v_pk_mul_f32 v[96:97], v[100:101], v[96:97]
	v_pk_mul_f32 v[98:99], v[102:103], v[98:99]
	v_pk_mul_f32 v[108:109], v[108:109], v[252:253] op_sel_hi:[1,0]
	v_pk_mul_f32 v[110:111], v[110:111], v[252:253] op_sel_hi:[1,0]
	v_pk_mul_f32 v[100:101], v[100:101], v[252:253] op_sel_hi:[1,0]
	v_pk_mul_f32 v[102:103], v[102:103], v[252:253] op_sel_hi:[1,0]
	v_exp_f32_e32 v108, v108
	v_exp_f32_e32 v109, v109
	v_exp_f32_e32 v110, v110
	v_exp_f32_e32 v111, v111
	v_exp_f32_e32 v100, v100
	v_exp_f32_e32 v101, v101
	v_exp_f32_e32 v102, v102
	v_exp_f32_e32 v103, v103
	v_pk_fma_f32 v[108:109], v[108:109], v[254:255], v[254:255] op_sel_hi:[1,0,0]
	v_pk_fma_f32 v[110:111], v[110:111], v[254:255], v[254:255] op_sel_hi:[1,0,0]
	v_pk_fma_f32 v[100:101], v[100:101], v[254:255], v[254:255] op_sel_hi:[1,0,0]
	v_pk_fma_f32 v[102:103], v[102:103], v[254:255], v[254:255] op_sel_hi:[1,0,0]
	v_rcp_f32_e32 v108, v108
	v_rcp_f32_e32 v109, v109
	v_rcp_f32_e32 v110, v110
	v_rcp_f32_e32 v111, v111
	v_rcp_f32_e32 v100, v100
	v_rcp_f32_e32 v101, v101
	v_rcp_f32_e32 v102, v102
	v_rcp_f32_e32 v103, v103
	v_pk_mul_f32 v[104:105], v[104:105], v[108:109]
	v_pk_mul_f32 v[106:107], v[106:107], v[110:111]
	v_pk_mul_f32 v[96:97], v[96:97], v[100:101]
	v_pk_mul_f32 v[98:99], v[98:99], v[102:103]
	v_cvt_pk_bf16_f32 v104, v104, v105
	v_cvt_pk_bf16_f32 v105, v106, v107
	v_cvt_pk_bf16_f32 v106, v96, v97
	v_cvt_pk_bf16_f32 v107, v98, v99
	global_store_dwordx4 v234, v[104:107], s[10:11]
	v_add_u32_e32 v235, 0x16000, v234
	v_mul_f32_e32 v252, 0xbfb8aa3b, v244
	v_mul_f32_e32 v254, v244, v244
	v_rcp_f32_e32 v254, v254
	v_pk_mul_f32 v[88:89], v[92:93], v[88:89]
	v_pk_mul_f32 v[90:91], v[94:95], v[90:91]
	v_pk_mul_f32 v[80:81], v[84:85], v[80:81]
	v_pk_mul_f32 v[82:83], v[86:87], v[82:83]
	v_pk_mul_f32 v[92:93], v[92:93], v[252:253] op_sel_hi:[1,0]
	v_pk_mul_f32 v[94:95], v[94:95], v[252:253] op_sel_hi:[1,0]
	v_pk_mul_f32 v[84:85], v[84:85], v[252:253] op_sel_hi:[1,0]
	v_pk_mul_f32 v[86:87], v[86:87], v[252:253] op_sel_hi:[1,0]
	v_exp_f32_e32 v92, v92
	v_exp_f32_e32 v93, v93
	v_exp_f32_e32 v94, v94
	v_exp_f32_e32 v95, v95
	v_exp_f32_e32 v84, v84
	v_exp_f32_e32 v85, v85
	v_exp_f32_e32 v86, v86
	v_exp_f32_e32 v87, v87
	v_pk_fma_f32 v[92:93], v[92:93], v[254:255], v[254:255] op_sel_hi:[1,0,0]
	v_pk_fma_f32 v[94:95], v[94:95], v[254:255], v[254:255] op_sel_hi:[1,0,0]
	v_pk_fma_f32 v[84:85], v[84:85], v[254:255], v[254:255] op_sel_hi:[1,0,0]
	v_pk_fma_f32 v[86:87], v[86:87], v[254:255], v[254:255] op_sel_hi:[1,0,0]
	v_rcp_f32_e32 v92, v92
	v_rcp_f32_e32 v93, v93
	v_rcp_f32_e32 v94, v94
	v_rcp_f32_e32 v95, v95
	v_rcp_f32_e32 v84, v84
	v_rcp_f32_e32 v85, v85
	v_rcp_f32_e32 v86, v86
	v_rcp_f32_e32 v87, v87
	v_pk_mul_f32 v[88:89], v[88:89], v[92:93]
	v_pk_mul_f32 v[90:91], v[90:91], v[94:95]
	v_pk_mul_f32 v[80:81], v[80:81], v[84:85]
	v_pk_mul_f32 v[82:83], v[82:83], v[86:87]
	v_cvt_pk_bf16_f32 v88, v88, v89
	v_cvt_pk_bf16_f32 v89, v90, v91
	v_cvt_pk_bf16_f32 v90, v80, v81
	v_cvt_pk_bf16_f32 v91, v82, v83
	global_store_dwordx4 v235, v[88:91], s[10:11]
	v_add_u32_e32 v234, 0x16000, v235
	v_mul_f32_e32 v252, 0xbfb8aa3b, v248
	v_mul_f32_e32 v254, v248, v248
	v_rcp_f32_e32 v254, v254
	v_pk_mul_f32 v[72:73], v[76:77], v[72:73]
	v_pk_mul_f32 v[74:75], v[78:79], v[74:75]
	v_pk_mul_f32 v[64:65], v[68:69], v[64:65]
	v_pk_mul_f32 v[66:67], v[70:71], v[66:67]
	v_pk_mul_f32 v[76:77], v[76:77], v[252:253] op_sel_hi:[1,0]
	v_pk_mul_f32 v[78:79], v[78:79], v[252:253] op_sel_hi:[1,0]
	v_pk_mul_f32 v[68:69], v[68:69], v[252:253] op_sel_hi:[1,0]
	v_pk_mul_f32 v[70:71], v[70:71], v[252:253] op_sel_hi:[1,0]
	v_exp_f32_e32 v76, v76
	v_exp_f32_e32 v77, v77
	v_exp_f32_e32 v78, v78
	v_exp_f32_e32 v79, v79
	v_exp_f32_e32 v68, v68
	v_exp_f32_e32 v69, v69
	v_exp_f32_e32 v70, v70
	v_exp_f32_e32 v71, v71
	v_pk_fma_f32 v[76:77], v[76:77], v[254:255], v[254:255] op_sel_hi:[1,0,0]
	v_pk_fma_f32 v[78:79], v[78:79], v[254:255], v[254:255] op_sel_hi:[1,0,0]
	v_pk_fma_f32 v[68:69], v[68:69], v[254:255], v[254:255] op_sel_hi:[1,0,0]
	v_pk_fma_f32 v[70:71], v[70:71], v[254:255], v[254:255] op_sel_hi:[1,0,0]
	v_rcp_f32_e32 v76, v76
	v_rcp_f32_e32 v77, v77
	v_rcp_f32_e32 v78, v78
	v_rcp_f32_e32 v79, v79
	v_rcp_f32_e32 v68, v68
	v_rcp_f32_e32 v69, v69
	v_rcp_f32_e32 v70, v70
	v_rcp_f32_e32 v71, v71
	v_pk_mul_f32 v[72:73], v[72:73], v[76:77]
	v_pk_mul_f32 v[74:75], v[74:75], v[78:79]
	v_pk_mul_f32 v[64:65], v[64:65], v[68:69]
	v_pk_mul_f32 v[66:67], v[66:67], v[70:71]
	v_cvt_pk_bf16_f32 v72, v72, v73
	v_cvt_pk_bf16_f32 v73, v74, v75
	v_cvt_pk_bf16_f32 v74, v64, v65
	v_cvt_pk_bf16_f32 v75, v66, v67
	global_store_dwordx4 v234, v[72:75], s[10:11]
	s_waitcnt vmcnt(12)
	s_waitcnt lgkmcnt(0)
	.p2align 3
	s_setprio 1
	s_barrier
	v_mfma_f32_16x16x32_bf16 v[60:63], v[160:163], v[194:197], v[60:63]
	v_mfma_f32_16x16x32_bf16 v[60:63], v[164:167], v[198:201], v[60:63]
	v_mfma_f32_16x16x32_bf16 v[52:55], v[172:175], v[198:201], v[52:55]
	v_mfma_f32_16x16x32_bf16 v[52:55], v[168:171], v[194:197], v[52:55]
	v_mfma_f32_16x16x32_bf16 v[36:39], v[168:171], v[202:205], v[36:39]
	v_mfma_f32_16x16x32_bf16 v[36:39], v[172:175], v[206:209], v[36:39]
	v_mfma_f32_16x16x32_bf16 v[44:47], v[164:167], v[206:209], v[44:47]
	v_mfma_f32_16x16x32_bf16 v[44:47], v[160:163], v[202:205], v[44:47]
	v_mfma_f32_16x16x32_bf16 v[28:31], v[160:163], v[210:213], v[28:31]
	v_mfma_f32_16x16x32_bf16 v[28:31], v[164:167], v[214:217], v[28:31]
	v_mfma_f32_16x16x32_bf16 v[20:23], v[172:175], v[214:217], v[20:23]
	v_mfma_f32_16x16x32_bf16 v[20:23], v[168:171], v[210:213], v[20:23]
	v_mfma_f32_16x16x32_bf16 v[4:7], v[168:171], v[218:221], v[4:7]
	v_mfma_f32_16x16x32_bf16 v[4:7], v[172:175], v[222:225], v[4:7]
	v_mfma_f32_16x16x32_bf16 v[12:15], v[164:167], v[222:225], v[12:15]
	v_mfma_f32_16x16x32_bf16 v[12:15], v[160:163], v[218:221], v[12:15]
	s_setprio 0
	s_setprio 1
	v_mfma_f32_16x16x32_bf16 v[56:59], v[176:179], v[194:197], v[56:59]
	v_mfma_f32_16x16x32_bf16 v[56:59], v[180:183], v[198:201], v[56:59]
	v_mfma_f32_16x16x32_bf16 v[48:51], v[190:193], v[198:201], v[48:51]
	v_mfma_f32_16x16x32_bf16 v[48:51], v[186:189], v[194:197], v[48:51]
	v_mfma_f32_16x16x32_bf16 v[32:35], v[186:189], v[202:205], v[32:35]
	v_mfma_f32_16x16x32_bf16 v[32:35], v[190:193], v[206:209], v[32:35]
	v_mfma_f32_16x16x32_bf16 v[40:43], v[180:183], v[206:209], v[40:43]
	v_mfma_f32_16x16x32_bf16 v[40:43], v[176:179], v[202:205], v[40:43]
	v_mfma_f32_16x16x32_bf16 v[24:27], v[176:179], v[210:213], v[24:27]
	v_mfma_f32_16x16x32_bf16 v[24:27], v[180:183], v[214:217], v[24:27]
	v_mfma_f32_16x16x32_bf16 v[16:19], v[190:193], v[214:217], v[16:19]
	v_mfma_f32_16x16x32_bf16 v[16:19], v[186:189], v[210:213], v[16:19]
	v_mfma_f32_16x16x32_bf16 v[0:3], v[186:189], v[218:221], v[0:3]
	v_mfma_f32_16x16x32_bf16 v[0:3], v[190:193], v[222:225], v[0:3]
	v_mfma_f32_16x16x32_bf16 v[8:11], v[180:183], v[222:225], v[8:11]
	v_mfma_f32_16x16x32_bf16 v[8:11], v[176:179], v[218:221], v[8:11]
	s_barrier
	s_setprio 0
	s_add_i32 s75, s75, 2
	s_add_u32 s71, s71, 0x100
	s_addc_u32 s74, s74, 0
	s_add_u32 s44, s44, 0x100
	s_addc_u32 s45, s45, 0

.LBB0_158:
	s_add_u32 s81, s56, 0x100
	s_addc_u32 s82, s57, 0
	s_mov_b32 s83, -2
	s_waitcnt lgkmcnt(0)
	s_cmp_eq_u32 s70, 1
	s_cbranch_scc1 .Lfa_1
	ds_read_b128 v[128:131], v189
	v_xor_b32_e32 v253, 64, v189
	ds_read_b128 v[132:135], v253
	ds_read_b128 v[136:139], v189 offset:2048
	ds_read_b128 v[140:143], v253 offset:2048
	ds_read_b128 v[144:147], v190
	v_xor_b32_e32 v253, 64, v190
	ds_read_b128 v[148:151], v253
	ds_read_b128 v[172:175], v190 offset:2048
	ds_read_b128 v[176:179], v253 offset:2048
	s_add_u32 s56, s54, 0x100
	s_addc_u32 s57, s55, 0
	s_cmp_eq_u32 s83, 40
	s_cselect_b32 s61, s15, s57
	s_cselect_b32 s60, s14, s56
	s_cselect_b32 s59, s53, s82
	s_cselect_b32 s58, s52, s81
	v_lshl_add_u64 v[222:223], s[54:55], 0, v[166:167]
	s_add_i32 m0, s66, 0xc000
	ds_read_b128 v[180:183], v191
	v_xor_b32_e32 v253, 64, v191
	ds_read_b128 v[194:197], v253
	ds_read_b128 v[198:201], v191 offset:2048
	ds_read_b128 v[202:205], v253 offset:2048
	ds_read_b128 v[206:209], v191 offset:4096
	ds_read_b128 v[210:213], v253 offset:4096
	ds_read_b128 v[214:217], v191 offset:6144
	ds_read_b128 v[218:221], v253 offset:6144
	global_load_lds_dwordx4 v[222:223], off
	v_lshl_add_u64 v[222:223], s[54:55], 0, v[164:165]
	s_add_i32 m0, s66, 0xe000
	s_nop 0
	global_load_lds_dwordx4 v[222:223], off
	s_waitcnt vmcnt(24)
	s_waitcnt lgkmcnt(0)
	.p2align 3
	s_setprio 1
	s_barrier
	v_mfma_f32_16x16x32_bf16 v[124:127], v[128:131], v[180:183], 0
	v_mfma_f32_16x16x32_bf16 v[120:123], v[136:139], v[180:183], 0
	v_mfma_f32_16x16x32_bf16 v[108:111], v[128:131], v[198:201], 0
	v_mfma_f32_16x16x32_bf16 v[104:107], v[136:139], v[198:201], 0
	v_mfma_f32_16x16x32_bf16 v[92:95], v[128:131], v[206:209], 0
	v_mfma_f32_16x16x32_bf16 v[88:91], v[136:139], v[206:209], 0
	v_mfma_f32_16x16x32_bf16 v[76:79], v[128:131], v[214:217], 0
	v_mfma_f32_16x16x32_bf16 v[72:75], v[136:139], v[214:217], 0
	v_mfma_f32_16x16x32_bf16 v[124:127], v[132:135], v[194:197], v[124:127]
	v_mfma_f32_16x16x32_bf16 v[120:123], v[140:143], v[194:197], v[120:123]
	v_mfma_f32_16x16x32_bf16 v[108:111], v[132:135], v[202:205], v[108:111]
	v_mfma_f32_16x16x32_bf16 v[104:107], v[140:143], v[202:205], v[104:107]
	v_mfma_f32_16x16x32_bf16 v[92:95], v[132:135], v[210:213], v[92:95]
	v_mfma_f32_16x16x32_bf16 v[88:91], v[140:143], v[210:213], v[88:91]
	v_mfma_f32_16x16x32_bf16 v[76:79], v[132:135], v[218:221], v[76:79]
	v_mfma_f32_16x16x32_bf16 v[72:75], v[140:143], v[218:221], v[72:75]
	s_setprio 0
	s_setprio 1
	v_mfma_f32_16x16x32_bf16 v[116:119], v[144:147], v[180:183], 0
	v_mfma_f32_16x16x32_bf16 v[112:115], v[172:175], v[180:183], 0
	v_mfma_f32_16x16x32_bf16 v[100:103], v[144:147], v[198:201], 0
	v_mfma_f32_16x16x32_bf16 v[96:99], v[172:175], v[198:201], 0
	v_mfma_f32_16x16x32_bf16 v[84:87], v[144:147], v[206:209], 0
	v_mfma_f32_16x16x32_bf16 v[80:83], v[172:175], v[206:209], 0
	v_mfma_f32_16x16x32_bf16 v[68:71], v[144:147], v[214:217], 0
	v_mfma_f32_16x16x32_bf16 v[64:67], v[172:175], v[214:217], 0
	v_mfma_f32_16x16x32_bf16 v[116:119], v[148:151], v[194:197], v[116:119]
	v_mfma_f32_16x16x32_bf16 v[112:115], v[176:179], v[194:197], v[112:115]
	v_mfma_f32_16x16x32_bf16 v[100:103], v[148:151], v[202:205], v[100:103]
	v_mfma_f32_16x16x32_bf16 v[96:99], v[176:179], v[202:205], v[96:99]
	v_mfma_f32_16x16x32_bf16 v[84:87], v[148:151], v[210:213], v[84:87]
	v_mfma_f32_16x16x32_bf16 v[80:83], v[176:179], v[210:213], v[80:83]
	v_mfma_f32_16x16x32_bf16 v[68:71], v[148:151], v[218:221], v[68:71]
	v_mfma_f32_16x16x32_bf16 v[64:67], v[176:179], v[218:221], v[64:67]
	s_barrier
	s_setprio 0
	s_add_i32 s54, s77, s65
	v_lshl_add_u64 v[222:223], s[58:59], 0, v[154:155]
	s_mov_b32 m0, s54
	ds_read_b128 v[180:183], v191 offset:16384
	v_xor_b32_e32 v253, 64, v191
	ds_read_b128 v[194:197], v253 offset:16384
	ds_read_b128 v[198:201], v191 offset:18432
	ds_read_b128 v[202:205], v253 offset:18432
	ds_read_b128 v[206:209], v191 offset:20480
	ds_read_b128 v[210:213], v253 offset:20480
	ds_read_b128 v[214:217], v191 offset:22528
	ds_read_b128 v[218:221], v253 offset:22528
	global_load_lds_dwordx4 v[222:223], off
	s_add_i32 m0, s54, 0x2000
	s_add_u32 s54, s58, 0xb0000
	v_lshl_add_u64 v[224:225], s[58:59], 0, v[162:163]
	s_addc_u32 s55, s59, 0
	s_add_i32 s84, s78, s65
	global_load_lds_dwordx4 v[224:225], off
	v_lshl_add_u64 v[226:227], s[54:55], 0, v[154:155]
	s_mov_b32 m0, s84
	v_lshl_add_u64 v[228:229], s[60:61], 0, v[160:161]
	global_load_lds_dwordx4 v[226:227], off
	v_lshl_add_u64 v[226:227], s[54:55], 0, v[162:163]
	s_add_i32 m0, s84, 0x2000
	s_nop 0
	global_load_lds_dwordx4 v[226:227], off
	v_lshl_add_u64 v[226:227], s[60:61], 0, v[152:153]
	s_mov_b32 m0, s66
	s_nop 0
	global_load_lds_dwordx4 v[226:227], off
	s_mov_b32 m0, s67
	s_nop 0
	global_load_lds_dwordx4 v[228:229], off
	s_waitcnt vmcnt(24)
	s_waitcnt lgkmcnt(0)
	.p2align 3
	s_setprio 1
	s_barrier
	v_mfma_f32_16x16x32_bf16 v[60:63], v[128:131], v[180:183], 0
	v_mfma_f32_16x16x32_bf16 v[56:59], v[136:139], v[180:183], 0
	v_mfma_f32_16x16x32_bf16 v[44:47], v[128:131], v[198:201], 0
	v_mfma_f32_16x16x32_bf16 v[40:43], v[136:139], v[198:201], 0
	v_mfma_f32_16x16x32_bf16 v[28:31], v[128:131], v[206:209], 0
	v_mfma_f32_16x16x32_bf16 v[24:27], v[136:139], v[206:209], 0
	v_mfma_f32_16x16x32_bf16 v[12:15], v[128:131], v[214:217], 0
	v_mfma_f32_16x16x32_bf16 v[8:11], v[136:139], v[214:217], 0
	v_mfma_f32_16x16x32_bf16 v[60:63], v[132:135], v[194:197], v[60:63]
	v_mfma_f32_16x16x32_bf16 v[56:59], v[140:143], v[194:197], v[56:59]
	v_mfma_f32_16x16x32_bf16 v[44:47], v[132:135], v[202:205], v[44:47]
	v_mfma_f32_16x16x32_bf16 v[40:43], v[140:143], v[202:205], v[40:43]
	v_mfma_f32_16x16x32_bf16 v[28:31], v[132:135], v[210:213], v[28:31]
	v_mfma_f32_16x16x32_bf16 v[24:27], v[140:143], v[210:213], v[24:27]
	v_mfma_f32_16x16x32_bf16 v[12:15], v[132:135], v[218:221], v[12:15]
	v_mfma_f32_16x16x32_bf16 v[8:11], v[140:143], v[218:221], v[8:11]
	s_setprio 0
	s_setprio 1
	v_mfma_f32_16x16x32_bf16 v[52:55], v[144:147], v[180:183], 0
	v_mfma_f32_16x16x32_bf16 v[48:51], v[172:175], v[180:183], 0
	v_mfma_f32_16x16x32_bf16 v[36:39], v[144:147], v[198:201], 0
	v_mfma_f32_16x16x32_bf16 v[32:35], v[172:175], v[198:201], 0
	v_mfma_f32_16x16x32_bf16 v[20:23], v[144:147], v[206:209], 0
	v_mfma_f32_16x16x32_bf16 v[16:19], v[172:175], v[206:209], 0
	v_mfma_f32_16x16x32_bf16 v[4:7], v[144:147], v[214:217], 0
	v_mfma_f32_16x16x32_bf16 v[0:3], v[172:175], v[214:217], 0
	v_mfma_f32_16x16x32_bf16 v[52:55], v[148:151], v[194:197], v[52:55]
	v_mfma_f32_16x16x32_bf16 v[48:51], v[176:179], v[194:197], v[48:51]
	v_mfma_f32_16x16x32_bf16 v[36:39], v[148:151], v[202:205], v[36:39]
	v_mfma_f32_16x16x32_bf16 v[32:35], v[176:179], v[202:205], v[32:35]
	v_mfma_f32_16x16x32_bf16 v[20:23], v[148:151], v[210:213], v[20:23]
	v_mfma_f32_16x16x32_bf16 v[16:19], v[176:179], v[210:213], v[16:19]
	v_mfma_f32_16x16x32_bf16 v[4:7], v[148:151], v[218:221], v[4:7]
	v_mfma_f32_16x16x32_bf16 v[0:3], v[176:179], v[218:221], v[0:3]
	s_barrier
	s_setprio 0
	s_add_i32 s84, 0, 0x18000
	s_add_i32 s85, 0, 0x1c000
	v_add_u32_e32 v140, s84, v186
	v_add_u32_e32 v176, s85, v186
	ds_read_b128 v[128:131], v140
	v_xor_b32_e32 v253, 64, v140
	ds_read_b128 v[132:135], v253
	ds_read_b128 v[136:139], v140 offset:2048
	ds_read_b128 v[140:143], v253 offset:2048
	ds_read_b128 v[144:147], v176
	v_xor_b32_e32 v253, 64, v176
	ds_read_b128 v[148:151], v253
	ds_read_b128 v[172:175], v176 offset:2048
	ds_read_b128 v[176:179], v253 offset:2048
	s_add_u32 s54, s60, 0xb0000
	s_addc_u32 s55, s61, 0
	s_mov_b32 m0, s68
	v_lshl_add_u64 v[230:231], s[54:55], 0, v[152:153]
	ds_read_b128 v[180:183], v191 offset:32768
	v_xor_b32_e32 v253, 64, v191
	ds_read_b128 v[194:197], v253 offset:32768
	ds_read_b128 v[198:201], v191 offset:34816
	ds_read_b128 v[202:205], v253 offset:34816
	ds_read_b128 v[206:209], v191 offset:36864
	ds_read_b128 v[210:213], v253 offset:36864
	ds_read_b128 v[214:217], v191 offset:38912
	ds_read_b128 v[218:221], v253 offset:38912
	global_load_lds_dwordx4 v[230:231], off
	v_lshl_add_u64 v[230:231], s[54:55], 0, v[160:161]
	s_mov_b32 m0, s69
	s_nop 0
	global_load_lds_dwordx4 v[230:231], off
	s_waitcnt vmcnt(8)
	s_waitcnt lgkmcnt(0)
	.p2align 3
	s_setprio 1
	s_barrier
	v_mfma_f32_16x16x32_bf16 v[124:127], v[128:131], v[180:183], v[124:127]
	v_mfma_f32_16x16x32_bf16 v[124:127], v[132:135], v[194:197], v[124:127]
	v_mfma_f32_16x16x32_bf16 v[120:123], v[140:143], v[194:197], v[120:123]
	v_mfma_f32_16x16x32_bf16 v[120:123], v[136:139], v[180:183], v[120:123]
	v_mfma_f32_16x16x32_bf16 v[104:107], v[136:139], v[198:201], v[104:107]
	v_mfma_f32_16x16x32_bf16 v[104:107], v[140:143], v[202:205], v[104:107]
	v_mfma_f32_16x16x32_bf16 v[108:111], v[132:135], v[202:205], v[108:111]
	v_mfma_f32_16x16x32_bf16 v[108:111], v[128:131], v[198:201], v[108:111]
	v_mfma_f32_16x16x32_bf16 v[92:95], v[128:131], v[206:209], v[92:95]
	v_mfma_f32_16x16x32_bf16 v[92:95], v[132:135], v[210:213], v[92:95]
	v_mfma_f32_16x16x32_bf16 v[88:91], v[140:143], v[210:213], v[88:91]
	v_mfma_f32_16x16x32_bf16 v[88:91], v[136:139], v[206:209], v[88:91]
	v_mfma_f32_16x16x32_bf16 v[72:75], v[136:139], v[214:217], v[72:75]
	v_mfma_f32_16x16x32_bf16 v[72:75], v[140:143], v[218:221], v[72:75]
	v_mfma_f32_16x16x32_bf16 v[76:79], v[132:135], v[218:221], v[76:79]
	v_mfma_f32_16x16x32_bf16 v[76:79], v[128:131], v[214:217], v[76:79]
	s_setprio 0
	s_setprio 1
	v_mfma_f32_16x16x32_bf16 v[116:119], v[144:147], v[180:183], v[116:119]
	v_mfma_f32_16x16x32_bf16 v[116:119], v[148:151], v[194:197], v[116:119]
	v_mfma_f32_16x16x32_bf16 v[112:115], v[176:179], v[194:197], v[112:115]
	v_mfma_f32_16x16x32_bf16 v[112:115], v[172:175], v[180:183], v[112:115]
	v_mfma_f32_16x16x32_bf16 v[96:99], v[172:175], v[198:201], v[96:99]
	v_mfma_f32_16x16x32_bf16 v[96:99], v[176:179], v[202:205], v[96:99]
	v_mfma_f32_16x16x32_bf16 v[100:103], v[148:151], v[202:205], v[100:103]
	v_mfma_f32_16x16x32_bf16 v[100:103], v[144:147], v[198:201], v[100:103]
	v_mfma_f32_16x16x32_bf16 v[84:87], v[144:147], v[206:209], v[84:87]
	v_mfma_f32_16x16x32_bf16 v[84:87], v[148:151], v[210:213], v[84:87]
	v_mfma_f32_16x16x32_bf16 v[80:83], v[176:179], v[210:213], v[80:83]
	v_mfma_f32_16x16x32_bf16 v[80:83], v[172:175], v[206:209], v[80:83]
	v_mfma_f32_16x16x32_bf16 v[64:67], v[172:175], v[214:217], v[64:67]
	v_mfma_f32_16x16x32_bf16 v[64:67], v[176:179], v[218:221], v[64:67]
	v_mfma_f32_16x16x32_bf16 v[68:71], v[148:151], v[218:221], v[68:71]
	v_mfma_f32_16x16x32_bf16 v[68:71], v[144:147], v[214:217], v[68:71]
	s_barrier
	s_setprio 0
	s_add_i32 s54, s84, s65
	v_lshl_add_u64 v[222:223], v[222:223], 0, s[28:29]
	s_mov_b32 m0, s54
	ds_read_b128 v[180:183], v191 offset:49152
	v_xor_b32_e32 v253, 64, v191
	ds_read_b128 v[194:197], v253 offset:49152
	ds_read_b128 v[198:201], v191 offset:51200
	ds_read_b128 v[202:205], v253 offset:51200
	ds_read_b128 v[206:209], v191 offset:53248
	ds_read_b128 v[210:213], v253 offset:53248
	ds_read_b128 v[214:217], v191 offset:55296
	ds_read_b128 v[218:221], v253 offset:55296
	global_load_lds_dwordx4 v[222:223], off
	s_add_i32 m0, s54, 0x2000
	s_add_u32 s54, s58, 0xb0080
	v_lshl_add_u64 v[222:223], v[224:225], 0, s[28:29]
	s_addc_u32 s55, s59, 0
	s_add_i32 s58, s85, s65
	global_load_lds_dwordx4 v[222:223], off
	v_lshl_add_u64 v[222:223], s[54:55], 0, v[154:155]
	s_mov_b32 m0, s58
	s_nop 0
	global_load_lds_dwordx4 v[222:223], off
	v_lshl_add_u64 v[222:223], s[54:55], 0, v[162:163]
	s_add_i32 m0, s58, 0x2000
	s_nop 0
	global_load_lds_dwordx4 v[222:223], off
	v_lshl_add_u64 v[222:223], v[226:227], 0, s[28:29]
	s_mov_b32 m0, s3
	s_nop 0
	global_load_lds_dwordx4 v[222:223], off
	v_lshl_add_u64 v[222:223], v[228:229], 0, s[28:29]
	s_mov_b32 m0, s71
	s_nop 0
	global_load_lds_dwordx4 v[222:223], off
	s_waitcnt vmcnt(8)
	s_waitcnt lgkmcnt(0)
	.p2align 3
	s_setprio 1
	s_barrier
	v_mfma_f32_16x16x32_bf16 v[60:63], v[128:131], v[180:183], v[60:63]
	v_mfma_f32_16x16x32_bf16 v[60:63], v[132:135], v[194:197], v[60:63]
	v_mfma_f32_16x16x32_bf16 v[56:59], v[140:143], v[194:197], v[56:59]
	v_mfma_f32_16x16x32_bf16 v[56:59], v[136:139], v[180:183], v[56:59]
	v_mfma_f32_16x16x32_bf16 v[40:43], v[136:139], v[198:201], v[40:43]
	v_mfma_f32_16x16x32_bf16 v[40:43], v[140:143], v[202:205], v[40:43]
	v_mfma_f32_16x16x32_bf16 v[44:47], v[132:135], v[202:205], v[44:47]
	v_mfma_f32_16x16x32_bf16 v[44:47], v[128:131], v[198:201], v[44:47]
	v_mfma_f32_16x16x32_bf16 v[28:31], v[128:131], v[206:209], v[28:31]
	v_mfma_f32_16x16x32_bf16 v[28:31], v[132:135], v[210:213], v[28:31]
	v_mfma_f32_16x16x32_bf16 v[24:27], v[140:143], v[210:213], v[24:27]
	v_mfma_f32_16x16x32_bf16 v[24:27], v[136:139], v[206:209], v[24:27]
	v_mfma_f32_16x16x32_bf16 v[8:11], v[136:139], v[214:217], v[8:11]
	v_mfma_f32_16x16x32_bf16 v[8:11], v[140:143], v[218:221], v[8:11]
	v_mfma_f32_16x16x32_bf16 v[12:15], v[132:135], v[218:221], v[12:15]
	v_mfma_f32_16x16x32_bf16 v[12:15], v[128:131], v[214:217], v[12:15]
	s_setprio 0
	s_setprio 1
	v_mfma_f32_16x16x32_bf16 v[52:55], v[144:147], v[180:183], v[52:55]
	v_mfma_f32_16x16x32_bf16 v[52:55], v[148:151], v[194:197], v[52:55]
	v_mfma_f32_16x16x32_bf16 v[48:51], v[176:179], v[194:197], v[48:51]
	v_mfma_f32_16x16x32_bf16 v[48:51], v[172:175], v[180:183], v[48:51]
	v_mfma_f32_16x16x32_bf16 v[32:35], v[172:175], v[198:201], v[32:35]
	v_mfma_f32_16x16x32_bf16 v[32:35], v[176:179], v[202:205], v[32:35]
	v_mfma_f32_16x16x32_bf16 v[36:39], v[148:151], v[202:205], v[36:39]
	v_mfma_f32_16x16x32_bf16 v[36:39], v[144:147], v[198:201], v[36:39]
	v_mfma_f32_16x16x32_bf16 v[20:23], v[144:147], v[206:209], v[20:23]
	v_mfma_f32_16x16x32_bf16 v[20:23], v[148:151], v[210:213], v[20:23]
	v_mfma_f32_16x16x32_bf16 v[16:19], v[176:179], v[210:213], v[16:19]
	v_mfma_f32_16x16x32_bf16 v[16:19], v[172:175], v[206:209], v[16:19]
	v_mfma_f32_16x16x32_bf16 v[0:3], v[172:175], v[214:217], v[0:3]
	v_mfma_f32_16x16x32_bf16 v[0:3], v[176:179], v[218:221], v[0:3]
	v_mfma_f32_16x16x32_bf16 v[4:7], v[148:151], v[218:221], v[4:7]
	v_mfma_f32_16x16x32_bf16 v[4:7], v[144:147], v[214:217], v[4:7]
	s_barrier
	s_setprio 0
	s_add_i32 s83, s83, 2
	s_add_u32 s81, s81, 0x100
	s_addc_u32 s82, s82, 0
	s_cmp_gt_u32 s83, 41
	s_mov_b64 s[54:55], s[56:57]
	s_branch .LBB0_159
.Lfa_1:
	ds_read_b128 v[128:131], v189
	v_xor_b32_e32 v253, 64, v189
	ds_read_b128 v[132:135], v253
	ds_read_b128 v[136:139], v189 offset:2048
	ds_read_b128 v[140:143], v253 offset:2048
	ds_read_b128 v[144:147], v190
	v_xor_b32_e32 v253, 64, v190
	ds_read_b128 v[148:151], v253
	ds_read_b128 v[172:175], v190 offset:2048
	ds_read_b128 v[176:179], v253 offset:2048
	s_add_u32 s56, s54, 0x100
	s_addc_u32 s57, s55, 0
	s_cmp_eq_u32 s83, 40
	s_cselect_b32 s61, s15, s57
	s_cselect_b32 s60, s14, s56
	s_cselect_b32 s59, s53, s82
	s_cselect_b32 s58, s52, s81
	v_lshl_add_u64 v[222:223], s[54:55], 0, v[166:167]
	s_add_i32 m0, s66, 0xc000
	ds_read_b128 v[180:183], v191
	v_xor_b32_e32 v253, 64, v191
	ds_read_b128 v[194:197], v253
	ds_read_b128 v[198:201], v191 offset:2048
	ds_read_b128 v[202:205], v253 offset:2048
	ds_read_b128 v[206:209], v191 offset:4096
	ds_read_b128 v[210:213], v253 offset:4096
	ds_read_b128 v[214:217], v191 offset:6144
	ds_read_b128 v[218:221], v253 offset:6144
	global_load_lds_dwordx4 v[222:223], off
	v_lshl_add_u64 v[222:223], s[54:55], 0, v[164:165]
	s_add_i32 m0, s66, 0xe000
	s_nop 0
	global_load_lds_dwordx4 v[222:223], off
	s_waitcnt vmcnt(8)
	s_waitcnt lgkmcnt(0)
	.p2align 3
	s_setprio 1
	s_barrier
	v_mfma_f32_16x16x32_bf16 v[124:127], v[128:131], v[180:183], 0
	v_mfma_f32_16x16x32_bf16 v[120:123], v[136:139], v[180:183], 0
	v_mfma_f32_16x16x32_bf16 v[108:111], v[128:131], v[198:201], 0
	v_mfma_f32_16x16x32_bf16 v[104:107], v[136:139], v[198:201], 0
	v_mfma_f32_16x16x32_bf16 v[92:95], v[128:131], v[206:209], 0
	v_mfma_f32_16x16x32_bf16 v[88:91], v[136:139], v[206:209], 0
	v_mfma_f32_16x16x32_bf16 v[76:79], v[128:131], v[214:217], 0
	v_mfma_f32_16x16x32_bf16 v[72:75], v[136:139], v[214:217], 0
	v_mfma_f32_16x16x32_bf16 v[124:127], v[132:135], v[194:197], v[124:127]
	v_mfma_f32_16x16x32_bf16 v[120:123], v[140:143], v[194:197], v[120:123]
	v_mfma_f32_16x16x32_bf16 v[108:111], v[132:135], v[202:205], v[108:111]
	v_mfma_f32_16x16x32_bf16 v[104:107], v[140:143], v[202:205], v[104:107]
	v_mfma_f32_16x16x32_bf16 v[92:95], v[132:135], v[210:213], v[92:95]
	v_mfma_f32_16x16x32_bf16 v[88:91], v[140:143], v[210:213], v[88:91]
	v_mfma_f32_16x16x32_bf16 v[76:79], v[132:135], v[218:221], v[76:79]
	v_mfma_f32_16x16x32_bf16 v[72:75], v[140:143], v[218:221], v[72:75]
	s_setprio 0
	s_setprio 1
	v_mfma_f32_16x16x32_bf16 v[116:119], v[144:147], v[180:183], 0
	v_mfma_f32_16x16x32_bf16 v[112:115], v[172:175], v[180:183], 0
	v_mfma_f32_16x16x32_bf16 v[100:103], v[144:147], v[198:201], 0
	v_mfma_f32_16x16x32_bf16 v[96:99], v[172:175], v[198:201], 0
	v_mfma_f32_16x16x32_bf16 v[84:87], v[144:147], v[206:209], 0
	v_mfma_f32_16x16x32_bf16 v[80:83], v[172:175], v[206:209], 0
	v_mfma_f32_16x16x32_bf16 v[68:71], v[144:147], v[214:217], 0
	v_mfma_f32_16x16x32_bf16 v[64:67], v[172:175], v[214:217], 0
	v_mfma_f32_16x16x32_bf16 v[116:119], v[148:151], v[194:197], v[116:119]
	v_mfma_f32_16x16x32_bf16 v[112:115], v[176:179], v[194:197], v[112:115]
	v_mfma_f32_16x16x32_bf16 v[100:103], v[148:151], v[202:205], v[100:103]
	v_mfma_f32_16x16x32_bf16 v[96:99], v[176:179], v[202:205], v[96:99]
	v_mfma_f32_16x16x32_bf16 v[84:87], v[148:151], v[210:213], v[84:87]
	v_mfma_f32_16x16x32_bf16 v[80:83], v[176:179], v[210:213], v[80:83]
	v_mfma_f32_16x16x32_bf16 v[68:71], v[148:151], v[218:221], v[68:71]
	v_mfma_f32_16x16x32_bf16 v[64:67], v[176:179], v[218:221], v[64:67]
	s_barrier
	s_setprio 0
	s_add_i32 s54, s77, s65
	v_lshl_add_u64 v[222:223], s[58:59], 0, v[154:155]
	s_mov_b32 m0, s54
	ds_read_b128 v[180:183], v191 offset:16384
	v_xor_b32_e32 v253, 64, v191
	ds_read_b128 v[194:197], v253 offset:16384
	ds_read_b128 v[198:201], v191 offset:18432
	ds_read_b128 v[202:205], v253 offset:18432
	ds_read_b128 v[206:209], v191 offset:20480
	ds_read_b128 v[210:213], v253 offset:20480
	ds_read_b128 v[214:217], v191 offset:22528
	ds_read_b128 v[218:221], v253 offset:22528
	global_load_lds_dwordx4 v[222:223], off
	s_add_i32 m0, s54, 0x2000
	s_add_u32 s54, s58, 0xb0000
	v_lshl_add_u64 v[224:225], s[58:59], 0, v[162:163]
	s_addc_u32 s55, s59, 0
	s_add_i32 s84, s78, s65
	global_load_lds_dwordx4 v[224:225], off
	v_lshl_add_u64 v[226:227], s[54:55], 0, v[154:155]
	s_mov_b32 m0, s84
	v_lshl_add_u64 v[228:229], s[60:61], 0, v[160:161]
	global_load_lds_dwordx4 v[226:227], off
	v_lshl_add_u64 v[226:227], s[54:55], 0, v[162:163]
	s_add_i32 m0, s84, 0x2000
	s_nop 0
	global_load_lds_dwordx4 v[226:227], off
	v_lshl_add_u64 v[226:227], s[60:61], 0, v[152:153]
	s_mov_b32 m0, s66
	s_nop 0
	global_load_lds_dwordx4 v[226:227], off
	s_mov_b32 m0, s67
	s_nop 0
	global_load_lds_dwordx4 v[228:229], off
	s_waitcnt vmcnt(8)
	s_waitcnt lgkmcnt(0)
	.p2align 3
	s_setprio 1
	s_barrier
	v_mfma_f32_16x16x32_bf16 v[60:63], v[128:131], v[180:183], 0
	v_mfma_f32_16x16x32_bf16 v[56:59], v[136:139], v[180:183], 0
	v_mfma_f32_16x16x32_bf16 v[44:47], v[128:131], v[198:201], 0
	v_mfma_f32_16x16x32_bf16 v[40:43], v[136:139], v[198:201], 0
	v_mfma_f32_16x16x32_bf16 v[28:31], v[128:131], v[206:209], 0
	v_mfma_f32_16x16x32_bf16 v[24:27], v[136:139], v[206:209], 0
	v_mfma_f32_16x16x32_bf16 v[12:15], v[128:131], v[214:217], 0
	v_mfma_f32_16x16x32_bf16 v[8:11], v[136:139], v[214:217], 0
	v_mfma_f32_16x16x32_bf16 v[60:63], v[132:135], v[194:197], v[60:63]
	v_mfma_f32_16x16x32_bf16 v[56:59], v[140:143], v[194:197], v[56:59]
	v_mfma_f32_16x16x32_bf16 v[44:47], v[132:135], v[202:205], v[44:47]
	v_mfma_f32_16x16x32_bf16 v[40:43], v[140:143], v[202:205], v[40:43]
	v_mfma_f32_16x16x32_bf16 v[28:31], v[132:135], v[210:213], v[28:31]
	v_mfma_f32_16x16x32_bf16 v[24:27], v[140:143], v[210:213], v[24:27]
	v_mfma_f32_16x16x32_bf16 v[12:15], v[132:135], v[218:221], v[12:15]
	v_mfma_f32_16x16x32_bf16 v[8:11], v[140:143], v[218:221], v[8:11]
	s_setprio 0
	s_setprio 1
	v_mfma_f32_16x16x32_bf16 v[52:55], v[144:147], v[180:183], 0
	v_mfma_f32_16x16x32_bf16 v[48:51], v[172:175], v[180:183], 0
	v_mfma_f32_16x16x32_bf16 v[36:39], v[144:147], v[198:201], 0
	v_mfma_f32_16x16x32_bf16 v[32:35], v[172:175], v[198:201], 0
	v_mfma_f32_16x16x32_bf16 v[20:23], v[144:147], v[206:209], 0
	v_mfma_f32_16x16x32_bf16 v[16:19], v[172:175], v[206:209], 0
	v_mfma_f32_16x16x32_bf16 v[4:7], v[144:147], v[214:217], 0
	v_mfma_f32_16x16x32_bf16 v[0:3], v[172:175], v[214:217], 0
	v_mfma_f32_16x16x32_bf16 v[52:55], v[148:151], v[194:197], v[52:55]
	v_mfma_f32_16x16x32_bf16 v[48:51], v[176:179], v[194:197], v[48:51]
	v_mfma_f32_16x16x32_bf16 v[36:39], v[148:151], v[202:205], v[36:39]
	v_mfma_f32_16x16x32_bf16 v[32:35], v[176:179], v[202:205], v[32:35]
	v_mfma_f32_16x16x32_bf16 v[20:23], v[148:151], v[210:213], v[20:23]
	v_mfma_f32_16x16x32_bf16 v[16:19], v[176:179], v[210:213], v[16:19]
	v_mfma_f32_16x16x32_bf16 v[4:7], v[148:151], v[218:221], v[4:7]
	v_mfma_f32_16x16x32_bf16 v[0:3], v[176:179], v[218:221], v[0:3]
	s_barrier
	s_setprio 0
	s_add_i32 s84, 0, 0x18000
	s_add_i32 s85, 0, 0x1c000
	v_add_u32_e32 v140, s84, v186
	v_add_u32_e32 v176, s85, v186
	ds_read_b128 v[128:131], v140
	v_xor_b32_e32 v253, 64, v140
	ds_read_b128 v[132:135], v253
	ds_read_b128 v[136:139], v140 offset:2048
	ds_read_b128 v[140:143], v253 offset:2048
	ds_read_b128 v[144:147], v176
	v_xor_b32_e32 v253, 64, v176
	ds_read_b128 v[148:151], v253
	ds_read_b128 v[172:175], v176 offset:2048
	ds_read_b128 v[176:179], v253 offset:2048
	s_add_u32 s54, s60, 0xb0000
	s_addc_u32 s55, s61, 0
	s_mov_b32 m0, s68
	v_lshl_add_u64 v[230:231], s[54:55], 0, v[152:153]
	ds_read_b128 v[180:183], v191 offset:32768
	v_xor_b32_e32 v253, 64, v191
	ds_read_b128 v[194:197], v253 offset:32768
	ds_read_b128 v[198:201], v191 offset:34816
	ds_read_b128 v[202:205], v253 offset:34816
	ds_read_b128 v[206:209], v191 offset:36864
	ds_read_b128 v[210:213], v253 offset:36864
	ds_read_b128 v[214:217], v191 offset:38912
	ds_read_b128 v[218:221], v253 offset:38912
	global_load_lds_dwordx4 v[230:231], off
	v_lshl_add_u64 v[230:231], s[54:55], 0, v[160:161]
	s_mov_b32 m0, s69
	s_nop 0
	global_load_lds_dwordx4 v[230:231], off
	s_waitcnt vmcnt(8)
	s_waitcnt lgkmcnt(0)
	.p2align 3
	s_setprio 1
	s_barrier
	v_mfma_f32_16x16x32_bf16 v[124:127], v[128:131], v[180:183], v[124:127]
	v_mfma_f32_16x16x32_bf16 v[124:127], v[132:135], v[194:197], v[124:127]
	v_mfma_f32_16x16x32_bf16 v[120:123], v[140:143], v[194:197], v[120:123]
	v_mfma_f32_16x16x32_bf16 v[120:123], v[136:139], v[180:183], v[120:123]
	v_mfma_f32_16x16x32_bf16 v[104:107], v[136:139], v[198:201], v[104:107]
	v_mfma_f32_16x16x32_bf16 v[104:107], v[140:143], v[202:205], v[104:107]
	v_mfma_f32_16x16x32_bf16 v[108:111], v[132:135], v[202:205], v[108:111]
	v_mfma_f32_16x16x32_bf16 v[108:111], v[128:131], v[198:201], v[108:111]
	v_mfma_f32_16x16x32_bf16 v[92:95], v[128:131], v[206:209], v[92:95]
	v_mfma_f32_16x16x32_bf16 v[92:95], v[132:135], v[210:213], v[92:95]
	v_mfma_f32_16x16x32_bf16 v[88:91], v[140:143], v[210:213], v[88:91]
	v_mfma_f32_16x16x32_bf16 v[88:91], v[136:139], v[206:209], v[88:91]
	v_mfma_f32_16x16x32_bf16 v[72:75], v[136:139], v[214:217], v[72:75]
	v_mfma_f32_16x16x32_bf16 v[72:75], v[140:143], v[218:221], v[72:75]
	v_mfma_f32_16x16x32_bf16 v[76:79], v[132:135], v[218:221], v[76:79]
	v_mfma_f32_16x16x32_bf16 v[76:79], v[128:131], v[214:217], v[76:79]
	s_setprio 0
	s_setprio 1
	v_mfma_f32_16x16x32_bf16 v[116:119], v[144:147], v[180:183], v[116:119]
	v_mfma_f32_16x16x32_bf16 v[116:119], v[148:151], v[194:197], v[116:119]
	v_mfma_f32_16x16x32_bf16 v[112:115], v[176:179], v[194:197], v[112:115]
	v_mfma_f32_16x16x32_bf16 v[112:115], v[172:175], v[180:183], v[112:115]
	v_mfma_f32_16x16x32_bf16 v[96:99], v[172:175], v[198:201], v[96:99]
	v_mfma_f32_16x16x32_bf16 v[96:99], v[176:179], v[202:205], v[96:99]
	v_mfma_f32_16x16x32_bf16 v[100:103], v[148:151], v[202:205], v[100:103]
	v_mfma_f32_16x16x32_bf16 v[100:103], v[144:147], v[198:201], v[100:103]
	v_mfma_f32_16x16x32_bf16 v[84:87], v[144:147], v[206:209], v[84:87]
	v_mfma_f32_16x16x32_bf16 v[84:87], v[148:151], v[210:213], v[84:87]
	v_mfma_f32_16x16x32_bf16 v[80:83], v[176:179], v[210:213], v[80:83]
	v_mfma_f32_16x16x32_bf16 v[80:83], v[172:175], v[206:209], v[80:83]
	v_mfma_f32_16x16x32_bf16 v[64:67], v[172:175], v[214:217], v[64:67]
	v_mfma_f32_16x16x32_bf16 v[64:67], v[176:179], v[218:221], v[64:67]
	v_mfma_f32_16x16x32_bf16 v[68:71], v[148:151], v[218:221], v[68:71]
	v_mfma_f32_16x16x32_bf16 v[68:71], v[144:147], v[214:217], v[68:71]
	s_barrier
	s_setprio 0
	s_add_i32 s54, s84, s65
	v_lshl_add_u64 v[222:223], v[222:223], 0, s[28:29]
	s_mov_b32 m0, s54
	ds_read_b128 v[180:183], v191 offset:49152
	v_xor_b32_e32 v253, 64, v191
	ds_read_b128 v[194:197], v253 offset:49152
	ds_read_b128 v[198:201], v191 offset:51200
	ds_read_b128 v[202:205], v253 offset:51200
	ds_read_b128 v[206:209], v191 offset:53248
	ds_read_b128 v[210:213], v253 offset:53248
	ds_read_b128 v[214:217], v191 offset:55296
	ds_read_b128 v[218:221], v253 offset:55296
	global_load_lds_dwordx4 v[222:223], off
	s_add_i32 m0, s54, 0x2000
	s_add_u32 s54, s58, 0xb0080
	v_lshl_add_u64 v[222:223], v[224:225], 0, s[28:29]
	s_addc_u32 s55, s59, 0
	s_add_i32 s58, s85, s65
	global_load_lds_dwordx4 v[222:223], off
	v_lshl_add_u64 v[222:223], s[54:55], 0, v[154:155]
	s_mov_b32 m0, s58
	s_nop 0
	global_load_lds_dwordx4 v[222:223], off
	v_lshl_add_u64 v[222:223], s[54:55], 0, v[162:163]
	s_add_i32 m0, s58, 0x2000
	s_nop 0
	global_load_lds_dwordx4 v[222:223], off
	v_lshl_add_u64 v[222:223], v[226:227], 0, s[28:29]
	s_mov_b32 m0, s3
	s_nop 0
	global_load_lds_dwordx4 v[222:223], off
	v_lshl_add_u64 v[222:223], v[228:229], 0, s[28:29]
	s_mov_b32 m0, s71
	s_nop 0
	global_load_lds_dwordx4 v[222:223], off
	s_waitcnt vmcnt(8)
	s_waitcnt lgkmcnt(0)
	.p2align 3
	s_setprio 1
	s_barrier
	v_mfma_f32_16x16x32_bf16 v[60:63], v[128:131], v[180:183], v[60:63]
	v_mfma_f32_16x16x32_bf16 v[60:63], v[132:135], v[194:197], v[60:63]
	v_mfma_f32_16x16x32_bf16 v[56:59], v[140:143], v[194:197], v[56:59]
	v_mfma_f32_16x16x32_bf16 v[56:59], v[136:139], v[180:183], v[56:59]
	v_mfma_f32_16x16x32_bf16 v[40:43], v[136:139], v[198:201], v[40:43]
	v_mfma_f32_16x16x32_bf16 v[40:43], v[140:143], v[202:205], v[40:43]
	v_mfma_f32_16x16x32_bf16 v[44:47], v[132:135], v[202:205], v[44:47]
	v_mfma_f32_16x16x32_bf16 v[44:47], v[128:131], v[198:201], v[44:47]
	v_mfma_f32_16x16x32_bf16 v[28:31], v[128:131], v[206:209], v[28:31]
	v_mfma_f32_16x16x32_bf16 v[28:31], v[132:135], v[210:213], v[28:31]
	v_mfma_f32_16x16x32_bf16 v[24:27], v[140:143], v[210:213], v[24:27]
	v_mfma_f32_16x16x32_bf16 v[24:27], v[136:139], v[206:209], v[24:27]
	v_mfma_f32_16x16x32_bf16 v[8:11], v[136:139], v[214:217], v[8:11]
	v_mfma_f32_16x16x32_bf16 v[8:11], v[140:143], v[218:221], v[8:11]
	v_mfma_f32_16x16x32_bf16 v[12:15], v[132:135], v[218:221], v[12:15]
	v_mfma_f32_16x16x32_bf16 v[12:15], v[128:131], v[214:217], v[12:15]
	s_setprio 0
	s_setprio 1
	v_mfma_f32_16x16x32_bf16 v[52:55], v[144:147], v[180:183], v[52:55]
	v_mfma_f32_16x16x32_bf16 v[52:55], v[148:151], v[194:197], v[52:55]
	v_mfma_f32_16x16x32_bf16 v[48:51], v[176:179], v[194:197], v[48:51]
	v_mfma_f32_16x16x32_bf16 v[48:51], v[172:175], v[180:183], v[48:51]
	v_mfma_f32_16x16x32_bf16 v[32:35], v[172:175], v[198:201], v[32:35]
	v_mfma_f32_16x16x32_bf16 v[32:35], v[176:179], v[202:205], v[32:35]
	v_mfma_f32_16x16x32_bf16 v[36:39], v[148:151], v[202:205], v[36:39]
	v_mfma_f32_16x16x32_bf16 v[36:39], v[144:147], v[198:201], v[36:39]
	v_mfma_f32_16x16x32_bf16 v[20:23], v[144:147], v[206:209], v[20:23]
	v_mfma_f32_16x16x32_bf16 v[20:23], v[148:151], v[210:213], v[20:23]
	v_mfma_f32_16x16x32_bf16 v[16:19], v[176:179], v[210:213], v[16:19]
	v_mfma_f32_16x16x32_bf16 v[16:19], v[172:175], v[206:209], v[16:19]
	v_mfma_f32_16x16x32_bf16 v[0:3], v[172:175], v[214:217], v[0:3]
	v_mfma_f32_16x16x32_bf16 v[0:3], v[176:179], v[218:221], v[0:3]
	v_mfma_f32_16x16x32_bf16 v[4:7], v[148:151], v[218:221], v[4:7]
	v_mfma_f32_16x16x32_bf16 v[4:7], v[144:147], v[214:217], v[4:7]
	s_barrier
	s_setprio 0
	s_add_i32 s83, s83, 2
	s_add_u32 s81, s81, 0x100
	s_addc_u32 s82, s82, 0
	s_cmp_gt_u32 s83, 41
	s_mov_b64 s[54:55], s[56:57]
.LBB0_159:
	ds_read_b128 v[128:131], v189
	v_xor_b32_e32 v253, 64, v189
	ds_read_b128 v[132:135], v253
	ds_read_b128 v[136:139], v189 offset:2048
	ds_read_b128 v[140:143], v253 offset:2048
	ds_read_b128 v[144:147], v190
	v_xor_b32_e32 v253, 64, v190
	ds_read_b128 v[148:151], v253
	ds_read_b128 v[172:175], v190 offset:2048
	ds_read_b128 v[176:179], v253 offset:2048
	s_add_u32 s56, s54, 0x100
	s_addc_u32 s57, s55, 0
	s_cmp_eq_u32 s83, 40
	s_cselect_b32 s61, s15, s57
	s_cselect_b32 s60, s14, s56
	s_cselect_b32 s59, s53, s82
	s_cselect_b32 s58, s52, s81
	v_lshl_add_u64 v[222:223], s[54:55], 0, v[166:167]
	s_add_i32 m0, s66, 0xc000
	ds_read_b128 v[180:183], v191
	v_xor_b32_e32 v253, 64, v191
	ds_read_b128 v[194:197], v253
	ds_read_b128 v[198:201], v191 offset:2048
	ds_read_b128 v[202:205], v253 offset:2048
	ds_read_b128 v[206:209], v191 offset:4096
	ds_read_b128 v[210:213], v253 offset:4096
	ds_read_b128 v[214:217], v191 offset:6144
	ds_read_b128 v[218:221], v253 offset:6144
	global_load_lds_dwordx4 v[222:223], off
	v_lshl_add_u64 v[222:223], s[54:55], 0, v[164:165]
	s_add_i32 m0, s66, 0xe000
	s_nop 0
	global_load_lds_dwordx4 v[222:223], off
	s_waitcnt vmcnt(8)
	s_waitcnt lgkmcnt(0)
	.p2align 3
	s_setprio 1
	s_barrier
	v_mfma_f32_16x16x32_bf16 v[124:127], v[128:131], v[180:183], v[124:127]
	v_mfma_f32_16x16x32_bf16 v[124:127], v[132:135], v[194:197], v[124:127]
	v_mfma_f32_16x16x32_bf16 v[120:123], v[140:143], v[194:197], v[120:123]
	v_mfma_f32_16x16x32_bf16 v[120:123], v[136:139], v[180:183], v[120:123]
	v_mfma_f32_16x16x32_bf16 v[104:107], v[136:139], v[198:201], v[104:107]
	v_mfma_f32_16x16x32_bf16 v[104:107], v[140:143], v[202:205], v[104:107]
	v_mfma_f32_16x16x32_bf16 v[108:111], v[132:135], v[202:205], v[108:111]
	v_mfma_f32_16x16x32_bf16 v[108:111], v[128:131], v[198:201], v[108:111]
	v_mfma_f32_16x16x32_bf16 v[92:95], v[128:131], v[206:209], v[92:95]
	v_mfma_f32_16x16x32_bf16 v[92:95], v[132:135], v[210:213], v[92:95]
	v_mfma_f32_16x16x32_bf16 v[88:91], v[140:143], v[210:213], v[88:91]
	v_mfma_f32_16x16x32_bf16 v[88:91], v[136:139], v[206:209], v[88:91]
	v_mfma_f32_16x16x32_bf16 v[72:75], v[136:139], v[214:217], v[72:75]
	v_mfma_f32_16x16x32_bf16 v[72:75], v[140:143], v[218:221], v[72:75]
	v_mfma_f32_16x16x32_bf16 v[76:79], v[132:135], v[218:221], v[76:79]
	v_mfma_f32_16x16x32_bf16 v[76:79], v[128:131], v[214:217], v[76:79]
	s_setprio 0
	s_setprio 1
	v_mfma_f32_16x16x32_bf16 v[116:119], v[144:147], v[180:183], v[116:119]
	v_mfma_f32_16x16x32_bf16 v[116:119], v[148:151], v[194:197], v[116:119]
	v_mfma_f32_16x16x32_bf16 v[112:115], v[176:179], v[194:197], v[112:115]
	v_mfma_f32_16x16x32_bf16 v[112:115], v[172:175], v[180:183], v[112:115]
	v_mfma_f32_16x16x32_bf16 v[96:99], v[172:175], v[198:201], v[96:99]
	v_mfma_f32_16x16x32_bf16 v[96:99], v[176:179], v[202:205], v[96:99]
	v_mfma_f32_16x16x32_bf16 v[100:103], v[148:151], v[202:205], v[100:103]
	v_mfma_f32_16x16x32_bf16 v[100:103], v[144:147], v[198:201], v[100:103]
	v_mfma_f32_16x16x32_bf16 v[84:87], v[144:147], v[206:209], v[84:87]
	v_mfma_f32_16x16x32_bf16 v[84:87], v[148:151], v[210:213], v[84:87]
	v_mfma_f32_16x16x32_bf16 v[80:83], v[176:179], v[210:213], v[80:83]
	v_mfma_f32_16x16x32_bf16 v[80:83], v[172:175], v[206:209], v[80:83]
	v_mfma_f32_16x16x32_bf16 v[64:67], v[172:175], v[214:217], v[64:67]
	v_mfma_f32_16x16x32_bf16 v[64:67], v[176:179], v[218:221], v[64:67]
	v_mfma_f32_16x16x32_bf16 v[68:71], v[148:151], v[218:221], v[68:71]
	v_mfma_f32_16x16x32_bf16 v[68:71], v[144:147], v[214:217], v[68:71]
	s_barrier
	s_setprio 0
	s_add_i32 s54, s77, s65
	v_lshl_add_u64 v[222:223], s[58:59], 0, v[154:155]
	s_mov_b32 m0, s54
	ds_read_b128 v[180:183], v191 offset:16384
	v_xor_b32_e32 v253, 64, v191
	ds_read_b128 v[194:197], v253 offset:16384
	ds_read_b128 v[198:201], v191 offset:18432
	ds_read_b128 v[202:205], v253 offset:18432
	ds_read_b128 v[206:209], v191 offset:20480
	ds_read_b128 v[210:213], v253 offset:20480
	ds_read_b128 v[214:217], v191 offset:22528
	ds_read_b128 v[218:221], v253 offset:22528
	global_load_lds_dwordx4 v[222:223], off
	s_add_i32 m0, s54, 0x2000
	s_add_u32 s54, s58, 0xb0000
	v_lshl_add_u64 v[224:225], s[58:59], 0, v[162:163]
	s_addc_u32 s55, s59, 0
	s_add_i32 s84, s78, s65
	global_load_lds_dwordx4 v[224:225], off
	v_lshl_add_u64 v[226:227], s[54:55], 0, v[154:155]
	s_mov_b32 m0, s84
	v_lshl_add_u64 v[228:229], s[60:61], 0, v[160:161]
	global_load_lds_dwordx4 v[226:227], off
	v_lshl_add_u64 v[226:227], s[54:55], 0, v[162:163]
	s_add_i32 m0, s84, 0x2000
	s_nop 0
	global_load_lds_dwordx4 v[226:227], off
	v_lshl_add_u64 v[226:227], s[60:61], 0, v[152:153]
	s_mov_b32 m0, s66
	s_nop 0
	global_load_lds_dwordx4 v[226:227], off
	s_mov_b32 m0, s67
	s_nop 0
	global_load_lds_dwordx4 v[228:229], off
	s_waitcnt vmcnt(8)
	s_waitcnt lgkmcnt(0)
	.p2align 3
	s_setprio 1
	s_barrier
	v_mfma_f32_16x16x32_bf16 v[60:63], v[128:131], v[180:183], v[60:63]
	v_mfma_f32_16x16x32_bf16 v[60:63], v[132:135], v[194:197], v[60:63]
	v_mfma_f32_16x16x32_bf16 v[56:59], v[140:143], v[194:197], v[56:59]
	v_mfma_f32_16x16x32_bf16 v[56:59], v[136:139], v[180:183], v[56:59]
	v_mfma_f32_16x16x32_bf16 v[40:43], v[136:139], v[198:201], v[40:43]
	v_mfma_f32_16x16x32_bf16 v[40:43], v[140:143], v[202:205], v[40:43]
	v_mfma_f32_16x16x32_bf16 v[44:47], v[132:135], v[202:205], v[44:47]
	v_mfma_f32_16x16x32_bf16 v[44:47], v[128:131], v[198:201], v[44:47]
	v_mfma_f32_16x16x32_bf16 v[28:31], v[128:131], v[206:209], v[28:31]
	v_mfma_f32_16x16x32_bf16 v[28:31], v[132:135], v[210:213], v[28:31]
	v_mfma_f32_16x16x32_bf16 v[24:27], v[140:143], v[210:213], v[24:27]
	v_mfma_f32_16x16x32_bf16 v[24:27], v[136:139], v[206:209], v[24:27]
	v_mfma_f32_16x16x32_bf16 v[8:11], v[136:139], v[214:217], v[8:11]
	v_mfma_f32_16x16x32_bf16 v[8:11], v[140:143], v[218:221], v[8:11]
	v_mfma_f32_16x16x32_bf16 v[12:15], v[132:135], v[218:221], v[12:15]
	v_mfma_f32_16x16x32_bf16 v[12:15], v[128:131], v[214:217], v[12:15]
	s_setprio 0
	s_setprio 1
	v_mfma_f32_16x16x32_bf16 v[52:55], v[144:147], v[180:183], v[52:55]
	v_mfma_f32_16x16x32_bf16 v[52:55], v[148:151], v[194:197], v[52:55]
	v_mfma_f32_16x16x32_bf16 v[48:51], v[176:179], v[194:197], v[48:51]
	v_mfma_f32_16x16x32_bf16 v[48:51], v[172:175], v[180:183], v[48:51]
	v_mfma_f32_16x16x32_bf16 v[32:35], v[172:175], v[198:201], v[32:35]
	v_mfma_f32_16x16x32_bf16 v[32:35], v[176:179], v[202:205], v[32:35]
	v_mfma_f32_16x16x32_bf16 v[36:39], v[148:151], v[202:205], v[36:39]
	v_mfma_f32_16x16x32_bf16 v[36:39], v[144:147], v[198:201], v[36:39]
	v_mfma_f32_16x16x32_bf16 v[20:23], v[144:147], v[206:209], v[20:23]
	v_mfma_f32_16x16x32_bf16 v[20:23], v[148:151], v[210:213], v[20:23]
	v_mfma_f32_16x16x32_bf16 v[16:19], v[176:179], v[210:213], v[16:19]
	v_mfma_f32_16x16x32_bf16 v[16:19], v[172:175], v[206:209], v[16:19]
	v_mfma_f32_16x16x32_bf16 v[0:3], v[172:175], v[214:217], v[0:3]
	v_mfma_f32_16x16x32_bf16 v[0:3], v[176:179], v[218:221], v[0:3]
	v_mfma_f32_16x16x32_bf16 v[4:7], v[148:151], v[218:221], v[4:7]
	v_mfma_f32_16x16x32_bf16 v[4:7], v[144:147], v[214:217], v[4:7]
	s_barrier
	s_setprio 0
	s_add_i32 s84, 0, 0x18000
	s_add_i32 s85, 0, 0x1c000
	v_add_u32_e32 v140, s84, v186
	v_add_u32_e32 v176, s85, v186
	ds_read_b128 v[128:131], v140
	v_xor_b32_e32 v253, 64, v140
	ds_read_b128 v[132:135], v253
	ds_read_b128 v[136:139], v140 offset:2048
	ds_read_b128 v[140:143], v253 offset:2048
	ds_read_b128 v[144:147], v176
	v_xor_b32_e32 v253, 64, v176
	ds_read_b128 v[148:151], v253
	ds_read_b128 v[172:175], v176 offset:2048
	ds_read_b128 v[176:179], v253 offset:2048
	s_add_u32 s54, s60, 0xb0000
	s_addc_u32 s55, s61, 0
	s_mov_b32 m0, s68
	v_lshl_add_u64 v[230:231], s[54:55], 0, v[152:153]
	ds_read_b128 v[180:183], v191 offset:32768
	v_xor_b32_e32 v253, 64, v191
	ds_read_b128 v[194:197], v253 offset:32768
	ds_read_b128 v[198:201], v191 offset:34816
	ds_read_b128 v[202:205], v253 offset:34816
	ds_read_b128 v[206:209], v191 offset:36864
	ds_read_b128 v[210:213], v253 offset:36864
	ds_read_b128 v[214:217], v191 offset:38912
	ds_read_b128 v[218:221], v253 offset:38912
	global_load_lds_dwordx4 v[230:231], off
	v_lshl_add_u64 v[230:231], s[54:55], 0, v[160:161]
	s_mov_b32 m0, s69
	s_nop 0
	global_load_lds_dwordx4 v[230:231], off
	s_waitcnt vmcnt(8)
	s_waitcnt lgkmcnt(0)
	.p2align 3
	s_setprio 1
	s_barrier
	v_mfma_f32_16x16x32_bf16 v[124:127], v[128:131], v[180:183], v[124:127]
	v_mfma_f32_16x16x32_bf16 v[124:127], v[132:135], v[194:197], v[124:127]
	v_mfma_f32_16x16x32_bf16 v[120:123], v[140:143], v[194:197], v[120:123]
	v_mfma_f32_16x16x32_bf16 v[120:123], v[136:139], v[180:183], v[120:123]
	v_mfma_f32_16x16x32_bf16 v[104:107], v[136:139], v[198:201], v[104:107]
	v_mfma_f32_16x16x32_bf16 v[104:107], v[140:143], v[202:205], v[104:107]
	v_mfma_f32_16x16x32_bf16 v[108:111], v[132:135], v[202:205], v[108:111]
	v_mfma_f32_16x16x32_bf16 v[108:111], v[128:131], v[198:201], v[108:111]
	v_mfma_f32_16x16x32_bf16 v[92:95], v[128:131], v[206:209], v[92:95]
	v_mfma_f32_16x16x32_bf16 v[92:95], v[132:135], v[210:213], v[92:95]
	v_mfma_f32_16x16x32_bf16 v[88:91], v[140:143], v[210:213], v[88:91]
	v_mfma_f32_16x16x32_bf16 v[88:91], v[136:139], v[206:209], v[88:91]
	v_mfma_f32_16x16x32_bf16 v[72:75], v[136:139], v[214:217], v[72:75]
	v_mfma_f32_16x16x32_bf16 v[72:75], v[140:143], v[218:221], v[72:75]
	v_mfma_f32_16x16x32_bf16 v[76:79], v[132:135], v[218:221], v[76:79]
	v_mfma_f32_16x16x32_bf16 v[76:79], v[128:131], v[214:217], v[76:79]
	s_setprio 0
	s_setprio 1
	v_mfma_f32_16x16x32_bf16 v[116:119], v[144:147], v[180:183], v[116:119]
	v_mfma_f32_16x16x32_bf16 v[116:119], v[148:151], v[194:197], v[116:119]
	v_mfma_f32_16x16x32_bf16 v[112:115], v[176:179], v[194:197], v[112:115]
	v_mfma_f32_16x16x32_bf16 v[112:115], v[172:175], v[180:183], v[112:115]
	v_mfma_f32_16x16x32_bf16 v[96:99], v[172:175], v[198:201], v[96:99]
	v_mfma_f32_16x16x32_bf16 v[96:99], v[176:179], v[202:205], v[96:99]
	v_mfma_f32_16x16x32_bf16 v[100:103], v[148:151], v[202:205], v[100:103]
	v_mfma_f32_16x16x32_bf16 v[100:103], v[144:147], v[198:201], v[100:103]
	v_mfma_f32_16x16x32_bf16 v[84:87], v[144:147], v[206:209], v[84:87]
	v_mfma_f32_16x16x32_bf16 v[84:87], v[148:151], v[210:213], v[84:87]
	v_mfma_f32_16x16x32_bf16 v[80:83], v[176:179], v[210:213], v[80:83]
	v_mfma_f32_16x16x32_bf16 v[80:83], v[172:175], v[206:209], v[80:83]
	v_mfma_f32_16x16x32_bf16 v[64:67], v[172:175], v[214:217], v[64:67]
	v_mfma_f32_16x16x32_bf16 v[64:67], v[176:179], v[218:221], v[64:67]
	v_mfma_f32_16x16x32_bf16 v[68:71], v[148:151], v[218:221], v[68:71]
	v_mfma_f32_16x16x32_bf16 v[68:71], v[144:147], v[214:217], v[68:71]
	s_barrier
	s_setprio 0
	s_add_i32 s54, s84, s65
	v_lshl_add_u64 v[222:223], v[222:223], 0, s[28:29]
	s_mov_b32 m0, s54
	ds_read_b128 v[180:183], v191 offset:49152
	v_xor_b32_e32 v253, 64, v191
	ds_read_b128 v[194:197], v253 offset:49152
	ds_read_b128 v[198:201], v191 offset:51200
	ds_read_b128 v[202:205], v253 offset:51200
	ds_read_b128 v[206:209], v191 offset:53248
	ds_read_b128 v[210:213], v253 offset:53248
	ds_read_b128 v[214:217], v191 offset:55296
	ds_read_b128 v[218:221], v253 offset:55296
	global_load_lds_dwordx4 v[222:223], off
	s_add_i32 m0, s54, 0x2000
	s_add_u32 s54, s58, 0xb0080
	v_lshl_add_u64 v[222:223], v[224:225], 0, s[28:29]
	s_addc_u32 s55, s59, 0
	s_add_i32 s58, s85, s65
	global_load_lds_dwordx4 v[222:223], off
	v_lshl_add_u64 v[222:223], s[54:55], 0, v[154:155]
	s_mov_b32 m0, s58
	s_nop 0
	global_load_lds_dwordx4 v[222:223], off
	v_lshl_add_u64 v[222:223], s[54:55], 0, v[162:163]
	s_add_i32 m0, s58, 0x2000
	s_nop 0
	global_load_lds_dwordx4 v[222:223], off
	v_lshl_add_u64 v[222:223], v[226:227], 0, s[28:29]
	s_mov_b32 m0, s3
	s_nop 0
	global_load_lds_dwordx4 v[222:223], off
	v_lshl_add_u64 v[222:223], v[228:229], 0, s[28:29]
	s_mov_b32 m0, s71
	s_nop 0
	global_load_lds_dwordx4 v[222:223], off
	s_waitcnt vmcnt(8)
	s_waitcnt lgkmcnt(0)
	.p2align 3
	s_setprio 1
	s_barrier
	v_mfma_f32_16x16x32_bf16 v[60:63], v[128:131], v[180:183], v[60:63]
	v_mfma_f32_16x16x32_bf16 v[60:63], v[132:135], v[194:197], v[60:63]
	v_mfma_f32_16x16x32_bf16 v[56:59], v[140:143], v[194:197], v[56:59]
	v_mfma_f32_16x16x32_bf16 v[56:59], v[136:139], v[180:183], v[56:59]
	v_mfma_f32_16x16x32_bf16 v[40:43], v[136:139], v[198:201], v[40:43]
	v_mfma_f32_16x16x32_bf16 v[40:43], v[140:143], v[202:205], v[40:43]
	v_mfma_f32_16x16x32_bf16 v[44:47], v[132:135], v[202:205], v[44:47]
	v_mfma_f32_16x16x32_bf16 v[44:47], v[128:131], v[198:201], v[44:47]
	v_mfma_f32_16x16x32_bf16 v[28:31], v[128:131], v[206:209], v[28:31]
	v_mfma_f32_16x16x32_bf16 v[28:31], v[132:135], v[210:213], v[28:31]
	v_mfma_f32_16x16x32_bf16 v[24:27], v[140:143], v[210:213], v[24:27]
	v_mfma_f32_16x16x32_bf16 v[24:27], v[136:139], v[206:209], v[24:27]
	v_mfma_f32_16x16x32_bf16 v[8:11], v[136:139], v[214:217], v[8:11]
	v_mfma_f32_16x16x32_bf16 v[8:11], v[140:143], v[218:221], v[8:11]
	v_mfma_f32_16x16x32_bf16 v[12:15], v[132:135], v[218:221], v[12:15]
	v_mfma_f32_16x16x32_bf16 v[12:15], v[128:131], v[214:217], v[12:15]
	s_setprio 0
	s_setprio 1
	v_mfma_f32_16x16x32_bf16 v[52:55], v[144:147], v[180:183], v[52:55]
	v_mfma_f32_16x16x32_bf16 v[52:55], v[148:151], v[194:197], v[52:55]
	v_mfma_f32_16x16x32_bf16 v[48:51], v[176:179], v[194:197], v[48:51]
	v_mfma_f32_16x16x32_bf16 v[48:51], v[172:175], v[180:183], v[48:51]
	v_mfma_f32_16x16x32_bf16 v[32:35], v[172:175], v[198:201], v[32:35]
	v_mfma_f32_16x16x32_bf16 v[32:35], v[176:179], v[202:205], v[32:35]
	v_mfma_f32_16x16x32_bf16 v[36:39], v[148:151], v[202:205], v[36:39]
	v_mfma_f32_16x16x32_bf16 v[36:39], v[144:147], v[198:201], v[36:39]
	v_mfma_f32_16x16x32_bf16 v[20:23], v[144:147], v[206:209], v[20:23]
	v_mfma_f32_16x16x32_bf16 v[20:23], v[148:151], v[210:213], v[20:23]
	v_mfma_f32_16x16x32_bf16 v[16:19], v[176:179], v[210:213], v[16:19]
	v_mfma_f32_16x16x32_bf16 v[16:19], v[172:175], v[206:209], v[16:19]
	v_mfma_f32_16x16x32_bf16 v[0:3], v[172:175], v[214:217], v[0:3]
	v_mfma_f32_16x16x32_bf16 v[0:3], v[176:179], v[218:221], v[0:3]
	v_mfma_f32_16x16x32_bf16 v[4:7], v[148:151], v[218:221], v[4:7]
	v_mfma_f32_16x16x32_bf16 v[4:7], v[144:147], v[214:217], v[4:7]
	s_barrier
	s_setprio 0
	s_add_i32 s83, s83, 2
	s_add_u32 s81, s81, 0x100
	s_addc_u32 s82, s82, 0
	s_cmp_gt_u32 s83, 41
	s_mov_b64 s[54:55], s[56:57]
	s_cbranch_scc0 .LBB0_159
	s_and_b64 vcc, exec, s[30:31]
	s_cbranch_vccz .LBB0_162
	s_barrier

.LBB0_254:
	s_ashr_i32 s61, s60, 31
	s_lshl_b64 s[62:63], s[60:61], 19
	s_add_u32 s62, s35, s62
	s_addc_u32 s63, s47, s63
	s_and_b64 s[64:65], s[12:13], exec
	s_cselect_b32 s3, s63, s69
	s_cselect_b32 s61, s62, s68
	s_ashr_i32 s59, s58, 31
	s_lshl_b64 s[64:65], s[58:59], 19
	s_add_u32 s64, s49, s64
	s_addc_u32 s65, s70, s65
	s_and_b64 s[92:93], s[12:13], exec
	s_cselect_b32 s91, s65, s67
	s_cselect_b32 s92, s64, s66
	s_lshl_b32 s59, s14, 8
	v_add_u32_e32 v0, s59, v182
	s_add_u32 s93, s66, 0x100
	s_waitcnt lgkmcnt(0)
	v_ashrrev_i32_e32 v1, 31, v0
	s_addc_u32 s94, s67, 0
	v_lshl_add_u64 v[72:73], v[0:1], 4, s[26:27]
	s_add_u32 s14, s68, 0x40080
	s_addc_u32 s15, s69, 0
	s_mov_b32 s95, -2
	s_mov_b64 s[66:67], 0
	s_cmp_eq_u32 s90, 1
	s_cbranch_scc1 .Lfa_2
	v_add_u32_e32 v74, s83, v181
	ds_read_b128 v[88:91], v74
	v_xor_b32_e32 v253, 64, v74
	ds_read_b128 v[108:111], v253
	ds_read_b128 v[128:131], v74 offset:2048
	ds_read_b128 v[144:147], v253 offset:2048
	v_add_u32_e32 v74, s84, v181
	ds_read_b128 v[148:151], v74
	v_xor_b32_e32 v253, 64, v74
	ds_read_b128 v[152:155], v253
	ds_read_b128 v[176:179], v74 offset:2048
	ds_read_b128 v[190:193], v253 offset:2048
	s_add_u32 s68, s14, 0xfffc0080
	s_addc_u32 s69, s15, -1
	s_and_b64 s[66:67], s[66:67], exec
	s_cselect_b32 s69, s3, s69
	s_cselect_b32 s68, s61, s68
	s_cselect_b32 s67, s91, s94
	s_cselect_b32 s66, s92, s93
	v_lshl_add_u64 v[74:75], s[14:15], 0, v[170:171]
	s_add_i32 m0, s74, 0xc000
	ds_read_b128 v[194:197], v187
	v_xor_b32_e32 v253, 64, v187
	ds_read_b128 v[198:201], v253
	ds_read_b128 v[202:205], v187 offset:2048
	ds_read_b128 v[206:209], v253 offset:2048
	ds_read_b128 v[210:213], v187 offset:4096
	ds_read_b128 v[214:217], v253 offset:4096
	ds_read_b128 v[218:221], v187 offset:6144
	ds_read_b128 v[222:225], v253 offset:6144
	global_load_lds_dwordx4 v[74:75], off
	v_lshl_add_u64 v[74:75], s[14:15], 0, v[168:169]
	s_add_i32 m0, s74, 0xe000
	s_nop 0
	global_load_lds_dwordx4 v[74:75], off
	s_waitcnt vmcnt(24)
	s_waitcnt lgkmcnt(0)
	.p2align 3
	s_setprio 1
	s_barrier
	v_mfma_f32_16x16x32_bf16 v[140:143], v[88:91], v[194:197], 0
	v_mfma_f32_16x16x32_bf16 v[136:139], v[128:131], v[194:197], 0
	v_mfma_f32_16x16x32_bf16 v[120:123], v[88:91], v[202:205], 0
	v_mfma_f32_16x16x32_bf16 v[116:119], v[128:131], v[202:205], 0
	v_mfma_f32_16x16x32_bf16 v[100:103], v[88:91], v[210:213], 0
	v_mfma_f32_16x16x32_bf16 v[96:99], v[128:131], v[210:213], 0
	v_mfma_f32_16x16x32_bf16 v[80:83], v[88:91], v[218:221], 0
	v_mfma_f32_16x16x32_bf16 v[74:77], v[128:131], v[218:221], 0
	v_mfma_f32_16x16x32_bf16 v[140:143], v[108:111], v[198:201], v[140:143]
	v_mfma_f32_16x16x32_bf16 v[136:139], v[144:147], v[198:201], v[136:139]
	v_mfma_f32_16x16x32_bf16 v[120:123], v[108:111], v[206:209], v[120:123]
	v_mfma_f32_16x16x32_bf16 v[116:119], v[144:147], v[206:209], v[116:119]
	v_mfma_f32_16x16x32_bf16 v[100:103], v[108:111], v[214:217], v[100:103]
	v_mfma_f32_16x16x32_bf16 v[96:99], v[144:147], v[214:217], v[96:99]
	v_mfma_f32_16x16x32_bf16 v[80:83], v[108:111], v[222:225], v[80:83]
	v_mfma_f32_16x16x32_bf16 v[74:77], v[144:147], v[222:225], v[74:77]
	s_setprio 0
	s_setprio 1
	v_mfma_f32_16x16x32_bf16 v[132:135], v[148:151], v[194:197], 0
	v_mfma_f32_16x16x32_bf16 v[124:127], v[176:179], v[194:197], 0
	v_mfma_f32_16x16x32_bf16 v[112:115], v[148:151], v[202:205], 0
	v_mfma_f32_16x16x32_bf16 v[104:107], v[176:179], v[202:205], 0
	v_mfma_f32_16x16x32_bf16 v[92:95], v[148:151], v[210:213], 0
	v_mfma_f32_16x16x32_bf16 v[84:87], v[176:179], v[210:213], 0
	v_mfma_f32_16x16x32_bf16 v[68:71], v[148:151], v[218:221], 0
	v_mfma_f32_16x16x32_bf16 v[64:67], v[176:179], v[218:221], 0
	v_mfma_f32_16x16x32_bf16 v[132:135], v[152:155], v[198:201], v[132:135]
	v_mfma_f32_16x16x32_bf16 v[124:127], v[190:193], v[198:201], v[124:127]
	v_mfma_f32_16x16x32_bf16 v[112:115], v[152:155], v[206:209], v[112:115]
	v_mfma_f32_16x16x32_bf16 v[104:107], v[190:193], v[206:209], v[104:107]
	v_mfma_f32_16x16x32_bf16 v[92:95], v[152:155], v[214:217], v[92:95]
	v_mfma_f32_16x16x32_bf16 v[84:87], v[190:193], v[214:217], v[84:87]
	v_mfma_f32_16x16x32_bf16 v[68:71], v[152:155], v[222:225], v[68:71]
	v_mfma_f32_16x16x32_bf16 v[64:67], v[190:193], v[222:225], v[64:67]
	s_barrier
	s_setprio 0
	s_add_i32 s96, s83, s71
	v_lshl_add_u64 v[226:227], s[66:67], 0, v[162:163]
	s_mov_b32 m0, s96
	ds_read_b128 v[194:197], v187 offset:16384
	v_xor_b32_e32 v253, 64, v187
	ds_read_b128 v[198:201], v253 offset:16384
	ds_read_b128 v[202:205], v187 offset:18432
	ds_read_b128 v[206:209], v253 offset:18432
	ds_read_b128 v[210:213], v187 offset:20480
	ds_read_b128 v[214:217], v253 offset:20480
	ds_read_b128 v[218:221], v187 offset:22528
	ds_read_b128 v[222:225], v253 offset:22528
	global_load_lds_dwordx4 v[226:227], off
	s_add_i32 m0, s96, 0x2000
	s_add_u32 s96, s66, 0x40000
	v_lshl_add_u64 v[228:229], s[66:67], 0, v[166:167]
	s_addc_u32 s97, s67, 0
	s_add_i32 vcc_lo, s84, s71
	global_load_lds_dwordx4 v[228:229], off
	v_lshl_add_u64 v[78:79], s[96:97], 0, v[162:163]
	s_mov_b32 m0, vcc_lo
	v_lshl_add_u64 v[230:231], s[68:69], 0, v[160:161]
	global_load_lds_dwordx4 v[78:79], off
	v_lshl_add_u64 v[78:79], s[96:97], 0, v[166:167]
	s_add_i32 m0, vcc_lo, 0x2000
	v_lshl_add_u64 v[232:233], s[68:69], 0, v[164:165]
	global_load_lds_dwordx4 v[78:79], off
	s_mov_b32 m0, s74
	s_nop 0
	global_load_lds_dwordx4 v[230:231], off
	s_mov_b32 m0, s75
	s_nop 0
	global_load_lds_dwordx4 v[232:233], off
	s_waitcnt vmcnt(24)
	s_waitcnt lgkmcnt(0)
	.p2align 3
	s_setprio 1
	s_barrier
	v_mfma_f32_16x16x32_bf16 v[60:63], v[88:91], v[194:197], 0
	v_mfma_f32_16x16x32_bf16 v[56:59], v[128:131], v[194:197], 0
	v_mfma_f32_16x16x32_bf16 v[44:47], v[88:91], v[202:205], 0
	v_mfma_f32_16x16x32_bf16 v[40:43], v[128:131], v[202:205], 0
	v_mfma_f32_16x16x32_bf16 v[28:31], v[88:91], v[210:213], 0
	v_mfma_f32_16x16x32_bf16 v[24:27], v[128:131], v[210:213], 0
	v_mfma_f32_16x16x32_bf16 v[12:15], v[88:91], v[218:221], 0
	v_mfma_f32_16x16x32_bf16 v[8:11], v[128:131], v[218:221], 0
	v_mfma_f32_16x16x32_bf16 v[60:63], v[108:111], v[198:201], v[60:63]
	v_mfma_f32_16x16x32_bf16 v[56:59], v[144:147], v[198:201], v[56:59]
	v_mfma_f32_16x16x32_bf16 v[44:47], v[108:111], v[206:209], v[44:47]
	v_mfma_f32_16x16x32_bf16 v[40:43], v[144:147], v[206:209], v[40:43]
	v_mfma_f32_16x16x32_bf16 v[28:31], v[108:111], v[214:217], v[28:31]
	v_mfma_f32_16x16x32_bf16 v[24:27], v[144:147], v[214:217], v[24:27]
	v_mfma_f32_16x16x32_bf16 v[12:15], v[108:111], v[222:225], v[12:15]
	v_mfma_f32_16x16x32_bf16 v[8:11], v[144:147], v[222:225], v[8:11]
	s_setprio 0
	s_setprio 1
	v_mfma_f32_16x16x32_bf16 v[52:55], v[148:151], v[194:197], 0
	v_mfma_f32_16x16x32_bf16 v[48:51], v[176:179], v[194:197], 0
	v_mfma_f32_16x16x32_bf16 v[36:39], v[148:151], v[202:205], 0
	v_mfma_f32_16x16x32_bf16 v[32:35], v[176:179], v[202:205], 0
	v_mfma_f32_16x16x32_bf16 v[20:23], v[148:151], v[210:213], 0
	v_mfma_f32_16x16x32_bf16 v[16:19], v[176:179], v[210:213], 0
	v_mfma_f32_16x16x32_bf16 v[4:7], v[148:151], v[218:221], 0
	v_mfma_f32_16x16x32_bf16 v[0:3], v[176:179], v[218:221], 0
	v_mfma_f32_16x16x32_bf16 v[52:55], v[152:155], v[198:201], v[52:55]
	v_mfma_f32_16x16x32_bf16 v[48:51], v[190:193], v[198:201], v[48:51]
	v_mfma_f32_16x16x32_bf16 v[36:39], v[152:155], v[206:209], v[36:39]
	v_mfma_f32_16x16x32_bf16 v[32:35], v[190:193], v[206:209], v[32:35]
	v_mfma_f32_16x16x32_bf16 v[20:23], v[152:155], v[214:217], v[20:23]
	v_mfma_f32_16x16x32_bf16 v[16:19], v[190:193], v[214:217], v[16:19]
	v_mfma_f32_16x16x32_bf16 v[4:7], v[152:155], v[222:225], v[4:7]
	v_mfma_f32_16x16x32_bf16 v[0:3], v[190:193], v[222:225], v[0:3]
	s_barrier
	s_setprio 0
	s_add_i32 s96, 0, 0x18000
	v_add_u32_e32 v78, s96, v181
	s_add_i32 s97, 0, 0x1c000
	ds_read_b128 v[88:91], v78
	v_xor_b32_e32 v253, 64, v78
	ds_read_b128 v[108:111], v253
	ds_read_b128 v[128:131], v78 offset:2048
	ds_read_b128 v[144:147], v253 offset:2048
	v_add_u32_e32 v78, s97, v181
	ds_read_b128 v[148:151], v78
	v_xor_b32_e32 v253, 64, v78
	ds_read_b128 v[152:155], v253
	ds_read_b128 v[176:179], v78 offset:2048
	ds_read_b128 v[190:193], v253 offset:2048
	s_add_u32 s68, s68, 0x40000
	s_addc_u32 s69, s69, 0
	s_mov_b32 m0, s76
	v_lshl_add_u64 v[78:79], s[68:69], 0, v[160:161]
	ds_read_b128 v[194:197], v187 offset:32768
	v_xor_b32_e32 v253, 64, v187
	ds_read_b128 v[198:201], v253 offset:32768
	ds_read_b128 v[202:205], v187 offset:34816
	ds_read_b128 v[206:209], v253 offset:34816
	ds_read_b128 v[210:213], v187 offset:36864
	ds_read_b128 v[214:217], v253 offset:36864
	ds_read_b128 v[218:221], v187 offset:38912
	ds_read_b128 v[222:225], v253 offset:38912
	global_load_lds_dwordx4 v[78:79], off
	v_lshl_add_u64 v[78:79], s[68:69], 0, v[164:165]
	s_mov_b32 m0, s77
	s_nop 0
	global_load_lds_dwordx4 v[78:79], off
	s_waitcnt vmcnt(8)
	s_waitcnt lgkmcnt(0)
	.p2align 3
	s_setprio 1
	s_barrier
	v_mfma_f32_16x16x32_bf16 v[140:143], v[88:91], v[194:197], v[140:143]
	v_mfma_f32_16x16x32_bf16 v[136:139], v[128:131], v[194:197], v[136:139]
	v_mfma_f32_16x16x32_bf16 v[120:123], v[88:91], v[202:205], v[120:123]
	v_mfma_f32_16x16x32_bf16 v[116:119], v[128:131], v[202:205], v[116:119]
	v_mfma_f32_16x16x32_bf16 v[100:103], v[88:91], v[210:213], v[100:103]
	v_mfma_f32_16x16x32_bf16 v[96:99], v[128:131], v[210:213], v[96:99]
	v_mfma_f32_16x16x32_bf16 v[78:81], v[88:91], v[218:221], v[80:83]
	v_mfma_f32_16x16x32_bf16 v[74:77], v[128:131], v[218:221], v[74:77]
	v_mfma_f32_16x16x32_bf16 v[140:143], v[108:111], v[198:201], v[140:143]
	v_mfma_f32_16x16x32_bf16 v[136:139], v[144:147], v[198:201], v[136:139]
	v_mfma_f32_16x16x32_bf16 v[120:123], v[108:111], v[206:209], v[120:123]
	v_mfma_f32_16x16x32_bf16 v[116:119], v[144:147], v[206:209], v[116:119]
	v_mfma_f32_16x16x32_bf16 v[100:103], v[108:111], v[214:217], v[100:103]
	v_mfma_f32_16x16x32_bf16 v[96:99], v[144:147], v[214:217], v[96:99]
	v_mfma_f32_16x16x32_bf16 v[80:83], v[108:111], v[222:225], v[78:81]
	v_mfma_f32_16x16x32_bf16 v[76:79], v[144:147], v[222:225], v[74:77]
	s_setprio 0
	s_setprio 1
	v_mfma_f32_16x16x32_bf16 v[132:135], v[148:151], v[194:197], v[132:135]
	v_mfma_f32_16x16x32_bf16 v[132:135], v[152:155], v[198:201], v[132:135]
	v_mfma_f32_16x16x32_bf16 v[124:127], v[190:193], v[198:201], v[124:127]
	v_mfma_f32_16x16x32_bf16 v[124:127], v[176:179], v[194:197], v[124:127]
	v_mfma_f32_16x16x32_bf16 v[104:107], v[176:179], v[202:205], v[104:107]
	v_mfma_f32_16x16x32_bf16 v[104:107], v[190:193], v[206:209], v[104:107]
	v_mfma_f32_16x16x32_bf16 v[112:115], v[152:155], v[206:209], v[112:115]
	v_mfma_f32_16x16x32_bf16 v[112:115], v[148:151], v[202:205], v[112:115]
	v_mfma_f32_16x16x32_bf16 v[92:95], v[148:151], v[210:213], v[92:95]
	v_mfma_f32_16x16x32_bf16 v[92:95], v[152:155], v[214:217], v[92:95]
	v_mfma_f32_16x16x32_bf16 v[84:87], v[190:193], v[214:217], v[84:87]
	v_mfma_f32_16x16x32_bf16 v[84:87], v[176:179], v[210:213], v[84:87]
	v_mfma_f32_16x16x32_bf16 v[64:67], v[176:179], v[218:221], v[64:67]
	v_mfma_f32_16x16x32_bf16 v[64:67], v[190:193], v[222:225], v[64:67]
	v_mfma_f32_16x16x32_bf16 v[68:71], v[152:155], v[222:225], v[68:71]
	v_mfma_f32_16x16x32_bf16 v[68:71], v[148:151], v[218:221], v[68:71]
	s_barrier
	s_setprio 0
	s_add_i32 s68, s96, s71
	v_lshl_add_u64 v[74:75], v[226:227], 0, s[28:29]
	s_mov_b32 m0, s68
	ds_read_b128 v[194:197], v187 offset:49152
	v_xor_b32_e32 v253, 64, v187
	ds_read_b128 v[198:201], v253 offset:49152
	ds_read_b128 v[202:205], v187 offset:51200
	ds_read_b128 v[206:209], v253 offset:51200
	ds_read_b128 v[210:213], v187 offset:53248
	ds_read_b128 v[214:217], v253 offset:53248
	ds_read_b128 v[218:221], v187 offset:55296
	ds_read_b128 v[222:225], v253 offset:55296
	global_load_lds_dwordx4 v[74:75], off
	s_add_i32 m0, s68, 0x2000
	s_add_u32 s66, s66, 0x40080
	v_lshl_add_u64 v[74:75], v[228:229], 0, s[28:29]
	s_addc_u32 s67, s67, 0
	s_add_i32 s68, s97, s71
	global_load_lds_dwordx4 v[74:75], off
	v_lshl_add_u64 v[74:75], s[66:67], 0, v[162:163]
	s_mov_b32 m0, s68
	s_nop 0
	global_load_lds_dwordx4 v[74:75], off
	v_lshl_add_u64 v[74:75], s[66:67], 0, v[166:167]
	s_add_i32 m0, s68, 0x2000
	s_nop 0
	global_load_lds_dwordx4 v[74:75], off
	v_lshl_add_u64 v[74:75], v[230:231], 0, s[28:29]
	s_mov_b32 m0, s78
	s_nop 0
	global_load_lds_dwordx4 v[74:75], off
	v_lshl_add_u64 v[74:75], v[232:233], 0, s[28:29]
	s_mov_b32 m0, s79
	s_nop 0
	global_load_lds_dwordx4 v[74:75], off
	s_waitcnt vmcnt(8)
	s_waitcnt lgkmcnt(0)
	.p2align 3
	s_setprio 1
	s_barrier
	v_mfma_f32_16x16x32_bf16 v[60:63], v[88:91], v[194:197], v[60:63]
	v_mfma_f32_16x16x32_bf16 v[60:63], v[108:111], v[198:201], v[60:63]
	v_mfma_f32_16x16x32_bf16 v[56:59], v[144:147], v[198:201], v[56:59]
	v_mfma_f32_16x16x32_bf16 v[56:59], v[128:131], v[194:197], v[56:59]
	v_mfma_f32_16x16x32_bf16 v[40:43], v[128:131], v[202:205], v[40:43]
	v_mfma_f32_16x16x32_bf16 v[40:43], v[144:147], v[206:209], v[40:43]
	v_mfma_f32_16x16x32_bf16 v[44:47], v[108:111], v[206:209], v[44:47]
	v_mfma_f32_16x16x32_bf16 v[44:47], v[88:91], v[202:205], v[44:47]
	v_mfma_f32_16x16x32_bf16 v[28:31], v[88:91], v[210:213], v[28:31]
	v_mfma_f32_16x16x32_bf16 v[28:31], v[108:111], v[214:217], v[28:31]
	v_mfma_f32_16x16x32_bf16 v[24:27], v[144:147], v[214:217], v[24:27]
	v_mfma_f32_16x16x32_bf16 v[24:27], v[128:131], v[210:213], v[24:27]
	v_mfma_f32_16x16x32_bf16 v[8:11], v[128:131], v[218:221], v[8:11]
	v_mfma_f32_16x16x32_bf16 v[8:11], v[144:147], v[222:225], v[8:11]
	v_mfma_f32_16x16x32_bf16 v[12:15], v[108:111], v[222:225], v[12:15]
	v_mfma_f32_16x16x32_bf16 v[12:15], v[88:91], v[218:221], v[12:15]
	s_setprio 0
	s_setprio 1
	v_mfma_f32_16x16x32_bf16 v[52:55], v[148:151], v[194:197], v[52:55]
	v_mfma_f32_16x16x32_bf16 v[52:55], v[152:155], v[198:201], v[52:55]
	v_mfma_f32_16x16x32_bf16 v[48:51], v[190:193], v[198:201], v[48:51]
	v_mfma_f32_16x16x32_bf16 v[48:51], v[176:179], v[194:197], v[48:51]
	v_mfma_f32_16x16x32_bf16 v[32:35], v[176:179], v[202:205], v[32:35]
	v_mfma_f32_16x16x32_bf16 v[32:35], v[190:193], v[206:209], v[32:35]
	v_mfma_f32_16x16x32_bf16 v[36:39], v[152:155], v[206:209], v[36:39]
	v_mfma_f32_16x16x32_bf16 v[36:39], v[148:151], v[202:205], v[36:39]
	v_mfma_f32_16x16x32_bf16 v[20:23], v[148:151], v[210:213], v[20:23]
	v_mfma_f32_16x16x32_bf16 v[20:23], v[152:155], v[214:217], v[20:23]
	v_mfma_f32_16x16x32_bf16 v[16:19], v[190:193], v[214:217], v[16:19]
	v_mfma_f32_16x16x32_bf16 v[16:19], v[176:179], v[210:213], v[16:19]
	v_mfma_f32_16x16x32_bf16 v[0:3], v[176:179], v[218:221], v[0:3]
	v_mfma_f32_16x16x32_bf16 v[0:3], v[190:193], v[222:225], v[0:3]
	v_mfma_f32_16x16x32_bf16 v[4:7], v[152:155], v[222:225], v[4:7]
	v_mfma_f32_16x16x32_bf16 v[4:7], v[148:151], v[218:221], v[4:7]
	s_barrier
	s_setprio 0
	s_add_i32 s95, s95, 2
	s_add_u32 s93, s93, 0x100
	s_addc_u32 s94, s94, 0
	s_add_u32 s14, s14, 0x100
	s_addc_u32 s15, s15, 0
	s_branch .LBB0_256
.Lfa_2:
	v_add_u32_e32 v74, s83, v181
	ds_read_b128 v[88:91], v74
	v_xor_b32_e32 v253, 64, v74
	ds_read_b128 v[108:111], v253
	ds_read_b128 v[128:131], v74 offset:2048
	ds_read_b128 v[144:147], v253 offset:2048
	v_add_u32_e32 v74, s84, v181
	ds_read_b128 v[148:151], v74
	v_xor_b32_e32 v253, 64, v74
	ds_read_b128 v[152:155], v253
	ds_read_b128 v[176:179], v74 offset:2048
	ds_read_b128 v[190:193], v253 offset:2048
	s_add_u32 s68, s14, 0xfffc0080
	s_addc_u32 s69, s15, -1
	s_and_b64 s[66:67], s[66:67], exec
	s_cselect_b32 s69, s3, s69
	s_cselect_b32 s68, s61, s68
	s_cselect_b32 s67, s91, s94
	s_cselect_b32 s66, s92, s93
	v_lshl_add_u64 v[74:75], s[14:15], 0, v[170:171]
	s_add_i32 m0, s74, 0xc000
	ds_read_b128 v[194:197], v187
	v_xor_b32_e32 v253, 64, v187
	ds_read_b128 v[198:201], v253
	ds_read_b128 v[202:205], v187 offset:2048
	ds_read_b128 v[206:209], v253 offset:2048
	ds_read_b128 v[210:213], v187 offset:4096
	ds_read_b128 v[214:217], v253 offset:4096
	ds_read_b128 v[218:221], v187 offset:6144
	ds_read_b128 v[222:225], v253 offset:6144
	global_load_lds_dwordx4 v[74:75], off
	v_lshl_add_u64 v[74:75], s[14:15], 0, v[168:169]
	s_add_i32 m0, s74, 0xe000
	s_nop 0
	global_load_lds_dwordx4 v[74:75], off
	s_waitcnt vmcnt(8)
	s_waitcnt lgkmcnt(0)
	.p2align 3
	s_setprio 1
	s_barrier
	v_mfma_f32_16x16x32_bf16 v[140:143], v[88:91], v[194:197], 0
	v_mfma_f32_16x16x32_bf16 v[136:139], v[128:131], v[194:197], 0
	v_mfma_f32_16x16x32_bf16 v[120:123], v[88:91], v[202:205], 0
	v_mfma_f32_16x16x32_bf16 v[116:119], v[128:131], v[202:205], 0
	v_mfma_f32_16x16x32_bf16 v[100:103], v[88:91], v[210:213], 0
	v_mfma_f32_16x16x32_bf16 v[96:99], v[128:131], v[210:213], 0
	v_mfma_f32_16x16x32_bf16 v[80:83], v[88:91], v[218:221], 0
	v_mfma_f32_16x16x32_bf16 v[74:77], v[128:131], v[218:221], 0
	v_mfma_f32_16x16x32_bf16 v[140:143], v[108:111], v[198:201], v[140:143]
	v_mfma_f32_16x16x32_bf16 v[136:139], v[144:147], v[198:201], v[136:139]
	v_mfma_f32_16x16x32_bf16 v[120:123], v[108:111], v[206:209], v[120:123]
	v_mfma_f32_16x16x32_bf16 v[116:119], v[144:147], v[206:209], v[116:119]
	v_mfma_f32_16x16x32_bf16 v[100:103], v[108:111], v[214:217], v[100:103]
	v_mfma_f32_16x16x32_bf16 v[96:99], v[144:147], v[214:217], v[96:99]
	v_mfma_f32_16x16x32_bf16 v[80:83], v[108:111], v[222:225], v[80:83]
	v_mfma_f32_16x16x32_bf16 v[74:77], v[144:147], v[222:225], v[74:77]
	s_setprio 0
	s_setprio 1
	v_mfma_f32_16x16x32_bf16 v[132:135], v[148:151], v[194:197], 0
	v_mfma_f32_16x16x32_bf16 v[124:127], v[176:179], v[194:197], 0
	v_mfma_f32_16x16x32_bf16 v[112:115], v[148:151], v[202:205], 0
	v_mfma_f32_16x16x32_bf16 v[104:107], v[176:179], v[202:205], 0
	v_mfma_f32_16x16x32_bf16 v[92:95], v[148:151], v[210:213], 0
	v_mfma_f32_16x16x32_bf16 v[84:87], v[176:179], v[210:213], 0
	v_mfma_f32_16x16x32_bf16 v[68:71], v[148:151], v[218:221], 0
	v_mfma_f32_16x16x32_bf16 v[64:67], v[176:179], v[218:221], 0
	v_mfma_f32_16x16x32_bf16 v[132:135], v[152:155], v[198:201], v[132:135]
	v_mfma_f32_16x16x32_bf16 v[124:127], v[190:193], v[198:201], v[124:127]
	v_mfma_f32_16x16x32_bf16 v[112:115], v[152:155], v[206:209], v[112:115]
	v_mfma_f32_16x16x32_bf16 v[104:107], v[190:193], v[206:209], v[104:107]
	v_mfma_f32_16x16x32_bf16 v[92:95], v[152:155], v[214:217], v[92:95]
	v_mfma_f32_16x16x32_bf16 v[84:87], v[190:193], v[214:217], v[84:87]
	v_mfma_f32_16x16x32_bf16 v[68:71], v[152:155], v[222:225], v[68:71]
	v_mfma_f32_16x16x32_bf16 v[64:67], v[190:193], v[222:225], v[64:67]
	s_barrier
	s_setprio 0
	s_add_i32 s96, s83, s71
	v_lshl_add_u64 v[226:227], s[66:67], 0, v[162:163]
	s_mov_b32 m0, s96
	ds_read_b128 v[194:197], v187 offset:16384
	v_xor_b32_e32 v253, 64, v187
	ds_read_b128 v[198:201], v253 offset:16384
	ds_read_b128 v[202:205], v187 offset:18432
	ds_read_b128 v[206:209], v253 offset:18432
	ds_read_b128 v[210:213], v187 offset:20480
	ds_read_b128 v[214:217], v253 offset:20480
	ds_read_b128 v[218:221], v187 offset:22528
	ds_read_b128 v[222:225], v253 offset:22528
	global_load_lds_dwordx4 v[226:227], off
	s_add_i32 m0, s96, 0x2000
	s_add_u32 s96, s66, 0x40000
	v_lshl_add_u64 v[228:229], s[66:67], 0, v[166:167]
	s_addc_u32 s97, s67, 0
	s_add_i32 vcc_lo, s84, s71
	global_load_lds_dwordx4 v[228:229], off
	v_lshl_add_u64 v[78:79], s[96:97], 0, v[162:163]
	s_mov_b32 m0, vcc_lo
	v_lshl_add_u64 v[230:231], s[68:69], 0, v[160:161]
	global_load_lds_dwordx4 v[78:79], off
	v_lshl_add_u64 v[78:79], s[96:97], 0, v[166:167]
	s_add_i32 m0, vcc_lo, 0x2000
	v_lshl_add_u64 v[232:233], s[68:69], 0, v[164:165]
	global_load_lds_dwordx4 v[78:79], off
	s_mov_b32 m0, s74
	s_nop 0
	global_load_lds_dwordx4 v[230:231], off
	s_mov_b32 m0, s75
	s_nop 0
	global_load_lds_dwordx4 v[232:233], off
	s_waitcnt vmcnt(8)
	s_waitcnt lgkmcnt(0)
	.p2align 3
	s_setprio 1
	s_barrier
	v_mfma_f32_16x16x32_bf16 v[60:63], v[88:91], v[194:197], 0
	v_mfma_f32_16x16x32_bf16 v[56:59], v[128:131], v[194:197], 0
	v_mfma_f32_16x16x32_bf16 v[44:47], v[88:91], v[202:205], 0
	v_mfma_f32_16x16x32_bf16 v[40:43], v[128:131], v[202:205], 0
	v_mfma_f32_16x16x32_bf16 v[28:31], v[88:91], v[210:213], 0
	v_mfma_f32_16x16x32_bf16 v[24:27], v[128:131], v[210:213], 0
	v_mfma_f32_16x16x32_bf16 v[12:15], v[88:91], v[218:221], 0
	v_mfma_f32_16x16x32_bf16 v[8:11], v[128:131], v[218:221], 0
	v_mfma_f32_16x16x32_bf16 v[60:63], v[108:111], v[198:201], v[60:63]
	v_mfma_f32_16x16x32_bf16 v[56:59], v[144:147], v[198:201], v[56:59]
	v_mfma_f32_16x16x32_bf16 v[44:47], v[108:111], v[206:209], v[44:47]
	v_mfma_f32_16x16x32_bf16 v[40:43], v[144:147], v[206:209], v[40:43]
	v_mfma_f32_16x16x32_bf16 v[28:31], v[108:111], v[214:217], v[28:31]
	v_mfma_f32_16x16x32_bf16 v[24:27], v[144:147], v[214:217], v[24:27]
	v_mfma_f32_16x16x32_bf16 v[12:15], v[108:111], v[222:225], v[12:15]
	v_mfma_f32_16x16x32_bf16 v[8:11], v[144:147], v[222:225], v[8:11]
	s_setprio 0
	s_setprio 1
	v_mfma_f32_16x16x32_bf16 v[52:55], v[148:151], v[194:197], 0
	v_mfma_f32_16x16x32_bf16 v[48:51], v[176:179], v[194:197], 0
	v_mfma_f32_16x16x32_bf16 v[36:39], v[148:151], v[202:205], 0
	v_mfma_f32_16x16x32_bf16 v[32:35], v[176:179], v[202:205], 0
	v_mfma_f32_16x16x32_bf16 v[20:23], v[148:151], v[210:213], 0
	v_mfma_f32_16x16x32_bf16 v[16:19], v[176:179], v[210:213], 0
	v_mfma_f32_16x16x32_bf16 v[4:7], v[148:151], v[218:221], 0
	v_mfma_f32_16x16x32_bf16 v[0:3], v[176:179], v[218:221], 0
	v_mfma_f32_16x16x32_bf16 v[52:55], v[152:155], v[198:201], v[52:55]
	v_mfma_f32_16x16x32_bf16 v[48:51], v[190:193], v[198:201], v[48:51]
	v_mfma_f32_16x16x32_bf16 v[36:39], v[152:155], v[206:209], v[36:39]
	v_mfma_f32_16x16x32_bf16 v[32:35], v[190:193], v[206:209], v[32:35]
	v_mfma_f32_16x16x32_bf16 v[20:23], v[152:155], v[214:217], v[20:23]
	v_mfma_f32_16x16x32_bf16 v[16:19], v[190:193], v[214:217], v[16:19]
	v_mfma_f32_16x16x32_bf16 v[4:7], v[152:155], v[222:225], v[4:7]
	v_mfma_f32_16x16x32_bf16 v[0:3], v[190:193], v[222:225], v[0:3]
	s_barrier
	s_setprio 0
	s_add_i32 s96, 0, 0x18000
	v_add_u32_e32 v78, s96, v181
	s_add_i32 s97, 0, 0x1c000
	ds_read_b128 v[88:91], v78
	v_xor_b32_e32 v253, 64, v78
	ds_read_b128 v[108:111], v253
	ds_read_b128 v[128:131], v78 offset:2048
	ds_read_b128 v[144:147], v253 offset:2048
	v_add_u32_e32 v78, s97, v181
	ds_read_b128 v[148:151], v78
	v_xor_b32_e32 v253, 64, v78
	ds_read_b128 v[152:155], v253
	ds_read_b128 v[176:179], v78 offset:2048
	ds_read_b128 v[190:193], v253 offset:2048
	s_add_u32 s68, s68, 0x40000
	s_addc_u32 s69, s69, 0
	s_mov_b32 m0, s76
	v_lshl_add_u64 v[78:79], s[68:69], 0, v[160:161]
	ds_read_b128 v[194:197], v187 offset:32768
	v_xor_b32_e32 v253, 64, v187
	ds_read_b128 v[198:201], v253 offset:32768
	ds_read_b128 v[202:205], v187 offset:34816
	ds_read_b128 v[206:209], v253 offset:34816
	ds_read_b128 v[210:213], v187 offset:36864
	ds_read_b128 v[214:217], v253 offset:36864
	ds_read_b128 v[218:221], v187 offset:38912
	ds_read_b128 v[222:225], v253 offset:38912
	global_load_lds_dwordx4 v[78:79], off
	v_lshl_add_u64 v[78:79], s[68:69], 0, v[164:165]
	s_mov_b32 m0, s77
	s_nop 0
	global_load_lds_dwordx4 v[78:79], off
	s_waitcnt vmcnt(8)
	s_waitcnt lgkmcnt(0)
	.p2align 3
	s_setprio 1
	s_barrier
	v_mfma_f32_16x16x32_bf16 v[140:143], v[88:91], v[194:197], v[140:143]
	v_mfma_f32_16x16x32_bf16 v[136:139], v[128:131], v[194:197], v[136:139]
	v_mfma_f32_16x16x32_bf16 v[120:123], v[88:91], v[202:205], v[120:123]
	v_mfma_f32_16x16x32_bf16 v[116:119], v[128:131], v[202:205], v[116:119]
	v_mfma_f32_16x16x32_bf16 v[100:103], v[88:91], v[210:213], v[100:103]
	v_mfma_f32_16x16x32_bf16 v[96:99], v[128:131], v[210:213], v[96:99]
	v_mfma_f32_16x16x32_bf16 v[78:81], v[88:91], v[218:221], v[80:83]
	v_mfma_f32_16x16x32_bf16 v[74:77], v[128:131], v[218:221], v[74:77]
	v_mfma_f32_16x16x32_bf16 v[140:143], v[108:111], v[198:201], v[140:143]
	v_mfma_f32_16x16x32_bf16 v[136:139], v[144:147], v[198:201], v[136:139]
	v_mfma_f32_16x16x32_bf16 v[120:123], v[108:111], v[206:209], v[120:123]
	v_mfma_f32_16x16x32_bf16 v[116:119], v[144:147], v[206:209], v[116:119]
	v_mfma_f32_16x16x32_bf16 v[100:103], v[108:111], v[214:217], v[100:103]
	v_mfma_f32_16x16x32_bf16 v[96:99], v[144:147], v[214:217], v[96:99]
	v_mfma_f32_16x16x32_bf16 v[80:83], v[108:111], v[222:225], v[78:81]
	v_mfma_f32_16x16x32_bf16 v[76:79], v[144:147], v[222:225], v[74:77]
	s_setprio 0
	s_setprio 1
	v_mfma_f32_16x16x32_bf16 v[132:135], v[148:151], v[194:197], v[132:135]
	v_mfma_f32_16x16x32_bf16 v[132:135], v[152:155], v[198:201], v[132:135]
	v_mfma_f32_16x16x32_bf16 v[124:127], v[190:193], v[198:201], v[124:127]
	v_mfma_f32_16x16x32_bf16 v[124:127], v[176:179], v[194:197], v[124:127]
	v_mfma_f32_16x16x32_bf16 v[104:107], v[176:179], v[202:205], v[104:107]
	v_mfma_f32_16x16x32_bf16 v[104:107], v[190:193], v[206:209], v[104:107]
	v_mfma_f32_16x16x32_bf16 v[112:115], v[152:155], v[206:209], v[112:115]
	v_mfma_f32_16x16x32_bf16 v[112:115], v[148:151], v[202:205], v[112:115]
	v_mfma_f32_16x16x32_bf16 v[92:95], v[148:151], v[210:213], v[92:95]
	v_mfma_f32_16x16x32_bf16 v[92:95], v[152:155], v[214:217], v[92:95]
	v_mfma_f32_16x16x32_bf16 v[84:87], v[190:193], v[214:217], v[84:87]
	v_mfma_f32_16x16x32_bf16 v[84:87], v[176:179], v[210:213], v[84:87]
	v_mfma_f32_16x16x32_bf16 v[64:67], v[176:179], v[218:221], v[64:67]
	v_mfma_f32_16x16x32_bf16 v[64:67], v[190:193], v[222:225], v[64:67]
	v_mfma_f32_16x16x32_bf16 v[68:71], v[152:155], v[222:225], v[68:71]
	v_mfma_f32_16x16x32_bf16 v[68:71], v[148:151], v[218:221], v[68:71]
	s_barrier
	s_setprio 0
	s_add_i32 s68, s96, s71
	v_lshl_add_u64 v[74:75], v[226:227], 0, s[28:29]
	s_mov_b32 m0, s68
	ds_read_b128 v[194:197], v187 offset:49152
	v_xor_b32_e32 v253, 64, v187
	ds_read_b128 v[198:201], v253 offset:49152
	ds_read_b128 v[202:205], v187 offset:51200
	ds_read_b128 v[206:209], v253 offset:51200
	ds_read_b128 v[210:213], v187 offset:53248
	ds_read_b128 v[214:217], v253 offset:53248
	ds_read_b128 v[218:221], v187 offset:55296
	ds_read_b128 v[222:225], v253 offset:55296
	global_load_lds_dwordx4 v[74:75], off
	s_add_i32 m0, s68, 0x2000
	s_add_u32 s66, s66, 0x40080
	v_lshl_add_u64 v[74:75], v[228:229], 0, s[28:29]
	s_addc_u32 s67, s67, 0
	s_add_i32 s68, s97, s71
	global_load_lds_dwordx4 v[74:75], off
	v_lshl_add_u64 v[74:75], s[66:67], 0, v[162:163]
	s_mov_b32 m0, s68
	s_nop 0
	global_load_lds_dwordx4 v[74:75], off
	v_lshl_add_u64 v[74:75], s[66:67], 0, v[166:167]
	s_add_i32 m0, s68, 0x2000
	s_nop 0
	global_load_lds_dwordx4 v[74:75], off
	v_lshl_add_u64 v[74:75], v[230:231], 0, s[28:29]
	s_mov_b32 m0, s78
	s_nop 0
	global_load_lds_dwordx4 v[74:75], off
	v_lshl_add_u64 v[74:75], v[232:233], 0, s[28:29]
	s_mov_b32 m0, s79
	s_nop 0
	global_load_lds_dwordx4 v[74:75], off
	s_waitcnt vmcnt(8)
	s_waitcnt lgkmcnt(0)
	.p2align 3
	s_setprio 1
	s_barrier
	v_mfma_f32_16x16x32_bf16 v[60:63], v[88:91], v[194:197], v[60:63]
	v_mfma_f32_16x16x32_bf16 v[60:63], v[108:111], v[198:201], v[60:63]
	v_mfma_f32_16x16x32_bf16 v[56:59], v[144:147], v[198:201], v[56:59]
	v_mfma_f32_16x16x32_bf16 v[56:59], v[128:131], v[194:197], v[56:59]
	v_mfma_f32_16x16x32_bf16 v[40:43], v[128:131], v[202:205], v[40:43]
	v_mfma_f32_16x16x32_bf16 v[40:43], v[144:147], v[206:209], v[40:43]
	v_mfma_f32_16x16x32_bf16 v[44:47], v[108:111], v[206:209], v[44:47]
	v_mfma_f32_16x16x32_bf16 v[44:47], v[88:91], v[202:205], v[44:47]
	v_mfma_f32_16x16x32_bf16 v[28:31], v[88:91], v[210:213], v[28:31]
	v_mfma_f32_16x16x32_bf16 v[28:31], v[108:111], v[214:217], v[28:31]
	v_mfma_f32_16x16x32_bf16 v[24:27], v[144:147], v[214:217], v[24:27]
	v_mfma_f32_16x16x32_bf16 v[24:27], v[128:131], v[210:213], v[24:27]
	v_mfma_f32_16x16x32_bf16 v[8:11], v[128:131], v[218:221], v[8:11]
	v_mfma_f32_16x16x32_bf16 v[8:11], v[144:147], v[222:225], v[8:11]
	v_mfma_f32_16x16x32_bf16 v[12:15], v[108:111], v[222:225], v[12:15]
	v_mfma_f32_16x16x32_bf16 v[12:15], v[88:91], v[218:221], v[12:15]
	s_setprio 0
	s_setprio 1
	v_mfma_f32_16x16x32_bf16 v[52:55], v[148:151], v[194:197], v[52:55]
	v_mfma_f32_16x16x32_bf16 v[52:55], v[152:155], v[198:201], v[52:55]
	v_mfma_f32_16x16x32_bf16 v[48:51], v[190:193], v[198:201], v[48:51]
	v_mfma_f32_16x16x32_bf16 v[48:51], v[176:179], v[194:197], v[48:51]
	v_mfma_f32_16x16x32_bf16 v[32:35], v[176:179], v[202:205], v[32:35]
	v_mfma_f32_16x16x32_bf16 v[32:35], v[190:193], v[206:209], v[32:35]
	v_mfma_f32_16x16x32_bf16 v[36:39], v[152:155], v[206:209], v[36:39]
	v_mfma_f32_16x16x32_bf16 v[36:39], v[148:151], v[202:205], v[36:39]
	v_mfma_f32_16x16x32_bf16 v[20:23], v[148:151], v[210:213], v[20:23]
	v_mfma_f32_16x16x32_bf16 v[20:23], v[152:155], v[214:217], v[20:23]
	v_mfma_f32_16x16x32_bf16 v[16:19], v[190:193], v[214:217], v[16:19]
	v_mfma_f32_16x16x32_bf16 v[16:19], v[176:179], v[210:213], v[16:19]
	v_mfma_f32_16x16x32_bf16 v[0:3], v[176:179], v[218:221], v[0:3]
	v_mfma_f32_16x16x32_bf16 v[0:3], v[190:193], v[222:225], v[0:3]
	v_mfma_f32_16x16x32_bf16 v[4:7], v[152:155], v[222:225], v[4:7]
	v_mfma_f32_16x16x32_bf16 v[4:7], v[148:151], v[218:221], v[4:7]
	s_barrier
	s_setprio 0
	s_add_i32 s95, s95, 2
	s_add_u32 s93, s93, 0x100
	s_addc_u32 s94, s94, 0
	s_add_u32 s14, s14, 0x100
	s_addc_u32 s15, s15, 0
	s_branch .LBB0_256
.LBB0_255:
	v_add_u32_e32 v74, s83, v181
	ds_read_b128 v[88:91], v74
	v_xor_b32_e32 v253, 64, v74
	ds_read_b128 v[108:111], v253
	ds_read_b128 v[128:131], v74 offset:2048
	ds_read_b128 v[144:147], v253 offset:2048
	v_add_u32_e32 v74, s84, v181
	ds_read_b128 v[148:151], v74
	v_xor_b32_e32 v253, 64, v74
	ds_read_b128 v[152:155], v253
	ds_read_b128 v[176:179], v74 offset:2048
	ds_read_b128 v[190:193], v253 offset:2048
	s_add_u32 s68, s14, 0xfffc0080
	s_addc_u32 s69, s15, -1
	s_and_b64 s[66:67], s[66:67], exec
	s_cselect_b32 s69, s3, s69
	s_cselect_b32 s68, s61, s68
	s_cselect_b32 s67, s91, s94
	s_cselect_b32 s66, s92, s93
	v_lshl_add_u64 v[74:75], s[14:15], 0, v[170:171]
	s_add_i32 m0, s74, 0xc000
	ds_read_b128 v[194:197], v187
	v_xor_b32_e32 v253, 64, v187
	ds_read_b128 v[198:201], v253
	ds_read_b128 v[202:205], v187 offset:2048
	ds_read_b128 v[206:209], v253 offset:2048
	ds_read_b128 v[210:213], v187 offset:4096
	ds_read_b128 v[214:217], v253 offset:4096
	ds_read_b128 v[218:221], v187 offset:6144
	ds_read_b128 v[222:225], v253 offset:6144
	global_load_lds_dwordx4 v[74:75], off
	v_lshl_add_u64 v[74:75], s[14:15], 0, v[168:169]
	s_add_i32 m0, s74, 0xe000
	s_nop 0
	global_load_lds_dwordx4 v[74:75], off
	s_waitcnt vmcnt(8)
	s_waitcnt lgkmcnt(0)
	.p2align 3
	s_setprio 1
	s_barrier
	v_mfma_f32_16x16x32_bf16 v[140:143], v[88:91], v[194:197], v[140:143]
	v_mfma_f32_16x16x32_bf16 v[136:139], v[128:131], v[194:197], v[136:139]
	v_mfma_f32_16x16x32_bf16 v[120:123], v[88:91], v[202:205], v[120:123]
	v_mfma_f32_16x16x32_bf16 v[116:119], v[128:131], v[202:205], v[116:119]
	v_mfma_f32_16x16x32_bf16 v[100:103], v[88:91], v[210:213], v[100:103]
	v_mfma_f32_16x16x32_bf16 v[96:99], v[128:131], v[210:213], v[96:99]
	v_mfma_f32_16x16x32_bf16 v[80:83], v[88:91], v[218:221], v[80:83]
	v_mfma_f32_16x16x32_bf16 v[74:77], v[128:131], v[218:221], v[76:79]
	v_mfma_f32_16x16x32_bf16 v[140:143], v[108:111], v[198:201], v[140:143]
	v_mfma_f32_16x16x32_bf16 v[136:139], v[144:147], v[198:201], v[136:139]
	v_mfma_f32_16x16x32_bf16 v[120:123], v[108:111], v[206:209], v[120:123]
	v_mfma_f32_16x16x32_bf16 v[116:119], v[144:147], v[206:209], v[116:119]
	v_mfma_f32_16x16x32_bf16 v[100:103], v[108:111], v[214:217], v[100:103]
	v_mfma_f32_16x16x32_bf16 v[96:99], v[144:147], v[214:217], v[96:99]
	v_mfma_f32_16x16x32_bf16 v[80:83], v[108:111], v[222:225], v[80:83]
	v_mfma_f32_16x16x32_bf16 v[74:77], v[144:147], v[222:225], v[74:77]
	s_setprio 0
	s_setprio 1
	v_mfma_f32_16x16x32_bf16 v[132:135], v[148:151], v[194:197], v[132:135]
	v_mfma_f32_16x16x32_bf16 v[132:135], v[152:155], v[198:201], v[132:135]
	v_mfma_f32_16x16x32_bf16 v[124:127], v[190:193], v[198:201], v[124:127]
	v_mfma_f32_16x16x32_bf16 v[124:127], v[176:179], v[194:197], v[124:127]
	v_mfma_f32_16x16x32_bf16 v[104:107], v[176:179], v[202:205], v[104:107]
	v_mfma_f32_16x16x32_bf16 v[104:107], v[190:193], v[206:209], v[104:107]
	v_mfma_f32_16x16x32_bf16 v[112:115], v[152:155], v[206:209], v[112:115]
	v_mfma_f32_16x16x32_bf16 v[112:115], v[148:151], v[202:205], v[112:115]
	v_mfma_f32_16x16x32_bf16 v[92:95], v[148:151], v[210:213], v[92:95]
	v_mfma_f32_16x16x32_bf16 v[92:95], v[152:155], v[214:217], v[92:95]
	v_mfma_f32_16x16x32_bf16 v[84:87], v[190:193], v[214:217], v[84:87]
	v_mfma_f32_16x16x32_bf16 v[84:87], v[176:179], v[210:213], v[84:87]
	v_mfma_f32_16x16x32_bf16 v[64:67], v[176:179], v[218:221], v[64:67]
	v_mfma_f32_16x16x32_bf16 v[64:67], v[190:193], v[222:225], v[64:67]
	v_mfma_f32_16x16x32_bf16 v[68:71], v[152:155], v[222:225], v[68:71]
	v_mfma_f32_16x16x32_bf16 v[68:71], v[148:151], v[218:221], v[68:71]
	s_barrier
	s_setprio 0
	s_add_i32 s96, s83, s71
	v_lshl_add_u64 v[226:227], s[66:67], 0, v[162:163]
	s_mov_b32 m0, s96
	ds_read_b128 v[194:197], v187 offset:16384
	v_xor_b32_e32 v253, 64, v187
	ds_read_b128 v[198:201], v253 offset:16384
	ds_read_b128 v[202:205], v187 offset:18432
	ds_read_b128 v[206:209], v253 offset:18432
	ds_read_b128 v[210:213], v187 offset:20480
	ds_read_b128 v[214:217], v253 offset:20480
	ds_read_b128 v[218:221], v187 offset:22528
	ds_read_b128 v[222:225], v253 offset:22528
	global_load_lds_dwordx4 v[226:227], off
	s_add_i32 m0, s96, 0x2000
	s_add_u32 s96, s66, 0x40000
	v_lshl_add_u64 v[228:229], s[66:67], 0, v[166:167]
	s_addc_u32 s97, s67, 0
	s_add_i32 vcc_lo, s84, s71
	global_load_lds_dwordx4 v[228:229], off
	v_lshl_add_u64 v[78:79], s[96:97], 0, v[162:163]
	s_mov_b32 m0, vcc_lo
	v_lshl_add_u64 v[230:231], s[68:69], 0, v[160:161]
	global_load_lds_dwordx4 v[78:79], off
	v_lshl_add_u64 v[78:79], s[96:97], 0, v[166:167]
	s_add_i32 m0, vcc_lo, 0x2000
	v_lshl_add_u64 v[232:233], s[68:69], 0, v[164:165]
	global_load_lds_dwordx4 v[78:79], off
	s_mov_b32 m0, s74
	s_nop 0
	global_load_lds_dwordx4 v[230:231], off
	s_mov_b32 m0, s75
	s_nop 0
	global_load_lds_dwordx4 v[232:233], off
	s_waitcnt vmcnt(8)
	s_waitcnt lgkmcnt(0)
	.p2align 3
	s_setprio 1
	s_barrier
	v_mfma_f32_16x16x32_bf16 v[60:63], v[88:91], v[194:197], v[60:63]
	v_mfma_f32_16x16x32_bf16 v[60:63], v[108:111], v[198:201], v[60:63]
	v_mfma_f32_16x16x32_bf16 v[56:59], v[144:147], v[198:201], v[56:59]
	v_mfma_f32_16x16x32_bf16 v[56:59], v[128:131], v[194:197], v[56:59]
	v_mfma_f32_16x16x32_bf16 v[40:43], v[128:131], v[202:205], v[40:43]
	v_mfma_f32_16x16x32_bf16 v[40:43], v[144:147], v[206:209], v[40:43]
	v_mfma_f32_16x16x32_bf16 v[44:47], v[108:111], v[206:209], v[44:47]
	v_mfma_f32_16x16x32_bf16 v[44:47], v[88:91], v[202:205], v[44:47]
	v_mfma_f32_16x16x32_bf16 v[28:31], v[88:91], v[210:213], v[28:31]
	v_mfma_f32_16x16x32_bf16 v[28:31], v[108:111], v[214:217], v[28:31]
	v_mfma_f32_16x16x32_bf16 v[24:27], v[144:147], v[214:217], v[24:27]
	v_mfma_f32_16x16x32_bf16 v[24:27], v[128:131], v[210:213], v[24:27]
	v_mfma_f32_16x16x32_bf16 v[8:11], v[128:131], v[218:221], v[8:11]
	v_mfma_f32_16x16x32_bf16 v[8:11], v[144:147], v[222:225], v[8:11]
	v_mfma_f32_16x16x32_bf16 v[12:15], v[108:111], v[222:225], v[12:15]
	v_mfma_f32_16x16x32_bf16 v[12:15], v[88:91], v[218:221], v[12:15]
	s_setprio 0
	s_setprio 1
	v_mfma_f32_16x16x32_bf16 v[52:55], v[148:151], v[194:197], v[52:55]
	v_mfma_f32_16x16x32_bf16 v[52:55], v[152:155], v[198:201], v[52:55]
	v_mfma_f32_16x16x32_bf16 v[48:51], v[190:193], v[198:201], v[48:51]
	v_mfma_f32_16x16x32_bf16 v[48:51], v[176:179], v[194:197], v[48:51]
	v_mfma_f32_16x16x32_bf16 v[32:35], v[176:179], v[202:205], v[32:35]
	v_mfma_f32_16x16x32_bf16 v[32:35], v[190:193], v[206:209], v[32:35]
	v_mfma_f32_16x16x32_bf16 v[36:39], v[152:155], v[206:209], v[36:39]
	v_mfma_f32_16x16x32_bf16 v[36:39], v[148:151], v[202:205], v[36:39]
	v_mfma_f32_16x16x32_bf16 v[20:23], v[148:151], v[210:213], v[20:23]
	v_mfma_f32_16x16x32_bf16 v[20:23], v[152:155], v[214:217], v[20:23]
	v_mfma_f32_16x16x32_bf16 v[16:19], v[190:193], v[214:217], v[16:19]
	v_mfma_f32_16x16x32_bf16 v[16:19], v[176:179], v[210:213], v[16:19]
	v_mfma_f32_16x16x32_bf16 v[0:3], v[176:179], v[218:221], v[0:3]
	v_mfma_f32_16x16x32_bf16 v[0:3], v[190:193], v[222:225], v[0:3]
	v_mfma_f32_16x16x32_bf16 v[4:7], v[152:155], v[222:225], v[4:7]
	v_mfma_f32_16x16x32_bf16 v[4:7], v[148:151], v[218:221], v[4:7]
	s_barrier
	s_setprio 0
	s_add_i32 s96, 0, 0x18000
	v_add_u32_e32 v78, s96, v181
	s_add_i32 s97, 0, 0x1c000
	ds_read_b128 v[88:91], v78
	v_xor_b32_e32 v253, 64, v78
	ds_read_b128 v[108:111], v253
	ds_read_b128 v[128:131], v78 offset:2048
	ds_read_b128 v[144:147], v253 offset:2048
	v_add_u32_e32 v78, s97, v181
	ds_read_b128 v[148:151], v78
	v_xor_b32_e32 v253, 64, v78
	ds_read_b128 v[152:155], v253
	ds_read_b128 v[176:179], v78 offset:2048
	ds_read_b128 v[190:193], v253 offset:2048
	s_add_u32 s68, s68, 0x40000
	s_addc_u32 s69, s69, 0
	s_mov_b32 m0, s76
	v_lshl_add_u64 v[78:79], s[68:69], 0, v[160:161]
	ds_read_b128 v[194:197], v187 offset:32768
	v_xor_b32_e32 v253, 64, v187
	ds_read_b128 v[198:201], v253 offset:32768
	ds_read_b128 v[202:205], v187 offset:34816
	ds_read_b128 v[206:209], v253 offset:34816
	ds_read_b128 v[210:213], v187 offset:36864
	ds_read_b128 v[214:217], v253 offset:36864
	ds_read_b128 v[218:221], v187 offset:38912
	ds_read_b128 v[222:225], v253 offset:38912
	global_load_lds_dwordx4 v[78:79], off
	v_lshl_add_u64 v[78:79], s[68:69], 0, v[164:165]
	s_mov_b32 m0, s77
	s_nop 0
	global_load_lds_dwordx4 v[78:79], off
	s_waitcnt vmcnt(8)
	s_waitcnt lgkmcnt(0)
	.p2align 3
	s_setprio 1
	s_barrier
	v_mfma_f32_16x16x32_bf16 v[140:143], v[88:91], v[194:197], v[140:143]
	v_mfma_f32_16x16x32_bf16 v[136:139], v[128:131], v[194:197], v[136:139]
	v_mfma_f32_16x16x32_bf16 v[120:123], v[88:91], v[202:205], v[120:123]
	v_mfma_f32_16x16x32_bf16 v[116:119], v[128:131], v[202:205], v[116:119]
	v_mfma_f32_16x16x32_bf16 v[100:103], v[88:91], v[210:213], v[100:103]
	v_mfma_f32_16x16x32_bf16 v[96:99], v[128:131], v[210:213], v[96:99]
	v_mfma_f32_16x16x32_bf16 v[78:81], v[88:91], v[218:221], v[80:83]
	v_mfma_f32_16x16x32_bf16 v[74:77], v[128:131], v[218:221], v[74:77]
	v_mfma_f32_16x16x32_bf16 v[140:143], v[108:111], v[198:201], v[140:143]
	v_mfma_f32_16x16x32_bf16 v[136:139], v[144:147], v[198:201], v[136:139]
	v_mfma_f32_16x16x32_bf16 v[120:123], v[108:111], v[206:209], v[120:123]
	v_mfma_f32_16x16x32_bf16 v[116:119], v[144:147], v[206:209], v[116:119]
	v_mfma_f32_16x16x32_bf16 v[100:103], v[108:111], v[214:217], v[100:103]
	v_mfma_f32_16x16x32_bf16 v[96:99], v[144:147], v[214:217], v[96:99]
	v_mfma_f32_16x16x32_bf16 v[80:83], v[108:111], v[222:225], v[78:81]
	v_mfma_f32_16x16x32_bf16 v[76:79], v[144:147], v[222:225], v[74:77]
	s_setprio 0
	s_setprio 1
	v_mfma_f32_16x16x32_bf16 v[132:135], v[148:151], v[194:197], v[132:135]
	v_mfma_f32_16x16x32_bf16 v[132:135], v[152:155], v[198:201], v[132:135]
	v_mfma_f32_16x16x32_bf16 v[124:127], v[190:193], v[198:201], v[124:127]
	v_mfma_f32_16x16x32_bf16 v[124:127], v[176:179], v[194:197], v[124:127]
	v_mfma_f32_16x16x32_bf16 v[104:107], v[176:179], v[202:205], v[104:107]
	v_mfma_f32_16x16x32_bf16 v[104:107], v[190:193], v[206:209], v[104:107]
	v_mfma_f32_16x16x32_bf16 v[112:115], v[152:155], v[206:209], v[112:115]
	v_mfma_f32_16x16x32_bf16 v[112:115], v[148:151], v[202:205], v[112:115]
	v_mfma_f32_16x16x32_bf16 v[92:95], v[148:151], v[210:213], v[92:95]
	v_mfma_f32_16x16x32_bf16 v[92:95], v[152:155], v[214:217], v[92:95]
	v_mfma_f32_16x16x32_bf16 v[84:87], v[190:193], v[214:217], v[84:87]
	v_mfma_f32_16x16x32_bf16 v[84:87], v[176:179], v[210:213], v[84:87]
	v_mfma_f32_16x16x32_bf16 v[64:67], v[176:179], v[218:221], v[64:67]
	v_mfma_f32_16x16x32_bf16 v[64:67], v[190:193], v[222:225], v[64:67]
	v_mfma_f32_16x16x32_bf16 v[68:71], v[152:155], v[222:225], v[68:71]
	v_mfma_f32_16x16x32_bf16 v[68:71], v[148:151], v[218:221], v[68:71]
	s_barrier
	s_setprio 0
	s_add_i32 s68, s96, s71
	v_lshl_add_u64 v[74:75], v[226:227], 0, s[28:29]
	s_mov_b32 m0, s68
	ds_read_b128 v[194:197], v187 offset:49152
	v_xor_b32_e32 v253, 64, v187
	ds_read_b128 v[198:201], v253 offset:49152
	ds_read_b128 v[202:205], v187 offset:51200
	ds_read_b128 v[206:209], v253 offset:51200
	ds_read_b128 v[210:213], v187 offset:53248
	ds_read_b128 v[214:217], v253 offset:53248
	ds_read_b128 v[218:221], v187 offset:55296
	ds_read_b128 v[222:225], v253 offset:55296
	global_load_lds_dwordx4 v[74:75], off
	s_add_i32 m0, s68, 0x2000
	s_add_u32 s66, s66, 0x40080
	v_lshl_add_u64 v[74:75], v[228:229], 0, s[28:29]
	s_addc_u32 s67, s67, 0
	s_add_i32 s68, s97, s71
	global_load_lds_dwordx4 v[74:75], off
	v_lshl_add_u64 v[74:75], s[66:67], 0, v[162:163]
	s_mov_b32 m0, s68
	s_nop 0
	global_load_lds_dwordx4 v[74:75], off
	v_lshl_add_u64 v[74:75], s[66:67], 0, v[166:167]
	s_add_i32 m0, s68, 0x2000
	s_nop 0
	global_load_lds_dwordx4 v[74:75], off
	v_lshl_add_u64 v[74:75], v[230:231], 0, s[28:29]
	s_mov_b32 m0, s78
	s_nop 0
	global_load_lds_dwordx4 v[74:75], off
	v_lshl_add_u64 v[74:75], v[232:233], 0, s[28:29]
	s_mov_b32 m0, s79
	s_nop 0
	global_load_lds_dwordx4 v[74:75], off
	s_waitcnt vmcnt(8)
	s_waitcnt lgkmcnt(0)
	.p2align 3
	s_setprio 1
	s_barrier
	v_mfma_f32_16x16x32_bf16 v[60:63], v[88:91], v[194:197], v[60:63]
	v_mfma_f32_16x16x32_bf16 v[60:63], v[108:111], v[198:201], v[60:63]
	v_mfma_f32_16x16x32_bf16 v[56:59], v[144:147], v[198:201], v[56:59]
	v_mfma_f32_16x16x32_bf16 v[56:59], v[128:131], v[194:197], v[56:59]
	v_mfma_f32_16x16x32_bf16 v[40:43], v[128:131], v[202:205], v[40:43]
	v_mfma_f32_16x16x32_bf16 v[40:43], v[144:147], v[206:209], v[40:43]
	v_mfma_f32_16x16x32_bf16 v[44:47], v[108:111], v[206:209], v[44:47]
	v_mfma_f32_16x16x32_bf16 v[44:47], v[88:91], v[202:205], v[44:47]
	v_mfma_f32_16x16x32_bf16 v[28:31], v[88:91], v[210:213], v[28:31]
	v_mfma_f32_16x16x32_bf16 v[28:31], v[108:111], v[214:217], v[28:31]
	v_mfma_f32_16x16x32_bf16 v[24:27], v[144:147], v[214:217], v[24:27]
	v_mfma_f32_16x16x32_bf16 v[24:27], v[128:131], v[210:213], v[24:27]
	v_mfma_f32_16x16x32_bf16 v[8:11], v[128:131], v[218:221], v[8:11]
	v_mfma_f32_16x16x32_bf16 v[8:11], v[144:147], v[222:225], v[8:11]
	v_mfma_f32_16x16x32_bf16 v[12:15], v[108:111], v[222:225], v[12:15]
	v_mfma_f32_16x16x32_bf16 v[12:15], v[88:91], v[218:221], v[12:15]
	s_setprio 0
	s_setprio 1
	v_mfma_f32_16x16x32_bf16 v[52:55], v[148:151], v[194:197], v[52:55]
	v_mfma_f32_16x16x32_bf16 v[52:55], v[152:155], v[198:201], v[52:55]
	v_mfma_f32_16x16x32_bf16 v[48:51], v[190:193], v[198:201], v[48:51]
	v_mfma_f32_16x16x32_bf16 v[48:51], v[176:179], v[194:197], v[48:51]
	v_mfma_f32_16x16x32_bf16 v[32:35], v[176:179], v[202:205], v[32:35]
	v_mfma_f32_16x16x32_bf16 v[32:35], v[190:193], v[206:209], v[32:35]
	v_mfma_f32_16x16x32_bf16 v[36:39], v[152:155], v[206:209], v[36:39]
	v_mfma_f32_16x16x32_bf16 v[36:39], v[148:151], v[202:205], v[36:39]
	v_mfma_f32_16x16x32_bf16 v[20:23], v[148:151], v[210:213], v[20:23]
	v_mfma_f32_16x16x32_bf16 v[20:23], v[152:155], v[214:217], v[20:23]
	v_mfma_f32_16x16x32_bf16 v[16:19], v[190:193], v[214:217], v[16:19]
	v_mfma_f32_16x16x32_bf16 v[16:19], v[176:179], v[210:213], v[16:19]
	v_mfma_f32_16x16x32_bf16 v[0:3], v[176:179], v[218:221], v[0:3]
	v_mfma_f32_16x16x32_bf16 v[0:3], v[190:193], v[222:225], v[0:3]
	v_mfma_f32_16x16x32_bf16 v[4:7], v[152:155], v[222:225], v[4:7]
	v_mfma_f32_16x16x32_bf16 v[4:7], v[148:151], v[218:221], v[4:7]
	s_barrier
	s_setprio 0
	s_add_i32 s95, s95, 2
	s_add_u32 s93, s93, 0x100
	s_addc_u32 s94, s94, 0
	s_add_u32 s14, s14, 0x100
	s_addc_u32 s15, s15, 0
	s_cmp_gt_u32 s95, 13
	s_cbranch_scc1 .LBB0_258

.LBB0_439:
	s_ashr_i32 s53, s52, 31
	s_lshl_b64 s[54:55], s[52:53], 20
	s_add_u32 s54, s35, s54
	s_addc_u32 s55, s66, s55
	s_and_b64 s[56:57], s[12:13], exec
	s_cselect_b32 s15, s55, s63
	s_cselect_b32 s53, s54, s62
	s_ashr_i32 s51, s50, 31
	s_lshl_b64 s[56:57], s[50:51], 20
	s_add_u32 s56, s67, s56
	s_addc_u32 s57, s68, s57
	s_and_b64 s[64:65], s[12:13], exec
	s_cselect_b32 s51, s57, s61
	s_cselect_b32 s59, s56, s60
	s_add_u32 s81, s60, 0x100
	s_addc_u32 s82, s61, 0
	s_add_u32 s60, s62, 0x80080
	s_addc_u32 s61, s63, 0
	s_mov_b32 s83, -2
	s_waitcnt lgkmcnt(0)
	s_cmp_eq_u32 s74, 1
	s_cbranch_scc1 .Lfa_3
	ds_read_b128 v[128:131], v189
	v_xor_b32_e32 v253, 64, v189
	ds_read_b128 v[132:135], v253
	ds_read_b128 v[136:139], v189 offset:2048
	ds_read_b128 v[140:143], v253 offset:2048
	ds_read_b128 v[144:147], v190
	v_xor_b32_e32 v253, 64, v190
	ds_read_b128 v[148:151], v253
	ds_read_b128 v[172:175], v190 offset:2048
	ds_read_b128 v[176:179], v253 offset:2048
	s_add_u32 s62, s60, 0xfff80080
	s_addc_u32 s63, s61, -1
	s_cmp_eq_u32 s83, 28
	s_cselect_b32 s65, s15, s63
	s_cselect_b32 s64, s53, s62
	s_cselect_b32 s63, s51, s82
	s_cselect_b32 s62, s59, s81
	v_lshl_add_u64 v[222:223], s[60:61], 0, v[166:167]
	s_add_i32 m0, s70, 0xc000
	ds_read_b128 v[180:183], v191
	v_xor_b32_e32 v253, 64, v191
	ds_read_b128 v[194:197], v253
	ds_read_b128 v[198:201], v191 offset:2048
	ds_read_b128 v[202:205], v253 offset:2048
	ds_read_b128 v[206:209], v191 offset:4096
	ds_read_b128 v[210:213], v253 offset:4096
	ds_read_b128 v[214:217], v191 offset:6144
	ds_read_b128 v[218:221], v253 offset:6144
	global_load_lds_dwordx4 v[222:223], off
	v_lshl_add_u64 v[222:223], s[60:61], 0, v[164:165]
	s_add_i32 m0, s70, 0xe000
	s_nop 0
	global_load_lds_dwordx4 v[222:223], off
	s_waitcnt vmcnt(24)
	s_waitcnt lgkmcnt(0)
	.p2align 3
	s_setprio 1
	s_barrier
	v_mfma_f32_16x16x32_bf16 v[124:127], v[128:131], v[180:183], 0
	v_mfma_f32_16x16x32_bf16 v[120:123], v[136:139], v[180:183], 0
	v_mfma_f32_16x16x32_bf16 v[108:111], v[128:131], v[198:201], 0
	v_mfma_f32_16x16x32_bf16 v[104:107], v[136:139], v[198:201], 0
	v_mfma_f32_16x16x32_bf16 v[92:95], v[128:131], v[206:209], 0
	v_mfma_f32_16x16x32_bf16 v[88:91], v[136:139], v[206:209], 0
	v_mfma_f32_16x16x32_bf16 v[76:79], v[128:131], v[214:217], 0
	v_mfma_f32_16x16x32_bf16 v[72:75], v[136:139], v[214:217], 0
	v_mfma_f32_16x16x32_bf16 v[124:127], v[132:135], v[194:197], v[124:127]
	v_mfma_f32_16x16x32_bf16 v[120:123], v[140:143], v[194:197], v[120:123]
	v_mfma_f32_16x16x32_bf16 v[108:111], v[132:135], v[202:205], v[108:111]
	v_mfma_f32_16x16x32_bf16 v[104:107], v[140:143], v[202:205], v[104:107]
	v_mfma_f32_16x16x32_bf16 v[92:95], v[132:135], v[210:213], v[92:95]
	v_mfma_f32_16x16x32_bf16 v[88:91], v[140:143], v[210:213], v[88:91]
	v_mfma_f32_16x16x32_bf16 v[76:79], v[132:135], v[218:221], v[76:79]
	v_mfma_f32_16x16x32_bf16 v[72:75], v[140:143], v[218:221], v[72:75]
	s_setprio 0
	s_setprio 1
	v_mfma_f32_16x16x32_bf16 v[116:119], v[144:147], v[180:183], 0
	v_mfma_f32_16x16x32_bf16 v[112:115], v[172:175], v[180:183], 0
	v_mfma_f32_16x16x32_bf16 v[100:103], v[144:147], v[198:201], 0
	v_mfma_f32_16x16x32_bf16 v[96:99], v[172:175], v[198:201], 0
	v_mfma_f32_16x16x32_bf16 v[84:87], v[144:147], v[206:209], 0
	v_mfma_f32_16x16x32_bf16 v[80:83], v[172:175], v[206:209], 0
	v_mfma_f32_16x16x32_bf16 v[68:71], v[144:147], v[214:217], 0
	v_mfma_f32_16x16x32_bf16 v[64:67], v[172:175], v[214:217], 0
	v_mfma_f32_16x16x32_bf16 v[116:119], v[148:151], v[194:197], v[116:119]
	v_mfma_f32_16x16x32_bf16 v[112:115], v[176:179], v[194:197], v[112:115]
	v_mfma_f32_16x16x32_bf16 v[100:103], v[148:151], v[202:205], v[100:103]
	v_mfma_f32_16x16x32_bf16 v[96:99], v[176:179], v[202:205], v[96:99]
	v_mfma_f32_16x16x32_bf16 v[84:87], v[148:151], v[210:213], v[84:87]
	v_mfma_f32_16x16x32_bf16 v[80:83], v[176:179], v[210:213], v[80:83]
	v_mfma_f32_16x16x32_bf16 v[68:71], v[148:151], v[218:221], v[68:71]
	v_mfma_f32_16x16x32_bf16 v[64:67], v[176:179], v[218:221], v[64:67]
	s_barrier
	s_setprio 0
	s_add_i32 s84, s79, s69
	v_lshl_add_u64 v[222:223], s[62:63], 0, v[154:155]
	s_mov_b32 m0, s84
	ds_read_b128 v[180:183], v191 offset:16384
	v_xor_b32_e32 v253, 64, v191
	ds_read_b128 v[194:197], v253 offset:16384
	ds_read_b128 v[198:201], v191 offset:18432
	ds_read_b128 v[202:205], v253 offset:18432
	ds_read_b128 v[206:209], v191 offset:20480
	ds_read_b128 v[210:213], v253 offset:20480
	ds_read_b128 v[214:217], v191 offset:22528
	ds_read_b128 v[218:221], v253 offset:22528
	global_load_lds_dwordx4 v[222:223], off
	s_add_i32 m0, s84, 0x2000
	s_add_u32 s84, s62, 0x80000
	v_lshl_add_u64 v[224:225], s[62:63], 0, v[162:163]
	s_addc_u32 s85, s63, 0
	s_add_i32 s86, s80, s69
	global_load_lds_dwordx4 v[224:225], off
	v_lshl_add_u64 v[226:227], s[84:85], 0, v[154:155]
	s_mov_b32 m0, s86
	v_lshl_add_u64 v[228:229], s[64:65], 0, v[160:161]
	global_load_lds_dwordx4 v[226:227], off
	v_lshl_add_u64 v[226:227], s[84:85], 0, v[162:163]
	s_add_i32 m0, s86, 0x2000
	s_nop 0
	global_load_lds_dwordx4 v[226:227], off
	v_lshl_add_u64 v[226:227], s[64:65], 0, v[152:153]
	s_mov_b32 m0, s70
	s_nop 0
	global_load_lds_dwordx4 v[226:227], off
	s_mov_b32 m0, s71
	s_nop 0
	global_load_lds_dwordx4 v[228:229], off
	s_waitcnt vmcnt(24)
	s_waitcnt lgkmcnt(0)
	.p2align 3
	s_setprio 1
	s_barrier
	v_mfma_f32_16x16x32_bf16 v[60:63], v[128:131], v[180:183], 0
	v_mfma_f32_16x16x32_bf16 v[56:59], v[136:139], v[180:183], 0
	v_mfma_f32_16x16x32_bf16 v[44:47], v[128:131], v[198:201], 0
	v_mfma_f32_16x16x32_bf16 v[40:43], v[136:139], v[198:201], 0
	v_mfma_f32_16x16x32_bf16 v[28:31], v[128:131], v[206:209], 0
	v_mfma_f32_16x16x32_bf16 v[24:27], v[136:139], v[206:209], 0
	v_mfma_f32_16x16x32_bf16 v[12:15], v[128:131], v[214:217], 0
	v_mfma_f32_16x16x32_bf16 v[8:11], v[136:139], v[214:217], 0
	v_mfma_f32_16x16x32_bf16 v[60:63], v[132:135], v[194:197], v[60:63]
	v_mfma_f32_16x16x32_bf16 v[56:59], v[140:143], v[194:197], v[56:59]
	v_mfma_f32_16x16x32_bf16 v[44:47], v[132:135], v[202:205], v[44:47]
	v_mfma_f32_16x16x32_bf16 v[40:43], v[140:143], v[202:205], v[40:43]
	v_mfma_f32_16x16x32_bf16 v[28:31], v[132:135], v[210:213], v[28:31]
	v_mfma_f32_16x16x32_bf16 v[24:27], v[140:143], v[210:213], v[24:27]
	v_mfma_f32_16x16x32_bf16 v[12:15], v[132:135], v[218:221], v[12:15]
	v_mfma_f32_16x16x32_bf16 v[8:11], v[140:143], v[218:221], v[8:11]
	s_setprio 0
	s_setprio 1
	v_mfma_f32_16x16x32_bf16 v[52:55], v[144:147], v[180:183], 0
	v_mfma_f32_16x16x32_bf16 v[48:51], v[172:175], v[180:183], 0
	v_mfma_f32_16x16x32_bf16 v[36:39], v[144:147], v[198:201], 0
	v_mfma_f32_16x16x32_bf16 v[32:35], v[172:175], v[198:201], 0
	v_mfma_f32_16x16x32_bf16 v[20:23], v[144:147], v[206:209], 0
	v_mfma_f32_16x16x32_bf16 v[16:19], v[172:175], v[206:209], 0
	v_mfma_f32_16x16x32_bf16 v[4:7], v[144:147], v[214:217], 0
	v_mfma_f32_16x16x32_bf16 v[0:3], v[172:175], v[214:217], 0
	v_mfma_f32_16x16x32_bf16 v[52:55], v[148:151], v[194:197], v[52:55]
	v_mfma_f32_16x16x32_bf16 v[48:51], v[176:179], v[194:197], v[48:51]
	v_mfma_f32_16x16x32_bf16 v[36:39], v[148:151], v[202:205], v[36:39]
	v_mfma_f32_16x16x32_bf16 v[32:35], v[176:179], v[202:205], v[32:35]
	v_mfma_f32_16x16x32_bf16 v[20:23], v[148:151], v[210:213], v[20:23]
	v_mfma_f32_16x16x32_bf16 v[16:19], v[176:179], v[210:213], v[16:19]
	v_mfma_f32_16x16x32_bf16 v[4:7], v[148:151], v[218:221], v[4:7]
	v_mfma_f32_16x16x32_bf16 v[0:3], v[176:179], v[218:221], v[0:3]
	s_barrier
	s_setprio 0
	s_add_i32 s84, 0, 0x18000
	s_add_i32 s85, 0, 0x1c000
	v_add_u32_e32 v140, s84, v186
	v_add_u32_e32 v176, s85, v186
	ds_read_b128 v[128:131], v140
	v_xor_b32_e32 v253, 64, v140
	ds_read_b128 v[132:135], v253
	ds_read_b128 v[136:139], v140 offset:2048
	ds_read_b128 v[140:143], v253 offset:2048
	ds_read_b128 v[144:147], v176
	v_xor_b32_e32 v253, 64, v176
	ds_read_b128 v[148:151], v253
	ds_read_b128 v[172:175], v176 offset:2048
	ds_read_b128 v[176:179], v253 offset:2048
	s_add_u32 s64, s64, 0x80000
	s_addc_u32 s65, s65, 0
	s_mov_b32 m0, s72
	v_lshl_add_u64 v[230:231], s[64:65], 0, v[152:153]
	ds_read_b128 v[180:183], v191 offset:32768
	v_xor_b32_e32 v253, 64, v191
	ds_read_b128 v[194:197], v253 offset:32768
	ds_read_b128 v[198:201], v191 offset:34816
	ds_read_b128 v[202:205], v253 offset:34816
	ds_read_b128 v[206:209], v191 offset:36864
	ds_read_b128 v[210:213], v253 offset:36864
	ds_read_b128 v[214:217], v191 offset:38912
	ds_read_b128 v[218:221], v253 offset:38912
	global_load_lds_dwordx4 v[230:231], off
	v_lshl_add_u64 v[230:231], s[64:65], 0, v[160:161]
	s_mov_b32 m0, s73
	s_nop 0
	global_load_lds_dwordx4 v[230:231], off
	s_waitcnt vmcnt(8)
	s_waitcnt lgkmcnt(0)
	.p2align 3
	s_setprio 1
	s_barrier
	v_mfma_f32_16x16x32_bf16 v[124:127], v[128:131], v[180:183], v[124:127]
	v_mfma_f32_16x16x32_bf16 v[124:127], v[132:135], v[194:197], v[124:127]
	v_mfma_f32_16x16x32_bf16 v[120:123], v[140:143], v[194:197], v[120:123]
	v_mfma_f32_16x16x32_bf16 v[120:123], v[136:139], v[180:183], v[120:123]
	v_mfma_f32_16x16x32_bf16 v[104:107], v[136:139], v[198:201], v[104:107]
	v_mfma_f32_16x16x32_bf16 v[104:107], v[140:143], v[202:205], v[104:107]
	v_mfma_f32_16x16x32_bf16 v[108:111], v[132:135], v[202:205], v[108:111]
	v_mfma_f32_16x16x32_bf16 v[108:111], v[128:131], v[198:201], v[108:111]
	v_mfma_f32_16x16x32_bf16 v[92:95], v[128:131], v[206:209], v[92:95]
	v_mfma_f32_16x16x32_bf16 v[92:95], v[132:135], v[210:213], v[92:95]
	v_mfma_f32_16x16x32_bf16 v[88:91], v[140:143], v[210:213], v[88:91]
	v_mfma_f32_16x16x32_bf16 v[88:91], v[136:139], v[206:209], v[88:91]
	v_mfma_f32_16x16x32_bf16 v[72:75], v[136:139], v[214:217], v[72:75]
	v_mfma_f32_16x16x32_bf16 v[72:75], v[140:143], v[218:221], v[72:75]
	v_mfma_f32_16x16x32_bf16 v[76:79], v[132:135], v[218:221], v[76:79]
	v_mfma_f32_16x16x32_bf16 v[76:79], v[128:131], v[214:217], v[76:79]
	s_setprio 0
	s_setprio 1
	v_mfma_f32_16x16x32_bf16 v[116:119], v[144:147], v[180:183], v[116:119]
	v_mfma_f32_16x16x32_bf16 v[116:119], v[148:151], v[194:197], v[116:119]
	v_mfma_f32_16x16x32_bf16 v[112:115], v[176:179], v[194:197], v[112:115]
	v_mfma_f32_16x16x32_bf16 v[112:115], v[172:175], v[180:183], v[112:115]
	v_mfma_f32_16x16x32_bf16 v[96:99], v[172:175], v[198:201], v[96:99]
	v_mfma_f32_16x16x32_bf16 v[96:99], v[176:179], v[202:205], v[96:99]
	v_mfma_f32_16x16x32_bf16 v[100:103], v[148:151], v[202:205], v[100:103]
	v_mfma_f32_16x16x32_bf16 v[100:103], v[144:147], v[198:201], v[100:103]
	v_mfma_f32_16x16x32_bf16 v[84:87], v[144:147], v[206:209], v[84:87]
	v_mfma_f32_16x16x32_bf16 v[84:87], v[148:151], v[210:213], v[84:87]
	v_mfma_f32_16x16x32_bf16 v[80:83], v[176:179], v[210:213], v[80:83]
	v_mfma_f32_16x16x32_bf16 v[80:83], v[172:175], v[206:209], v[80:83]
	v_mfma_f32_16x16x32_bf16 v[64:67], v[172:175], v[214:217], v[64:67]
	v_mfma_f32_16x16x32_bf16 v[64:67], v[176:179], v[218:221], v[64:67]
	v_mfma_f32_16x16x32_bf16 v[68:71], v[148:151], v[218:221], v[68:71]
	v_mfma_f32_16x16x32_bf16 v[68:71], v[144:147], v[214:217], v[68:71]
	s_barrier
	s_setprio 0
	s_add_i32 s64, s84, s69
	v_lshl_add_u64 v[222:223], v[222:223], 0, s[26:27]
	s_mov_b32 m0, s64
	ds_read_b128 v[180:183], v191 offset:49152
	v_xor_b32_e32 v253, 64, v191
	ds_read_b128 v[194:197], v253 offset:49152
	ds_read_b128 v[198:201], v191 offset:51200
	ds_read_b128 v[202:205], v253 offset:51200
	ds_read_b128 v[206:209], v191 offset:53248
	ds_read_b128 v[210:213], v253 offset:53248
	ds_read_b128 v[214:217], v191 offset:55296
	ds_read_b128 v[218:221], v253 offset:55296
	global_load_lds_dwordx4 v[222:223], off
	s_add_i32 m0, s64, 0x2000
	s_add_u32 s62, s62, 0x80080
	v_lshl_add_u64 v[222:223], v[224:225], 0, s[26:27]
	s_addc_u32 s63, s63, 0
	s_add_i32 s64, s85, s69
	global_load_lds_dwordx4 v[222:223], off
	v_lshl_add_u64 v[222:223], s[62:63], 0, v[154:155]
	s_mov_b32 m0, s64
	s_nop 0
	global_load_lds_dwordx4 v[222:223], off
	v_lshl_add_u64 v[222:223], s[62:63], 0, v[162:163]
	s_add_i32 m0, s64, 0x2000
	s_nop 0
	global_load_lds_dwordx4 v[222:223], off
	v_lshl_add_u64 v[222:223], v[226:227], 0, s[26:27]
	s_mov_b32 m0, s3
	s_nop 0
	global_load_lds_dwordx4 v[222:223], off
	v_lshl_add_u64 v[222:223], v[228:229], 0, s[26:27]
	s_mov_b32 m0, s75
	s_nop 0
	global_load_lds_dwordx4 v[222:223], off
	s_waitcnt vmcnt(8)
	s_waitcnt lgkmcnt(0)
	.p2align 3
	s_setprio 1
	s_barrier
	v_mfma_f32_16x16x32_bf16 v[60:63], v[128:131], v[180:183], v[60:63]
	v_mfma_f32_16x16x32_bf16 v[60:63], v[132:135], v[194:197], v[60:63]
	v_mfma_f32_16x16x32_bf16 v[56:59], v[140:143], v[194:197], v[56:59]
	v_mfma_f32_16x16x32_bf16 v[56:59], v[136:139], v[180:183], v[56:59]
	v_mfma_f32_16x16x32_bf16 v[40:43], v[136:139], v[198:201], v[40:43]
	v_mfma_f32_16x16x32_bf16 v[40:43], v[140:143], v[202:205], v[40:43]
	v_mfma_f32_16x16x32_bf16 v[44:47], v[132:135], v[202:205], v[44:47]
	v_mfma_f32_16x16x32_bf16 v[44:47], v[128:131], v[198:201], v[44:47]
	v_mfma_f32_16x16x32_bf16 v[28:31], v[128:131], v[206:209], v[28:31]
	v_mfma_f32_16x16x32_bf16 v[28:31], v[132:135], v[210:213], v[28:31]
	v_mfma_f32_16x16x32_bf16 v[24:27], v[140:143], v[210:213], v[24:27]
	v_mfma_f32_16x16x32_bf16 v[24:27], v[136:139], v[206:209], v[24:27]
	v_mfma_f32_16x16x32_bf16 v[8:11], v[136:139], v[214:217], v[8:11]
	v_mfma_f32_16x16x32_bf16 v[8:11], v[140:143], v[218:221], v[8:11]
	v_mfma_f32_16x16x32_bf16 v[12:15], v[132:135], v[218:221], v[12:15]
	v_mfma_f32_16x16x32_bf16 v[12:15], v[128:131], v[214:217], v[12:15]
	s_setprio 0
	s_setprio 1
	v_mfma_f32_16x16x32_bf16 v[52:55], v[144:147], v[180:183], v[52:55]
	v_mfma_f32_16x16x32_bf16 v[52:55], v[148:151], v[194:197], v[52:55]
	v_mfma_f32_16x16x32_bf16 v[48:51], v[176:179], v[194:197], v[48:51]
	v_mfma_f32_16x16x32_bf16 v[48:51], v[172:175], v[180:183], v[48:51]
	v_mfma_f32_16x16x32_bf16 v[32:35], v[172:175], v[198:201], v[32:35]
	v_mfma_f32_16x16x32_bf16 v[32:35], v[176:179], v[202:205], v[32:35]
	v_mfma_f32_16x16x32_bf16 v[36:39], v[148:151], v[202:205], v[36:39]
	v_mfma_f32_16x16x32_bf16 v[36:39], v[144:147], v[198:201], v[36:39]
	v_mfma_f32_16x16x32_bf16 v[20:23], v[144:147], v[206:209], v[20:23]
	v_mfma_f32_16x16x32_bf16 v[20:23], v[148:151], v[210:213], v[20:23]
	v_mfma_f32_16x16x32_bf16 v[16:19], v[176:179], v[210:213], v[16:19]
	v_mfma_f32_16x16x32_bf16 v[16:19], v[172:175], v[206:209], v[16:19]
	v_mfma_f32_16x16x32_bf16 v[0:3], v[172:175], v[214:217], v[0:3]
	v_mfma_f32_16x16x32_bf16 v[0:3], v[176:179], v[218:221], v[0:3]
	v_mfma_f32_16x16x32_bf16 v[4:7], v[148:151], v[218:221], v[4:7]
	v_mfma_f32_16x16x32_bf16 v[4:7], v[144:147], v[214:217], v[4:7]
	s_barrier
	s_setprio 0
	s_add_i32 s83, s83, 2
	s_add_u32 s81, s81, 0x100
	s_addc_u32 s82, s82, 0
	s_add_u32 s60, s60, 0x100
	s_addc_u32 s61, s61, 0
	s_cmp_gt_u32 s83, 29
	s_branch .LBB0_440
.Lfa_3:
	ds_read_b128 v[128:131], v189
	v_xor_b32_e32 v253, 64, v189
	ds_read_b128 v[132:135], v253
	ds_read_b128 v[136:139], v189 offset:2048
	ds_read_b128 v[140:143], v253 offset:2048
	ds_read_b128 v[144:147], v190
	v_xor_b32_e32 v253, 64, v190
	ds_read_b128 v[148:151], v253
	ds_read_b128 v[172:175], v190 offset:2048
	ds_read_b128 v[176:179], v253 offset:2048
	s_add_u32 s62, s60, 0xfff80080
	s_addc_u32 s63, s61, -1
	s_cmp_eq_u32 s83, 28
	s_cselect_b32 s65, s15, s63
	s_cselect_b32 s64, s53, s62
	s_cselect_b32 s63, s51, s82
	s_cselect_b32 s62, s59, s81
	v_lshl_add_u64 v[222:223], s[60:61], 0, v[166:167]
	s_add_i32 m0, s70, 0xc000
	ds_read_b128 v[180:183], v191
	v_xor_b32_e32 v253, 64, v191
	ds_read_b128 v[194:197], v253
	ds_read_b128 v[198:201], v191 offset:2048
	ds_read_b128 v[202:205], v253 offset:2048
	ds_read_b128 v[206:209], v191 offset:4096
	ds_read_b128 v[210:213], v253 offset:4096
	ds_read_b128 v[214:217], v191 offset:6144
	ds_read_b128 v[218:221], v253 offset:6144
	global_load_lds_dwordx4 v[222:223], off
	v_lshl_add_u64 v[222:223], s[60:61], 0, v[164:165]
	s_add_i32 m0, s70, 0xe000
	s_nop 0
	global_load_lds_dwordx4 v[222:223], off
	s_waitcnt vmcnt(8)
	s_waitcnt lgkmcnt(0)
	.p2align 3
	s_setprio 1
	s_barrier
	v_mfma_f32_16x16x32_bf16 v[124:127], v[128:131], v[180:183], 0
	v_mfma_f32_16x16x32_bf16 v[120:123], v[136:139], v[180:183], 0
	v_mfma_f32_16x16x32_bf16 v[108:111], v[128:131], v[198:201], 0
	v_mfma_f32_16x16x32_bf16 v[104:107], v[136:139], v[198:201], 0
	v_mfma_f32_16x16x32_bf16 v[92:95], v[128:131], v[206:209], 0
	v_mfma_f32_16x16x32_bf16 v[88:91], v[136:139], v[206:209], 0
	v_mfma_f32_16x16x32_bf16 v[76:79], v[128:131], v[214:217], 0
	v_mfma_f32_16x16x32_bf16 v[72:75], v[136:139], v[214:217], 0
	v_mfma_f32_16x16x32_bf16 v[124:127], v[132:135], v[194:197], v[124:127]
	v_mfma_f32_16x16x32_bf16 v[120:123], v[140:143], v[194:197], v[120:123]
	v_mfma_f32_16x16x32_bf16 v[108:111], v[132:135], v[202:205], v[108:111]
	v_mfma_f32_16x16x32_bf16 v[104:107], v[140:143], v[202:205], v[104:107]
	v_mfma_f32_16x16x32_bf16 v[92:95], v[132:135], v[210:213], v[92:95]
	v_mfma_f32_16x16x32_bf16 v[88:91], v[140:143], v[210:213], v[88:91]
	v_mfma_f32_16x16x32_bf16 v[76:79], v[132:135], v[218:221], v[76:79]
	v_mfma_f32_16x16x32_bf16 v[72:75], v[140:143], v[218:221], v[72:75]
	s_setprio 0
	s_setprio 1
	v_mfma_f32_16x16x32_bf16 v[116:119], v[144:147], v[180:183], 0
	v_mfma_f32_16x16x32_bf16 v[112:115], v[172:175], v[180:183], 0
	v_mfma_f32_16x16x32_bf16 v[100:103], v[144:147], v[198:201], 0
	v_mfma_f32_16x16x32_bf16 v[96:99], v[172:175], v[198:201], 0
	v_mfma_f32_16x16x32_bf16 v[84:87], v[144:147], v[206:209], 0
	v_mfma_f32_16x16x32_bf16 v[80:83], v[172:175], v[206:209], 0
	v_mfma_f32_16x16x32_bf16 v[68:71], v[144:147], v[214:217], 0
	v_mfma_f32_16x16x32_bf16 v[64:67], v[172:175], v[214:217], 0
	v_mfma_f32_16x16x32_bf16 v[116:119], v[148:151], v[194:197], v[116:119]
	v_mfma_f32_16x16x32_bf16 v[112:115], v[176:179], v[194:197], v[112:115]
	v_mfma_f32_16x16x32_bf16 v[100:103], v[148:151], v[202:205], v[100:103]
	v_mfma_f32_16x16x32_bf16 v[96:99], v[176:179], v[202:205], v[96:99]
	v_mfma_f32_16x16x32_bf16 v[84:87], v[148:151], v[210:213], v[84:87]
	v_mfma_f32_16x16x32_bf16 v[80:83], v[176:179], v[210:213], v[80:83]
	v_mfma_f32_16x16x32_bf16 v[68:71], v[148:151], v[218:221], v[68:71]
	v_mfma_f32_16x16x32_bf16 v[64:67], v[176:179], v[218:221], v[64:67]
	s_barrier
	s_setprio 0
	s_add_i32 s84, s79, s69
	v_lshl_add_u64 v[222:223], s[62:63], 0, v[154:155]
	s_mov_b32 m0, s84
	ds_read_b128 v[180:183], v191 offset:16384
	v_xor_b32_e32 v253, 64, v191
	ds_read_b128 v[194:197], v253 offset:16384
	ds_read_b128 v[198:201], v191 offset:18432
	ds_read_b128 v[202:205], v253 offset:18432
	ds_read_b128 v[206:209], v191 offset:20480
	ds_read_b128 v[210:213], v253 offset:20480
	ds_read_b128 v[214:217], v191 offset:22528
	ds_read_b128 v[218:221], v253 offset:22528
	global_load_lds_dwordx4 v[222:223], off
	s_add_i32 m0, s84, 0x2000
	s_add_u32 s84, s62, 0x80000
	v_lshl_add_u64 v[224:225], s[62:63], 0, v[162:163]
	s_addc_u32 s85, s63, 0
	s_add_i32 s86, s80, s69
	global_load_lds_dwordx4 v[224:225], off
	v_lshl_add_u64 v[226:227], s[84:85], 0, v[154:155]
	s_mov_b32 m0, s86
	v_lshl_add_u64 v[228:229], s[64:65], 0, v[160:161]
	global_load_lds_dwordx4 v[226:227], off
	v_lshl_add_u64 v[226:227], s[84:85], 0, v[162:163]
	s_add_i32 m0, s86, 0x2000
	s_nop 0
	global_load_lds_dwordx4 v[226:227], off
	v_lshl_add_u64 v[226:227], s[64:65], 0, v[152:153]
	s_mov_b32 m0, s70
	s_nop 0
	global_load_lds_dwordx4 v[226:227], off
	s_mov_b32 m0, s71
	s_nop 0
	global_load_lds_dwordx4 v[228:229], off
	s_waitcnt vmcnt(8)
	s_waitcnt lgkmcnt(0)
	.p2align 3
	s_setprio 1
	s_barrier
	v_mfma_f32_16x16x32_bf16 v[60:63], v[128:131], v[180:183], 0
	v_mfma_f32_16x16x32_bf16 v[56:59], v[136:139], v[180:183], 0
	v_mfma_f32_16x16x32_bf16 v[44:47], v[128:131], v[198:201], 0
	v_mfma_f32_16x16x32_bf16 v[40:43], v[136:139], v[198:201], 0
	v_mfma_f32_16x16x32_bf16 v[28:31], v[128:131], v[206:209], 0
	v_mfma_f32_16x16x32_bf16 v[24:27], v[136:139], v[206:209], 0
	v_mfma_f32_16x16x32_bf16 v[12:15], v[128:131], v[214:217], 0
	v_mfma_f32_16x16x32_bf16 v[8:11], v[136:139], v[214:217], 0
	v_mfma_f32_16x16x32_bf16 v[60:63], v[132:135], v[194:197], v[60:63]
	v_mfma_f32_16x16x32_bf16 v[56:59], v[140:143], v[194:197], v[56:59]
	v_mfma_f32_16x16x32_bf16 v[44:47], v[132:135], v[202:205], v[44:47]
	v_mfma_f32_16x16x32_bf16 v[40:43], v[140:143], v[202:205], v[40:43]
	v_mfma_f32_16x16x32_bf16 v[28:31], v[132:135], v[210:213], v[28:31]
	v_mfma_f32_16x16x32_bf16 v[24:27], v[140:143], v[210:213], v[24:27]
	v_mfma_f32_16x16x32_bf16 v[12:15], v[132:135], v[218:221], v[12:15]
	v_mfma_f32_16x16x32_bf16 v[8:11], v[140:143], v[218:221], v[8:11]
	s_setprio 0
	s_setprio 1
	v_mfma_f32_16x16x32_bf16 v[52:55], v[144:147], v[180:183], 0
	v_mfma_f32_16x16x32_bf16 v[48:51], v[172:175], v[180:183], 0
	v_mfma_f32_16x16x32_bf16 v[36:39], v[144:147], v[198:201], 0
	v_mfma_f32_16x16x32_bf16 v[32:35], v[172:175], v[198:201], 0
	v_mfma_f32_16x16x32_bf16 v[20:23], v[144:147], v[206:209], 0
	v_mfma_f32_16x16x32_bf16 v[16:19], v[172:175], v[206:209], 0
	v_mfma_f32_16x16x32_bf16 v[4:7], v[144:147], v[214:217], 0
	v_mfma_f32_16x16x32_bf16 v[0:3], v[172:175], v[214:217], 0
	v_mfma_f32_16x16x32_bf16 v[52:55], v[148:151], v[194:197], v[52:55]
	v_mfma_f32_16x16x32_bf16 v[48:51], v[176:179], v[194:197], v[48:51]
	v_mfma_f32_16x16x32_bf16 v[36:39], v[148:151], v[202:205], v[36:39]
	v_mfma_f32_16x16x32_bf16 v[32:35], v[176:179], v[202:205], v[32:35]
	v_mfma_f32_16x16x32_bf16 v[20:23], v[148:151], v[210:213], v[20:23]
	v_mfma_f32_16x16x32_bf16 v[16:19], v[176:179], v[210:213], v[16:19]
	v_mfma_f32_16x16x32_bf16 v[4:7], v[148:151], v[218:221], v[4:7]
	v_mfma_f32_16x16x32_bf16 v[0:3], v[176:179], v[218:221], v[0:3]
	s_barrier
	s_setprio 0
	s_add_i32 s84, 0, 0x18000
	s_add_i32 s85, 0, 0x1c000
	v_add_u32_e32 v140, s84, v186
	v_add_u32_e32 v176, s85, v186
	ds_read_b128 v[128:131], v140
	v_xor_b32_e32 v253, 64, v140
	ds_read_b128 v[132:135], v253
	ds_read_b128 v[136:139], v140 offset:2048
	ds_read_b128 v[140:143], v253 offset:2048
	ds_read_b128 v[144:147], v176
	v_xor_b32_e32 v253, 64, v176
	ds_read_b128 v[148:151], v253
	ds_read_b128 v[172:175], v176 offset:2048
	ds_read_b128 v[176:179], v253 offset:2048
	s_add_u32 s64, s64, 0x80000
	s_addc_u32 s65, s65, 0
	s_mov_b32 m0, s72
	v_lshl_add_u64 v[230:231], s[64:65], 0, v[152:153]
	ds_read_b128 v[180:183], v191 offset:32768
	v_xor_b32_e32 v253, 64, v191
	ds_read_b128 v[194:197], v253 offset:32768
	ds_read_b128 v[198:201], v191 offset:34816
	ds_read_b128 v[202:205], v253 offset:34816
	ds_read_b128 v[206:209], v191 offset:36864
	ds_read_b128 v[210:213], v253 offset:36864
	ds_read_b128 v[214:217], v191 offset:38912
	ds_read_b128 v[218:221], v253 offset:38912
	global_load_lds_dwordx4 v[230:231], off
	v_lshl_add_u64 v[230:231], s[64:65], 0, v[160:161]
	s_mov_b32 m0, s73
	s_nop 0
	global_load_lds_dwordx4 v[230:231], off
	s_waitcnt vmcnt(8)
	s_waitcnt lgkmcnt(0)
	.p2align 3
	s_setprio 1
	s_barrier
	v_mfma_f32_16x16x32_bf16 v[124:127], v[128:131], v[180:183], v[124:127]
	v_mfma_f32_16x16x32_bf16 v[124:127], v[132:135], v[194:197], v[124:127]
	v_mfma_f32_16x16x32_bf16 v[120:123], v[140:143], v[194:197], v[120:123]
	v_mfma_f32_16x16x32_bf16 v[120:123], v[136:139], v[180:183], v[120:123]
	v_mfma_f32_16x16x32_bf16 v[104:107], v[136:139], v[198:201], v[104:107]
	v_mfma_f32_16x16x32_bf16 v[104:107], v[140:143], v[202:205], v[104:107]
	v_mfma_f32_16x16x32_bf16 v[108:111], v[132:135], v[202:205], v[108:111]
	v_mfma_f32_16x16x32_bf16 v[108:111], v[128:131], v[198:201], v[108:111]
	v_mfma_f32_16x16x32_bf16 v[92:95], v[128:131], v[206:209], v[92:95]
	v_mfma_f32_16x16x32_bf16 v[92:95], v[132:135], v[210:213], v[92:95]
	v_mfma_f32_16x16x32_bf16 v[88:91], v[140:143], v[210:213], v[88:91]
	v_mfma_f32_16x16x32_bf16 v[88:91], v[136:139], v[206:209], v[88:91]
	v_mfma_f32_16x16x32_bf16 v[72:75], v[136:139], v[214:217], v[72:75]
	v_mfma_f32_16x16x32_bf16 v[72:75], v[140:143], v[218:221], v[72:75]
	v_mfma_f32_16x16x32_bf16 v[76:79], v[132:135], v[218:221], v[76:79]
	v_mfma_f32_16x16x32_bf16 v[76:79], v[128:131], v[214:217], v[76:79]
	s_setprio 0
	s_setprio 1
	v_mfma_f32_16x16x32_bf16 v[116:119], v[144:147], v[180:183], v[116:119]
	v_mfma_f32_16x16x32_bf16 v[116:119], v[148:151], v[194:197], v[116:119]
	v_mfma_f32_16x16x32_bf16 v[112:115], v[176:179], v[194:197], v[112:115]
	v_mfma_f32_16x16x32_bf16 v[112:115], v[172:175], v[180:183], v[112:115]
	v_mfma_f32_16x16x32_bf16 v[96:99], v[172:175], v[198:201], v[96:99]
	v_mfma_f32_16x16x32_bf16 v[96:99], v[176:179], v[202:205], v[96:99]
	v_mfma_f32_16x16x32_bf16 v[100:103], v[148:151], v[202:205], v[100:103]
	v_mfma_f32_16x16x32_bf16 v[100:103], v[144:147], v[198:201], v[100:103]
	v_mfma_f32_16x16x32_bf16 v[84:87], v[144:147], v[206:209], v[84:87]
	v_mfma_f32_16x16x32_bf16 v[84:87], v[148:151], v[210:213], v[84:87]
	v_mfma_f32_16x16x32_bf16 v[80:83], v[176:179], v[210:213], v[80:83]
	v_mfma_f32_16x16x32_bf16 v[80:83], v[172:175], v[206:209], v[80:83]
	v_mfma_f32_16x16x32_bf16 v[64:67], v[172:175], v[214:217], v[64:67]
	v_mfma_f32_16x16x32_bf16 v[64:67], v[176:179], v[218:221], v[64:67]
	v_mfma_f32_16x16x32_bf16 v[68:71], v[148:151], v[218:221], v[68:71]
	v_mfma_f32_16x16x32_bf16 v[68:71], v[144:147], v[214:217], v[68:71]
	s_barrier
	s_setprio 0
	s_add_i32 s64, s84, s69
	v_lshl_add_u64 v[222:223], v[222:223], 0, s[26:27]
	s_mov_b32 m0, s64
	ds_read_b128 v[180:183], v191 offset:49152
	v_xor_b32_e32 v253, 64, v191
	ds_read_b128 v[194:197], v253 offset:49152
	ds_read_b128 v[198:201], v191 offset:51200
	ds_read_b128 v[202:205], v253 offset:51200
	ds_read_b128 v[206:209], v191 offset:53248
	ds_read_b128 v[210:213], v253 offset:53248
	ds_read_b128 v[214:217], v191 offset:55296
	ds_read_b128 v[218:221], v253 offset:55296
	global_load_lds_dwordx4 v[222:223], off
	s_add_i32 m0, s64, 0x2000
	s_add_u32 s62, s62, 0x80080
	v_lshl_add_u64 v[222:223], v[224:225], 0, s[26:27]
	s_addc_u32 s63, s63, 0
	s_add_i32 s64, s85, s69
	global_load_lds_dwordx4 v[222:223], off
	v_lshl_add_u64 v[222:223], s[62:63], 0, v[154:155]
	s_mov_b32 m0, s64
	s_nop 0
	global_load_lds_dwordx4 v[222:223], off
	v_lshl_add_u64 v[222:223], s[62:63], 0, v[162:163]
	s_add_i32 m0, s64, 0x2000
	s_nop 0
	global_load_lds_dwordx4 v[222:223], off
	v_lshl_add_u64 v[222:223], v[226:227], 0, s[26:27]
	s_mov_b32 m0, s3
	s_nop 0
	global_load_lds_dwordx4 v[222:223], off
	v_lshl_add_u64 v[222:223], v[228:229], 0, s[26:27]
	s_mov_b32 m0, s75
	s_nop 0
	global_load_lds_dwordx4 v[222:223], off
	s_waitcnt vmcnt(8)
	s_waitcnt lgkmcnt(0)
	.p2align 3
	s_setprio 1
	s_barrier
	v_mfma_f32_16x16x32_bf16 v[60:63], v[128:131], v[180:183], v[60:63]
	v_mfma_f32_16x16x32_bf16 v[60:63], v[132:135], v[194:197], v[60:63]
	v_mfma_f32_16x16x32_bf16 v[56:59], v[140:143], v[194:197], v[56:59]
	v_mfma_f32_16x16x32_bf16 v[56:59], v[136:139], v[180:183], v[56:59]
	v_mfma_f32_16x16x32_bf16 v[40:43], v[136:139], v[198:201], v[40:43]
	v_mfma_f32_16x16x32_bf16 v[40:43], v[140:143], v[202:205], v[40:43]
	v_mfma_f32_16x16x32_bf16 v[44:47], v[132:135], v[202:205], v[44:47]
	v_mfma_f32_16x16x32_bf16 v[44:47], v[128:131], v[198:201], v[44:47]
	v_mfma_f32_16x16x32_bf16 v[28:31], v[128:131], v[206:209], v[28:31]
	v_mfma_f32_16x16x32_bf16 v[28:31], v[132:135], v[210:213], v[28:31]
	v_mfma_f32_16x16x32_bf16 v[24:27], v[140:143], v[210:213], v[24:27]
	v_mfma_f32_16x16x32_bf16 v[24:27], v[136:139], v[206:209], v[24:27]
	v_mfma_f32_16x16x32_bf16 v[8:11], v[136:139], v[214:217], v[8:11]
	v_mfma_f32_16x16x32_bf16 v[8:11], v[140:143], v[218:221], v[8:11]
	v_mfma_f32_16x16x32_bf16 v[12:15], v[132:135], v[218:221], v[12:15]
	v_mfma_f32_16x16x32_bf16 v[12:15], v[128:131], v[214:217], v[12:15]
	s_setprio 0
	s_setprio 1
	v_mfma_f32_16x16x32_bf16 v[52:55], v[144:147], v[180:183], v[52:55]
	v_mfma_f32_16x16x32_bf16 v[52:55], v[148:151], v[194:197], v[52:55]
	v_mfma_f32_16x16x32_bf16 v[48:51], v[176:179], v[194:197], v[48:51]
	v_mfma_f32_16x16x32_bf16 v[48:51], v[172:175], v[180:183], v[48:51]
	v_mfma_f32_16x16x32_bf16 v[32:35], v[172:175], v[198:201], v[32:35]
	v_mfma_f32_16x16x32_bf16 v[32:35], v[176:179], v[202:205], v[32:35]
	v_mfma_f32_16x16x32_bf16 v[36:39], v[148:151], v[202:205], v[36:39]
	v_mfma_f32_16x16x32_bf16 v[36:39], v[144:147], v[198:201], v[36:39]
	v_mfma_f32_16x16x32_bf16 v[20:23], v[144:147], v[206:209], v[20:23]
	v_mfma_f32_16x16x32_bf16 v[20:23], v[148:151], v[210:213], v[20:23]
	v_mfma_f32_16x16x32_bf16 v[16:19], v[176:179], v[210:213], v[16:19]
	v_mfma_f32_16x16x32_bf16 v[16:19], v[172:175], v[206:209], v[16:19]
	v_mfma_f32_16x16x32_bf16 v[0:3], v[172:175], v[214:217], v[0:3]
	v_mfma_f32_16x16x32_bf16 v[0:3], v[176:179], v[218:221], v[0:3]
	v_mfma_f32_16x16x32_bf16 v[4:7], v[148:151], v[218:221], v[4:7]
	v_mfma_f32_16x16x32_bf16 v[4:7], v[144:147], v[214:217], v[4:7]
	s_barrier
	s_setprio 0
	s_add_i32 s83, s83, 2
	s_add_u32 s81, s81, 0x100
	s_addc_u32 s82, s82, 0
	s_add_u32 s60, s60, 0x100
	s_addc_u32 s61, s61, 0
	s_cmp_gt_u32 s83, 29
.LBB0_440:
	ds_read_b128 v[128:131], v189
	v_xor_b32_e32 v253, 64, v189
	ds_read_b128 v[132:135], v253
	ds_read_b128 v[136:139], v189 offset:2048
	ds_read_b128 v[140:143], v253 offset:2048
	ds_read_b128 v[144:147], v190
	v_xor_b32_e32 v253, 64, v190
	ds_read_b128 v[148:151], v253
	ds_read_b128 v[172:175], v190 offset:2048
	ds_read_b128 v[176:179], v253 offset:2048
	s_add_u32 s62, s60, 0xfff80080
	s_addc_u32 s63, s61, -1
	s_cmp_eq_u32 s83, 28
	s_cselect_b32 s65, s15, s63
	s_cselect_b32 s64, s53, s62
	s_cselect_b32 s63, s51, s82
	s_cselect_b32 s62, s59, s81
	v_lshl_add_u64 v[222:223], s[60:61], 0, v[166:167]
	s_add_i32 m0, s70, 0xc000
	ds_read_b128 v[180:183], v191
	v_xor_b32_e32 v253, 64, v191
	ds_read_b128 v[194:197], v253
	ds_read_b128 v[198:201], v191 offset:2048
	ds_read_b128 v[202:205], v253 offset:2048
	ds_read_b128 v[206:209], v191 offset:4096
	ds_read_b128 v[210:213], v253 offset:4096
	ds_read_b128 v[214:217], v191 offset:6144
	ds_read_b128 v[218:221], v253 offset:6144
	global_load_lds_dwordx4 v[222:223], off
	v_lshl_add_u64 v[222:223], s[60:61], 0, v[164:165]
	s_add_i32 m0, s70, 0xe000
	s_nop 0
	global_load_lds_dwordx4 v[222:223], off
	s_waitcnt vmcnt(8)
	s_waitcnt lgkmcnt(0)
	.p2align 3
	s_setprio 1
	s_barrier
	v_mfma_f32_16x16x32_bf16 v[124:127], v[128:131], v[180:183], v[124:127]
	v_mfma_f32_16x16x32_bf16 v[124:127], v[132:135], v[194:197], v[124:127]
	v_mfma_f32_16x16x32_bf16 v[120:123], v[140:143], v[194:197], v[120:123]
	v_mfma_f32_16x16x32_bf16 v[120:123], v[136:139], v[180:183], v[120:123]
	v_mfma_f32_16x16x32_bf16 v[104:107], v[136:139], v[198:201], v[104:107]
	v_mfma_f32_16x16x32_bf16 v[104:107], v[140:143], v[202:205], v[104:107]
	v_mfma_f32_16x16x32_bf16 v[108:111], v[132:135], v[202:205], v[108:111]
	v_mfma_f32_16x16x32_bf16 v[108:111], v[128:131], v[198:201], v[108:111]
	v_mfma_f32_16x16x32_bf16 v[92:95], v[128:131], v[206:209], v[92:95]
	v_mfma_f32_16x16x32_bf16 v[92:95], v[132:135], v[210:213], v[92:95]
	v_mfma_f32_16x16x32_bf16 v[88:91], v[140:143], v[210:213], v[88:91]
	v_mfma_f32_16x16x32_bf16 v[88:91], v[136:139], v[206:209], v[88:91]
	v_mfma_f32_16x16x32_bf16 v[72:75], v[136:139], v[214:217], v[72:75]
	v_mfma_f32_16x16x32_bf16 v[72:75], v[140:143], v[218:221], v[72:75]
	v_mfma_f32_16x16x32_bf16 v[76:79], v[132:135], v[218:221], v[76:79]
	v_mfma_f32_16x16x32_bf16 v[76:79], v[128:131], v[214:217], v[76:79]
	s_setprio 0
	s_setprio 1
	v_mfma_f32_16x16x32_bf16 v[116:119], v[144:147], v[180:183], v[116:119]
	v_mfma_f32_16x16x32_bf16 v[116:119], v[148:151], v[194:197], v[116:119]
	v_mfma_f32_16x16x32_bf16 v[112:115], v[176:179], v[194:197], v[112:115]
	v_mfma_f32_16x16x32_bf16 v[112:115], v[172:175], v[180:183], v[112:115]
	v_mfma_f32_16x16x32_bf16 v[96:99], v[172:175], v[198:201], v[96:99]
	v_mfma_f32_16x16x32_bf16 v[96:99], v[176:179], v[202:205], v[96:99]
	v_mfma_f32_16x16x32_bf16 v[100:103], v[148:151], v[202:205], v[100:103]
	v_mfma_f32_16x16x32_bf16 v[100:103], v[144:147], v[198:201], v[100:103]
	v_mfma_f32_16x16x32_bf16 v[84:87], v[144:147], v[206:209], v[84:87]
	v_mfma_f32_16x16x32_bf16 v[84:87], v[148:151], v[210:213], v[84:87]
	v_mfma_f32_16x16x32_bf16 v[80:83], v[176:179], v[210:213], v[80:83]
	v_mfma_f32_16x16x32_bf16 v[80:83], v[172:175], v[206:209], v[80:83]
	v_mfma_f32_16x16x32_bf16 v[64:67], v[172:175], v[214:217], v[64:67]
	v_mfma_f32_16x16x32_bf16 v[64:67], v[176:179], v[218:221], v[64:67]
	v_mfma_f32_16x16x32_bf16 v[68:71], v[148:151], v[218:221], v[68:71]
	v_mfma_f32_16x16x32_bf16 v[68:71], v[144:147], v[214:217], v[68:71]
	s_barrier
	s_setprio 0
	s_add_i32 s84, s79, s69
	v_lshl_add_u64 v[222:223], s[62:63], 0, v[154:155]
	s_mov_b32 m0, s84
	ds_read_b128 v[180:183], v191 offset:16384
	v_xor_b32_e32 v253, 64, v191
	ds_read_b128 v[194:197], v253 offset:16384
	ds_read_b128 v[198:201], v191 offset:18432
	ds_read_b128 v[202:205], v253 offset:18432
	ds_read_b128 v[206:209], v191 offset:20480
	ds_read_b128 v[210:213], v253 offset:20480
	ds_read_b128 v[214:217], v191 offset:22528
	ds_read_b128 v[218:221], v253 offset:22528
	global_load_lds_dwordx4 v[222:223], off
	s_add_i32 m0, s84, 0x2000
	s_add_u32 s84, s62, 0x80000
	v_lshl_add_u64 v[224:225], s[62:63], 0, v[162:163]
	s_addc_u32 s85, s63, 0
	s_add_i32 s86, s80, s69
	global_load_lds_dwordx4 v[224:225], off
	v_lshl_add_u64 v[226:227], s[84:85], 0, v[154:155]
	s_mov_b32 m0, s86
	v_lshl_add_u64 v[228:229], s[64:65], 0, v[160:161]
	global_load_lds_dwordx4 v[226:227], off
	v_lshl_add_u64 v[226:227], s[84:85], 0, v[162:163]
	s_add_i32 m0, s86, 0x2000
	s_nop 0
	global_load_lds_dwordx4 v[226:227], off
	v_lshl_add_u64 v[226:227], s[64:65], 0, v[152:153]
	s_mov_b32 m0, s70
	s_nop 0
	global_load_lds_dwordx4 v[226:227], off
	s_mov_b32 m0, s71
	s_nop 0
	global_load_lds_dwordx4 v[228:229], off
	s_waitcnt vmcnt(8)
	s_waitcnt lgkmcnt(0)
	.p2align 3
	s_setprio 1
	s_barrier
	v_mfma_f32_16x16x32_bf16 v[60:63], v[128:131], v[180:183], v[60:63]
	v_mfma_f32_16x16x32_bf16 v[60:63], v[132:135], v[194:197], v[60:63]
	v_mfma_f32_16x16x32_bf16 v[56:59], v[140:143], v[194:197], v[56:59]
	v_mfma_f32_16x16x32_bf16 v[56:59], v[136:139], v[180:183], v[56:59]
	v_mfma_f32_16x16x32_bf16 v[40:43], v[136:139], v[198:201], v[40:43]
	v_mfma_f32_16x16x32_bf16 v[40:43], v[140:143], v[202:205], v[40:43]
	v_mfma_f32_16x16x32_bf16 v[44:47], v[132:135], v[202:205], v[44:47]
	v_mfma_f32_16x16x32_bf16 v[44:47], v[128:131], v[198:201], v[44:47]
	v_mfma_f32_16x16x32_bf16 v[28:31], v[128:131], v[206:209], v[28:31]
	v_mfma_f32_16x16x32_bf16 v[28:31], v[132:135], v[210:213], v[28:31]
	v_mfma_f32_16x16x32_bf16 v[24:27], v[140:143], v[210:213], v[24:27]
	v_mfma_f32_16x16x32_bf16 v[24:27], v[136:139], v[206:209], v[24:27]
	v_mfma_f32_16x16x32_bf16 v[8:11], v[136:139], v[214:217], v[8:11]
	v_mfma_f32_16x16x32_bf16 v[8:11], v[140:143], v[218:221], v[8:11]
	v_mfma_f32_16x16x32_bf16 v[12:15], v[132:135], v[218:221], v[12:15]
	v_mfma_f32_16x16x32_bf16 v[12:15], v[128:131], v[214:217], v[12:15]
	s_setprio 0
	s_setprio 1
	v_mfma_f32_16x16x32_bf16 v[52:55], v[144:147], v[180:183], v[52:55]
	v_mfma_f32_16x16x32_bf16 v[52:55], v[148:151], v[194:197], v[52:55]
	v_mfma_f32_16x16x32_bf16 v[48:51], v[176:179], v[194:197], v[48:51]
	v_mfma_f32_16x16x32_bf16 v[48:51], v[172:175], v[180:183], v[48:51]
	v_mfma_f32_16x16x32_bf16 v[32:35], v[172:175], v[198:201], v[32:35]
	v_mfma_f32_16x16x32_bf16 v[32:35], v[176:179], v[202:205], v[32:35]
	v_mfma_f32_16x16x32_bf16 v[36:39], v[148:151], v[202:205], v[36:39]
	v_mfma_f32_16x16x32_bf16 v[36:39], v[144:147], v[198:201], v[36:39]
	v_mfma_f32_16x16x32_bf16 v[20:23], v[144:147], v[206:209], v[20:23]
	v_mfma_f32_16x16x32_bf16 v[20:23], v[148:151], v[210:213], v[20:23]
	v_mfma_f32_16x16x32_bf16 v[16:19], v[176:179], v[210:213], v[16:19]
	v_mfma_f32_16x16x32_bf16 v[16:19], v[172:175], v[206:209], v[16:19]
	v_mfma_f32_16x16x32_bf16 v[0:3], v[172:175], v[214:217], v[0:3]
	v_mfma_f32_16x16x32_bf16 v[0:3], v[176:179], v[218:221], v[0:3]
	v_mfma_f32_16x16x32_bf16 v[4:7], v[148:151], v[218:221], v[4:7]
	v_mfma_f32_16x16x32_bf16 v[4:7], v[144:147], v[214:217], v[4:7]
	s_barrier
	s_setprio 0
	s_add_i32 s84, 0, 0x18000
	s_add_i32 s85, 0, 0x1c000
	v_add_u32_e32 v140, s84, v186
	v_add_u32_e32 v176, s85, v186
	ds_read_b128 v[128:131], v140
	v_xor_b32_e32 v253, 64, v140
	ds_read_b128 v[132:135], v253
	ds_read_b128 v[136:139], v140 offset:2048
	ds_read_b128 v[140:143], v253 offset:2048
	ds_read_b128 v[144:147], v176
	v_xor_b32_e32 v253, 64, v176
	ds_read_b128 v[148:151], v253
	ds_read_b128 v[172:175], v176 offset:2048
	ds_read_b128 v[176:179], v253 offset:2048
	s_add_u32 s64, s64, 0x80000
	s_addc_u32 s65, s65, 0
	s_mov_b32 m0, s72
	v_lshl_add_u64 v[230:231], s[64:65], 0, v[152:153]
	ds_read_b128 v[180:183], v191 offset:32768
	v_xor_b32_e32 v253, 64, v191
	ds_read_b128 v[194:197], v253 offset:32768
	ds_read_b128 v[198:201], v191 offset:34816
	ds_read_b128 v[202:205], v253 offset:34816
	ds_read_b128 v[206:209], v191 offset:36864
	ds_read_b128 v[210:213], v253 offset:36864
	ds_read_b128 v[214:217], v191 offset:38912
	ds_read_b128 v[218:221], v253 offset:38912
	global_load_lds_dwordx4 v[230:231], off
	v_lshl_add_u64 v[230:231], s[64:65], 0, v[160:161]
	s_mov_b32 m0, s73
	s_nop 0
	global_load_lds_dwordx4 v[230:231], off
	s_waitcnt vmcnt(8)
	s_waitcnt lgkmcnt(0)
	.p2align 3
	s_setprio 1
	s_barrier
	v_mfma_f32_16x16x32_bf16 v[124:127], v[128:131], v[180:183], v[124:127]
	v_mfma_f32_16x16x32_bf16 v[124:127], v[132:135], v[194:197], v[124:127]
	v_mfma_f32_16x16x32_bf16 v[120:123], v[140:143], v[194:197], v[120:123]
	v_mfma_f32_16x16x32_bf16 v[120:123], v[136:139], v[180:183], v[120:123]
	v_mfma_f32_16x16x32_bf16 v[104:107], v[136:139], v[198:201], v[104:107]
	v_mfma_f32_16x16x32_bf16 v[104:107], v[140:143], v[202:205], v[104:107]
	v_mfma_f32_16x16x32_bf16 v[108:111], v[132:135], v[202:205], v[108:111]
	v_mfma_f32_16x16x32_bf16 v[108:111], v[128:131], v[198:201], v[108:111]
	v_mfma_f32_16x16x32_bf16 v[92:95], v[128:131], v[206:209], v[92:95]
	v_mfma_f32_16x16x32_bf16 v[92:95], v[132:135], v[210:213], v[92:95]
	v_mfma_f32_16x16x32_bf16 v[88:91], v[140:143], v[210:213], v[88:91]
	v_mfma_f32_16x16x32_bf16 v[88:91], v[136:139], v[206:209], v[88:91]
	v_mfma_f32_16x16x32_bf16 v[72:75], v[136:139], v[214:217], v[72:75]
	v_mfma_f32_16x16x32_bf16 v[72:75], v[140:143], v[218:221], v[72:75]
	v_mfma_f32_16x16x32_bf16 v[76:79], v[132:135], v[218:221], v[76:79]
	v_mfma_f32_16x16x32_bf16 v[76:79], v[128:131], v[214:217], v[76:79]
	s_setprio 0
	s_setprio 1
	v_mfma_f32_16x16x32_bf16 v[116:119], v[144:147], v[180:183], v[116:119]
	v_mfma_f32_16x16x32_bf16 v[116:119], v[148:151], v[194:197], v[116:119]
	v_mfma_f32_16x16x32_bf16 v[112:115], v[176:179], v[194:197], v[112:115]
	v_mfma_f32_16x16x32_bf16 v[112:115], v[172:175], v[180:183], v[112:115]
	v_mfma_f32_16x16x32_bf16 v[96:99], v[172:175], v[198:201], v[96:99]
	v_mfma_f32_16x16x32_bf16 v[96:99], v[176:179], v[202:205], v[96:99]
	v_mfma_f32_16x16x32_bf16 v[100:103], v[148:151], v[202:205], v[100:103]
	v_mfma_f32_16x16x32_bf16 v[100:103], v[144:147], v[198:201], v[100:103]
	v_mfma_f32_16x16x32_bf16 v[84:87], v[144:147], v[206:209], v[84:87]
	v_mfma_f32_16x16x32_bf16 v[84:87], v[148:151], v[210:213], v[84:87]
	v_mfma_f32_16x16x32_bf16 v[80:83], v[176:179], v[210:213], v[80:83]
	v_mfma_f32_16x16x32_bf16 v[80:83], v[172:175], v[206:209], v[80:83]
	v_mfma_f32_16x16x32_bf16 v[64:67], v[172:175], v[214:217], v[64:67]
	v_mfma_f32_16x16x32_bf16 v[64:67], v[176:179], v[218:221], v[64:67]
	v_mfma_f32_16x16x32_bf16 v[68:71], v[148:151], v[218:221], v[68:71]
	v_mfma_f32_16x16x32_bf16 v[68:71], v[144:147], v[214:217], v[68:71]
	s_barrier
	s_setprio 0
	s_add_i32 s64, s84, s69
	v_lshl_add_u64 v[222:223], v[222:223], 0, s[26:27]
	s_mov_b32 m0, s64
	ds_read_b128 v[180:183], v191 offset:49152
	v_xor_b32_e32 v253, 64, v191
	ds_read_b128 v[194:197], v253 offset:49152
	ds_read_b128 v[198:201], v191 offset:51200
	ds_read_b128 v[202:205], v253 offset:51200
	ds_read_b128 v[206:209], v191 offset:53248
	ds_read_b128 v[210:213], v253 offset:53248
	ds_read_b128 v[214:217], v191 offset:55296
	ds_read_b128 v[218:221], v253 offset:55296
	global_load_lds_dwordx4 v[222:223], off
	s_add_i32 m0, s64, 0x2000
	s_add_u32 s62, s62, 0x80080
	v_lshl_add_u64 v[222:223], v[224:225], 0, s[26:27]
	s_addc_u32 s63, s63, 0
	s_add_i32 s64, s85, s69
	global_load_lds_dwordx4 v[222:223], off
	v_lshl_add_u64 v[222:223], s[62:63], 0, v[154:155]
	s_mov_b32 m0, s64
	s_nop 0
	global_load_lds_dwordx4 v[222:223], off
	v_lshl_add_u64 v[222:223], s[62:63], 0, v[162:163]
	s_add_i32 m0, s64, 0x2000
	s_nop 0
	global_load_lds_dwordx4 v[222:223], off
	v_lshl_add_u64 v[222:223], v[226:227], 0, s[26:27]
	s_mov_b32 m0, s3
	s_nop 0
	global_load_lds_dwordx4 v[222:223], off
	v_lshl_add_u64 v[222:223], v[228:229], 0, s[26:27]
	s_mov_b32 m0, s75
	s_nop 0
	global_load_lds_dwordx4 v[222:223], off
	s_waitcnt vmcnt(8)
	s_waitcnt lgkmcnt(0)
	.p2align 3
	s_setprio 1
	s_barrier
	v_mfma_f32_16x16x32_bf16 v[60:63], v[128:131], v[180:183], v[60:63]
	v_mfma_f32_16x16x32_bf16 v[60:63], v[132:135], v[194:197], v[60:63]
	v_mfma_f32_16x16x32_bf16 v[56:59], v[140:143], v[194:197], v[56:59]
	v_mfma_f32_16x16x32_bf16 v[56:59], v[136:139], v[180:183], v[56:59]
	v_mfma_f32_16x16x32_bf16 v[40:43], v[136:139], v[198:201], v[40:43]
	v_mfma_f32_16x16x32_bf16 v[40:43], v[140:143], v[202:205], v[40:43]
	v_mfma_f32_16x16x32_bf16 v[44:47], v[132:135], v[202:205], v[44:47]
	v_mfma_f32_16x16x32_bf16 v[44:47], v[128:131], v[198:201], v[44:47]
	v_mfma_f32_16x16x32_bf16 v[28:31], v[128:131], v[206:209], v[28:31]
	v_mfma_f32_16x16x32_bf16 v[28:31], v[132:135], v[210:213], v[28:31]
	v_mfma_f32_16x16x32_bf16 v[24:27], v[140:143], v[210:213], v[24:27]
	v_mfma_f32_16x16x32_bf16 v[24:27], v[136:139], v[206:209], v[24:27]
	v_mfma_f32_16x16x32_bf16 v[8:11], v[136:139], v[214:217], v[8:11]
	v_mfma_f32_16x16x32_bf16 v[8:11], v[140:143], v[218:221], v[8:11]
	v_mfma_f32_16x16x32_bf16 v[12:15], v[132:135], v[218:221], v[12:15]
	v_mfma_f32_16x16x32_bf16 v[12:15], v[128:131], v[214:217], v[12:15]
	s_setprio 0
	s_setprio 1
	v_mfma_f32_16x16x32_bf16 v[52:55], v[144:147], v[180:183], v[52:55]
	v_mfma_f32_16x16x32_bf16 v[52:55], v[148:151], v[194:197], v[52:55]
	v_mfma_f32_16x16x32_bf16 v[48:51], v[176:179], v[194:197], v[48:51]
	v_mfma_f32_16x16x32_bf16 v[48:51], v[172:175], v[180:183], v[48:51]
	v_mfma_f32_16x16x32_bf16 v[32:35], v[172:175], v[198:201], v[32:35]
	v_mfma_f32_16x16x32_bf16 v[32:35], v[176:179], v[202:205], v[32:35]
	v_mfma_f32_16x16x32_bf16 v[36:39], v[148:151], v[202:205], v[36:39]
	v_mfma_f32_16x16x32_bf16 v[36:39], v[144:147], v[198:201], v[36:39]
	v_mfma_f32_16x16x32_bf16 v[20:23], v[144:147], v[206:209], v[20:23]
	v_mfma_f32_16x16x32_bf16 v[20:23], v[148:151], v[210:213], v[20:23]
	v_mfma_f32_16x16x32_bf16 v[16:19], v[176:179], v[210:213], v[16:19]
	v_mfma_f32_16x16x32_bf16 v[16:19], v[172:175], v[206:209], v[16:19]
	v_mfma_f32_16x16x32_bf16 v[0:3], v[172:175], v[214:217], v[0:3]
	v_mfma_f32_16x16x32_bf16 v[0:3], v[176:179], v[218:221], v[0:3]
	v_mfma_f32_16x16x32_bf16 v[4:7], v[148:151], v[218:221], v[4:7]
	v_mfma_f32_16x16x32_bf16 v[4:7], v[144:147], v[214:217], v[4:7]
	s_barrier
	s_setprio 0
	s_add_i32 s83, s83, 2
	s_add_u32 s81, s81, 0x100
	s_addc_u32 s82, s82, 0
	s_add_u32 s60, s60, 0x100
	s_addc_u32 s61, s61, 0
	s_cmp_gt_u32 s83, 29
	s_cbranch_scc0 .LBB0_440
	s_and_b64 vcc, exec, s[28:29]
	s_cbranch_vccz .LBB0_443
	s_barrier

.LBB0_525:
	s_ashr_i32 s29, s28, 31
	s_lshl_b64 s[30:31], s[28:29], 19
	s_add_u32 s30, s3, s30
	s_addc_u32 s31, s35, s31
	s_and_b64 s[44:45], s[10:11], exec
	s_cselect_b32 s29, s31, s51
	s_cselect_b32 s70, s30, s50
	s_ashr_i32 s27, s26, 31
	s_lshl_b64 s[44:45], s[26:27], 19
	s_add_u32 s44, s52, s44
	s_addc_u32 s45, s53, s45
	s_and_b64 s[72:73], s[10:11], exec
	s_cselect_b32 s71, s45, s49
	s_cselect_b32 s72, s44, s48
	s_lshl_b32 s27, s46, 8
	v_add_u32_e32 v0, s27, v148
	s_add_u32 s73, s48, 0x100
	v_ashrrev_i32_e32 v1, 31, v0
	s_addc_u32 s74, s49, 0
	v_lshl_add_u64 v[144:145], v[0:1], 4, s[16:17]
	s_add_u32 s46, s50, 0x40080
	s_addc_u32 s47, s51, 0
	s_mov_b32 s75, -2
	s_mov_b64 s[48:49], 0
	s_cmp_eq_u32 s61, 1
	s_cbranch_scc1 .Lfa_4
	v_add_u32_e32 v153, s66, v147
	ds_read_b128 v[160:163], v153
	v_xor_b32_e32 v253, 64, v153
	ds_read_b128 v[164:167], v253
	ds_read_b128 v[168:171], v153 offset:2048
	ds_read_b128 v[172:175], v253 offset:2048
	v_add_u32_e32 v153, s67, v147
	ds_read_b128 v[176:179], v153
	v_xor_b32_e32 v253, 64, v153
	ds_read_b128 v[180:183], v253
	ds_read_b128 v[186:189], v153 offset:2048
	ds_read_b128 v[190:193], v253 offset:2048
	s_add_u32 s50, s46, 0xfffc0080
	s_addc_u32 s51, s47, -1
	s_and_b64 s[48:49], s[48:49], exec
	s_cselect_b32 s51, s29, s51
	s_cselect_b32 s50, s70, s50
	s_cselect_b32 s49, s71, s74
	s_cselect_b32 s48, s72, s73
	v_lshl_add_u64 v[154:155], s[46:47], 0, v[138:139]
	s_add_i32 m0, s57, 0xc000
	ds_read_b128 v[194:197], v150
	v_xor_b32_e32 v253, 64, v150
	ds_read_b128 v[198:201], v253
	ds_read_b128 v[202:205], v150 offset:2048
	ds_read_b128 v[206:209], v253 offset:2048
	ds_read_b128 v[210:213], v150 offset:4096
	ds_read_b128 v[214:217], v253 offset:4096
	ds_read_b128 v[218:221], v150 offset:6144
	ds_read_b128 v[222:225], v253 offset:6144
	global_load_lds_dwordx4 v[154:155], off
	v_lshl_add_u64 v[154:155], s[46:47], 0, v[136:137]
	s_add_i32 m0, s57, 0xe000
	s_nop 0
	global_load_lds_dwordx4 v[154:155], off
	s_waitcnt vmcnt(16)
	s_waitcnt lgkmcnt(0)
	.p2align 3
	s_setprio 1
	s_barrier
	v_mfma_f32_16x16x32_bf16 v[124:127], v[160:163], v[194:197], 0
	v_mfma_f32_16x16x32_bf16 v[116:119], v[168:171], v[194:197], 0
	v_mfma_f32_16x16x32_bf16 v[108:111], v[160:163], v[202:205], 0
	v_mfma_f32_16x16x32_bf16 v[100:103], v[168:171], v[202:205], 0
	v_mfma_f32_16x16x32_bf16 v[92:95], v[160:163], v[210:213], 0
	v_mfma_f32_16x16x32_bf16 v[84:87], v[168:171], v[210:213], 0
	v_mfma_f32_16x16x32_bf16 v[76:79], v[160:163], v[218:221], 0
	v_mfma_f32_16x16x32_bf16 v[68:71], v[168:171], v[218:221], 0
	v_mfma_f32_16x16x32_bf16 v[124:127], v[164:167], v[198:201], v[124:127]
	v_mfma_f32_16x16x32_bf16 v[116:119], v[172:175], v[198:201], v[116:119]
	v_mfma_f32_16x16x32_bf16 v[108:111], v[164:167], v[206:209], v[108:111]
	v_mfma_f32_16x16x32_bf16 v[100:103], v[172:175], v[206:209], v[100:103]
	v_mfma_f32_16x16x32_bf16 v[92:95], v[164:167], v[214:217], v[92:95]
	v_mfma_f32_16x16x32_bf16 v[84:87], v[172:175], v[214:217], v[84:87]
	v_mfma_f32_16x16x32_bf16 v[76:79], v[164:167], v[222:225], v[76:79]
	v_mfma_f32_16x16x32_bf16 v[68:71], v[172:175], v[222:225], v[68:71]
	s_setprio 0
	s_setprio 1
	v_mfma_f32_16x16x32_bf16 v[120:123], v[176:179], v[194:197], 0
	v_mfma_f32_16x16x32_bf16 v[112:115], v[186:189], v[194:197], 0
	v_mfma_f32_16x16x32_bf16 v[104:107], v[176:179], v[202:205], 0
	v_mfma_f32_16x16x32_bf16 v[96:99], v[186:189], v[202:205], 0
	v_mfma_f32_16x16x32_bf16 v[88:91], v[176:179], v[210:213], 0
	v_mfma_f32_16x16x32_bf16 v[80:83], v[186:189], v[210:213], 0
	v_mfma_f32_16x16x32_bf16 v[72:75], v[176:179], v[218:221], 0
	v_mfma_f32_16x16x32_bf16 v[64:67], v[186:189], v[218:221], 0
	v_mfma_f32_16x16x32_bf16 v[120:123], v[180:183], v[198:201], v[120:123]
	v_mfma_f32_16x16x32_bf16 v[112:115], v[190:193], v[198:201], v[112:115]
	v_mfma_f32_16x16x32_bf16 v[104:107], v[180:183], v[206:209], v[104:107]
	v_mfma_f32_16x16x32_bf16 v[96:99], v[190:193], v[206:209], v[96:99]
	v_mfma_f32_16x16x32_bf16 v[88:91], v[180:183], v[214:217], v[88:91]
	v_mfma_f32_16x16x32_bf16 v[80:83], v[190:193], v[214:217], v[80:83]
	v_mfma_f32_16x16x32_bf16 v[72:75], v[180:183], v[222:225], v[72:75]
	v_mfma_f32_16x16x32_bf16 v[64:67], v[190:193], v[222:225], v[64:67]
	s_barrier
	s_setprio 0
	s_add_i32 s76, s66, s54
	v_lshl_add_u64 v[154:155], s[48:49], 0, v[132:133]
	s_mov_b32 m0, s76
	ds_read_b128 v[194:197], v150 offset:16384
	v_xor_b32_e32 v253, 64, v150
	ds_read_b128 v[198:201], v253 offset:16384
	ds_read_b128 v[202:205], v150 offset:18432
	ds_read_b128 v[206:209], v253 offset:18432
	ds_read_b128 v[210:213], v150 offset:20480
	ds_read_b128 v[214:217], v253 offset:20480
	ds_read_b128 v[218:221], v150 offset:22528
	ds_read_b128 v[222:225], v253 offset:22528
	global_load_lds_dwordx4 v[154:155], off
	s_add_i32 m0, s76, 0x2000
	s_add_u32 s76, s48, 0x40000
	v_lshl_add_u64 v[226:227], s[48:49], 0, v[128:129]
	s_addc_u32 s77, s49, 0
	s_add_i32 s78, s67, s54
	global_load_lds_dwordx4 v[226:227], off
	v_lshl_add_u64 v[228:229], s[76:77], 0, v[132:133]
	s_mov_b32 m0, s78
	v_lshl_add_u64 v[230:231], s[50:51], 0, v[130:131]
	global_load_lds_dwordx4 v[228:229], off
	v_lshl_add_u64 v[228:229], s[76:77], 0, v[128:129]
	s_add_i32 m0, s78, 0x2000
	s_nop 0
	global_load_lds_dwordx4 v[228:229], off
	v_lshl_add_u64 v[228:229], s[50:51], 0, v[134:135]
	s_mov_b32 m0, s57
	s_nop 0
	global_load_lds_dwordx4 v[228:229], off
	s_mov_b32 m0, s58
	s_nop 0
	global_load_lds_dwordx4 v[230:231], off
	s_waitcnt vmcnt(16)
	s_waitcnt lgkmcnt(0)
	.p2align 3
	s_setprio 1
	s_barrier
	v_mfma_f32_16x16x32_bf16 v[60:63], v[160:163], v[194:197], 0
	v_mfma_f32_16x16x32_bf16 v[52:55], v[168:171], v[194:197], 0
	v_mfma_f32_16x16x32_bf16 v[44:47], v[160:163], v[202:205], 0
	v_mfma_f32_16x16x32_bf16 v[36:39], v[168:171], v[202:205], 0
	v_mfma_f32_16x16x32_bf16 v[28:31], v[160:163], v[210:213], 0
	v_mfma_f32_16x16x32_bf16 v[20:23], v[168:171], v[210:213], 0
	v_mfma_f32_16x16x32_bf16 v[12:15], v[160:163], v[218:221], 0
	v_mfma_f32_16x16x32_bf16 v[4:7], v[168:171], v[218:221], 0
	v_mfma_f32_16x16x32_bf16 v[60:63], v[164:167], v[198:201], v[60:63]
	v_mfma_f32_16x16x32_bf16 v[52:55], v[172:175], v[198:201], v[52:55]
	v_mfma_f32_16x16x32_bf16 v[44:47], v[164:167], v[206:209], v[44:47]
	v_mfma_f32_16x16x32_bf16 v[36:39], v[172:175], v[206:209], v[36:39]
	v_mfma_f32_16x16x32_bf16 v[28:31], v[164:167], v[214:217], v[28:31]
	v_mfma_f32_16x16x32_bf16 v[20:23], v[172:175], v[214:217], v[20:23]
	v_mfma_f32_16x16x32_bf16 v[12:15], v[164:167], v[222:225], v[12:15]
	v_mfma_f32_16x16x32_bf16 v[4:7], v[172:175], v[222:225], v[4:7]
	s_setprio 0
	s_setprio 1
	v_mfma_f32_16x16x32_bf16 v[56:59], v[176:179], v[194:197], 0
	v_mfma_f32_16x16x32_bf16 v[48:51], v[186:189], v[194:197], 0
	v_mfma_f32_16x16x32_bf16 v[40:43], v[176:179], v[202:205], 0
	v_mfma_f32_16x16x32_bf16 v[32:35], v[186:189], v[202:205], 0
	v_mfma_f32_16x16x32_bf16 v[24:27], v[176:179], v[210:213], 0
	v_mfma_f32_16x16x32_bf16 v[16:19], v[186:189], v[210:213], 0
	v_mfma_f32_16x16x32_bf16 v[8:11], v[176:179], v[218:221], 0
	v_mfma_f32_16x16x32_bf16 v[0:3], v[186:189], v[218:221], 0
	v_mfma_f32_16x16x32_bf16 v[56:59], v[180:183], v[198:201], v[56:59]
	v_mfma_f32_16x16x32_bf16 v[48:51], v[190:193], v[198:201], v[48:51]
	v_mfma_f32_16x16x32_bf16 v[40:43], v[180:183], v[206:209], v[40:43]
	v_mfma_f32_16x16x32_bf16 v[32:35], v[190:193], v[206:209], v[32:35]
	v_mfma_f32_16x16x32_bf16 v[24:27], v[180:183], v[214:217], v[24:27]
	v_mfma_f32_16x16x32_bf16 v[16:19], v[190:193], v[214:217], v[16:19]
	v_mfma_f32_16x16x32_bf16 v[8:11], v[180:183], v[222:225], v[8:11]
	v_mfma_f32_16x16x32_bf16 v[0:3], v[190:193], v[222:225], v[0:3]
	s_barrier
	s_setprio 0
	s_add_i32 s76, 0, 0x18000
	v_add_u32_e32 v153, s76, v147
	s_add_i32 s77, 0, 0x1c000
	ds_read_b128 v[160:163], v153
	v_xor_b32_e32 v253, 64, v153
	ds_read_b128 v[164:167], v253
	ds_read_b128 v[168:171], v153 offset:2048
	ds_read_b128 v[172:175], v253 offset:2048
	v_add_u32_e32 v153, s77, v147
	ds_read_b128 v[176:179], v153
	v_xor_b32_e32 v253, 64, v153
	ds_read_b128 v[180:183], v253
	ds_read_b128 v[186:189], v153 offset:2048
	ds_read_b128 v[190:193], v253 offset:2048
	s_add_u32 s50, s50, 0x40000
	s_addc_u32 s51, s51, 0
	s_mov_b32 m0, s59
	v_lshl_add_u64 v[232:233], s[50:51], 0, v[134:135]
	ds_read_b128 v[194:197], v150 offset:32768
	v_xor_b32_e32 v253, 64, v150
	ds_read_b128 v[198:201], v253 offset:32768
	ds_read_b128 v[202:205], v150 offset:34816
	ds_read_b128 v[206:209], v253 offset:34816
	ds_read_b128 v[210:213], v150 offset:36864
	ds_read_b128 v[214:217], v253 offset:36864
	ds_read_b128 v[218:221], v150 offset:38912
	ds_read_b128 v[222:225], v253 offset:38912
	global_load_lds_dwordx4 v[232:233], off
	v_lshl_add_u64 v[232:233], s[50:51], 0, v[130:131]
	s_mov_b32 m0, s60
	s_nop 0
	global_load_lds_dwordx4 v[232:233], off
	s_waitcnt vmcnt(8)
	s_waitcnt lgkmcnt(0)
	.p2align 3
	s_setprio 1
	s_barrier
	v_mfma_f32_16x16x32_bf16 v[124:127], v[160:163], v[194:197], v[124:127]
	v_mfma_f32_16x16x32_bf16 v[124:127], v[164:167], v[198:201], v[124:127]
	v_mfma_f32_16x16x32_bf16 v[116:119], v[172:175], v[198:201], v[116:119]
	v_mfma_f32_16x16x32_bf16 v[116:119], v[168:171], v[194:197], v[116:119]
	v_mfma_f32_16x16x32_bf16 v[100:103], v[168:171], v[202:205], v[100:103]
	v_mfma_f32_16x16x32_bf16 v[100:103], v[172:175], v[206:209], v[100:103]
	v_mfma_f32_16x16x32_bf16 v[108:111], v[164:167], v[206:209], v[108:111]
	v_mfma_f32_16x16x32_bf16 v[108:111], v[160:163], v[202:205], v[108:111]
	v_mfma_f32_16x16x32_bf16 v[92:95], v[160:163], v[210:213], v[92:95]
	v_mfma_f32_16x16x32_bf16 v[92:95], v[164:167], v[214:217], v[92:95]
	v_mfma_f32_16x16x32_bf16 v[84:87], v[172:175], v[214:217], v[84:87]
	v_mfma_f32_16x16x32_bf16 v[84:87], v[168:171], v[210:213], v[84:87]
	v_mfma_f32_16x16x32_bf16 v[68:71], v[168:171], v[218:221], v[68:71]
	v_mfma_f32_16x16x32_bf16 v[68:71], v[172:175], v[222:225], v[68:71]
	v_mfma_f32_16x16x32_bf16 v[76:79], v[164:167], v[222:225], v[76:79]
	v_mfma_f32_16x16x32_bf16 v[76:79], v[160:163], v[218:221], v[76:79]
	s_setprio 0
	s_setprio 1
	v_mfma_f32_16x16x32_bf16 v[120:123], v[176:179], v[194:197], v[120:123]
	v_mfma_f32_16x16x32_bf16 v[120:123], v[180:183], v[198:201], v[120:123]
	v_mfma_f32_16x16x32_bf16 v[112:115], v[190:193], v[198:201], v[112:115]
	v_mfma_f32_16x16x32_bf16 v[112:115], v[186:189], v[194:197], v[112:115]
	v_mfma_f32_16x16x32_bf16 v[96:99], v[186:189], v[202:205], v[96:99]
	v_mfma_f32_16x16x32_bf16 v[96:99], v[190:193], v[206:209], v[96:99]
	v_mfma_f32_16x16x32_bf16 v[104:107], v[180:183], v[206:209], v[104:107]
	v_mfma_f32_16x16x32_bf16 v[104:107], v[176:179], v[202:205], v[104:107]
	v_mfma_f32_16x16x32_bf16 v[88:91], v[176:179], v[210:213], v[88:91]
	v_mfma_f32_16x16x32_bf16 v[88:91], v[180:183], v[214:217], v[88:91]
	v_mfma_f32_16x16x32_bf16 v[80:83], v[190:193], v[214:217], v[80:83]
	v_mfma_f32_16x16x32_bf16 v[80:83], v[186:189], v[210:213], v[80:83]
	v_mfma_f32_16x16x32_bf16 v[64:67], v[186:189], v[218:221], v[64:67]
	v_mfma_f32_16x16x32_bf16 v[64:67], v[190:193], v[222:225], v[64:67]
	v_mfma_f32_16x16x32_bf16 v[72:75], v[180:183], v[222:225], v[72:75]
	v_mfma_f32_16x16x32_bf16 v[72:75], v[176:179], v[218:221], v[72:75]
	s_barrier
	s_setprio 0
	s_add_i32 s50, s76, s54
	v_lshl_add_u64 v[154:155], v[154:155], 0, s[20:21]
	s_mov_b32 m0, s50
	ds_read_b128 v[194:197], v150 offset:49152
	v_xor_b32_e32 v253, 64, v150
	ds_read_b128 v[198:201], v253 offset:49152
	ds_read_b128 v[202:205], v150 offset:51200
	ds_read_b128 v[206:209], v253 offset:51200
	ds_read_b128 v[210:213], v150 offset:53248
	ds_read_b128 v[214:217], v253 offset:53248
	ds_read_b128 v[218:221], v150 offset:55296
	ds_read_b128 v[222:225], v253 offset:55296
	global_load_lds_dwordx4 v[154:155], off
	s_add_i32 m0, s50, 0x2000
	s_add_u32 s48, s48, 0x40080
	v_lshl_add_u64 v[154:155], v[226:227], 0, s[20:21]
	s_addc_u32 s49, s49, 0
	s_add_i32 s50, s77, s54
	global_load_lds_dwordx4 v[154:155], off
	v_lshl_add_u64 v[154:155], s[48:49], 0, v[132:133]
	s_mov_b32 m0, s50
	s_nop 0
	global_load_lds_dwordx4 v[154:155], off
	v_lshl_add_u64 v[154:155], s[48:49], 0, v[128:129]
	s_add_i32 m0, s50, 0x2000
	s_nop 0
	global_load_lds_dwordx4 v[154:155], off
	v_lshl_add_u64 v[154:155], v[228:229], 0, s[20:21]
	s_mov_b32 m0, s62
	s_nop 0
	global_load_lds_dwordx4 v[154:155], off
	v_lshl_add_u64 v[154:155], v[230:231], 0, s[20:21]
	s_mov_b32 m0, s63
	s_nop 0
	global_load_lds_dwordx4 v[154:155], off
	s_waitcnt vmcnt(8)
	s_waitcnt lgkmcnt(0)
	.p2align 3
	s_setprio 1
	s_barrier
	v_mfma_f32_16x16x32_bf16 v[60:63], v[160:163], v[194:197], v[60:63]
	v_mfma_f32_16x16x32_bf16 v[60:63], v[164:167], v[198:201], v[60:63]
	v_mfma_f32_16x16x32_bf16 v[52:55], v[172:175], v[198:201], v[52:55]
	v_mfma_f32_16x16x32_bf16 v[52:55], v[168:171], v[194:197], v[52:55]
	v_mfma_f32_16x16x32_bf16 v[36:39], v[168:171], v[202:205], v[36:39]
	v_mfma_f32_16x16x32_bf16 v[36:39], v[172:175], v[206:209], v[36:39]
	v_mfma_f32_16x16x32_bf16 v[44:47], v[164:167], v[206:209], v[44:47]
	v_mfma_f32_16x16x32_bf16 v[44:47], v[160:163], v[202:205], v[44:47]
	v_mfma_f32_16x16x32_bf16 v[28:31], v[160:163], v[210:213], v[28:31]
	v_mfma_f32_16x16x32_bf16 v[28:31], v[164:167], v[214:217], v[28:31]
	v_mfma_f32_16x16x32_bf16 v[20:23], v[172:175], v[214:217], v[20:23]
	v_mfma_f32_16x16x32_bf16 v[20:23], v[168:171], v[210:213], v[20:23]
	v_mfma_f32_16x16x32_bf16 v[4:7], v[168:171], v[218:221], v[4:7]
	v_mfma_f32_16x16x32_bf16 v[4:7], v[172:175], v[222:225], v[4:7]
	v_mfma_f32_16x16x32_bf16 v[12:15], v[164:167], v[222:225], v[12:15]
	v_mfma_f32_16x16x32_bf16 v[12:15], v[160:163], v[218:221], v[12:15]
	s_setprio 0
	s_setprio 1
	v_mfma_f32_16x16x32_bf16 v[56:59], v[176:179], v[194:197], v[56:59]
	v_mfma_f32_16x16x32_bf16 v[56:59], v[180:183], v[198:201], v[56:59]
	v_mfma_f32_16x16x32_bf16 v[48:51], v[190:193], v[198:201], v[48:51]
	v_mfma_f32_16x16x32_bf16 v[48:51], v[186:189], v[194:197], v[48:51]
	v_mfma_f32_16x16x32_bf16 v[32:35], v[186:189], v[202:205], v[32:35]
	v_mfma_f32_16x16x32_bf16 v[32:35], v[190:193], v[206:209], v[32:35]
	v_mfma_f32_16x16x32_bf16 v[40:43], v[180:183], v[206:209], v[40:43]
	v_mfma_f32_16x16x32_bf16 v[40:43], v[176:179], v[202:205], v[40:43]
	v_mfma_f32_16x16x32_bf16 v[24:27], v[176:179], v[210:213], v[24:27]
	v_mfma_f32_16x16x32_bf16 v[24:27], v[180:183], v[214:217], v[24:27]
	v_mfma_f32_16x16x32_bf16 v[16:19], v[190:193], v[214:217], v[16:19]
	v_mfma_f32_16x16x32_bf16 v[16:19], v[186:189], v[210:213], v[16:19]
	v_mfma_f32_16x16x32_bf16 v[0:3], v[186:189], v[218:221], v[0:3]
	v_mfma_f32_16x16x32_bf16 v[0:3], v[190:193], v[222:225], v[0:3]
	v_mfma_f32_16x16x32_bf16 v[8:11], v[180:183], v[222:225], v[8:11]
	v_mfma_f32_16x16x32_bf16 v[8:11], v[176:179], v[218:221], v[8:11]
	s_barrier
	s_setprio 0
	s_add_i32 s75, s75, 2
	s_add_u32 s73, s73, 0x100
	s_addc_u32 s74, s74, 0
	s_add_u32 s46, s46, 0x100
	s_addc_u32 s47, s47, 0
	s_branch .LBB0_527
.Lfa_4:
	v_add_u32_e32 v153, s66, v147
	ds_read_b128 v[160:163], v153
	v_xor_b32_e32 v253, 64, v153
	ds_read_b128 v[164:167], v253
	ds_read_b128 v[168:171], v153 offset:2048
	ds_read_b128 v[172:175], v253 offset:2048
	v_add_u32_e32 v153, s67, v147
	ds_read_b128 v[176:179], v153
	v_xor_b32_e32 v253, 64, v153
	ds_read_b128 v[180:183], v253
	ds_read_b128 v[186:189], v153 offset:2048
	ds_read_b128 v[190:193], v253 offset:2048
	s_add_u32 s50, s46, 0xfffc0080
	s_addc_u32 s51, s47, -1
	s_and_b64 s[48:49], s[48:49], exec
	s_cselect_b32 s51, s29, s51
	s_cselect_b32 s50, s70, s50
	s_cselect_b32 s49, s71, s74
	s_cselect_b32 s48, s72, s73
	v_lshl_add_u64 v[154:155], s[46:47], 0, v[138:139]
	s_add_i32 m0, s57, 0xc000
	ds_read_b128 v[194:197], v150
	v_xor_b32_e32 v253, 64, v150
	ds_read_b128 v[198:201], v253
	ds_read_b128 v[202:205], v150 offset:2048
	ds_read_b128 v[206:209], v253 offset:2048
	ds_read_b128 v[210:213], v150 offset:4096
	ds_read_b128 v[214:217], v253 offset:4096
	ds_read_b128 v[218:221], v150 offset:6144
	ds_read_b128 v[222:225], v253 offset:6144
	global_load_lds_dwordx4 v[154:155], off
	v_lshl_add_u64 v[154:155], s[46:47], 0, v[136:137]
	s_add_i32 m0, s57, 0xe000
	s_nop 0
	global_load_lds_dwordx4 v[154:155], off
	s_waitcnt vmcnt(8)
	s_waitcnt lgkmcnt(0)
	.p2align 3
	s_setprio 1
	s_barrier
	v_mfma_f32_16x16x32_bf16 v[124:127], v[160:163], v[194:197], 0
	v_mfma_f32_16x16x32_bf16 v[116:119], v[168:171], v[194:197], 0
	v_mfma_f32_16x16x32_bf16 v[108:111], v[160:163], v[202:205], 0
	v_mfma_f32_16x16x32_bf16 v[100:103], v[168:171], v[202:205], 0
	v_mfma_f32_16x16x32_bf16 v[92:95], v[160:163], v[210:213], 0
	v_mfma_f32_16x16x32_bf16 v[84:87], v[168:171], v[210:213], 0
	v_mfma_f32_16x16x32_bf16 v[76:79], v[160:163], v[218:221], 0
	v_mfma_f32_16x16x32_bf16 v[68:71], v[168:171], v[218:221], 0
	v_mfma_f32_16x16x32_bf16 v[124:127], v[164:167], v[198:201], v[124:127]
	v_mfma_f32_16x16x32_bf16 v[116:119], v[172:175], v[198:201], v[116:119]
	v_mfma_f32_16x16x32_bf16 v[108:111], v[164:167], v[206:209], v[108:111]
	v_mfma_f32_16x16x32_bf16 v[100:103], v[172:175], v[206:209], v[100:103]
	v_mfma_f32_16x16x32_bf16 v[92:95], v[164:167], v[214:217], v[92:95]
	v_mfma_f32_16x16x32_bf16 v[84:87], v[172:175], v[214:217], v[84:87]
	v_mfma_f32_16x16x32_bf16 v[76:79], v[164:167], v[222:225], v[76:79]
	v_mfma_f32_16x16x32_bf16 v[68:71], v[172:175], v[222:225], v[68:71]
	s_setprio 0
	s_setprio 1
	v_mfma_f32_16x16x32_bf16 v[120:123], v[176:179], v[194:197], 0
	v_mfma_f32_16x16x32_bf16 v[112:115], v[186:189], v[194:197], 0
	v_mfma_f32_16x16x32_bf16 v[104:107], v[176:179], v[202:205], 0
	v_mfma_f32_16x16x32_bf16 v[96:99], v[186:189], v[202:205], 0
	v_mfma_f32_16x16x32_bf16 v[88:91], v[176:179], v[210:213], 0
	v_mfma_f32_16x16x32_bf16 v[80:83], v[186:189], v[210:213], 0
	v_mfma_f32_16x16x32_bf16 v[72:75], v[176:179], v[218:221], 0
	v_mfma_f32_16x16x32_bf16 v[64:67], v[186:189], v[218:221], 0
	v_mfma_f32_16x16x32_bf16 v[120:123], v[180:183], v[198:201], v[120:123]
	v_mfma_f32_16x16x32_bf16 v[112:115], v[190:193], v[198:201], v[112:115]
	v_mfma_f32_16x16x32_bf16 v[104:107], v[180:183], v[206:209], v[104:107]
	v_mfma_f32_16x16x32_bf16 v[96:99], v[190:193], v[206:209], v[96:99]
	v_mfma_f32_16x16x32_bf16 v[88:91], v[180:183], v[214:217], v[88:91]
	v_mfma_f32_16x16x32_bf16 v[80:83], v[190:193], v[214:217], v[80:83]
	v_mfma_f32_16x16x32_bf16 v[72:75], v[180:183], v[222:225], v[72:75]
	v_mfma_f32_16x16x32_bf16 v[64:67], v[190:193], v[222:225], v[64:67]
	s_barrier
	s_setprio 0
	s_add_i32 s76, s66, s54
	v_lshl_add_u64 v[154:155], s[48:49], 0, v[132:133]
	s_mov_b32 m0, s76
	ds_read_b128 v[194:197], v150 offset:16384
	v_xor_b32_e32 v253, 64, v150
	ds_read_b128 v[198:201], v253 offset:16384
	ds_read_b128 v[202:205], v150 offset:18432
	ds_read_b128 v[206:209], v253 offset:18432
	ds_read_b128 v[210:213], v150 offset:20480
	ds_read_b128 v[214:217], v253 offset:20480
	ds_read_b128 v[218:221], v150 offset:22528
	ds_read_b128 v[222:225], v253 offset:22528
	global_load_lds_dwordx4 v[154:155], off
	s_add_i32 m0, s76, 0x2000
	s_add_u32 s76, s48, 0x40000
	v_lshl_add_u64 v[226:227], s[48:49], 0, v[128:129]
	s_addc_u32 s77, s49, 0
	s_add_i32 s78, s67, s54
	global_load_lds_dwordx4 v[226:227], off
	v_lshl_add_u64 v[228:229], s[76:77], 0, v[132:133]
	s_mov_b32 m0, s78
	v_lshl_add_u64 v[230:231], s[50:51], 0, v[130:131]
	global_load_lds_dwordx4 v[228:229], off
	v_lshl_add_u64 v[228:229], s[76:77], 0, v[128:129]
	s_add_i32 m0, s78, 0x2000
	s_nop 0
	global_load_lds_dwordx4 v[228:229], off
	v_lshl_add_u64 v[228:229], s[50:51], 0, v[134:135]
	s_mov_b32 m0, s57
	s_nop 0
	global_load_lds_dwordx4 v[228:229], off
	s_mov_b32 m0, s58
	s_nop 0
	global_load_lds_dwordx4 v[230:231], off
	s_waitcnt vmcnt(8)
	s_waitcnt lgkmcnt(0)
	.p2align 3
	s_setprio 1
	s_barrier
	v_mfma_f32_16x16x32_bf16 v[60:63], v[160:163], v[194:197], 0
	v_mfma_f32_16x16x32_bf16 v[52:55], v[168:171], v[194:197], 0
	v_mfma_f32_16x16x32_bf16 v[44:47], v[160:163], v[202:205], 0
	v_mfma_f32_16x16x32_bf16 v[36:39], v[168:171], v[202:205], 0
	v_mfma_f32_16x16x32_bf16 v[28:31], v[160:163], v[210:213], 0
	v_mfma_f32_16x16x32_bf16 v[20:23], v[168:171], v[210:213], 0
	v_mfma_f32_16x16x32_bf16 v[12:15], v[160:163], v[218:221], 0
	v_mfma_f32_16x16x32_bf16 v[4:7], v[168:171], v[218:221], 0
	v_mfma_f32_16x16x32_bf16 v[60:63], v[164:167], v[198:201], v[60:63]
	v_mfma_f32_16x16x32_bf16 v[52:55], v[172:175], v[198:201], v[52:55]
	v_mfma_f32_16x16x32_bf16 v[44:47], v[164:167], v[206:209], v[44:47]
	v_mfma_f32_16x16x32_bf16 v[36:39], v[172:175], v[206:209], v[36:39]
	v_mfma_f32_16x16x32_bf16 v[28:31], v[164:167], v[214:217], v[28:31]
	v_mfma_f32_16x16x32_bf16 v[20:23], v[172:175], v[214:217], v[20:23]
	v_mfma_f32_16x16x32_bf16 v[12:15], v[164:167], v[222:225], v[12:15]
	v_mfma_f32_16x16x32_bf16 v[4:7], v[172:175], v[222:225], v[4:7]
	s_setprio 0
	s_setprio 1
	v_mfma_f32_16x16x32_bf16 v[56:59], v[176:179], v[194:197], 0
	v_mfma_f32_16x16x32_bf16 v[48:51], v[186:189], v[194:197], 0
	v_mfma_f32_16x16x32_bf16 v[40:43], v[176:179], v[202:205], 0
	v_mfma_f32_16x16x32_bf16 v[32:35], v[186:189], v[202:205], 0
	v_mfma_f32_16x16x32_bf16 v[24:27], v[176:179], v[210:213], 0
	v_mfma_f32_16x16x32_bf16 v[16:19], v[186:189], v[210:213], 0
	v_mfma_f32_16x16x32_bf16 v[8:11], v[176:179], v[218:221], 0
	v_mfma_f32_16x16x32_bf16 v[0:3], v[186:189], v[218:221], 0
	v_mfma_f32_16x16x32_bf16 v[56:59], v[180:183], v[198:201], v[56:59]
	v_mfma_f32_16x16x32_bf16 v[48:51], v[190:193], v[198:201], v[48:51]
	v_mfma_f32_16x16x32_bf16 v[40:43], v[180:183], v[206:209], v[40:43]
	v_mfma_f32_16x16x32_bf16 v[32:35], v[190:193], v[206:209], v[32:35]
	v_mfma_f32_16x16x32_bf16 v[24:27], v[180:183], v[214:217], v[24:27]
	v_mfma_f32_16x16x32_bf16 v[16:19], v[190:193], v[214:217], v[16:19]
	v_mfma_f32_16x16x32_bf16 v[8:11], v[180:183], v[222:225], v[8:11]
	v_mfma_f32_16x16x32_bf16 v[0:3], v[190:193], v[222:225], v[0:3]
	s_barrier
	s_setprio 0
	s_add_i32 s76, 0, 0x18000
	v_add_u32_e32 v153, s76, v147
	s_add_i32 s77, 0, 0x1c000
	ds_read_b128 v[160:163], v153
	v_xor_b32_e32 v253, 64, v153
	ds_read_b128 v[164:167], v253
	ds_read_b128 v[168:171], v153 offset:2048
	ds_read_b128 v[172:175], v253 offset:2048
	v_add_u32_e32 v153, s77, v147
	ds_read_b128 v[176:179], v153
	v_xor_b32_e32 v253, 64, v153
	ds_read_b128 v[180:183], v253
	ds_read_b128 v[186:189], v153 offset:2048
	ds_read_b128 v[190:193], v253 offset:2048
	s_add_u32 s50, s50, 0x40000
	s_addc_u32 s51, s51, 0
	s_mov_b32 m0, s59
	v_lshl_add_u64 v[232:233], s[50:51], 0, v[134:135]
	ds_read_b128 v[194:197], v150 offset:32768
	v_xor_b32_e32 v253, 64, v150
	ds_read_b128 v[198:201], v253 offset:32768
	ds_read_b128 v[202:205], v150 offset:34816
	ds_read_b128 v[206:209], v253 offset:34816
	ds_read_b128 v[210:213], v150 offset:36864
	ds_read_b128 v[214:217], v253 offset:36864
	ds_read_b128 v[218:221], v150 offset:38912
	ds_read_b128 v[222:225], v253 offset:38912
	global_load_lds_dwordx4 v[232:233], off
	v_lshl_add_u64 v[232:233], s[50:51], 0, v[130:131]
	s_mov_b32 m0, s60
	s_nop 0
	global_load_lds_dwordx4 v[232:233], off
	s_waitcnt vmcnt(8)
	s_waitcnt lgkmcnt(0)
	.p2align 3
	s_setprio 1
	s_barrier
	v_mfma_f32_16x16x32_bf16 v[124:127], v[160:163], v[194:197], v[124:127]
	v_mfma_f32_16x16x32_bf16 v[124:127], v[164:167], v[198:201], v[124:127]
	v_mfma_f32_16x16x32_bf16 v[116:119], v[172:175], v[198:201], v[116:119]
	v_mfma_f32_16x16x32_bf16 v[116:119], v[168:171], v[194:197], v[116:119]
	v_mfma_f32_16x16x32_bf16 v[100:103], v[168:171], v[202:205], v[100:103]
	v_mfma_f32_16x16x32_bf16 v[100:103], v[172:175], v[206:209], v[100:103]
	v_mfma_f32_16x16x32_bf16 v[108:111], v[164:167], v[206:209], v[108:111]
	v_mfma_f32_16x16x32_bf16 v[108:111], v[160:163], v[202:205], v[108:111]
	v_mfma_f32_16x16x32_bf16 v[92:95], v[160:163], v[210:213], v[92:95]
	v_mfma_f32_16x16x32_bf16 v[92:95], v[164:167], v[214:217], v[92:95]
	v_mfma_f32_16x16x32_bf16 v[84:87], v[172:175], v[214:217], v[84:87]
	v_mfma_f32_16x16x32_bf16 v[84:87], v[168:171], v[210:213], v[84:87]
	v_mfma_f32_16x16x32_bf16 v[68:71], v[168:171], v[218:221], v[68:71]
	v_mfma_f32_16x16x32_bf16 v[68:71], v[172:175], v[222:225], v[68:71]
	v_mfma_f32_16x16x32_bf16 v[76:79], v[164:167], v[222:225], v[76:79]
	v_mfma_f32_16x16x32_bf16 v[76:79], v[160:163], v[218:221], v[76:79]
	s_setprio 0
	s_setprio 1
	v_mfma_f32_16x16x32_bf16 v[120:123], v[176:179], v[194:197], v[120:123]
	v_mfma_f32_16x16x32_bf16 v[120:123], v[180:183], v[198:201], v[120:123]
	v_mfma_f32_16x16x32_bf16 v[112:115], v[190:193], v[198:201], v[112:115]
	v_mfma_f32_16x16x32_bf16 v[112:115], v[186:189], v[194:197], v[112:115]
	v_mfma_f32_16x16x32_bf16 v[96:99], v[186:189], v[202:205], v[96:99]
	v_mfma_f32_16x16x32_bf16 v[96:99], v[190:193], v[206:209], v[96:99]
	v_mfma_f32_16x16x32_bf16 v[104:107], v[180:183], v[206:209], v[104:107]
	v_mfma_f32_16x16x32_bf16 v[104:107], v[176:179], v[202:205], v[104:107]
	v_mfma_f32_16x16x32_bf16 v[88:91], v[176:179], v[210:213], v[88:91]
	v_mfma_f32_16x16x32_bf16 v[88:91], v[180:183], v[214:217], v[88:91]
	v_mfma_f32_16x16x32_bf16 v[80:83], v[190:193], v[214:217], v[80:83]
	v_mfma_f32_16x16x32_bf16 v[80:83], v[186:189], v[210:213], v[80:83]
	v_mfma_f32_16x16x32_bf16 v[64:67], v[186:189], v[218:221], v[64:67]
	v_mfma_f32_16x16x32_bf16 v[64:67], v[190:193], v[222:225], v[64:67]
	v_mfma_f32_16x16x32_bf16 v[72:75], v[180:183], v[222:225], v[72:75]
	v_mfma_f32_16x16x32_bf16 v[72:75], v[176:179], v[218:221], v[72:75]
	s_barrier
	s_setprio 0
	s_add_i32 s50, s76, s54
	v_lshl_add_u64 v[154:155], v[154:155], 0, s[20:21]
	s_mov_b32 m0, s50
	ds_read_b128 v[194:197], v150 offset:49152
	v_xor_b32_e32 v253, 64, v150
	ds_read_b128 v[198:201], v253 offset:49152
	ds_read_b128 v[202:205], v150 offset:51200
	ds_read_b128 v[206:209], v253 offset:51200
	ds_read_b128 v[210:213], v150 offset:53248
	ds_read_b128 v[214:217], v253 offset:53248
	ds_read_b128 v[218:221], v150 offset:55296
	ds_read_b128 v[222:225], v253 offset:55296
	global_load_lds_dwordx4 v[154:155], off
	s_add_i32 m0, s50, 0x2000
	s_add_u32 s48, s48, 0x40080
	v_lshl_add_u64 v[154:155], v[226:227], 0, s[20:21]
	s_addc_u32 s49, s49, 0
	s_add_i32 s50, s77, s54
	global_load_lds_dwordx4 v[154:155], off
	v_lshl_add_u64 v[154:155], s[48:49], 0, v[132:133]
	s_mov_b32 m0, s50
	s_nop 0
	global_load_lds_dwordx4 v[154:155], off
	v_lshl_add_u64 v[154:155], s[48:49], 0, v[128:129]
	s_add_i32 m0, s50, 0x2000
	s_nop 0
	global_load_lds_dwordx4 v[154:155], off
	v_lshl_add_u64 v[154:155], v[228:229], 0, s[20:21]
	s_mov_b32 m0, s62
	s_nop 0
	global_load_lds_dwordx4 v[154:155], off
	v_lshl_add_u64 v[154:155], v[230:231], 0, s[20:21]
	s_mov_b32 m0, s63
	s_nop 0
	global_load_lds_dwordx4 v[154:155], off
	s_waitcnt vmcnt(8)
	s_waitcnt lgkmcnt(0)
	.p2align 3
	s_setprio 1
	s_barrier
	v_mfma_f32_16x16x32_bf16 v[60:63], v[160:163], v[194:197], v[60:63]
	v_mfma_f32_16x16x32_bf16 v[60:63], v[164:167], v[198:201], v[60:63]
	v_mfma_f32_16x16x32_bf16 v[52:55], v[172:175], v[198:201], v[52:55]
	v_mfma_f32_16x16x32_bf16 v[52:55], v[168:171], v[194:197], v[52:55]
	v_mfma_f32_16x16x32_bf16 v[36:39], v[168:171], v[202:205], v[36:39]
	v_mfma_f32_16x16x32_bf16 v[36:39], v[172:175], v[206:209], v[36:39]
	v_mfma_f32_16x16x32_bf16 v[44:47], v[164:167], v[206:209], v[44:47]
	v_mfma_f32_16x16x32_bf16 v[44:47], v[160:163], v[202:205], v[44:47]
	v_mfma_f32_16x16x32_bf16 v[28:31], v[160:163], v[210:213], v[28:31]
	v_mfma_f32_16x16x32_bf16 v[28:31], v[164:167], v[214:217], v[28:31]
	v_mfma_f32_16x16x32_bf16 v[20:23], v[172:175], v[214:217], v[20:23]
	v_mfma_f32_16x16x32_bf16 v[20:23], v[168:171], v[210:213], v[20:23]
	v_mfma_f32_16x16x32_bf16 v[4:7], v[168:171], v[218:221], v[4:7]
	v_mfma_f32_16x16x32_bf16 v[4:7], v[172:175], v[222:225], v[4:7]
	v_mfma_f32_16x16x32_bf16 v[12:15], v[164:167], v[222:225], v[12:15]
	v_mfma_f32_16x16x32_bf16 v[12:15], v[160:163], v[218:221], v[12:15]
	s_setprio 0
	s_setprio 1
	v_mfma_f32_16x16x32_bf16 v[56:59], v[176:179], v[194:197], v[56:59]
	v_mfma_f32_16x16x32_bf16 v[56:59], v[180:183], v[198:201], v[56:59]
	v_mfma_f32_16x16x32_bf16 v[48:51], v[190:193], v[198:201], v[48:51]
	v_mfma_f32_16x16x32_bf16 v[48:51], v[186:189], v[194:197], v[48:51]
	v_mfma_f32_16x16x32_bf16 v[32:35], v[186:189], v[202:205], v[32:35]
	v_mfma_f32_16x16x32_bf16 v[32:35], v[190:193], v[206:209], v[32:35]
	v_mfma_f32_16x16x32_bf16 v[40:43], v[180:183], v[206:209], v[40:43]
	v_mfma_f32_16x16x32_bf16 v[40:43], v[176:179], v[202:205], v[40:43]
	v_mfma_f32_16x16x32_bf16 v[24:27], v[176:179], v[210:213], v[24:27]
	v_mfma_f32_16x16x32_bf16 v[24:27], v[180:183], v[214:217], v[24:27]
	v_mfma_f32_16x16x32_bf16 v[16:19], v[190:193], v[214:217], v[16:19]
	v_mfma_f32_16x16x32_bf16 v[16:19], v[186:189], v[210:213], v[16:19]
	v_mfma_f32_16x16x32_bf16 v[0:3], v[186:189], v[218:221], v[0:3]
	v_mfma_f32_16x16x32_bf16 v[0:3], v[190:193], v[222:225], v[0:3]
	v_mfma_f32_16x16x32_bf16 v[8:11], v[180:183], v[222:225], v[8:11]
	v_mfma_f32_16x16x32_bf16 v[8:11], v[176:179], v[218:221], v[8:11]
	s_barrier
	s_setprio 0
	s_add_i32 s75, s75, 2
	s_add_u32 s73, s73, 0x100
	s_addc_u32 s74, s74, 0
	s_add_u32 s46, s46, 0x100
	s_addc_u32 s47, s47, 0
	s_branch .LBB0_527
.LBB0_526:
	v_add_u32_e32 v153, s66, v147
	ds_read_b128 v[160:163], v153
	v_xor_b32_e32 v253, 64, v153
	ds_read_b128 v[164:167], v253
	ds_read_b128 v[168:171], v153 offset:2048
	ds_read_b128 v[172:175], v253 offset:2048
	v_add_u32_e32 v153, s67, v147
	ds_read_b128 v[176:179], v153
	v_xor_b32_e32 v253, 64, v153
	ds_read_b128 v[180:183], v253
	ds_read_b128 v[186:189], v153 offset:2048
	ds_read_b128 v[190:193], v253 offset:2048
	s_add_u32 s50, s46, 0xfffc0080
	s_addc_u32 s51, s47, -1
	s_and_b64 s[48:49], s[48:49], exec
	s_cselect_b32 s51, s29, s51
	s_cselect_b32 s50, s70, s50
	s_cselect_b32 s49, s71, s74
	s_cselect_b32 s48, s72, s73
	v_lshl_add_u64 v[154:155], s[46:47], 0, v[138:139]
	s_add_i32 m0, s57, 0xc000
	ds_read_b128 v[194:197], v150
	v_xor_b32_e32 v253, 64, v150
	ds_read_b128 v[198:201], v253
	ds_read_b128 v[202:205], v150 offset:2048
	ds_read_b128 v[206:209], v253 offset:2048
	ds_read_b128 v[210:213], v150 offset:4096
	ds_read_b128 v[214:217], v253 offset:4096
	ds_read_b128 v[218:221], v150 offset:6144
	ds_read_b128 v[222:225], v253 offset:6144
	global_load_lds_dwordx4 v[154:155], off
	v_lshl_add_u64 v[154:155], s[46:47], 0, v[136:137]
	s_add_i32 m0, s57, 0xe000
	s_nop 0
	global_load_lds_dwordx4 v[154:155], off
	s_waitcnt vmcnt(8)
	s_waitcnt lgkmcnt(0)
	.p2align 3
	s_setprio 1
	s_barrier
	v_mfma_f32_16x16x32_bf16 v[124:127], v[160:163], v[194:197], v[124:127]
	v_mfma_f32_16x16x32_bf16 v[124:127], v[164:167], v[198:201], v[124:127]
	v_mfma_f32_16x16x32_bf16 v[116:119], v[172:175], v[198:201], v[116:119]
	v_mfma_f32_16x16x32_bf16 v[116:119], v[168:171], v[194:197], v[116:119]
	v_mfma_f32_16x16x32_bf16 v[100:103], v[168:171], v[202:205], v[100:103]
	v_mfma_f32_16x16x32_bf16 v[100:103], v[172:175], v[206:209], v[100:103]
	v_mfma_f32_16x16x32_bf16 v[108:111], v[164:167], v[206:209], v[108:111]
	v_mfma_f32_16x16x32_bf16 v[108:111], v[160:163], v[202:205], v[108:111]
	v_mfma_f32_16x16x32_bf16 v[92:95], v[160:163], v[210:213], v[92:95]
	v_mfma_f32_16x16x32_bf16 v[92:95], v[164:167], v[214:217], v[92:95]
	v_mfma_f32_16x16x32_bf16 v[84:87], v[172:175], v[214:217], v[84:87]
	v_mfma_f32_16x16x32_bf16 v[84:87], v[168:171], v[210:213], v[84:87]
	v_mfma_f32_16x16x32_bf16 v[68:71], v[168:171], v[218:221], v[68:71]
	v_mfma_f32_16x16x32_bf16 v[68:71], v[172:175], v[222:225], v[68:71]
	v_mfma_f32_16x16x32_bf16 v[76:79], v[164:167], v[222:225], v[76:79]
	v_mfma_f32_16x16x32_bf16 v[76:79], v[160:163], v[218:221], v[76:79]
	s_setprio 0
	s_setprio 1
	v_mfma_f32_16x16x32_bf16 v[120:123], v[176:179], v[194:197], v[120:123]
	v_mfma_f32_16x16x32_bf16 v[120:123], v[180:183], v[198:201], v[120:123]
	v_mfma_f32_16x16x32_bf16 v[112:115], v[190:193], v[198:201], v[112:115]
	v_mfma_f32_16x16x32_bf16 v[112:115], v[186:189], v[194:197], v[112:115]
	v_mfma_f32_16x16x32_bf16 v[96:99], v[186:189], v[202:205], v[96:99]
	v_mfma_f32_16x16x32_bf16 v[96:99], v[190:193], v[206:209], v[96:99]
	v_mfma_f32_16x16x32_bf16 v[104:107], v[180:183], v[206:209], v[104:107]
	v_mfma_f32_16x16x32_bf16 v[104:107], v[176:179], v[202:205], v[104:107]
	v_mfma_f32_16x16x32_bf16 v[88:91], v[176:179], v[210:213], v[88:91]
	v_mfma_f32_16x16x32_bf16 v[88:91], v[180:183], v[214:217], v[88:91]
	v_mfma_f32_16x16x32_bf16 v[80:83], v[190:193], v[214:217], v[80:83]
	v_mfma_f32_16x16x32_bf16 v[80:83], v[186:189], v[210:213], v[80:83]
	v_mfma_f32_16x16x32_bf16 v[64:67], v[186:189], v[218:221], v[64:67]
	v_mfma_f32_16x16x32_bf16 v[64:67], v[190:193], v[222:225], v[64:67]
	v_mfma_f32_16x16x32_bf16 v[72:75], v[180:183], v[222:225], v[72:75]
	v_mfma_f32_16x16x32_bf16 v[72:75], v[176:179], v[218:221], v[72:75]
	s_barrier
	s_setprio 0
	s_add_i32 s76, s66, s54
	v_lshl_add_u64 v[154:155], s[48:49], 0, v[132:133]
	s_mov_b32 m0, s76
	ds_read_b128 v[194:197], v150 offset:16384
	v_xor_b32_e32 v253, 64, v150
	ds_read_b128 v[198:201], v253 offset:16384
	ds_read_b128 v[202:205], v150 offset:18432
	ds_read_b128 v[206:209], v253 offset:18432
	ds_read_b128 v[210:213], v150 offset:20480
	ds_read_b128 v[214:217], v253 offset:20480
	ds_read_b128 v[218:221], v150 offset:22528
	ds_read_b128 v[222:225], v253 offset:22528
	global_load_lds_dwordx4 v[154:155], off
	s_add_i32 m0, s76, 0x2000
	s_add_u32 s76, s48, 0x40000
	v_lshl_add_u64 v[226:227], s[48:49], 0, v[128:129]
	s_addc_u32 s77, s49, 0
	s_add_i32 s78, s67, s54
	global_load_lds_dwordx4 v[226:227], off
	v_lshl_add_u64 v[228:229], s[76:77], 0, v[132:133]
	s_mov_b32 m0, s78
	v_lshl_add_u64 v[230:231], s[50:51], 0, v[130:131]
	global_load_lds_dwordx4 v[228:229], off
	v_lshl_add_u64 v[228:229], s[76:77], 0, v[128:129]
	s_add_i32 m0, s78, 0x2000
	s_nop 0
	global_load_lds_dwordx4 v[228:229], off
	v_lshl_add_u64 v[228:229], s[50:51], 0, v[134:135]
	s_mov_b32 m0, s57
	s_nop 0
	global_load_lds_dwordx4 v[228:229], off
	s_mov_b32 m0, s58
	s_nop 0
	global_load_lds_dwordx4 v[230:231], off
	s_waitcnt vmcnt(8)
	s_waitcnt lgkmcnt(0)
	.p2align 3
	s_setprio 1
	s_barrier
	v_mfma_f32_16x16x32_bf16 v[60:63], v[160:163], v[194:197], v[60:63]
	v_mfma_f32_16x16x32_bf16 v[60:63], v[164:167], v[198:201], v[60:63]
	v_mfma_f32_16x16x32_bf16 v[52:55], v[172:175], v[198:201], v[52:55]
	v_mfma_f32_16x16x32_bf16 v[52:55], v[168:171], v[194:197], v[52:55]
	v_mfma_f32_16x16x32_bf16 v[36:39], v[168:171], v[202:205], v[36:39]
	v_mfma_f32_16x16x32_bf16 v[36:39], v[172:175], v[206:209], v[36:39]
	v_mfma_f32_16x16x32_bf16 v[44:47], v[164:167], v[206:209], v[44:47]
	v_mfma_f32_16x16x32_bf16 v[44:47], v[160:163], v[202:205], v[44:47]
	v_mfma_f32_16x16x32_bf16 v[28:31], v[160:163], v[210:213], v[28:31]
	v_mfma_f32_16x16x32_bf16 v[28:31], v[164:167], v[214:217], v[28:31]
	v_mfma_f32_16x16x32_bf16 v[20:23], v[172:175], v[214:217], v[20:23]
	v_mfma_f32_16x16x32_bf16 v[20:23], v[168:171], v[210:213], v[20:23]
	v_mfma_f32_16x16x32_bf16 v[4:7], v[168:171], v[218:221], v[4:7]
	v_mfma_f32_16x16x32_bf16 v[4:7], v[172:175], v[222:225], v[4:7]
	v_mfma_f32_16x16x32_bf16 v[12:15], v[164:167], v[222:225], v[12:15]
	v_mfma_f32_16x16x32_bf16 v[12:15], v[160:163], v[218:221], v[12:15]
	s_setprio 0
	s_setprio 1
	v_mfma_f32_16x16x32_bf16 v[56:59], v[176:179], v[194:197], v[56:59]
	v_mfma_f32_16x16x32_bf16 v[56:59], v[180:183], v[198:201], v[56:59]
	v_mfma_f32_16x16x32_bf16 v[48:51], v[190:193], v[198:201], v[48:51]
	v_mfma_f32_16x16x32_bf16 v[48:51], v[186:189], v[194:197], v[48:51]
	v_mfma_f32_16x16x32_bf16 v[32:35], v[186:189], v[202:205], v[32:35]
	v_mfma_f32_16x16x32_bf16 v[32:35], v[190:193], v[206:209], v[32:35]
	v_mfma_f32_16x16x32_bf16 v[40:43], v[180:183], v[206:209], v[40:43]
	v_mfma_f32_16x16x32_bf16 v[40:43], v[176:179], v[202:205], v[40:43]
	v_mfma_f32_16x16x32_bf16 v[24:27], v[176:179], v[210:213], v[24:27]
	v_mfma_f32_16x16x32_bf16 v[24:27], v[180:183], v[214:217], v[24:27]
	v_mfma_f32_16x16x32_bf16 v[16:19], v[190:193], v[214:217], v[16:19]
	v_mfma_f32_16x16x32_bf16 v[16:19], v[186:189], v[210:213], v[16:19]
	v_mfma_f32_16x16x32_bf16 v[0:3], v[186:189], v[218:221], v[0:3]
	v_mfma_f32_16x16x32_bf16 v[0:3], v[190:193], v[222:225], v[0:3]
	v_mfma_f32_16x16x32_bf16 v[8:11], v[180:183], v[222:225], v[8:11]
	v_mfma_f32_16x16x32_bf16 v[8:11], v[176:179], v[218:221], v[8:11]
	s_barrier
	s_setprio 0
	s_add_i32 s76, 0, 0x18000
	v_add_u32_e32 v153, s76, v147
	s_add_i32 s77, 0, 0x1c000
	ds_read_b128 v[160:163], v153
	v_xor_b32_e32 v253, 64, v153
	ds_read_b128 v[164:167], v253
	ds_read_b128 v[168:171], v153 offset:2048
	ds_read_b128 v[172:175], v253 offset:2048
	v_add_u32_e32 v153, s77, v147
	ds_read_b128 v[176:179], v153
	v_xor_b32_e32 v253, 64, v153
	ds_read_b128 v[180:183], v253
	ds_read_b128 v[186:189], v153 offset:2048
	ds_read_b128 v[190:193], v253 offset:2048
	s_add_u32 s50, s50, 0x40000
	s_addc_u32 s51, s51, 0
	s_mov_b32 m0, s59
	v_lshl_add_u64 v[232:233], s[50:51], 0, v[134:135]
	ds_read_b128 v[194:197], v150 offset:32768
	v_xor_b32_e32 v253, 64, v150
	ds_read_b128 v[198:201], v253 offset:32768
	ds_read_b128 v[202:205], v150 offset:34816
	ds_read_b128 v[206:209], v253 offset:34816
	ds_read_b128 v[210:213], v150 offset:36864
	ds_read_b128 v[214:217], v253 offset:36864
	ds_read_b128 v[218:221], v150 offset:38912
	ds_read_b128 v[222:225], v253 offset:38912
	global_load_lds_dwordx4 v[232:233], off
	v_lshl_add_u64 v[232:233], s[50:51], 0, v[130:131]
	s_mov_b32 m0, s60
	s_nop 0
	global_load_lds_dwordx4 v[232:233], off
	s_waitcnt vmcnt(8)
	s_waitcnt lgkmcnt(0)
	.p2align 3
	s_setprio 1
	s_barrier
	v_mfma_f32_16x16x32_bf16 v[124:127], v[160:163], v[194:197], v[124:127]
	v_mfma_f32_16x16x32_bf16 v[124:127], v[164:167], v[198:201], v[124:127]
	v_mfma_f32_16x16x32_bf16 v[116:119], v[172:175], v[198:201], v[116:119]
	v_mfma_f32_16x16x32_bf16 v[116:119], v[168:171], v[194:197], v[116:119]
	v_mfma_f32_16x16x32_bf16 v[100:103], v[168:171], v[202:205], v[100:103]
	v_mfma_f32_16x16x32_bf16 v[100:103], v[172:175], v[206:209], v[100:103]
	v_mfma_f32_16x16x32_bf16 v[108:111], v[164:167], v[206:209], v[108:111]
	v_mfma_f32_16x16x32_bf16 v[108:111], v[160:163], v[202:205], v[108:111]
	v_mfma_f32_16x16x32_bf16 v[92:95], v[160:163], v[210:213], v[92:95]
	v_mfma_f32_16x16x32_bf16 v[92:95], v[164:167], v[214:217], v[92:95]
	v_mfma_f32_16x16x32_bf16 v[84:87], v[172:175], v[214:217], v[84:87]
	v_mfma_f32_16x16x32_bf16 v[84:87], v[168:171], v[210:213], v[84:87]
	v_mfma_f32_16x16x32_bf16 v[68:71], v[168:171], v[218:221], v[68:71]
	v_mfma_f32_16x16x32_bf16 v[68:71], v[172:175], v[222:225], v[68:71]
	v_mfma_f32_16x16x32_bf16 v[76:79], v[164:167], v[222:225], v[76:79]
	v_mfma_f32_16x16x32_bf16 v[76:79], v[160:163], v[218:221], v[76:79]
	s_setprio 0
	s_setprio 1
	v_mfma_f32_16x16x32_bf16 v[120:123], v[176:179], v[194:197], v[120:123]
	v_mfma_f32_16x16x32_bf16 v[120:123], v[180:183], v[198:201], v[120:123]
	v_mfma_f32_16x16x32_bf16 v[112:115], v[190:193], v[198:201], v[112:115]
	v_mfma_f32_16x16x32_bf16 v[112:115], v[186:189], v[194:197], v[112:115]
	v_mfma_f32_16x16x32_bf16 v[96:99], v[186:189], v[202:205], v[96:99]
	v_mfma_f32_16x16x32_bf16 v[96:99], v[190:193], v[206:209], v[96:99]
	v_mfma_f32_16x16x32_bf16 v[104:107], v[180:183], v[206:209], v[104:107]
	v_mfma_f32_16x16x32_bf16 v[104:107], v[176:179], v[202:205], v[104:107]
	v_mfma_f32_16x16x32_bf16 v[88:91], v[176:179], v[210:213], v[88:91]
	v_mfma_f32_16x16x32_bf16 v[88:91], v[180:183], v[214:217], v[88:91]
	v_mfma_f32_16x16x32_bf16 v[80:83], v[190:193], v[214:217], v[80:83]
	v_mfma_f32_16x16x32_bf16 v[80:83], v[186:189], v[210:213], v[80:83]
	v_mfma_f32_16x16x32_bf16 v[64:67], v[186:189], v[218:221], v[64:67]
	v_mfma_f32_16x16x32_bf16 v[64:67], v[190:193], v[222:225], v[64:67]
	v_mfma_f32_16x16x32_bf16 v[72:75], v[180:183], v[222:225], v[72:75]
	v_mfma_f32_16x16x32_bf16 v[72:75], v[176:179], v[218:221], v[72:75]
	s_barrier
	s_setprio 0
	s_add_i32 s50, s76, s54
	v_lshl_add_u64 v[154:155], v[154:155], 0, s[20:21]
	s_mov_b32 m0, s50
	ds_read_b128 v[194:197], v150 offset:49152
	v_xor_b32_e32 v253, 64, v150
	ds_read_b128 v[198:201], v253 offset:49152
	ds_read_b128 v[202:205], v150 offset:51200
	ds_read_b128 v[206:209], v253 offset:51200
	ds_read_b128 v[210:213], v150 offset:53248
	ds_read_b128 v[214:217], v253 offset:53248
	ds_read_b128 v[218:221], v150 offset:55296
	ds_read_b128 v[222:225], v253 offset:55296
	global_load_lds_dwordx4 v[154:155], off
	s_add_i32 m0, s50, 0x2000
	s_add_u32 s48, s48, 0x40080
	v_lshl_add_u64 v[154:155], v[226:227], 0, s[20:21]
	s_addc_u32 s49, s49, 0
	s_add_i32 s50, s77, s54
	global_load_lds_dwordx4 v[154:155], off
	v_lshl_add_u64 v[154:155], s[48:49], 0, v[132:133]
	s_mov_b32 m0, s50
	s_nop 0
	global_load_lds_dwordx4 v[154:155], off
	v_lshl_add_u64 v[154:155], s[48:49], 0, v[128:129]
	s_add_i32 m0, s50, 0x2000
	s_nop 0
	global_load_lds_dwordx4 v[154:155], off
	v_lshl_add_u64 v[154:155], v[228:229], 0, s[20:21]
	s_mov_b32 m0, s62
	s_nop 0
	global_load_lds_dwordx4 v[154:155], off
	v_lshl_add_u64 v[154:155], v[230:231], 0, s[20:21]
	s_mov_b32 m0, s63
	s_nop 0
	global_load_lds_dwordx4 v[154:155], off
	s_waitcnt vmcnt(8)
	s_waitcnt lgkmcnt(0)
	.p2align 3
	s_setprio 1
	s_barrier
	v_mfma_f32_16x16x32_bf16 v[60:63], v[160:163], v[194:197], v[60:63]
	v_mfma_f32_16x16x32_bf16 v[60:63], v[164:167], v[198:201], v[60:63]
	v_mfma_f32_16x16x32_bf16 v[52:55], v[172:175], v[198:201], v[52:55]
	v_mfma_f32_16x16x32_bf16 v[52:55], v[168:171], v[194:197], v[52:55]
	v_mfma_f32_16x16x32_bf16 v[36:39], v[168:171], v[202:205], v[36:39]
	v_mfma_f32_16x16x32_bf16 v[36:39], v[172:175], v[206:209], v[36:39]
	v_mfma_f32_16x16x32_bf16 v[44:47], v[164:167], v[206:209], v[44:47]
	v_mfma_f32_16x16x32_bf16 v[44:47], v[160:163], v[202:205], v[44:47]
	v_mfma_f32_16x16x32_bf16 v[28:31], v[160:163], v[210:213], v[28:31]
	v_mfma_f32_16x16x32_bf16 v[28:31], v[164:167], v[214:217], v[28:31]
	v_mfma_f32_16x16x32_bf16 v[20:23], v[172:175], v[214:217], v[20:23]
	v_mfma_f32_16x16x32_bf16 v[20:23], v[168:171], v[210:213], v[20:23]
	v_mfma_f32_16x16x32_bf16 v[4:7], v[168:171], v[218:221], v[4:7]
	v_mfma_f32_16x16x32_bf16 v[4:7], v[172:175], v[222:225], v[4:7]
	v_mfma_f32_16x16x32_bf16 v[12:15], v[164:167], v[222:225], v[12:15]
	v_mfma_f32_16x16x32_bf16 v[12:15], v[160:163], v[218:221], v[12:15]
	s_setprio 0
	s_setprio 1
	v_mfma_f32_16x16x32_bf16 v[56:59], v[176:179], v[194:197], v[56:59]
	v_mfma_f32_16x16x32_bf16 v[56:59], v[180:183], v[198:201], v[56:59]
	v_mfma_f32_16x16x32_bf16 v[48:51], v[190:193], v[198:201], v[48:51]
	v_mfma_f32_16x16x32_bf16 v[48:51], v[186:189], v[194:197], v[48:51]
	v_mfma_f32_16x16x32_bf16 v[32:35], v[186:189], v[202:205], v[32:35]
	v_mfma_f32_16x16x32_bf16 v[32:35], v[190:193], v[206:209], v[32:35]
	v_mfma_f32_16x16x32_bf16 v[40:43], v[180:183], v[206:209], v[40:43]
	v_mfma_f32_16x16x32_bf16 v[40:43], v[176:179], v[202:205], v[40:43]
	v_mfma_f32_16x16x32_bf16 v[24:27], v[176:179], v[210:213], v[24:27]
	v_mfma_f32_16x16x32_bf16 v[24:27], v[180:183], v[214:217], v[24:27]
	v_mfma_f32_16x16x32_bf16 v[16:19], v[190:193], v[214:217], v[16:19]
	v_mfma_f32_16x16x32_bf16 v[16:19], v[186:189], v[210:213], v[16:19]
	v_mfma_f32_16x16x32_bf16 v[0:3], v[186:189], v[218:221], v[0:3]
	v_mfma_f32_16x16x32_bf16 v[0:3], v[190:193], v[222:225], v[0:3]
	v_mfma_f32_16x16x32_bf16 v[8:11], v[180:183], v[222:225], v[8:11]
	v_mfma_f32_16x16x32_bf16 v[8:11], v[176:179], v[218:221], v[8:11]
	s_barrier
	s_setprio 0
	s_add_i32 s75, s75, 2
	s_add_u32 s73, s73, 0x100
	s_addc_u32 s74, s74, 0
	s_add_u32 s46, s46, 0x100
	s_addc_u32 s47, s47, 0
	s_cmp_gt_u32 s75, 13
	s_cbranch_scc1 .LBB0_529

.Llast_4:
	v_add_u32_e32 v153, s66, v147
	ds_read_b128 v[160:163], v153
	v_xor_b32_e32 v253, 64, v153
	ds_read_b128 v[164:167], v253
	ds_read_b128 v[168:171], v153 offset:2048
	ds_read_b128 v[172:175], v253 offset:2048
	v_add_u32_e32 v153, s67, v147
	ds_read_b128 v[176:179], v153
	v_xor_b32_e32 v253, 64, v153
	ds_read_b128 v[180:183], v253
	ds_read_b128 v[186:189], v153 offset:2048
	ds_read_b128 v[190:193], v253 offset:2048
	s_add_u32 s50, s46, 0xfffc0080
	s_addc_u32 s51, s47, -1
	s_and_b64 s[48:49], s[48:49], exec
	s_cselect_b32 s51, s29, s51
	s_cselect_b32 s50, s70, s50
	s_cselect_b32 s49, s71, s74
	s_cselect_b32 s48, s72, s73
	v_lshl_add_u64 v[154:155], s[46:47], 0, v[138:139]
	s_add_i32 m0, s57, 0xc000
	ds_read_b128 v[194:197], v150
	v_xor_b32_e32 v253, 64, v150
	ds_read_b128 v[198:201], v253
	ds_read_b128 v[202:205], v150 offset:2048
	ds_read_b128 v[206:209], v253 offset:2048
	ds_read_b128 v[210:213], v150 offset:4096
	ds_read_b128 v[214:217], v253 offset:4096
	ds_read_b128 v[218:221], v150 offset:6144
	ds_read_b128 v[222:225], v253 offset:6144
	global_load_lds_dwordx4 v[154:155], off
	v_lshl_add_u64 v[154:155], s[46:47], 0, v[136:137]
	s_add_i32 m0, s57, 0xe000
	s_nop 0
	global_load_lds_dwordx4 v[154:155], off
	s_waitcnt vmcnt(8)
	s_waitcnt lgkmcnt(0)
	.p2align 3
	s_setprio 1
	s_barrier
	v_mfma_f32_16x16x32_bf16 v[124:127], v[160:163], v[194:197], v[124:127]
	v_mfma_f32_16x16x32_bf16 v[124:127], v[164:167], v[198:201], v[124:127]
	v_mfma_f32_16x16x32_bf16 v[116:119], v[172:175], v[198:201], v[116:119]
	v_mfma_f32_16x16x32_bf16 v[116:119], v[168:171], v[194:197], v[116:119]
	v_mfma_f32_16x16x32_bf16 v[100:103], v[168:171], v[202:205], v[100:103]
	v_mfma_f32_16x16x32_bf16 v[100:103], v[172:175], v[206:209], v[100:103]
	v_mfma_f32_16x16x32_bf16 v[108:111], v[164:167], v[206:209], v[108:111]
	v_mfma_f32_16x16x32_bf16 v[108:111], v[160:163], v[202:205], v[108:111]
	v_mfma_f32_16x16x32_bf16 v[92:95], v[160:163], v[210:213], v[92:95]
	v_mfma_f32_16x16x32_bf16 v[92:95], v[164:167], v[214:217], v[92:95]
	v_mfma_f32_16x16x32_bf16 v[84:87], v[172:175], v[214:217], v[84:87]
	v_mfma_f32_16x16x32_bf16 v[84:87], v[168:171], v[210:213], v[84:87]
	v_mfma_f32_16x16x32_bf16 v[68:71], v[168:171], v[218:221], v[68:71]
	v_mfma_f32_16x16x32_bf16 v[68:71], v[172:175], v[222:225], v[68:71]
	v_mfma_f32_16x16x32_bf16 v[76:79], v[164:167], v[222:225], v[76:79]
	v_mfma_f32_16x16x32_bf16 v[76:79], v[160:163], v[218:221], v[76:79]
	s_setprio 0
	s_setprio 1
	v_mfma_f32_16x16x32_bf16 v[120:123], v[176:179], v[194:197], v[120:123]
	v_mfma_f32_16x16x32_bf16 v[120:123], v[180:183], v[198:201], v[120:123]
	v_mfma_f32_16x16x32_bf16 v[112:115], v[190:193], v[198:201], v[112:115]
	v_mfma_f32_16x16x32_bf16 v[112:115], v[186:189], v[194:197], v[112:115]
	v_mfma_f32_16x16x32_bf16 v[96:99], v[186:189], v[202:205], v[96:99]
	v_mfma_f32_16x16x32_bf16 v[96:99], v[190:193], v[206:209], v[96:99]
	v_mfma_f32_16x16x32_bf16 v[104:107], v[180:183], v[206:209], v[104:107]
	v_mfma_f32_16x16x32_bf16 v[104:107], v[176:179], v[202:205], v[104:107]
	v_mfma_f32_16x16x32_bf16 v[88:91], v[176:179], v[210:213], v[88:91]
	v_mfma_f32_16x16x32_bf16 v[88:91], v[180:183], v[214:217], v[88:91]
	v_mfma_f32_16x16x32_bf16 v[80:83], v[190:193], v[214:217], v[80:83]
	v_mfma_f32_16x16x32_bf16 v[80:83], v[186:189], v[210:213], v[80:83]
	v_mfma_f32_16x16x32_bf16 v[64:67], v[186:189], v[218:221], v[64:67]
	v_mfma_f32_16x16x32_bf16 v[64:67], v[190:193], v[222:225], v[64:67]
	v_mfma_f32_16x16x32_bf16 v[72:75], v[180:183], v[222:225], v[72:75]
	v_mfma_f32_16x16x32_bf16 v[72:75], v[176:179], v[218:221], v[72:75]
	s_barrier
	s_setprio 0
	s_add_i32 s76, s66, s54
	v_lshl_add_u64 v[154:155], s[48:49], 0, v[132:133]
	s_mov_b32 m0, s76
	ds_read_b128 v[194:197], v150 offset:16384
	v_xor_b32_e32 v253, 64, v150
	ds_read_b128 v[198:201], v253 offset:16384
	ds_read_b128 v[202:205], v150 offset:18432
	ds_read_b128 v[206:209], v253 offset:18432
	ds_read_b128 v[210:213], v150 offset:20480
	ds_read_b128 v[214:217], v253 offset:20480
	ds_read_b128 v[218:221], v150 offset:22528
	ds_read_b128 v[222:225], v253 offset:22528
	global_load_lds_dwordx4 v[154:155], off
	s_add_i32 m0, s76, 0x2000
	s_add_u32 s76, s48, 0x40000
	v_lshl_add_u64 v[226:227], s[48:49], 0, v[128:129]
	s_addc_u32 s77, s49, 0
	s_add_i32 s78, s67, s54
	global_load_lds_dwordx4 v[226:227], off
	v_lshl_add_u64 v[228:229], s[76:77], 0, v[132:133]
	s_mov_b32 m0, s78
	v_lshl_add_u64 v[230:231], s[50:51], 0, v[130:131]
	global_load_lds_dwordx4 v[228:229], off
	v_lshl_add_u64 v[228:229], s[76:77], 0, v[128:129]
	s_add_i32 m0, s78, 0x2000
	s_nop 0
	global_load_lds_dwordx4 v[228:229], off
	v_lshl_add_u64 v[228:229], s[50:51], 0, v[134:135]
	s_mov_b32 m0, s57
	s_nop 0
	global_load_lds_dwordx4 v[228:229], off
	s_mov_b32 m0, s58
	s_nop 0
	global_load_lds_dwordx4 v[230:231], off
	s_waitcnt vmcnt(8)
	s_waitcnt lgkmcnt(0)
	.p2align 3
	s_setprio 1
	s_barrier
	v_mfma_f32_16x16x32_bf16 v[60:63], v[160:163], v[194:197], v[60:63]
	v_mfma_f32_16x16x32_bf16 v[60:63], v[164:167], v[198:201], v[60:63]
	v_mfma_f32_16x16x32_bf16 v[52:55], v[172:175], v[198:201], v[52:55]
	v_mfma_f32_16x16x32_bf16 v[52:55], v[168:171], v[194:197], v[52:55]
	v_mfma_f32_16x16x32_bf16 v[36:39], v[168:171], v[202:205], v[36:39]
	v_mfma_f32_16x16x32_bf16 v[36:39], v[172:175], v[206:209], v[36:39]
	v_mfma_f32_16x16x32_bf16 v[44:47], v[164:167], v[206:209], v[44:47]
	v_mfma_f32_16x16x32_bf16 v[44:47], v[160:163], v[202:205], v[44:47]
	v_mfma_f32_16x16x32_bf16 v[28:31], v[160:163], v[210:213], v[28:31]
	v_mfma_f32_16x16x32_bf16 v[28:31], v[164:167], v[214:217], v[28:31]
	v_mfma_f32_16x16x32_bf16 v[20:23], v[172:175], v[214:217], v[20:23]
	v_mfma_f32_16x16x32_bf16 v[20:23], v[168:171], v[210:213], v[20:23]
	v_mfma_f32_16x16x32_bf16 v[4:7], v[168:171], v[218:221], v[4:7]
	v_mfma_f32_16x16x32_bf16 v[4:7], v[172:175], v[222:225], v[4:7]
	v_mfma_f32_16x16x32_bf16 v[12:15], v[164:167], v[222:225], v[12:15]
	v_mfma_f32_16x16x32_bf16 v[12:15], v[160:163], v[218:221], v[12:15]
	s_setprio 0
	s_setprio 1
	v_mfma_f32_16x16x32_bf16 v[56:59], v[176:179], v[194:197], v[56:59]
	v_mfma_f32_16x16x32_bf16 v[56:59], v[180:183], v[198:201], v[56:59]
	v_mfma_f32_16x16x32_bf16 v[48:51], v[190:193], v[198:201], v[48:51]
	v_mfma_f32_16x16x32_bf16 v[48:51], v[186:189], v[194:197], v[48:51]
	v_mfma_f32_16x16x32_bf16 v[32:35], v[186:189], v[202:205], v[32:35]
	v_mfma_f32_16x16x32_bf16 v[32:35], v[190:193], v[206:209], v[32:35]
	v_mfma_f32_16x16x32_bf16 v[40:43], v[180:183], v[206:209], v[40:43]
	v_mfma_f32_16x16x32_bf16 v[40:43], v[176:179], v[202:205], v[40:43]
	v_mfma_f32_16x16x32_bf16 v[24:27], v[176:179], v[210:213], v[24:27]
	v_mfma_f32_16x16x32_bf16 v[24:27], v[180:183], v[214:217], v[24:27]
	v_mfma_f32_16x16x32_bf16 v[16:19], v[190:193], v[214:217], v[16:19]
	v_mfma_f32_16x16x32_bf16 v[16:19], v[186:189], v[210:213], v[16:19]
	v_mfma_f32_16x16x32_bf16 v[0:3], v[186:189], v[218:221], v[0:3]
	v_mfma_f32_16x16x32_bf16 v[0:3], v[190:193], v[222:225], v[0:3]
	v_mfma_f32_16x16x32_bf16 v[8:11], v[180:183], v[222:225], v[8:11]
	v_mfma_f32_16x16x32_bf16 v[8:11], v[176:179], v[218:221], v[8:11]
	s_barrier
	s_setprio 0
	s_add_i32 s76, 0, 0x18000
	v_add_u32_e32 v153, s76, v147
	s_add_i32 s77, 0, 0x1c000
	ds_read_b128 v[160:163], v153
	v_xor_b32_e32 v253, 64, v153
	ds_read_b128 v[164:167], v253
	ds_read_b128 v[168:171], v153 offset:2048
	ds_read_b128 v[172:175], v253 offset:2048
	v_add_u32_e32 v153, s77, v147
	ds_read_b128 v[176:179], v153
	v_xor_b32_e32 v253, 64, v153
	ds_read_b128 v[180:183], v253
	ds_read_b128 v[186:189], v153 offset:2048
	ds_read_b128 v[190:193], v253 offset:2048
	s_add_u32 s50, s50, 0x40000
	s_addc_u32 s51, s51, 0
	s_mov_b32 m0, s59
	v_lshl_add_u64 v[232:233], s[50:51], 0, v[134:135]
	ds_read_b128 v[194:197], v150 offset:32768
	v_xor_b32_e32 v253, 64, v150
	ds_read_b128 v[198:201], v253 offset:32768
	ds_read_b128 v[202:205], v150 offset:34816
	ds_read_b128 v[206:209], v253 offset:34816
	ds_read_b128 v[210:213], v150 offset:36864
	ds_read_b128 v[214:217], v253 offset:36864
	ds_read_b128 v[218:221], v150 offset:38912
	ds_read_b128 v[222:225], v253 offset:38912
	global_load_lds_dwordx4 v[232:233], off
	v_lshl_add_u64 v[232:233], s[50:51], 0, v[130:131]
	s_mov_b32 m0, s60
	s_nop 0
	global_load_lds_dwordx4 v[232:233], off
	s_waitcnt vmcnt(8)
	s_waitcnt lgkmcnt(0)
	.p2align 3
	s_setprio 1
	s_barrier
	v_mfma_f32_16x16x32_bf16 v[124:127], v[160:163], v[194:197], v[124:127]
	v_mfma_f32_16x16x32_bf16 v[124:127], v[164:167], v[198:201], v[124:127]
	v_mfma_f32_16x16x32_bf16 v[116:119], v[172:175], v[198:201], v[116:119]
	v_mfma_f32_16x16x32_bf16 v[116:119], v[168:171], v[194:197], v[116:119]
	v_mfma_f32_16x16x32_bf16 v[100:103], v[168:171], v[202:205], v[100:103]
	v_mfma_f32_16x16x32_bf16 v[100:103], v[172:175], v[206:209], v[100:103]
	v_mfma_f32_16x16x32_bf16 v[108:111], v[164:167], v[206:209], v[108:111]
	v_mfma_f32_16x16x32_bf16 v[108:111], v[160:163], v[202:205], v[108:111]
	v_mfma_f32_16x16x32_bf16 v[92:95], v[160:163], v[210:213], v[92:95]
	v_mfma_f32_16x16x32_bf16 v[92:95], v[164:167], v[214:217], v[92:95]
	v_mfma_f32_16x16x32_bf16 v[84:87], v[172:175], v[214:217], v[84:87]
	v_mfma_f32_16x16x32_bf16 v[84:87], v[168:171], v[210:213], v[84:87]
	v_mfma_f32_16x16x32_bf16 v[68:71], v[168:171], v[218:221], v[68:71]
	v_mfma_f32_16x16x32_bf16 v[68:71], v[172:175], v[222:225], v[68:71]
	v_mfma_f32_16x16x32_bf16 v[76:79], v[164:167], v[222:225], v[76:79]
	v_mfma_f32_16x16x32_bf16 v[76:79], v[160:163], v[218:221], v[76:79]
	s_setprio 0
	s_setprio 1
	v_mfma_f32_16x16x32_bf16 v[120:123], v[176:179], v[194:197], v[120:123]
	v_mfma_f32_16x16x32_bf16 v[120:123], v[180:183], v[198:201], v[120:123]
	v_mfma_f32_16x16x32_bf16 v[112:115], v[190:193], v[198:201], v[112:115]
	v_mfma_f32_16x16x32_bf16 v[112:115], v[186:189], v[194:197], v[112:115]
	v_mfma_f32_16x16x32_bf16 v[96:99], v[186:189], v[202:205], v[96:99]
	v_mfma_f32_16x16x32_bf16 v[96:99], v[190:193], v[206:209], v[96:99]
	v_mfma_f32_16x16x32_bf16 v[104:107], v[180:183], v[206:209], v[104:107]
	v_mfma_f32_16x16x32_bf16 v[104:107], v[176:179], v[202:205], v[104:107]
	v_mfma_f32_16x16x32_bf16 v[88:91], v[176:179], v[210:213], v[88:91]
	v_mfma_f32_16x16x32_bf16 v[88:91], v[180:183], v[214:217], v[88:91]
	v_mfma_f32_16x16x32_bf16 v[80:83], v[190:193], v[214:217], v[80:83]
	v_mfma_f32_16x16x32_bf16 v[80:83], v[186:189], v[210:213], v[80:83]
	v_mfma_f32_16x16x32_bf16 v[64:67], v[186:189], v[218:221], v[64:67]
	v_mfma_f32_16x16x32_bf16 v[64:67], v[190:193], v[222:225], v[64:67]
	v_mfma_f32_16x16x32_bf16 v[72:75], v[180:183], v[222:225], v[72:75]
	v_mfma_f32_16x16x32_bf16 v[72:75], v[176:179], v[218:221], v[72:75]
	s_barrier
	s_setprio 0
	v_add_u32_e32 v234, 0x21000, v151
	ds_read_b128 v[236:239], v234
	ds_read_b128 v[240:243], v234 offset:256
	ds_read_b128 v[244:247], v234 offset:512
	ds_read_b128 v[248:251], v234 offset:768
	v_add_u32_e32 v235, s27, v146
	v_mul_u32_u24_e32 v235, 0x1600, v235
	v_lshl_or_b32 v234, s69, 7, v149
	v_lshl_add_u32 v235, v234, 1, v235
	s_add_i32 s50, s76, s54
	v_lshl_add_u64 v[154:155], v[154:155], 0, s[20:21]
	s_mov_b32 m0, s50
	ds_read_b128 v[194:197], v150 offset:49152
	v_xor_b32_e32 v253, 64, v150
	ds_read_b128 v[198:201], v253 offset:49152
	ds_read_b128 v[202:205], v150 offset:51200
	ds_read_b128 v[206:209], v253 offset:51200
	ds_read_b128 v[210:213], v150 offset:53248
	ds_read_b128 v[214:217], v253 offset:53248
	ds_read_b128 v[218:221], v150 offset:55296
	ds_read_b128 v[222:225], v253 offset:55296
	global_load_lds_dwordx4 v[154:155], off
	s_add_i32 m0, s50, 0x2000
	s_add_u32 s48, s48, 0x40080
	v_lshl_add_u64 v[154:155], v[226:227], 0, s[20:21]
	s_addc_u32 s49, s49, 0
	s_add_i32 s50, s77, s54
	global_load_lds_dwordx4 v[154:155], off
	v_lshl_add_u64 v[154:155], s[48:49], 0, v[132:133]
	s_mov_b32 m0, s50
	s_nop 0
	global_load_lds_dwordx4 v[154:155], off
	v_lshl_add_u64 v[154:155], s[48:49], 0, v[128:129]
	s_add_i32 m0, s50, 0x2000
	s_nop 0
	global_load_lds_dwordx4 v[154:155], off
	v_lshl_add_u64 v[154:155], v[228:229], 0, s[20:21]
	s_mov_b32 m0, s62
	s_nop 0
	global_load_lds_dwordx4 v[154:155], off
	v_lshl_add_u64 v[154:155], v[230:231], 0, s[20:21]
	s_mov_b32 m0, s63
	s_nop 0
	global_load_lds_dwordx4 v[154:155], off
	s_waitcnt lgkmcnt(8)
	v_add_f32_e32 v236, v236, v237
	v_add_f32_e32 v238, v238, v239
	v_add_f32_e32 v240, v240, v241
	v_add_f32_e32 v242, v242, v243
	v_add_f32_e32 v244, v244, v245
	v_add_f32_e32 v246, v246, v247
	v_add_f32_e32 v248, v248, v249
	v_add_f32_e32 v250, v250, v251
	v_add_f32_e32 v236, v236, v238
	v_add_f32_e32 v240, v240, v242
	v_add_f32_e32 v244, v244, v246
	v_add_f32_e32 v248, v248, v250
	v_fmamk_f32 v236, v236, 0x3a800000, v152
	v_fmamk_f32 v240, v240, 0x3a800000, v152
	v_fmamk_f32 v244, v244, 0x3a800000, v152
	v_fmamk_f32 v248, v248, 0x3a800000, v152
	v_rsq_f32_e32 v236, v236
	v_rsq_f32_e32 v240, v240
	v_rsq_f32_e32 v244, v244
	v_rsq_f32_e32 v248, v248
	v_mul_f32_e32 v252, 0xbfb8aa3b, v236
	v_mul_f32_e32 v254, v236, v236
	v_rcp_f32_e32 v254, v254
	v_pk_mul_f32 v[120:121], v[124:125], v[120:121]
	v_pk_mul_f32 v[122:123], v[126:127], v[122:123]
	v_pk_mul_f32 v[112:113], v[116:117], v[112:113]
	v_pk_mul_f32 v[114:115], v[118:119], v[114:115]
	v_pk_mul_f32 v[124:125], v[124:125], v[252:253] op_sel_hi:[1,0]
	v_pk_mul_f32 v[126:127], v[126:127], v[252:253] op_sel_hi:[1,0]
	v_pk_mul_f32 v[116:117], v[116:117], v[252:253] op_sel_hi:[1,0]
	v_pk_mul_f32 v[118:119], v[118:119], v[252:253] op_sel_hi:[1,0]
	v_exp_f32_e32 v124, v124
	v_exp_f32_e32 v125, v125
	v_exp_f32_e32 v126, v126
	v_exp_f32_e32 v127, v127
	v_exp_f32_e32 v116, v116
	v_exp_f32_e32 v117, v117
	v_exp_f32_e32 v118, v118
	v_exp_f32_e32 v119, v119
	v_pk_fma_f32 v[124:125], v[124:125], v[254:255], v[254:255] op_sel_hi:[1,0,0]
	v_pk_fma_f32 v[126:127], v[126:127], v[254:255], v[254:255] op_sel_hi:[1,0,0]
	v_pk_fma_f32 v[116:117], v[116:117], v[254:255], v[254:255] op_sel_hi:[1,0,0]
	v_pk_fma_f32 v[118:119], v[118:119], v[254:255], v[254:255] op_sel_hi:[1,0,0]
	v_rcp_f32_e32 v124, v124
	v_rcp_f32_e32 v125, v125
	v_rcp_f32_e32 v126, v126
	v_rcp_f32_e32 v127, v127
	v_rcp_f32_e32 v116, v116
	v_rcp_f32_e32 v117, v117
	v_rcp_f32_e32 v118, v118
	v_rcp_f32_e32 v119, v119
	v_pk_mul_f32 v[120:121], v[120:121], v[124:125]
	v_pk_mul_f32 v[122:123], v[122:123], v[126:127]
	v_pk_mul_f32 v[112:113], v[112:113], v[116:117]
	v_pk_mul_f32 v[114:115], v[114:115], v[118:119]
	v_cvt_pk_bf16_f32 v120, v120, v121
	v_cvt_pk_bf16_f32 v121, v122, v123
	v_cvt_pk_bf16_f32 v122, v112, v113
	v_cvt_pk_bf16_f32 v123, v114, v115
	global_store_dwordx4 v235, v[120:123], s[14:15]
	v_add_u32_e32 v234, 0x16000, v235
	v_mul_f32_e32 v252, 0xbfb8aa3b, v240
	v_mul_f32_e32 v254, v240, v240
	v_rcp_f32_e32 v254, v254
	v_pk_mul_f32 v[104:105], v[108:109], v[104:105]
	v_pk_mul_f32 v[106:107], v[110:111], v[106:107]
	v_pk_mul_f32 v[96:97], v[100:101], v[96:97]
	v_pk_mul_f32 v[98:99], v[102:103], v[98:99]
	v_pk_mul_f32 v[108:109], v[108:109], v[252:253] op_sel_hi:[1,0]
	v_pk_mul_f32 v[110:111], v[110:111], v[252:253] op_sel_hi:[1,0]
	v_pk_mul_f32 v[100:101], v[100:101], v[252:253] op_sel_hi:[1,0]
	v_pk_mul_f32 v[102:103], v[102:103], v[252:253] op_sel_hi:[1,0]
	v_exp_f32_e32 v108, v108
	v_exp_f32_e32 v109, v109
	v_exp_f32_e32 v110, v110
	v_exp_f32_e32 v111, v111
	v_exp_f32_e32 v100, v100
	v_exp_f32_e32 v101, v101
	v_exp_f32_e32 v102, v102
	v_exp_f32_e32 v103, v103
	v_pk_fma_f32 v[108:109], v[108:109], v[254:255], v[254:255] op_sel_hi:[1,0,0]
	v_pk_fma_f32 v[110:111], v[110:111], v[254:255], v[254:255] op_sel_hi:[1,0,0]
	v_pk_fma_f32 v[100:101], v[100:101], v[254:255], v[254:255] op_sel_hi:[1,0,0]
	v_pk_fma_f32 v[102:103], v[102:103], v[254:255], v[254:255] op_sel_hi:[1,0,0]
	v_rcp_f32_e32 v108, v108
	v_rcp_f32_e32 v109, v109
	v_rcp_f32_e32 v110, v110
	v_rcp_f32_e32 v111, v111
	v_rcp_f32_e32 v100, v100
	v_rcp_f32_e32 v101, v101
	v_rcp_f32_e32 v102, v102
	v_rcp_f32_e32 v103, v103
	v_pk_mul_f32 v[104:105], v[104:105], v[108:109]
	v_pk_mul_f32 v[106:107], v[106:107], v[110:111]
	v_pk_mul_f32 v[96:97], v[96:97], v[100:101]
	v_pk_mul_f32 v[98:99], v[98:99], v[102:103]
	v_cvt_pk_bf16_f32 v104, v104, v105
	v_cvt_pk_bf16_f32 v105, v106, v107
	v_cvt_pk_bf16_f32 v106, v96, v97
	v_cvt_pk_bf16_f32 v107, v98, v99
	global_store_dwordx4 v234, v[104:107], s[14:15]
	v_add_u32_e32 v235, 0x16000, v234
	v_mul_f32_e32 v252, 0xbfb8aa3b, v244
	v_mul_f32_e32 v254, v244, v244
	v_rcp_f32_e32 v254, v254
	v_pk_mul_f32 v[88:89], v[92:93], v[88:89]
	v_pk_mul_f32 v[90:91], v[94:95], v[90:91]
	v_pk_mul_f32 v[80:81], v[84:85], v[80:81]
	v_pk_mul_f32 v[82:83], v[86:87], v[82:83]
	v_pk_mul_f32 v[92:93], v[92:93], v[252:253] op_sel_hi:[1,0]
	v_pk_mul_f32 v[94:95], v[94:95], v[252:253] op_sel_hi:[1,0]
	v_pk_mul_f32 v[84:85], v[84:85], v[252:253] op_sel_hi:[1,0]
	v_pk_mul_f32 v[86:87], v[86:87], v[252:253] op_sel_hi:[1,0]
	v_exp_f32_e32 v92, v92
	v_exp_f32_e32 v93, v93
	v_exp_f32_e32 v94, v94
	v_exp_f32_e32 v95, v95
	v_exp_f32_e32 v84, v84
	v_exp_f32_e32 v85, v85
	v_exp_f32_e32 v86, v86
	v_exp_f32_e32 v87, v87
	v_pk_fma_f32 v[92:93], v[92:93], v[254:255], v[254:255] op_sel_hi:[1,0,0]
	v_pk_fma_f32 v[94:95], v[94:95], v[254:255], v[254:255] op_sel_hi:[1,0,0]
	v_pk_fma_f32 v[84:85], v[84:85], v[254:255], v[254:255] op_sel_hi:[1,0,0]
	v_pk_fma_f32 v[86:87], v[86:87], v[254:255], v[254:255] op_sel_hi:[1,0,0]
	v_rcp_f32_e32 v92, v92
	v_rcp_f32_e32 v93, v93
	v_rcp_f32_e32 v94, v94
	v_rcp_f32_e32 v95, v95
	v_rcp_f32_e32 v84, v84
	v_rcp_f32_e32 v85, v85
	v_rcp_f32_e32 v86, v86
	v_rcp_f32_e32 v87, v87
	v_pk_mul_f32 v[88:89], v[88:89], v[92:93]
	v_pk_mul_f32 v[90:91], v[90:91], v[94:95]
	v_pk_mul_f32 v[80:81], v[80:81], v[84:85]
	v_pk_mul_f32 v[82:83], v[82:83], v[86:87]
	v_cvt_pk_bf16_f32 v88, v88, v89
	v_cvt_pk_bf16_f32 v89, v90, v91
	v_cvt_pk_bf16_f32 v90, v80, v81
	v_cvt_pk_bf16_f32 v91, v82, v83
	global_store_dwordx4 v235, v[88:91], s[14:15]
	v_add_u32_e32 v234, 0x16000, v235
	v_mul_f32_e32 v252, 0xbfb8aa3b, v248
	v_mul_f32_e32 v254, v248, v248
	v_rcp_f32_e32 v254, v254
	v_pk_mul_f32 v[72:73], v[76:77], v[72:73]
	v_pk_mul_f32 v[74:75], v[78:79], v[74:75]
	v_pk_mul_f32 v[64:65], v[68:69], v[64:65]
	v_pk_mul_f32 v[66:67], v[70:71], v[66:67]
	v_pk_mul_f32 v[76:77], v[76:77], v[252:253] op_sel_hi:[1,0]
	v_pk_mul_f32 v[78:79], v[78:79], v[252:253] op_sel_hi:[1,0]
	v_pk_mul_f32 v[68:69], v[68:69], v[252:253] op_sel_hi:[1,0]
	v_pk_mul_f32 v[70:71], v[70:71], v[252:253] op_sel_hi:[1,0]
	v_exp_f32_e32 v76, v76
	v_exp_f32_e32 v77, v77
	v_exp_f32_e32 v78, v78
	v_exp_f32_e32 v79, v79
	v_exp_f32_e32 v68, v68
	v_exp_f32_e32 v69, v69
	v_exp_f32_e32 v70, v70
	v_exp_f32_e32 v71, v71
	v_pk_fma_f32 v[76:77], v[76:77], v[254:255], v[254:255] op_sel_hi:[1,0,0]
	v_pk_fma_f32 v[78:79], v[78:79], v[254:255], v[254:255] op_sel_hi:[1,0,0]
	v_pk_fma_f32 v[68:69], v[68:69], v[254:255], v[254:255] op_sel_hi:[1,0,0]
	v_pk_fma_f32 v[70:71], v[70:71], v[254:255], v[254:255] op_sel_hi:[1,0,0]
	v_rcp_f32_e32 v76, v76
	v_rcp_f32_e32 v77, v77
	v_rcp_f32_e32 v78, v78
	v_rcp_f32_e32 v79, v79
	v_rcp_f32_e32 v68, v68
	v_rcp_f32_e32 v69, v69
	v_rcp_f32_e32 v70, v70
	v_rcp_f32_e32 v71, v71
	v_pk_mul_f32 v[72:73], v[72:73], v[76:77]
	v_pk_mul_f32 v[74:75], v[74:75], v[78:79]
	v_pk_mul_f32 v[64:65], v[64:65], v[68:69]
	v_pk_mul_f32 v[66:67], v[66:67], v[70:71]
	v_cvt_pk_bf16_f32 v72, v72, v73
	v_cvt_pk_bf16_f32 v73, v74, v75
	v_cvt_pk_bf16_f32 v74, v64, v65
	v_cvt_pk_bf16_f32 v75, v66, v67
	global_store_dwordx4 v234, v[72:75], s[14:15]
	s_waitcnt vmcnt(12)
	s_waitcnt lgkmcnt(0)
	.p2align 3
	s_setprio 1
	s_barrier
	v_mfma_f32_16x16x32_bf16 v[60:63], v[160:163], v[194:197], v[60:63]
	v_mfma_f32_16x16x32_bf16 v[60:63], v[164:167], v[198:201], v[60:63]
	v_mfma_f32_16x16x32_bf16 v[52:55], v[172:175], v[198:201], v[52:55]
	v_mfma_f32_16x16x32_bf16 v[52:55], v[168:171], v[194:197], v[52:55]
	v_mfma_f32_16x16x32_bf16 v[36:39], v[168:171], v[202:205], v[36:39]
	v_mfma_f32_16x16x32_bf16 v[36:39], v[172:175], v[206:209], v[36:39]
	v_mfma_f32_16x16x32_bf16 v[44:47], v[164:167], v[206:209], v[44:47]
	v_mfma_f32_16x16x32_bf16 v[44:47], v[160:163], v[202:205], v[44:47]
	v_mfma_f32_16x16x32_bf16 v[28:31], v[160:163], v[210:213], v[28:31]
	v_mfma_f32_16x16x32_bf16 v[28:31], v[164:167], v[214:217], v[28:31]
	v_mfma_f32_16x16x32_bf16 v[20:23], v[172:175], v[214:217], v[20:23]
	v_mfma_f32_16x16x32_bf16 v[20:23], v[168:171], v[210:213], v[20:23]
	v_mfma_f32_16x16x32_bf16 v[4:7], v[168:171], v[218:221], v[4:7]
	v_mfma_f32_16x16x32_bf16 v[4:7], v[172:175], v[222:225], v[4:7]
	v_mfma_f32_16x16x32_bf16 v[12:15], v[164:167], v[222:225], v[12:15]
	v_mfma_f32_16x16x32_bf16 v[12:15], v[160:163], v[218:221], v[12:15]
	s_setprio 0
	s_setprio 1
	v_mfma_f32_16x16x32_bf16 v[56:59], v[176:179], v[194:197], v[56:59]
	v_mfma_f32_16x16x32_bf16 v[56:59], v[180:183], v[198:201], v[56:59]
	v_mfma_f32_16x16x32_bf16 v[48:51], v[190:193], v[198:201], v[48:51]
	v_mfma_f32_16x16x32_bf16 v[48:51], v[186:189], v[194:197], v[48:51]
	v_mfma_f32_16x16x32_bf16 v[32:35], v[186:189], v[202:205], v[32:35]
	v_mfma_f32_16x16x32_bf16 v[32:35], v[190:193], v[206:209], v[32:35]
	v_mfma_f32_16x16x32_bf16 v[40:43], v[180:183], v[206:209], v[40:43]
	v_mfma_f32_16x16x32_bf16 v[40:43], v[176:179], v[202:205], v[40:43]
	v_mfma_f32_16x16x32_bf16 v[24:27], v[176:179], v[210:213], v[24:27]
	v_mfma_f32_16x16x32_bf16 v[24:27], v[180:183], v[214:217], v[24:27]
	v_mfma_f32_16x16x32_bf16 v[16:19], v[190:193], v[214:217], v[16:19]
	v_mfma_f32_16x16x32_bf16 v[16:19], v[186:189], v[210:213], v[16:19]
	v_mfma_f32_16x16x32_bf16 v[0:3], v[186:189], v[218:221], v[0:3]
	v_mfma_f32_16x16x32_bf16 v[0:3], v[190:193], v[222:225], v[0:3]
	v_mfma_f32_16x16x32_bf16 v[8:11], v[180:183], v[222:225], v[8:11]
	v_mfma_f32_16x16x32_bf16 v[8:11], v[176:179], v[218:221], v[8:11]
	s_barrier
	s_setprio 0
	s_add_i32 s75, s75, 2
	s_add_u32 s73, s73, 0x100
	s_addc_u32 s74, s74, 0
	s_add_u32 s46, s46, 0x100
	s_addc_u32 s47, s47, 0

.LBB0_609:
	s_add_u32 s79, s56, 0x100
	s_addc_u32 s80, s57, 0
	s_mov_b32 s81, -2
	s_waitcnt lgkmcnt(0)
	s_cmp_eq_u32 s70, 1
	s_cbranch_scc1 .Lfa_5
	ds_read_b128 v[128:131], v189
	v_xor_b32_e32 v253, 64, v189
	ds_read_b128 v[132:135], v253
	ds_read_b128 v[136:139], v189 offset:2048
	ds_read_b128 v[140:143], v253 offset:2048
	ds_read_b128 v[144:147], v190
	v_xor_b32_e32 v253, 64, v190
	ds_read_b128 v[148:151], v253
	ds_read_b128 v[172:175], v190 offset:2048
	ds_read_b128 v[176:179], v253 offset:2048
	s_add_u32 s56, s54, 0x100
	s_addc_u32 s57, s55, 0
	s_cmp_eq_u32 s81, 40
	s_cselect_b32 s61, s17, s57
	s_cselect_b32 s60, s16, s56
	s_cselect_b32 s59, s53, s80
	s_cselect_b32 s58, s52, s79
	v_lshl_add_u64 v[222:223], s[54:55], 0, v[166:167]
	s_add_i32 m0, s66, 0xc000
	ds_read_b128 v[180:183], v191
	v_xor_b32_e32 v253, 64, v191
	ds_read_b128 v[194:197], v253
	ds_read_b128 v[198:201], v191 offset:2048
	ds_read_b128 v[202:205], v253 offset:2048
	ds_read_b128 v[206:209], v191 offset:4096
	ds_read_b128 v[210:213], v253 offset:4096
	ds_read_b128 v[214:217], v191 offset:6144
	ds_read_b128 v[218:221], v253 offset:6144
	global_load_lds_dwordx4 v[222:223], off
	v_lshl_add_u64 v[222:223], s[54:55], 0, v[164:165]
	s_add_i32 m0, s66, 0xe000
	s_nop 0
	global_load_lds_dwordx4 v[222:223], off
	s_waitcnt vmcnt(24)
	s_waitcnt lgkmcnt(0)
	.p2align 3
	s_setprio 1
	s_barrier
	v_mfma_f32_16x16x32_bf16 v[124:127], v[128:131], v[180:183], 0
	v_mfma_f32_16x16x32_bf16 v[120:123], v[136:139], v[180:183], 0
	v_mfma_f32_16x16x32_bf16 v[108:111], v[128:131], v[198:201], 0
	v_mfma_f32_16x16x32_bf16 v[104:107], v[136:139], v[198:201], 0
	v_mfma_f32_16x16x32_bf16 v[92:95], v[128:131], v[206:209], 0
	v_mfma_f32_16x16x32_bf16 v[88:91], v[136:139], v[206:209], 0
	v_mfma_f32_16x16x32_bf16 v[76:79], v[128:131], v[214:217], 0
	v_mfma_f32_16x16x32_bf16 v[72:75], v[136:139], v[214:217], 0
	v_mfma_f32_16x16x32_bf16 v[124:127], v[132:135], v[194:197], v[124:127]
	v_mfma_f32_16x16x32_bf16 v[120:123], v[140:143], v[194:197], v[120:123]
	v_mfma_f32_16x16x32_bf16 v[108:111], v[132:135], v[202:205], v[108:111]
	v_mfma_f32_16x16x32_bf16 v[104:107], v[140:143], v[202:205], v[104:107]
	v_mfma_f32_16x16x32_bf16 v[92:95], v[132:135], v[210:213], v[92:95]
	v_mfma_f32_16x16x32_bf16 v[88:91], v[140:143], v[210:213], v[88:91]
	v_mfma_f32_16x16x32_bf16 v[76:79], v[132:135], v[218:221], v[76:79]
	v_mfma_f32_16x16x32_bf16 v[72:75], v[140:143], v[218:221], v[72:75]
	s_setprio 0
	s_setprio 1
	v_mfma_f32_16x16x32_bf16 v[116:119], v[144:147], v[180:183], 0
	v_mfma_f32_16x16x32_bf16 v[112:115], v[172:175], v[180:183], 0
	v_mfma_f32_16x16x32_bf16 v[100:103], v[144:147], v[198:201], 0
	v_mfma_f32_16x16x32_bf16 v[96:99], v[172:175], v[198:201], 0
	v_mfma_f32_16x16x32_bf16 v[84:87], v[144:147], v[206:209], 0
	v_mfma_f32_16x16x32_bf16 v[80:83], v[172:175], v[206:209], 0
	v_mfma_f32_16x16x32_bf16 v[68:71], v[144:147], v[214:217], 0
	v_mfma_f32_16x16x32_bf16 v[64:67], v[172:175], v[214:217], 0
	v_mfma_f32_16x16x32_bf16 v[116:119], v[148:151], v[194:197], v[116:119]
	v_mfma_f32_16x16x32_bf16 v[112:115], v[176:179], v[194:197], v[112:115]
	v_mfma_f32_16x16x32_bf16 v[100:103], v[148:151], v[202:205], v[100:103]
	v_mfma_f32_16x16x32_bf16 v[96:99], v[176:179], v[202:205], v[96:99]
	v_mfma_f32_16x16x32_bf16 v[84:87], v[148:151], v[210:213], v[84:87]
	v_mfma_f32_16x16x32_bf16 v[80:83], v[176:179], v[210:213], v[80:83]
	v_mfma_f32_16x16x32_bf16 v[68:71], v[148:151], v[218:221], v[68:71]
	v_mfma_f32_16x16x32_bf16 v[64:67], v[176:179], v[218:221], v[64:67]
	s_barrier
	s_setprio 0
	s_add_i32 s54, s75, s65
	v_lshl_add_u64 v[222:223], s[58:59], 0, v[154:155]
	s_mov_b32 m0, s54
	ds_read_b128 v[180:183], v191 offset:16384
	v_xor_b32_e32 v253, 64, v191
	ds_read_b128 v[194:197], v253 offset:16384
	ds_read_b128 v[198:201], v191 offset:18432
	ds_read_b128 v[202:205], v253 offset:18432
	ds_read_b128 v[206:209], v191 offset:20480
	ds_read_b128 v[210:213], v253 offset:20480
	ds_read_b128 v[214:217], v191 offset:22528
	ds_read_b128 v[218:221], v253 offset:22528
	global_load_lds_dwordx4 v[222:223], off
	s_add_i32 m0, s54, 0x2000
	s_add_u32 s54, s58, 0xb0000
	v_lshl_add_u64 v[224:225], s[58:59], 0, v[162:163]
	s_addc_u32 s55, s59, 0
	s_add_i32 s82, s76, s65
	global_load_lds_dwordx4 v[224:225], off
	v_lshl_add_u64 v[226:227], s[54:55], 0, v[154:155]
	s_mov_b32 m0, s82
	v_lshl_add_u64 v[228:229], s[60:61], 0, v[160:161]
	global_load_lds_dwordx4 v[226:227], off
	v_lshl_add_u64 v[226:227], s[54:55], 0, v[162:163]
	s_add_i32 m0, s82, 0x2000
	s_nop 0
	global_load_lds_dwordx4 v[226:227], off
	v_lshl_add_u64 v[226:227], s[60:61], 0, v[152:153]
	s_mov_b32 m0, s66
	s_nop 0
	global_load_lds_dwordx4 v[226:227], off
	s_mov_b32 m0, s67
	s_nop 0
	global_load_lds_dwordx4 v[228:229], off
	s_waitcnt vmcnt(24)
	s_waitcnt lgkmcnt(0)
	.p2align 3
	s_setprio 1
	s_barrier
	v_mfma_f32_16x16x32_bf16 v[60:63], v[128:131], v[180:183], 0
	v_mfma_f32_16x16x32_bf16 v[56:59], v[136:139], v[180:183], 0
	v_mfma_f32_16x16x32_bf16 v[44:47], v[128:131], v[198:201], 0
	v_mfma_f32_16x16x32_bf16 v[40:43], v[136:139], v[198:201], 0
	v_mfma_f32_16x16x32_bf16 v[28:31], v[128:131], v[206:209], 0
	v_mfma_f32_16x16x32_bf16 v[24:27], v[136:139], v[206:209], 0
	v_mfma_f32_16x16x32_bf16 v[12:15], v[128:131], v[214:217], 0
	v_mfma_f32_16x16x32_bf16 v[8:11], v[136:139], v[214:217], 0
	v_mfma_f32_16x16x32_bf16 v[60:63], v[132:135], v[194:197], v[60:63]
	v_mfma_f32_16x16x32_bf16 v[56:59], v[140:143], v[194:197], v[56:59]
	v_mfma_f32_16x16x32_bf16 v[44:47], v[132:135], v[202:205], v[44:47]
	v_mfma_f32_16x16x32_bf16 v[40:43], v[140:143], v[202:205], v[40:43]
	v_mfma_f32_16x16x32_bf16 v[28:31], v[132:135], v[210:213], v[28:31]
	v_mfma_f32_16x16x32_bf16 v[24:27], v[140:143], v[210:213], v[24:27]
	v_mfma_f32_16x16x32_bf16 v[12:15], v[132:135], v[218:221], v[12:15]
	v_mfma_f32_16x16x32_bf16 v[8:11], v[140:143], v[218:221], v[8:11]
	s_setprio 0
	s_setprio 1
	v_mfma_f32_16x16x32_bf16 v[52:55], v[144:147], v[180:183], 0
	v_mfma_f32_16x16x32_bf16 v[48:51], v[172:175], v[180:183], 0
	v_mfma_f32_16x16x32_bf16 v[36:39], v[144:147], v[198:201], 0
	v_mfma_f32_16x16x32_bf16 v[32:35], v[172:175], v[198:201], 0
	v_mfma_f32_16x16x32_bf16 v[20:23], v[144:147], v[206:209], 0
	v_mfma_f32_16x16x32_bf16 v[16:19], v[172:175], v[206:209], 0
	v_mfma_f32_16x16x32_bf16 v[4:7], v[144:147], v[214:217], 0
	v_mfma_f32_16x16x32_bf16 v[0:3], v[172:175], v[214:217], 0
	v_mfma_f32_16x16x32_bf16 v[52:55], v[148:151], v[194:197], v[52:55]
	v_mfma_f32_16x16x32_bf16 v[48:51], v[176:179], v[194:197], v[48:51]
	v_mfma_f32_16x16x32_bf16 v[36:39], v[148:151], v[202:205], v[36:39]
	v_mfma_f32_16x16x32_bf16 v[32:35], v[176:179], v[202:205], v[32:35]
	v_mfma_f32_16x16x32_bf16 v[20:23], v[148:151], v[210:213], v[20:23]
	v_mfma_f32_16x16x32_bf16 v[16:19], v[176:179], v[210:213], v[16:19]
	v_mfma_f32_16x16x32_bf16 v[4:7], v[148:151], v[218:221], v[4:7]
	v_mfma_f32_16x16x32_bf16 v[0:3], v[176:179], v[218:221], v[0:3]
	s_barrier
	s_setprio 0
	s_add_i32 s82, 0, 0x18000
	s_add_i32 s83, 0, 0x1c000
	v_add_u32_e32 v140, s82, v186
	v_add_u32_e32 v176, s83, v186
	ds_read_b128 v[128:131], v140
	v_xor_b32_e32 v253, 64, v140
	ds_read_b128 v[132:135], v253
	ds_read_b128 v[136:139], v140 offset:2048
	ds_read_b128 v[140:143], v253 offset:2048
	ds_read_b128 v[144:147], v176
	v_xor_b32_e32 v253, 64, v176
	ds_read_b128 v[148:151], v253
	ds_read_b128 v[172:175], v176 offset:2048
	ds_read_b128 v[176:179], v253 offset:2048
	s_add_u32 s54, s60, 0xb0000
	s_addc_u32 s55, s61, 0
	s_mov_b32 m0, s68
	v_lshl_add_u64 v[230:231], s[54:55], 0, v[152:153]
	ds_read_b128 v[180:183], v191 offset:32768
	v_xor_b32_e32 v253, 64, v191
	ds_read_b128 v[194:197], v253 offset:32768
	ds_read_b128 v[198:201], v191 offset:34816
	ds_read_b128 v[202:205], v253 offset:34816
	ds_read_b128 v[206:209], v191 offset:36864
	ds_read_b128 v[210:213], v253 offset:36864
	ds_read_b128 v[214:217], v191 offset:38912
	ds_read_b128 v[218:221], v253 offset:38912
	global_load_lds_dwordx4 v[230:231], off
	v_lshl_add_u64 v[230:231], s[54:55], 0, v[160:161]
	s_mov_b32 m0, s69
	s_nop 0
	global_load_lds_dwordx4 v[230:231], off
	s_waitcnt vmcnt(8)
	s_waitcnt lgkmcnt(0)
	.p2align 3
	s_setprio 1
	s_barrier
	v_mfma_f32_16x16x32_bf16 v[124:127], v[128:131], v[180:183], v[124:127]
	v_mfma_f32_16x16x32_bf16 v[124:127], v[132:135], v[194:197], v[124:127]
	v_mfma_f32_16x16x32_bf16 v[120:123], v[140:143], v[194:197], v[120:123]
	v_mfma_f32_16x16x32_bf16 v[120:123], v[136:139], v[180:183], v[120:123]
	v_mfma_f32_16x16x32_bf16 v[104:107], v[136:139], v[198:201], v[104:107]
	v_mfma_f32_16x16x32_bf16 v[104:107], v[140:143], v[202:205], v[104:107]
	v_mfma_f32_16x16x32_bf16 v[108:111], v[132:135], v[202:205], v[108:111]
	v_mfma_f32_16x16x32_bf16 v[108:111], v[128:131], v[198:201], v[108:111]
	v_mfma_f32_16x16x32_bf16 v[92:95], v[128:131], v[206:209], v[92:95]
	v_mfma_f32_16x16x32_bf16 v[92:95], v[132:135], v[210:213], v[92:95]
	v_mfma_f32_16x16x32_bf16 v[88:91], v[140:143], v[210:213], v[88:91]
	v_mfma_f32_16x16x32_bf16 v[88:91], v[136:139], v[206:209], v[88:91]
	v_mfma_f32_16x16x32_bf16 v[72:75], v[136:139], v[214:217], v[72:75]
	v_mfma_f32_16x16x32_bf16 v[72:75], v[140:143], v[218:221], v[72:75]
	v_mfma_f32_16x16x32_bf16 v[76:79], v[132:135], v[218:221], v[76:79]
	v_mfma_f32_16x16x32_bf16 v[76:79], v[128:131], v[214:217], v[76:79]
	s_setprio 0
	s_setprio 1
	v_mfma_f32_16x16x32_bf16 v[116:119], v[144:147], v[180:183], v[116:119]
	v_mfma_f32_16x16x32_bf16 v[116:119], v[148:151], v[194:197], v[116:119]
	v_mfma_f32_16x16x32_bf16 v[112:115], v[176:179], v[194:197], v[112:115]
	v_mfma_f32_16x16x32_bf16 v[112:115], v[172:175], v[180:183], v[112:115]
	v_mfma_f32_16x16x32_bf16 v[96:99], v[172:175], v[198:201], v[96:99]
	v_mfma_f32_16x16x32_bf16 v[96:99], v[176:179], v[202:205], v[96:99]
	v_mfma_f32_16x16x32_bf16 v[100:103], v[148:151], v[202:205], v[100:103]
	v_mfma_f32_16x16x32_bf16 v[100:103], v[144:147], v[198:201], v[100:103]
	v_mfma_f32_16x16x32_bf16 v[84:87], v[144:147], v[206:209], v[84:87]
	v_mfma_f32_16x16x32_bf16 v[84:87], v[148:151], v[210:213], v[84:87]
	v_mfma_f32_16x16x32_bf16 v[80:83], v[176:179], v[210:213], v[80:83]
	v_mfma_f32_16x16x32_bf16 v[80:83], v[172:175], v[206:209], v[80:83]
	v_mfma_f32_16x16x32_bf16 v[64:67], v[172:175], v[214:217], v[64:67]
	v_mfma_f32_16x16x32_bf16 v[64:67], v[176:179], v[218:221], v[64:67]
	v_mfma_f32_16x16x32_bf16 v[68:71], v[148:151], v[218:221], v[68:71]
	v_mfma_f32_16x16x32_bf16 v[68:71], v[144:147], v[214:217], v[68:71]
	s_barrier
	s_setprio 0
	s_add_i32 s54, s82, s65
	v_lshl_add_u64 v[222:223], v[222:223], 0, s[28:29]
	s_mov_b32 m0, s54
	ds_read_b128 v[180:183], v191 offset:49152
	v_xor_b32_e32 v253, 64, v191
	ds_read_b128 v[194:197], v253 offset:49152
	ds_read_b128 v[198:201], v191 offset:51200
	ds_read_b128 v[202:205], v253 offset:51200
	ds_read_b128 v[206:209], v191 offset:53248
	ds_read_b128 v[210:213], v253 offset:53248
	ds_read_b128 v[214:217], v191 offset:55296
	ds_read_b128 v[218:221], v253 offset:55296
	global_load_lds_dwordx4 v[222:223], off
	s_add_i32 m0, s54, 0x2000
	s_add_u32 s54, s58, 0xb0080
	v_lshl_add_u64 v[222:223], v[224:225], 0, s[28:29]
	s_addc_u32 s55, s59, 0
	s_add_i32 s58, s83, s65
	global_load_lds_dwordx4 v[222:223], off
	v_lshl_add_u64 v[222:223], s[54:55], 0, v[154:155]
	s_mov_b32 m0, s58
	s_nop 0
	global_load_lds_dwordx4 v[222:223], off
	v_lshl_add_u64 v[222:223], s[54:55], 0, v[162:163]
	s_add_i32 m0, s58, 0x2000
	s_nop 0
	global_load_lds_dwordx4 v[222:223], off
	v_lshl_add_u64 v[222:223], v[226:227], 0, s[28:29]
	s_mov_b32 m0, s3
	s_nop 0
	global_load_lds_dwordx4 v[222:223], off
	v_lshl_add_u64 v[222:223], v[228:229], 0, s[28:29]
	s_mov_b32 m0, s71
	s_nop 0
	global_load_lds_dwordx4 v[222:223], off
	s_waitcnt vmcnt(8)
	s_waitcnt lgkmcnt(0)
	.p2align 3
	s_setprio 1
	s_barrier
	v_mfma_f32_16x16x32_bf16 v[60:63], v[128:131], v[180:183], v[60:63]
	v_mfma_f32_16x16x32_bf16 v[60:63], v[132:135], v[194:197], v[60:63]
	v_mfma_f32_16x16x32_bf16 v[56:59], v[140:143], v[194:197], v[56:59]
	v_mfma_f32_16x16x32_bf16 v[56:59], v[136:139], v[180:183], v[56:59]
	v_mfma_f32_16x16x32_bf16 v[40:43], v[136:139], v[198:201], v[40:43]
	v_mfma_f32_16x16x32_bf16 v[40:43], v[140:143], v[202:205], v[40:43]
	v_mfma_f32_16x16x32_bf16 v[44:47], v[132:135], v[202:205], v[44:47]
	v_mfma_f32_16x16x32_bf16 v[44:47], v[128:131], v[198:201], v[44:47]
	v_mfma_f32_16x16x32_bf16 v[28:31], v[128:131], v[206:209], v[28:31]
	v_mfma_f32_16x16x32_bf16 v[28:31], v[132:135], v[210:213], v[28:31]
	v_mfma_f32_16x16x32_bf16 v[24:27], v[140:143], v[210:213], v[24:27]
	v_mfma_f32_16x16x32_bf16 v[24:27], v[136:139], v[206:209], v[24:27]
	v_mfma_f32_16x16x32_bf16 v[8:11], v[136:139], v[214:217], v[8:11]
	v_mfma_f32_16x16x32_bf16 v[8:11], v[140:143], v[218:221], v[8:11]
	v_mfma_f32_16x16x32_bf16 v[12:15], v[132:135], v[218:221], v[12:15]
	v_mfma_f32_16x16x32_bf16 v[12:15], v[128:131], v[214:217], v[12:15]
	s_setprio 0
	s_setprio 1
	v_mfma_f32_16x16x32_bf16 v[52:55], v[144:147], v[180:183], v[52:55]
	v_mfma_f32_16x16x32_bf16 v[52:55], v[148:151], v[194:197], v[52:55]
	v_mfma_f32_16x16x32_bf16 v[48:51], v[176:179], v[194:197], v[48:51]
	v_mfma_f32_16x16x32_bf16 v[48:51], v[172:175], v[180:183], v[48:51]
	v_mfma_f32_16x16x32_bf16 v[32:35], v[172:175], v[198:201], v[32:35]
	v_mfma_f32_16x16x32_bf16 v[32:35], v[176:179], v[202:205], v[32:35]
	v_mfma_f32_16x16x32_bf16 v[36:39], v[148:151], v[202:205], v[36:39]
	v_mfma_f32_16x16x32_bf16 v[36:39], v[144:147], v[198:201], v[36:39]
	v_mfma_f32_16x16x32_bf16 v[20:23], v[144:147], v[206:209], v[20:23]
	v_mfma_f32_16x16x32_bf16 v[20:23], v[148:151], v[210:213], v[20:23]
	v_mfma_f32_16x16x32_bf16 v[16:19], v[176:179], v[210:213], v[16:19]
	v_mfma_f32_16x16x32_bf16 v[16:19], v[172:175], v[206:209], v[16:19]
	v_mfma_f32_16x16x32_bf16 v[0:3], v[172:175], v[214:217], v[0:3]
	v_mfma_f32_16x16x32_bf16 v[0:3], v[176:179], v[218:221], v[0:3]
	v_mfma_f32_16x16x32_bf16 v[4:7], v[148:151], v[218:221], v[4:7]
	v_mfma_f32_16x16x32_bf16 v[4:7], v[144:147], v[214:217], v[4:7]
	s_barrier
	s_setprio 0
	s_add_i32 s81, s81, 2
	s_add_u32 s79, s79, 0x100
	s_addc_u32 s80, s80, 0
	s_cmp_gt_u32 s81, 41
	s_mov_b64 s[54:55], s[56:57]
	s_branch .LBB0_610
.Lfa_5:
	ds_read_b128 v[128:131], v189
	v_xor_b32_e32 v253, 64, v189
	ds_read_b128 v[132:135], v253
	ds_read_b128 v[136:139], v189 offset:2048
	ds_read_b128 v[140:143], v253 offset:2048
	ds_read_b128 v[144:147], v190
	v_xor_b32_e32 v253, 64, v190
	ds_read_b128 v[148:151], v253
	ds_read_b128 v[172:175], v190 offset:2048
	ds_read_b128 v[176:179], v253 offset:2048
	s_add_u32 s56, s54, 0x100
	s_addc_u32 s57, s55, 0
	s_cmp_eq_u32 s81, 40
	s_cselect_b32 s61, s17, s57
	s_cselect_b32 s60, s16, s56
	s_cselect_b32 s59, s53, s80
	s_cselect_b32 s58, s52, s79
	v_lshl_add_u64 v[222:223], s[54:55], 0, v[166:167]
	s_add_i32 m0, s66, 0xc000
	ds_read_b128 v[180:183], v191
	v_xor_b32_e32 v253, 64, v191
	ds_read_b128 v[194:197], v253
	ds_read_b128 v[198:201], v191 offset:2048
	ds_read_b128 v[202:205], v253 offset:2048
	ds_read_b128 v[206:209], v191 offset:4096
	ds_read_b128 v[210:213], v253 offset:4096
	ds_read_b128 v[214:217], v191 offset:6144
	ds_read_b128 v[218:221], v253 offset:6144
	global_load_lds_dwordx4 v[222:223], off
	v_lshl_add_u64 v[222:223], s[54:55], 0, v[164:165]
	s_add_i32 m0, s66, 0xe000
	s_nop 0
	global_load_lds_dwordx4 v[222:223], off
	s_waitcnt vmcnt(8)
	s_waitcnt lgkmcnt(0)
	.p2align 3
	s_setprio 1
	s_barrier
	v_mfma_f32_16x16x32_bf16 v[124:127], v[128:131], v[180:183], 0
	v_mfma_f32_16x16x32_bf16 v[120:123], v[136:139], v[180:183], 0
	v_mfma_f32_16x16x32_bf16 v[108:111], v[128:131], v[198:201], 0
	v_mfma_f32_16x16x32_bf16 v[104:107], v[136:139], v[198:201], 0
	v_mfma_f32_16x16x32_bf16 v[92:95], v[128:131], v[206:209], 0
	v_mfma_f32_16x16x32_bf16 v[88:91], v[136:139], v[206:209], 0
	v_mfma_f32_16x16x32_bf16 v[76:79], v[128:131], v[214:217], 0
	v_mfma_f32_16x16x32_bf16 v[72:75], v[136:139], v[214:217], 0
	v_mfma_f32_16x16x32_bf16 v[124:127], v[132:135], v[194:197], v[124:127]
	v_mfma_f32_16x16x32_bf16 v[120:123], v[140:143], v[194:197], v[120:123]
	v_mfma_f32_16x16x32_bf16 v[108:111], v[132:135], v[202:205], v[108:111]
	v_mfma_f32_16x16x32_bf16 v[104:107], v[140:143], v[202:205], v[104:107]
	v_mfma_f32_16x16x32_bf16 v[92:95], v[132:135], v[210:213], v[92:95]
	v_mfma_f32_16x16x32_bf16 v[88:91], v[140:143], v[210:213], v[88:91]
	v_mfma_f32_16x16x32_bf16 v[76:79], v[132:135], v[218:221], v[76:79]
	v_mfma_f32_16x16x32_bf16 v[72:75], v[140:143], v[218:221], v[72:75]
	s_setprio 0
	s_setprio 1
	v_mfma_f32_16x16x32_bf16 v[116:119], v[144:147], v[180:183], 0
	v_mfma_f32_16x16x32_bf16 v[112:115], v[172:175], v[180:183], 0
	v_mfma_f32_16x16x32_bf16 v[100:103], v[144:147], v[198:201], 0
	v_mfma_f32_16x16x32_bf16 v[96:99], v[172:175], v[198:201], 0
	v_mfma_f32_16x16x32_bf16 v[84:87], v[144:147], v[206:209], 0
	v_mfma_f32_16x16x32_bf16 v[80:83], v[172:175], v[206:209], 0
	v_mfma_f32_16x16x32_bf16 v[68:71], v[144:147], v[214:217], 0
	v_mfma_f32_16x16x32_bf16 v[64:67], v[172:175], v[214:217], 0
	v_mfma_f32_16x16x32_bf16 v[116:119], v[148:151], v[194:197], v[116:119]
	v_mfma_f32_16x16x32_bf16 v[112:115], v[176:179], v[194:197], v[112:115]
	v_mfma_f32_16x16x32_bf16 v[100:103], v[148:151], v[202:205], v[100:103]
	v_mfma_f32_16x16x32_bf16 v[96:99], v[176:179], v[202:205], v[96:99]
	v_mfma_f32_16x16x32_bf16 v[84:87], v[148:151], v[210:213], v[84:87]
	v_mfma_f32_16x16x32_bf16 v[80:83], v[176:179], v[210:213], v[80:83]
	v_mfma_f32_16x16x32_bf16 v[68:71], v[148:151], v[218:221], v[68:71]
	v_mfma_f32_16x16x32_bf16 v[64:67], v[176:179], v[218:221], v[64:67]
	s_barrier
	s_setprio 0
	s_add_i32 s54, s75, s65
	v_lshl_add_u64 v[222:223], s[58:59], 0, v[154:155]
	s_mov_b32 m0, s54
	ds_read_b128 v[180:183], v191 offset:16384
	v_xor_b32_e32 v253, 64, v191
	ds_read_b128 v[194:197], v253 offset:16384
	ds_read_b128 v[198:201], v191 offset:18432
	ds_read_b128 v[202:205], v253 offset:18432
	ds_read_b128 v[206:209], v191 offset:20480
	ds_read_b128 v[210:213], v253 offset:20480
	ds_read_b128 v[214:217], v191 offset:22528
	ds_read_b128 v[218:221], v253 offset:22528
	global_load_lds_dwordx4 v[222:223], off
	s_add_i32 m0, s54, 0x2000
	s_add_u32 s54, s58, 0xb0000
	v_lshl_add_u64 v[224:225], s[58:59], 0, v[162:163]
	s_addc_u32 s55, s59, 0
	s_add_i32 s82, s76, s65
	global_load_lds_dwordx4 v[224:225], off
	v_lshl_add_u64 v[226:227], s[54:55], 0, v[154:155]
	s_mov_b32 m0, s82
	v_lshl_add_u64 v[228:229], s[60:61], 0, v[160:161]
	global_load_lds_dwordx4 v[226:227], off
	v_lshl_add_u64 v[226:227], s[54:55], 0, v[162:163]
	s_add_i32 m0, s82, 0x2000
	s_nop 0
	global_load_lds_dwordx4 v[226:227], off
	v_lshl_add_u64 v[226:227], s[60:61], 0, v[152:153]
	s_mov_b32 m0, s66
	s_nop 0
	global_load_lds_dwordx4 v[226:227], off
	s_mov_b32 m0, s67
	s_nop 0
	global_load_lds_dwordx4 v[228:229], off
	s_waitcnt vmcnt(8)
	s_waitcnt lgkmcnt(0)
	.p2align 3
	s_setprio 1
	s_barrier
	v_mfma_f32_16x16x32_bf16 v[60:63], v[128:131], v[180:183], 0
	v_mfma_f32_16x16x32_bf16 v[56:59], v[136:139], v[180:183], 0
	v_mfma_f32_16x16x32_bf16 v[44:47], v[128:131], v[198:201], 0
	v_mfma_f32_16x16x32_bf16 v[40:43], v[136:139], v[198:201], 0
	v_mfma_f32_16x16x32_bf16 v[28:31], v[128:131], v[206:209], 0
	v_mfma_f32_16x16x32_bf16 v[24:27], v[136:139], v[206:209], 0
	v_mfma_f32_16x16x32_bf16 v[12:15], v[128:131], v[214:217], 0
	v_mfma_f32_16x16x32_bf16 v[8:11], v[136:139], v[214:217], 0
	v_mfma_f32_16x16x32_bf16 v[60:63], v[132:135], v[194:197], v[60:63]
	v_mfma_f32_16x16x32_bf16 v[56:59], v[140:143], v[194:197], v[56:59]
	v_mfma_f32_16x16x32_bf16 v[44:47], v[132:135], v[202:205], v[44:47]
	v_mfma_f32_16x16x32_bf16 v[40:43], v[140:143], v[202:205], v[40:43]
	v_mfma_f32_16x16x32_bf16 v[28:31], v[132:135], v[210:213], v[28:31]
	v_mfma_f32_16x16x32_bf16 v[24:27], v[140:143], v[210:213], v[24:27]
	v_mfma_f32_16x16x32_bf16 v[12:15], v[132:135], v[218:221], v[12:15]
	v_mfma_f32_16x16x32_bf16 v[8:11], v[140:143], v[218:221], v[8:11]
	s_setprio 0
	s_setprio 1
	v_mfma_f32_16x16x32_bf16 v[52:55], v[144:147], v[180:183], 0
	v_mfma_f32_16x16x32_bf16 v[48:51], v[172:175], v[180:183], 0
	v_mfma_f32_16x16x32_bf16 v[36:39], v[144:147], v[198:201], 0
	v_mfma_f32_16x16x32_bf16 v[32:35], v[172:175], v[198:201], 0
	v_mfma_f32_16x16x32_bf16 v[20:23], v[144:147], v[206:209], 0
	v_mfma_f32_16x16x32_bf16 v[16:19], v[172:175], v[206:209], 0
	v_mfma_f32_16x16x32_bf16 v[4:7], v[144:147], v[214:217], 0
	v_mfma_f32_16x16x32_bf16 v[0:3], v[172:175], v[214:217], 0
	v_mfma_f32_16x16x32_bf16 v[52:55], v[148:151], v[194:197], v[52:55]
	v_mfma_f32_16x16x32_bf16 v[48:51], v[176:179], v[194:197], v[48:51]
	v_mfma_f32_16x16x32_bf16 v[36:39], v[148:151], v[202:205], v[36:39]
	v_mfma_f32_16x16x32_bf16 v[32:35], v[176:179], v[202:205], v[32:35]
	v_mfma_f32_16x16x32_bf16 v[20:23], v[148:151], v[210:213], v[20:23]
	v_mfma_f32_16x16x32_bf16 v[16:19], v[176:179], v[210:213], v[16:19]
	v_mfma_f32_16x16x32_bf16 v[4:7], v[148:151], v[218:221], v[4:7]
	v_mfma_f32_16x16x32_bf16 v[0:3], v[176:179], v[218:221], v[0:3]
	s_barrier
	s_setprio 0
	s_add_i32 s82, 0, 0x18000
	s_add_i32 s83, 0, 0x1c000
	v_add_u32_e32 v140, s82, v186
	v_add_u32_e32 v176, s83, v186
	ds_read_b128 v[128:131], v140
	v_xor_b32_e32 v253, 64, v140
	ds_read_b128 v[132:135], v253
	ds_read_b128 v[136:139], v140 offset:2048
	ds_read_b128 v[140:143], v253 offset:2048
	ds_read_b128 v[144:147], v176
	v_xor_b32_e32 v253, 64, v176
	ds_read_b128 v[148:151], v253
	ds_read_b128 v[172:175], v176 offset:2048
	ds_read_b128 v[176:179], v253 offset:2048
	s_add_u32 s54, s60, 0xb0000
	s_addc_u32 s55, s61, 0
	s_mov_b32 m0, s68
	v_lshl_add_u64 v[230:231], s[54:55], 0, v[152:153]
	ds_read_b128 v[180:183], v191 offset:32768
	v_xor_b32_e32 v253, 64, v191
	ds_read_b128 v[194:197], v253 offset:32768
	ds_read_b128 v[198:201], v191 offset:34816
	ds_read_b128 v[202:205], v253 offset:34816
	ds_read_b128 v[206:209], v191 offset:36864
	ds_read_b128 v[210:213], v253 offset:36864
	ds_read_b128 v[214:217], v191 offset:38912
	ds_read_b128 v[218:221], v253 offset:38912
	global_load_lds_dwordx4 v[230:231], off
	v_lshl_add_u64 v[230:231], s[54:55], 0, v[160:161]
	s_mov_b32 m0, s69
	s_nop 0
	global_load_lds_dwordx4 v[230:231], off
	s_waitcnt vmcnt(8)
	s_waitcnt lgkmcnt(0)
	.p2align 3
	s_setprio 1
	s_barrier
	v_mfma_f32_16x16x32_bf16 v[124:127], v[128:131], v[180:183], v[124:127]
	v_mfma_f32_16x16x32_bf16 v[124:127], v[132:135], v[194:197], v[124:127]
	v_mfma_f32_16x16x32_bf16 v[120:123], v[140:143], v[194:197], v[120:123]
	v_mfma_f32_16x16x32_bf16 v[120:123], v[136:139], v[180:183], v[120:123]
	v_mfma_f32_16x16x32_bf16 v[104:107], v[136:139], v[198:201], v[104:107]
	v_mfma_f32_16x16x32_bf16 v[104:107], v[140:143], v[202:205], v[104:107]
	v_mfma_f32_16x16x32_bf16 v[108:111], v[132:135], v[202:205], v[108:111]
	v_mfma_f32_16x16x32_bf16 v[108:111], v[128:131], v[198:201], v[108:111]
	v_mfma_f32_16x16x32_bf16 v[92:95], v[128:131], v[206:209], v[92:95]
	v_mfma_f32_16x16x32_bf16 v[92:95], v[132:135], v[210:213], v[92:95]
	v_mfma_f32_16x16x32_bf16 v[88:91], v[140:143], v[210:213], v[88:91]
	v_mfma_f32_16x16x32_bf16 v[88:91], v[136:139], v[206:209], v[88:91]
	v_mfma_f32_16x16x32_bf16 v[72:75], v[136:139], v[214:217], v[72:75]
	v_mfma_f32_16x16x32_bf16 v[72:75], v[140:143], v[218:221], v[72:75]
	v_mfma_f32_16x16x32_bf16 v[76:79], v[132:135], v[218:221], v[76:79]
	v_mfma_f32_16x16x32_bf16 v[76:79], v[128:131], v[214:217], v[76:79]
	s_setprio 0
	s_setprio 1
	v_mfma_f32_16x16x32_bf16 v[116:119], v[144:147], v[180:183], v[116:119]
	v_mfma_f32_16x16x32_bf16 v[116:119], v[148:151], v[194:197], v[116:119]
	v_mfma_f32_16x16x32_bf16 v[112:115], v[176:179], v[194:197], v[112:115]
	v_mfma_f32_16x16x32_bf16 v[112:115], v[172:175], v[180:183], v[112:115]
	v_mfma_f32_16x16x32_bf16 v[96:99], v[172:175], v[198:201], v[96:99]
	v_mfma_f32_16x16x32_bf16 v[96:99], v[176:179], v[202:205], v[96:99]
	v_mfma_f32_16x16x32_bf16 v[100:103], v[148:151], v[202:205], v[100:103]
	v_mfma_f32_16x16x32_bf16 v[100:103], v[144:147], v[198:201], v[100:103]
	v_mfma_f32_16x16x32_bf16 v[84:87], v[144:147], v[206:209], v[84:87]
	v_mfma_f32_16x16x32_bf16 v[84:87], v[148:151], v[210:213], v[84:87]
	v_mfma_f32_16x16x32_bf16 v[80:83], v[176:179], v[210:213], v[80:83]
	v_mfma_f32_16x16x32_bf16 v[80:83], v[172:175], v[206:209], v[80:83]
	v_mfma_f32_16x16x32_bf16 v[64:67], v[172:175], v[214:217], v[64:67]
	v_mfma_f32_16x16x32_bf16 v[64:67], v[176:179], v[218:221], v[64:67]
	v_mfma_f32_16x16x32_bf16 v[68:71], v[148:151], v[218:221], v[68:71]
	v_mfma_f32_16x16x32_bf16 v[68:71], v[144:147], v[214:217], v[68:71]
	s_barrier
	s_setprio 0
	s_add_i32 s54, s82, s65
	v_lshl_add_u64 v[222:223], v[222:223], 0, s[28:29]
	s_mov_b32 m0, s54
	ds_read_b128 v[180:183], v191 offset:49152
	v_xor_b32_e32 v253, 64, v191
	ds_read_b128 v[194:197], v253 offset:49152
	ds_read_b128 v[198:201], v191 offset:51200
	ds_read_b128 v[202:205], v253 offset:51200
	ds_read_b128 v[206:209], v191 offset:53248
	ds_read_b128 v[210:213], v253 offset:53248
	ds_read_b128 v[214:217], v191 offset:55296
	ds_read_b128 v[218:221], v253 offset:55296
	global_load_lds_dwordx4 v[222:223], off
	s_add_i32 m0, s54, 0x2000
	s_add_u32 s54, s58, 0xb0080
	v_lshl_add_u64 v[222:223], v[224:225], 0, s[28:29]
	s_addc_u32 s55, s59, 0
	s_add_i32 s58, s83, s65
	global_load_lds_dwordx4 v[222:223], off
	v_lshl_add_u64 v[222:223], s[54:55], 0, v[154:155]
	s_mov_b32 m0, s58
	s_nop 0
	global_load_lds_dwordx4 v[222:223], off
	v_lshl_add_u64 v[222:223], s[54:55], 0, v[162:163]
	s_add_i32 m0, s58, 0x2000
	s_nop 0
	global_load_lds_dwordx4 v[222:223], off
	v_lshl_add_u64 v[222:223], v[226:227], 0, s[28:29]
	s_mov_b32 m0, s3
	s_nop 0
	global_load_lds_dwordx4 v[222:223], off
	v_lshl_add_u64 v[222:223], v[228:229], 0, s[28:29]
	s_mov_b32 m0, s71
	s_nop 0
	global_load_lds_dwordx4 v[222:223], off
	s_waitcnt vmcnt(8)
	s_waitcnt lgkmcnt(0)
	.p2align 3
	s_setprio 1
	s_barrier
	v_mfma_f32_16x16x32_bf16 v[60:63], v[128:131], v[180:183], v[60:63]
	v_mfma_f32_16x16x32_bf16 v[60:63], v[132:135], v[194:197], v[60:63]
	v_mfma_f32_16x16x32_bf16 v[56:59], v[140:143], v[194:197], v[56:59]
	v_mfma_f32_16x16x32_bf16 v[56:59], v[136:139], v[180:183], v[56:59]
	v_mfma_f32_16x16x32_bf16 v[40:43], v[136:139], v[198:201], v[40:43]
	v_mfma_f32_16x16x32_bf16 v[40:43], v[140:143], v[202:205], v[40:43]
	v_mfma_f32_16x16x32_bf16 v[44:47], v[132:135], v[202:205], v[44:47]
	v_mfma_f32_16x16x32_bf16 v[44:47], v[128:131], v[198:201], v[44:47]
	v_mfma_f32_16x16x32_bf16 v[28:31], v[128:131], v[206:209], v[28:31]
	v_mfma_f32_16x16x32_bf16 v[28:31], v[132:135], v[210:213], v[28:31]
	v_mfma_f32_16x16x32_bf16 v[24:27], v[140:143], v[210:213], v[24:27]
	v_mfma_f32_16x16x32_bf16 v[24:27], v[136:139], v[206:209], v[24:27]
	v_mfma_f32_16x16x32_bf16 v[8:11], v[136:139], v[214:217], v[8:11]
	v_mfma_f32_16x16x32_bf16 v[8:11], v[140:143], v[218:221], v[8:11]
	v_mfma_f32_16x16x32_bf16 v[12:15], v[132:135], v[218:221], v[12:15]
	v_mfma_f32_16x16x32_bf16 v[12:15], v[128:131], v[214:217], v[12:15]
	s_setprio 0
	s_setprio 1
	v_mfma_f32_16x16x32_bf16 v[52:55], v[144:147], v[180:183], v[52:55]
	v_mfma_f32_16x16x32_bf16 v[52:55], v[148:151], v[194:197], v[52:55]
	v_mfma_f32_16x16x32_bf16 v[48:51], v[176:179], v[194:197], v[48:51]
	v_mfma_f32_16x16x32_bf16 v[48:51], v[172:175], v[180:183], v[48:51]
	v_mfma_f32_16x16x32_bf16 v[32:35], v[172:175], v[198:201], v[32:35]
	v_mfma_f32_16x16x32_bf16 v[32:35], v[176:179], v[202:205], v[32:35]
	v_mfma_f32_16x16x32_bf16 v[36:39], v[148:151], v[202:205], v[36:39]
	v_mfma_f32_16x16x32_bf16 v[36:39], v[144:147], v[198:201], v[36:39]
	v_mfma_f32_16x16x32_bf16 v[20:23], v[144:147], v[206:209], v[20:23]
	v_mfma_f32_16x16x32_bf16 v[20:23], v[148:151], v[210:213], v[20:23]
	v_mfma_f32_16x16x32_bf16 v[16:19], v[176:179], v[210:213], v[16:19]
	v_mfma_f32_16x16x32_bf16 v[16:19], v[172:175], v[206:209], v[16:19]
	v_mfma_f32_16x16x32_bf16 v[0:3], v[172:175], v[214:217], v[0:3]
	v_mfma_f32_16x16x32_bf16 v[0:3], v[176:179], v[218:221], v[0:3]
	v_mfma_f32_16x16x32_bf16 v[4:7], v[148:151], v[218:221], v[4:7]
	v_mfma_f32_16x16x32_bf16 v[4:7], v[144:147], v[214:217], v[4:7]
	s_barrier
	s_setprio 0
	s_add_i32 s81, s81, 2
	s_add_u32 s79, s79, 0x100
	s_addc_u32 s80, s80, 0
	s_cmp_gt_u32 s81, 41
	s_mov_b64 s[54:55], s[56:57]
.LBB0_610:
	ds_read_b128 v[128:131], v189
	v_xor_b32_e32 v253, 64, v189
	ds_read_b128 v[132:135], v253
	ds_read_b128 v[136:139], v189 offset:2048
	ds_read_b128 v[140:143], v253 offset:2048
	ds_read_b128 v[144:147], v190
	v_xor_b32_e32 v253, 64, v190
	ds_read_b128 v[148:151], v253
	ds_read_b128 v[172:175], v190 offset:2048
	ds_read_b128 v[176:179], v253 offset:2048
	s_add_u32 s56, s54, 0x100
	s_addc_u32 s57, s55, 0
	s_cmp_eq_u32 s81, 40
	s_cselect_b32 s61, s17, s57
	s_cselect_b32 s60, s16, s56
	s_cselect_b32 s59, s53, s80
	s_cselect_b32 s58, s52, s79
	v_lshl_add_u64 v[222:223], s[54:55], 0, v[166:167]
	s_add_i32 m0, s66, 0xc000
	ds_read_b128 v[180:183], v191
	v_xor_b32_e32 v253, 64, v191
	ds_read_b128 v[194:197], v253
	ds_read_b128 v[198:201], v191 offset:2048
	ds_read_b128 v[202:205], v253 offset:2048
	ds_read_b128 v[206:209], v191 offset:4096
	ds_read_b128 v[210:213], v253 offset:4096
	ds_read_b128 v[214:217], v191 offset:6144
	ds_read_b128 v[218:221], v253 offset:6144
	global_load_lds_dwordx4 v[222:223], off
	v_lshl_add_u64 v[222:223], s[54:55], 0, v[164:165]
	s_add_i32 m0, s66, 0xe000
	s_nop 0
	global_load_lds_dwordx4 v[222:223], off
	s_waitcnt vmcnt(8)
	s_waitcnt lgkmcnt(0)
	.p2align 3
	s_setprio 1
	s_barrier
	v_mfma_f32_16x16x32_bf16 v[124:127], v[128:131], v[180:183], v[124:127]
	v_mfma_f32_16x16x32_bf16 v[124:127], v[132:135], v[194:197], v[124:127]
	v_mfma_f32_16x16x32_bf16 v[120:123], v[140:143], v[194:197], v[120:123]
	v_mfma_f32_16x16x32_bf16 v[120:123], v[136:139], v[180:183], v[120:123]
	v_mfma_f32_16x16x32_bf16 v[104:107], v[136:139], v[198:201], v[104:107]
	v_mfma_f32_16x16x32_bf16 v[104:107], v[140:143], v[202:205], v[104:107]
	v_mfma_f32_16x16x32_bf16 v[108:111], v[132:135], v[202:205], v[108:111]
	v_mfma_f32_16x16x32_bf16 v[108:111], v[128:131], v[198:201], v[108:111]
	v_mfma_f32_16x16x32_bf16 v[92:95], v[128:131], v[206:209], v[92:95]
	v_mfma_f32_16x16x32_bf16 v[92:95], v[132:135], v[210:213], v[92:95]
	v_mfma_f32_16x16x32_bf16 v[88:91], v[140:143], v[210:213], v[88:91]
	v_mfma_f32_16x16x32_bf16 v[88:91], v[136:139], v[206:209], v[88:91]
	v_mfma_f32_16x16x32_bf16 v[72:75], v[136:139], v[214:217], v[72:75]
	v_mfma_f32_16x16x32_bf16 v[72:75], v[140:143], v[218:221], v[72:75]
	v_mfma_f32_16x16x32_bf16 v[76:79], v[132:135], v[218:221], v[76:79]
	v_mfma_f32_16x16x32_bf16 v[76:79], v[128:131], v[214:217], v[76:79]
	s_setprio 0
	s_setprio 1
	v_mfma_f32_16x16x32_bf16 v[116:119], v[144:147], v[180:183], v[116:119]
	v_mfma_f32_16x16x32_bf16 v[116:119], v[148:151], v[194:197], v[116:119]
	v_mfma_f32_16x16x32_bf16 v[112:115], v[176:179], v[194:197], v[112:115]
	v_mfma_f32_16x16x32_bf16 v[112:115], v[172:175], v[180:183], v[112:115]
	v_mfma_f32_16x16x32_bf16 v[96:99], v[172:175], v[198:201], v[96:99]
	v_mfma_f32_16x16x32_bf16 v[96:99], v[176:179], v[202:205], v[96:99]
	v_mfma_f32_16x16x32_bf16 v[100:103], v[148:151], v[202:205], v[100:103]
	v_mfma_f32_16x16x32_bf16 v[100:103], v[144:147], v[198:201], v[100:103]
	v_mfma_f32_16x16x32_bf16 v[84:87], v[144:147], v[206:209], v[84:87]
	v_mfma_f32_16x16x32_bf16 v[84:87], v[148:151], v[210:213], v[84:87]
	v_mfma_f32_16x16x32_bf16 v[80:83], v[176:179], v[210:213], v[80:83]
	v_mfma_f32_16x16x32_bf16 v[80:83], v[172:175], v[206:209], v[80:83]
	v_mfma_f32_16x16x32_bf16 v[64:67], v[172:175], v[214:217], v[64:67]
	v_mfma_f32_16x16x32_bf16 v[64:67], v[176:179], v[218:221], v[64:67]
	v_mfma_f32_16x16x32_bf16 v[68:71], v[148:151], v[218:221], v[68:71]
	v_mfma_f32_16x16x32_bf16 v[68:71], v[144:147], v[214:217], v[68:71]
	s_barrier
	s_setprio 0
	s_add_i32 s54, s75, s65
	v_lshl_add_u64 v[222:223], s[58:59], 0, v[154:155]
	s_mov_b32 m0, s54
	ds_read_b128 v[180:183], v191 offset:16384
	v_xor_b32_e32 v253, 64, v191
	ds_read_b128 v[194:197], v253 offset:16384
	ds_read_b128 v[198:201], v191 offset:18432
	ds_read_b128 v[202:205], v253 offset:18432
	ds_read_b128 v[206:209], v191 offset:20480
	ds_read_b128 v[210:213], v253 offset:20480
	ds_read_b128 v[214:217], v191 offset:22528
	ds_read_b128 v[218:221], v253 offset:22528
	global_load_lds_dwordx4 v[222:223], off
	s_add_i32 m0, s54, 0x2000
	s_add_u32 s54, s58, 0xb0000
	v_lshl_add_u64 v[224:225], s[58:59], 0, v[162:163]
	s_addc_u32 s55, s59, 0
	s_add_i32 s82, s76, s65
	global_load_lds_dwordx4 v[224:225], off
	v_lshl_add_u64 v[226:227], s[54:55], 0, v[154:155]
	s_mov_b32 m0, s82
	v_lshl_add_u64 v[228:229], s[60:61], 0, v[160:161]
	global_load_lds_dwordx4 v[226:227], off
	v_lshl_add_u64 v[226:227], s[54:55], 0, v[162:163]
	s_add_i32 m0, s82, 0x2000
	s_nop 0
	global_load_lds_dwordx4 v[226:227], off
	v_lshl_add_u64 v[226:227], s[60:61], 0, v[152:153]
	s_mov_b32 m0, s66
	s_nop 0
	global_load_lds_dwordx4 v[226:227], off
	s_mov_b32 m0, s67
	s_nop 0
	global_load_lds_dwordx4 v[228:229], off
	s_waitcnt vmcnt(8)
	s_waitcnt lgkmcnt(0)
	.p2align 3
	s_setprio 1
	s_barrier
	v_mfma_f32_16x16x32_bf16 v[60:63], v[128:131], v[180:183], v[60:63]
	v_mfma_f32_16x16x32_bf16 v[60:63], v[132:135], v[194:197], v[60:63]
	v_mfma_f32_16x16x32_bf16 v[56:59], v[140:143], v[194:197], v[56:59]
	v_mfma_f32_16x16x32_bf16 v[56:59], v[136:139], v[180:183], v[56:59]
	v_mfma_f32_16x16x32_bf16 v[40:43], v[136:139], v[198:201], v[40:43]
	v_mfma_f32_16x16x32_bf16 v[40:43], v[140:143], v[202:205], v[40:43]
	v_mfma_f32_16x16x32_bf16 v[44:47], v[132:135], v[202:205], v[44:47]
	v_mfma_f32_16x16x32_bf16 v[44:47], v[128:131], v[198:201], v[44:47]
	v_mfma_f32_16x16x32_bf16 v[28:31], v[128:131], v[206:209], v[28:31]
	v_mfma_f32_16x16x32_bf16 v[28:31], v[132:135], v[210:213], v[28:31]
	v_mfma_f32_16x16x32_bf16 v[24:27], v[140:143], v[210:213], v[24:27]
	v_mfma_f32_16x16x32_bf16 v[24:27], v[136:139], v[206:209], v[24:27]
	v_mfma_f32_16x16x32_bf16 v[8:11], v[136:139], v[214:217], v[8:11]
	v_mfma_f32_16x16x32_bf16 v[8:11], v[140:143], v[218:221], v[8:11]
	v_mfma_f32_16x16x32_bf16 v[12:15], v[132:135], v[218:221], v[12:15]
	v_mfma_f32_16x16x32_bf16 v[12:15], v[128:131], v[214:217], v[12:15]
	s_setprio 0
	s_setprio 1
	v_mfma_f32_16x16x32_bf16 v[52:55], v[144:147], v[180:183], v[52:55]
	v_mfma_f32_16x16x32_bf16 v[52:55], v[148:151], v[194:197], v[52:55]
	v_mfma_f32_16x16x32_bf16 v[48:51], v[176:179], v[194:197], v[48:51]
	v_mfma_f32_16x16x32_bf16 v[48:51], v[172:175], v[180:183], v[48:51]
	v_mfma_f32_16x16x32_bf16 v[32:35], v[172:175], v[198:201], v[32:35]
	v_mfma_f32_16x16x32_bf16 v[32:35], v[176:179], v[202:205], v[32:35]
	v_mfma_f32_16x16x32_bf16 v[36:39], v[148:151], v[202:205], v[36:39]
	v_mfma_f32_16x16x32_bf16 v[36:39], v[144:147], v[198:201], v[36:39]
	v_mfma_f32_16x16x32_bf16 v[20:23], v[144:147], v[206:209], v[20:23]
	v_mfma_f32_16x16x32_bf16 v[20:23], v[148:151], v[210:213], v[20:23]
	v_mfma_f32_16x16x32_bf16 v[16:19], v[176:179], v[210:213], v[16:19]
	v_mfma_f32_16x16x32_bf16 v[16:19], v[172:175], v[206:209], v[16:19]
	v_mfma_f32_16x16x32_bf16 v[0:3], v[172:175], v[214:217], v[0:3]
	v_mfma_f32_16x16x32_bf16 v[0:3], v[176:179], v[218:221], v[0:3]
	v_mfma_f32_16x16x32_bf16 v[4:7], v[148:151], v[218:221], v[4:7]
	v_mfma_f32_16x16x32_bf16 v[4:7], v[144:147], v[214:217], v[4:7]
	s_barrier
	s_setprio 0
	s_add_i32 s82, 0, 0x18000
	s_add_i32 s83, 0, 0x1c000
	v_add_u32_e32 v140, s82, v186
	v_add_u32_e32 v176, s83, v186
	ds_read_b128 v[128:131], v140
	v_xor_b32_e32 v253, 64, v140
	ds_read_b128 v[132:135], v253
	ds_read_b128 v[136:139], v140 offset:2048
	ds_read_b128 v[140:143], v253 offset:2048
	ds_read_b128 v[144:147], v176
	v_xor_b32_e32 v253, 64, v176
	ds_read_b128 v[148:151], v253
	ds_read_b128 v[172:175], v176 offset:2048
	ds_read_b128 v[176:179], v253 offset:2048
	s_add_u32 s54, s60, 0xb0000
	s_addc_u32 s55, s61, 0
	s_mov_b32 m0, s68
	v_lshl_add_u64 v[230:231], s[54:55], 0, v[152:153]
	ds_read_b128 v[180:183], v191 offset:32768
	v_xor_b32_e32 v253, 64, v191
	ds_read_b128 v[194:197], v253 offset:32768
	ds_read_b128 v[198:201], v191 offset:34816
	ds_read_b128 v[202:205], v253 offset:34816
	ds_read_b128 v[206:209], v191 offset:36864
	ds_read_b128 v[210:213], v253 offset:36864
	ds_read_b128 v[214:217], v191 offset:38912
	ds_read_b128 v[218:221], v253 offset:38912
	global_load_lds_dwordx4 v[230:231], off
	v_lshl_add_u64 v[230:231], s[54:55], 0, v[160:161]
	s_mov_b32 m0, s69
	s_nop 0
	global_load_lds_dwordx4 v[230:231], off
	s_waitcnt vmcnt(8)
	s_waitcnt lgkmcnt(0)
	.p2align 3
	s_setprio 1
	s_barrier
	v_mfma_f32_16x16x32_bf16 v[124:127], v[128:131], v[180:183], v[124:127]
	v_mfma_f32_16x16x32_bf16 v[124:127], v[132:135], v[194:197], v[124:127]
	v_mfma_f32_16x16x32_bf16 v[120:123], v[140:143], v[194:197], v[120:123]
	v_mfma_f32_16x16x32_bf16 v[120:123], v[136:139], v[180:183], v[120:123]
	v_mfma_f32_16x16x32_bf16 v[104:107], v[136:139], v[198:201], v[104:107]
	v_mfma_f32_16x16x32_bf16 v[104:107], v[140:143], v[202:205], v[104:107]
	v_mfma_f32_16x16x32_bf16 v[108:111], v[132:135], v[202:205], v[108:111]
	v_mfma_f32_16x16x32_bf16 v[108:111], v[128:131], v[198:201], v[108:111]
	v_mfma_f32_16x16x32_bf16 v[92:95], v[128:131], v[206:209], v[92:95]
	v_mfma_f32_16x16x32_bf16 v[92:95], v[132:135], v[210:213], v[92:95]
	v_mfma_f32_16x16x32_bf16 v[88:91], v[140:143], v[210:213], v[88:91]
	v_mfma_f32_16x16x32_bf16 v[88:91], v[136:139], v[206:209], v[88:91]
	v_mfma_f32_16x16x32_bf16 v[72:75], v[136:139], v[214:217], v[72:75]
	v_mfma_f32_16x16x32_bf16 v[72:75], v[140:143], v[218:221], v[72:75]
	v_mfma_f32_16x16x32_bf16 v[76:79], v[132:135], v[218:221], v[76:79]
	v_mfma_f32_16x16x32_bf16 v[76:79], v[128:131], v[214:217], v[76:79]
	s_setprio 0
	s_setprio 1
	v_mfma_f32_16x16x32_bf16 v[116:119], v[144:147], v[180:183], v[116:119]
	v_mfma_f32_16x16x32_bf16 v[116:119], v[148:151], v[194:197], v[116:119]
	v_mfma_f32_16x16x32_bf16 v[112:115], v[176:179], v[194:197], v[112:115]
	v_mfma_f32_16x16x32_bf16 v[112:115], v[172:175], v[180:183], v[112:115]
	v_mfma_f32_16x16x32_bf16 v[96:99], v[172:175], v[198:201], v[96:99]
	v_mfma_f32_16x16x32_bf16 v[96:99], v[176:179], v[202:205], v[96:99]
	v_mfma_f32_16x16x32_bf16 v[100:103], v[148:151], v[202:205], v[100:103]
	v_mfma_f32_16x16x32_bf16 v[100:103], v[144:147], v[198:201], v[100:103]
	v_mfma_f32_16x16x32_bf16 v[84:87], v[144:147], v[206:209], v[84:87]
	v_mfma_f32_16x16x32_bf16 v[84:87], v[148:151], v[210:213], v[84:87]
	v_mfma_f32_16x16x32_bf16 v[80:83], v[176:179], v[210:213], v[80:83]
	v_mfma_f32_16x16x32_bf16 v[80:83], v[172:175], v[206:209], v[80:83]
	v_mfma_f32_16x16x32_bf16 v[64:67], v[172:175], v[214:217], v[64:67]
	v_mfma_f32_16x16x32_bf16 v[64:67], v[176:179], v[218:221], v[64:67]
	v_mfma_f32_16x16x32_bf16 v[68:71], v[148:151], v[218:221], v[68:71]
	v_mfma_f32_16x16x32_bf16 v[68:71], v[144:147], v[214:217], v[68:71]
	s_barrier
	s_setprio 0
	s_add_i32 s54, s82, s65
	v_lshl_add_u64 v[222:223], v[222:223], 0, s[28:29]
	s_mov_b32 m0, s54
	ds_read_b128 v[180:183], v191 offset:49152
	v_xor_b32_e32 v253, 64, v191
	ds_read_b128 v[194:197], v253 offset:49152
	ds_read_b128 v[198:201], v191 offset:51200
	ds_read_b128 v[202:205], v253 offset:51200
	ds_read_b128 v[206:209], v191 offset:53248
	ds_read_b128 v[210:213], v253 offset:53248
	ds_read_b128 v[214:217], v191 offset:55296
	ds_read_b128 v[218:221], v253 offset:55296
	global_load_lds_dwordx4 v[222:223], off
	s_add_i32 m0, s54, 0x2000
	s_add_u32 s54, s58, 0xb0080
	v_lshl_add_u64 v[222:223], v[224:225], 0, s[28:29]
	s_addc_u32 s55, s59, 0
	s_add_i32 s58, s83, s65
	global_load_lds_dwordx4 v[222:223], off
	v_lshl_add_u64 v[222:223], s[54:55], 0, v[154:155]
	s_mov_b32 m0, s58
	s_nop 0
	global_load_lds_dwordx4 v[222:223], off
	v_lshl_add_u64 v[222:223], s[54:55], 0, v[162:163]
	s_add_i32 m0, s58, 0x2000
	s_nop 0
	global_load_lds_dwordx4 v[222:223], off
	v_lshl_add_u64 v[222:223], v[226:227], 0, s[28:29]
	s_mov_b32 m0, s3
	s_nop 0
	global_load_lds_dwordx4 v[222:223], off
	v_lshl_add_u64 v[222:223], v[228:229], 0, s[28:29]
	s_mov_b32 m0, s71
	s_nop 0
	global_load_lds_dwordx4 v[222:223], off
	s_waitcnt vmcnt(8)
	s_waitcnt lgkmcnt(0)
	.p2align 3
	s_setprio 1
	s_barrier
	v_mfma_f32_16x16x32_bf16 v[60:63], v[128:131], v[180:183], v[60:63]
	v_mfma_f32_16x16x32_bf16 v[60:63], v[132:135], v[194:197], v[60:63]
	v_mfma_f32_16x16x32_bf16 v[56:59], v[140:143], v[194:197], v[56:59]
	v_mfma_f32_16x16x32_bf16 v[56:59], v[136:139], v[180:183], v[56:59]
	v_mfma_f32_16x16x32_bf16 v[40:43], v[136:139], v[198:201], v[40:43]
	v_mfma_f32_16x16x32_bf16 v[40:43], v[140:143], v[202:205], v[40:43]
	v_mfma_f32_16x16x32_bf16 v[44:47], v[132:135], v[202:205], v[44:47]
	v_mfma_f32_16x16x32_bf16 v[44:47], v[128:131], v[198:201], v[44:47]
	v_mfma_f32_16x16x32_bf16 v[28:31], v[128:131], v[206:209], v[28:31]
	v_mfma_f32_16x16x32_bf16 v[28:31], v[132:135], v[210:213], v[28:31]
	v_mfma_f32_16x16x32_bf16 v[24:27], v[140:143], v[210:213], v[24:27]
	v_mfma_f32_16x16x32_bf16 v[24:27], v[136:139], v[206:209], v[24:27]
	v_mfma_f32_16x16x32_bf16 v[8:11], v[136:139], v[214:217], v[8:11]
	v_mfma_f32_16x16x32_bf16 v[8:11], v[140:143], v[218:221], v[8:11]
	v_mfma_f32_16x16x32_bf16 v[12:15], v[132:135], v[218:221], v[12:15]
	v_mfma_f32_16x16x32_bf16 v[12:15], v[128:131], v[214:217], v[12:15]
	s_setprio 0
	s_setprio 1
	v_mfma_f32_16x16x32_bf16 v[52:55], v[144:147], v[180:183], v[52:55]
	v_mfma_f32_16x16x32_bf16 v[52:55], v[148:151], v[194:197], v[52:55]
	v_mfma_f32_16x16x32_bf16 v[48:51], v[176:179], v[194:197], v[48:51]
	v_mfma_f32_16x16x32_bf16 v[48:51], v[172:175], v[180:183], v[48:51]
	v_mfma_f32_16x16x32_bf16 v[32:35], v[172:175], v[198:201], v[32:35]
	v_mfma_f32_16x16x32_bf16 v[32:35], v[176:179], v[202:205], v[32:35]
	v_mfma_f32_16x16x32_bf16 v[36:39], v[148:151], v[202:205], v[36:39]
	v_mfma_f32_16x16x32_bf16 v[36:39], v[144:147], v[198:201], v[36:39]
	v_mfma_f32_16x16x32_bf16 v[20:23], v[144:147], v[206:209], v[20:23]
	v_mfma_f32_16x16x32_bf16 v[20:23], v[148:151], v[210:213], v[20:23]
	v_mfma_f32_16x16x32_bf16 v[16:19], v[176:179], v[210:213], v[16:19]
	v_mfma_f32_16x16x32_bf16 v[16:19], v[172:175], v[206:209], v[16:19]
	v_mfma_f32_16x16x32_bf16 v[0:3], v[172:175], v[214:217], v[0:3]
	v_mfma_f32_16x16x32_bf16 v[0:3], v[176:179], v[218:221], v[0:3]
	v_mfma_f32_16x16x32_bf16 v[4:7], v[148:151], v[218:221], v[4:7]
	v_mfma_f32_16x16x32_bf16 v[4:7], v[144:147], v[214:217], v[4:7]
	s_barrier
	s_setprio 0
	s_add_i32 s81, s81, 2
	s_add_u32 s79, s79, 0x100
	s_addc_u32 s80, s80, 0
	s_cmp_gt_u32 s81, 41
	s_mov_b64 s[54:55], s[56:57]
	s_cbranch_scc0 .LBB0_610
	s_and_b64 vcc, exec, s[30:31]
	s_cbranch_vccz .LBB0_613
	s_barrier

.LBB0_873:
	s_ashr_i32 s49, s48, 31
	s_lshl_b64 s[50:51], s[48:49], 19
	s_add_u32 s50, s35, s50
	s_addc_u32 s51, s60, s51
	s_and_b64 s[52:53], s[10:11], exec
	s_cselect_b32 s49, s51, s59
	s_cselect_b32 s80, s50, s58
	s_ashr_i32 s47, s46, 31
	s_lshl_b64 s[52:53], s[46:47], 19
	s_add_u32 s52, s61, s52
	s_addc_u32 s53, s62, s53
	s_and_b64 s[82:83], s[10:11], exec
	s_cselect_b32 s81, s53, s57
	s_cselect_b32 s82, s52, s56
	s_lshl_b32 s47, s54, 8
	v_add_u32_e32 v0, s47, v151
	s_add_u32 s83, s56, 0x100
	v_ashrrev_i32_e32 v1, 31, v0
	s_addc_u32 s84, s57, 0
	v_lshl_add_u64 v[144:145], v[0:1], 4, s[20:21]
	s_add_u32 s54, s58, 0x40080
	s_addc_u32 s55, s59, 0
	s_mov_b32 s85, -2
	s_mov_b64 s[56:57], 0
	s_cmp_eq_u32 s68, 1
	s_cbranch_scc1 .Lfa_8
	v_add_u32_e32 v146, s73, v149
	ds_read_b128 v[162:165], v146
	v_xor_b32_e32 v253, 64, v146
	ds_read_b128 v[166:169], v253
	ds_read_b128 v[170:173], v146 offset:2048
	ds_read_b128 v[174:177], v253 offset:2048
	v_add_u32_e32 v146, s74, v149
	ds_read_b128 v[178:181], v146
	v_xor_b32_e32 v253, 64, v146
	ds_read_b128 v[186:189], v253
	ds_read_b128 v[190:193], v146 offset:2048
	ds_read_b128 v[194:197], v253 offset:2048
	s_add_u32 s58, s54, 0xfffc0080
	s_addc_u32 s59, s55, -1
	s_and_b64 s[56:57], s[56:57], exec
	s_cselect_b32 s59, s49, s59
	s_cselect_b32 s58, s80, s58
	s_cselect_b32 s57, s81, s84
	s_cselect_b32 s56, s82, s83
	v_lshl_add_u64 v[182:183], s[54:55], 0, v[138:139]
	s_add_i32 m0, s64, 0xc000
	ds_read_b128 v[198:201], v154
	v_xor_b32_e32 v253, 64, v154
	ds_read_b128 v[202:205], v253
	ds_read_b128 v[206:209], v154 offset:2048
	ds_read_b128 v[210:213], v253 offset:2048
	ds_read_b128 v[214:217], v154 offset:4096
	ds_read_b128 v[218:221], v253 offset:4096
	ds_read_b128 v[222:225], v154 offset:6144
	ds_read_b128 v[226:229], v253 offset:6144
	global_load_lds_dwordx4 v[182:183], off
	v_lshl_add_u64 v[182:183], s[54:55], 0, v[136:137]
	s_add_i32 m0, s64, 0xe000
	s_nop 0
	global_load_lds_dwordx4 v[182:183], off
	s_waitcnt vmcnt(24)
	s_waitcnt lgkmcnt(0)
	.p2align 3
	s_setprio 1
	s_barrier
	v_mfma_f32_16x16x32_bf16 v[124:127], v[162:165], v[198:201], 0
	v_mfma_f32_16x16x32_bf16 v[120:123], v[170:173], v[198:201], 0
	v_mfma_f32_16x16x32_bf16 v[112:115], v[162:165], v[206:209], 0
	v_mfma_f32_16x16x32_bf16 v[104:107], v[170:173], v[206:209], 0
	v_mfma_f32_16x16x32_bf16 v[96:99], v[162:165], v[214:217], 0
	v_mfma_f32_16x16x32_bf16 v[88:91], v[170:173], v[214:217], 0
	v_mfma_f32_16x16x32_bf16 v[80:83], v[162:165], v[222:225], 0
	v_mfma_f32_16x16x32_bf16 v[72:75], v[170:173], v[222:225], 0
	v_mfma_f32_16x16x32_bf16 v[124:127], v[166:169], v[202:205], v[124:127]
	v_mfma_f32_16x16x32_bf16 v[120:123], v[174:177], v[202:205], v[120:123]
	v_mfma_f32_16x16x32_bf16 v[112:115], v[166:169], v[210:213], v[112:115]
	v_mfma_f32_16x16x32_bf16 v[104:107], v[174:177], v[210:213], v[104:107]
	v_mfma_f32_16x16x32_bf16 v[96:99], v[166:169], v[218:221], v[96:99]
	v_mfma_f32_16x16x32_bf16 v[88:91], v[174:177], v[218:221], v[88:91]
	v_mfma_f32_16x16x32_bf16 v[80:83], v[166:169], v[226:229], v[80:83]
	v_mfma_f32_16x16x32_bf16 v[72:75], v[174:177], v[226:229], v[72:75]
	s_setprio 0
	s_setprio 1
	v_mfma_f32_16x16x32_bf16 v[116:119], v[178:181], v[198:201], 0
	v_mfma_f32_16x16x32_bf16 v[108:111], v[190:193], v[198:201], 0
	v_mfma_f32_16x16x32_bf16 v[100:103], v[178:181], v[206:209], 0
	v_mfma_f32_16x16x32_bf16 v[92:95], v[190:193], v[206:209], 0
	v_mfma_f32_16x16x32_bf16 v[84:87], v[178:181], v[214:217], 0
	v_mfma_f32_16x16x32_bf16 v[76:79], v[190:193], v[214:217], 0
	v_mfma_f32_16x16x32_bf16 v[68:71], v[178:181], v[222:225], 0
	v_mfma_f32_16x16x32_bf16 v[64:67], v[190:193], v[222:225], 0
	v_mfma_f32_16x16x32_bf16 v[116:119], v[186:189], v[202:205], v[116:119]
	v_mfma_f32_16x16x32_bf16 v[108:111], v[194:197], v[202:205], v[108:111]
	v_mfma_f32_16x16x32_bf16 v[100:103], v[186:189], v[210:213], v[100:103]
	v_mfma_f32_16x16x32_bf16 v[92:95], v[194:197], v[210:213], v[92:95]
	v_mfma_f32_16x16x32_bf16 v[84:87], v[186:189], v[218:221], v[84:87]
	v_mfma_f32_16x16x32_bf16 v[76:79], v[194:197], v[218:221], v[76:79]
	v_mfma_f32_16x16x32_bf16 v[68:71], v[186:189], v[226:229], v[68:71]
	v_mfma_f32_16x16x32_bf16 v[64:67], v[194:197], v[226:229], v[64:67]
	s_barrier
	s_setprio 0
	s_add_i32 s86, s73, s63
	v_lshl_add_u64 v[182:183], s[56:57], 0, v[130:131]
	s_mov_b32 m0, s86
	ds_read_b128 v[198:201], v154 offset:16384
	v_xor_b32_e32 v253, 64, v154
	ds_read_b128 v[202:205], v253 offset:16384
	ds_read_b128 v[206:209], v154 offset:18432
	ds_read_b128 v[210:213], v253 offset:18432
	ds_read_b128 v[214:217], v154 offset:20480
	ds_read_b128 v[218:221], v253 offset:20480
	ds_read_b128 v[222:225], v154 offset:22528
	ds_read_b128 v[226:229], v253 offset:22528
	global_load_lds_dwordx4 v[182:183], off
	s_add_i32 m0, s86, 0x2000
	s_add_u32 s86, s56, 0x40000
	v_lshl_add_u64 v[230:231], s[56:57], 0, v[134:135]
	s_addc_u32 s87, s57, 0
	s_add_i32 s88, s74, s63
	global_load_lds_dwordx4 v[230:231], off
	v_lshl_add_u64 v[232:233], s[86:87], 0, v[130:131]
	s_mov_b32 m0, s88
	v_lshl_add_u64 v[234:235], s[58:59], 0, v[132:133]
	global_load_lds_dwordx4 v[232:233], off
	v_lshl_add_u64 v[232:233], s[86:87], 0, v[134:135]
	s_add_i32 m0, s88, 0x2000
	s_nop 0
	global_load_lds_dwordx4 v[232:233], off
	v_lshl_add_u64 v[232:233], s[58:59], 0, v[128:129]
	s_mov_b32 m0, s64
	s_nop 0
	global_load_lds_dwordx4 v[232:233], off
	s_mov_b32 m0, s65
	s_nop 0
	global_load_lds_dwordx4 v[234:235], off
	s_waitcnt vmcnt(24)
	s_waitcnt lgkmcnt(0)
	.p2align 3
	s_setprio 1
	s_barrier
	v_mfma_f32_16x16x32_bf16 v[60:63], v[162:165], v[198:201], 0
	v_mfma_f32_16x16x32_bf16 v[56:59], v[170:173], v[198:201], 0
	v_mfma_f32_16x16x32_bf16 v[48:51], v[162:165], v[206:209], 0
	v_mfma_f32_16x16x32_bf16 v[40:43], v[170:173], v[206:209], 0
	v_mfma_f32_16x16x32_bf16 v[32:35], v[162:165], v[214:217], 0
	v_mfma_f32_16x16x32_bf16 v[24:27], v[170:173], v[214:217], 0
	v_mfma_f32_16x16x32_bf16 v[16:19], v[162:165], v[222:225], 0
	v_mfma_f32_16x16x32_bf16 v[8:11], v[170:173], v[222:225], 0
	v_mfma_f32_16x16x32_bf16 v[60:63], v[166:169], v[202:205], v[60:63]
	v_mfma_f32_16x16x32_bf16 v[56:59], v[174:177], v[202:205], v[56:59]
	v_mfma_f32_16x16x32_bf16 v[48:51], v[166:169], v[210:213], v[48:51]
	v_mfma_f32_16x16x32_bf16 v[40:43], v[174:177], v[210:213], v[40:43]
	v_mfma_f32_16x16x32_bf16 v[32:35], v[166:169], v[218:221], v[32:35]
	v_mfma_f32_16x16x32_bf16 v[24:27], v[174:177], v[218:221], v[24:27]
	v_mfma_f32_16x16x32_bf16 v[16:19], v[166:169], v[226:229], v[16:19]
	v_mfma_f32_16x16x32_bf16 v[8:11], v[174:177], v[226:229], v[8:11]
	s_setprio 0
	s_setprio 1
	v_mfma_f32_16x16x32_bf16 v[52:55], v[178:181], v[198:201], 0
	v_mfma_f32_16x16x32_bf16 v[44:47], v[190:193], v[198:201], 0
	v_mfma_f32_16x16x32_bf16 v[36:39], v[178:181], v[206:209], 0
	v_mfma_f32_16x16x32_bf16 v[28:31], v[190:193], v[206:209], 0
	v_mfma_f32_16x16x32_bf16 v[20:23], v[178:181], v[214:217], 0
	v_mfma_f32_16x16x32_bf16 v[12:15], v[190:193], v[214:217], 0
	v_mfma_f32_16x16x32_bf16 v[4:7], v[178:181], v[222:225], 0
	v_mfma_f32_16x16x32_bf16 v[0:3], v[190:193], v[222:225], 0
	v_mfma_f32_16x16x32_bf16 v[52:55], v[186:189], v[202:205], v[52:55]
	v_mfma_f32_16x16x32_bf16 v[44:47], v[194:197], v[202:205], v[44:47]
	v_mfma_f32_16x16x32_bf16 v[36:39], v[186:189], v[210:213], v[36:39]
	v_mfma_f32_16x16x32_bf16 v[28:31], v[194:197], v[210:213], v[28:31]
	v_mfma_f32_16x16x32_bf16 v[20:23], v[186:189], v[218:221], v[20:23]
	v_mfma_f32_16x16x32_bf16 v[12:15], v[194:197], v[218:221], v[12:15]
	v_mfma_f32_16x16x32_bf16 v[4:7], v[186:189], v[226:229], v[4:7]
	v_mfma_f32_16x16x32_bf16 v[0:3], v[194:197], v[226:229], v[0:3]
	s_barrier
	s_setprio 0
	s_add_i32 s86, 0, 0x18000
	v_add_u32_e32 v146, s86, v149
	s_add_i32 s87, 0, 0x1c000
	ds_read_b128 v[162:165], v146
	v_xor_b32_e32 v253, 64, v146
	ds_read_b128 v[166:169], v253
	ds_read_b128 v[170:173], v146 offset:2048
	ds_read_b128 v[174:177], v253 offset:2048
	v_add_u32_e32 v146, s87, v149
	ds_read_b128 v[178:181], v146
	v_xor_b32_e32 v253, 64, v146
	ds_read_b128 v[186:189], v253
	ds_read_b128 v[190:193], v146 offset:2048
	ds_read_b128 v[194:197], v253 offset:2048
	s_add_u32 s58, s58, 0x40000
	s_addc_u32 s59, s59, 0
	s_mov_b32 m0, s66
	v_lshl_add_u64 v[236:237], s[58:59], 0, v[128:129]
	ds_read_b128 v[198:201], v154 offset:32768
	v_xor_b32_e32 v253, 64, v154
	ds_read_b128 v[202:205], v253 offset:32768
	ds_read_b128 v[206:209], v154 offset:34816
	ds_read_b128 v[210:213], v253 offset:34816
	ds_read_b128 v[214:217], v154 offset:36864
	ds_read_b128 v[218:221], v253 offset:36864
	ds_read_b128 v[222:225], v154 offset:38912
	ds_read_b128 v[226:229], v253 offset:38912
	global_load_lds_dwordx4 v[236:237], off
	v_lshl_add_u64 v[236:237], s[58:59], 0, v[132:133]
	s_mov_b32 m0, s67
	s_nop 0
	global_load_lds_dwordx4 v[236:237], off
	s_waitcnt vmcnt(8)
	s_waitcnt lgkmcnt(0)
	.p2align 3
	s_setprio 1
	s_barrier
	v_mfma_f32_16x16x32_bf16 v[124:127], v[162:165], v[198:201], v[124:127]
	v_mfma_f32_16x16x32_bf16 v[124:127], v[166:169], v[202:205], v[124:127]
	v_mfma_f32_16x16x32_bf16 v[120:123], v[174:177], v[202:205], v[120:123]
	v_mfma_f32_16x16x32_bf16 v[120:123], v[170:173], v[198:201], v[120:123]
	v_mfma_f32_16x16x32_bf16 v[104:107], v[170:173], v[206:209], v[104:107]
	v_mfma_f32_16x16x32_bf16 v[104:107], v[174:177], v[210:213], v[104:107]
	v_mfma_f32_16x16x32_bf16 v[112:115], v[166:169], v[210:213], v[112:115]
	v_mfma_f32_16x16x32_bf16 v[112:115], v[162:165], v[206:209], v[112:115]
	v_mfma_f32_16x16x32_bf16 v[96:99], v[162:165], v[214:217], v[96:99]
	v_mfma_f32_16x16x32_bf16 v[96:99], v[166:169], v[218:221], v[96:99]
	v_mfma_f32_16x16x32_bf16 v[88:91], v[174:177], v[218:221], v[88:91]
	v_mfma_f32_16x16x32_bf16 v[88:91], v[170:173], v[214:217], v[88:91]
	v_mfma_f32_16x16x32_bf16 v[72:75], v[170:173], v[222:225], v[72:75]
	v_mfma_f32_16x16x32_bf16 v[72:75], v[174:177], v[226:229], v[72:75]
	v_mfma_f32_16x16x32_bf16 v[80:83], v[166:169], v[226:229], v[80:83]
	v_mfma_f32_16x16x32_bf16 v[80:83], v[162:165], v[222:225], v[80:83]
	s_setprio 0
	s_setprio 1
	v_mfma_f32_16x16x32_bf16 v[116:119], v[178:181], v[198:201], v[116:119]
	v_mfma_f32_16x16x32_bf16 v[116:119], v[186:189], v[202:205], v[116:119]
	v_mfma_f32_16x16x32_bf16 v[108:111], v[194:197], v[202:205], v[108:111]
	v_mfma_f32_16x16x32_bf16 v[108:111], v[190:193], v[198:201], v[108:111]
	v_mfma_f32_16x16x32_bf16 v[92:95], v[190:193], v[206:209], v[92:95]
	v_mfma_f32_16x16x32_bf16 v[92:95], v[194:197], v[210:213], v[92:95]
	v_mfma_f32_16x16x32_bf16 v[100:103], v[186:189], v[210:213], v[100:103]
	v_mfma_f32_16x16x32_bf16 v[100:103], v[178:181], v[206:209], v[100:103]
	v_mfma_f32_16x16x32_bf16 v[84:87], v[178:181], v[214:217], v[84:87]
	v_mfma_f32_16x16x32_bf16 v[84:87], v[186:189], v[218:221], v[84:87]
	v_mfma_f32_16x16x32_bf16 v[76:79], v[194:197], v[218:221], v[76:79]
	v_mfma_f32_16x16x32_bf16 v[76:79], v[190:193], v[214:217], v[76:79]
	v_mfma_f32_16x16x32_bf16 v[64:67], v[190:193], v[222:225], v[64:67]
	v_mfma_f32_16x16x32_bf16 v[64:67], v[194:197], v[226:229], v[64:67]
	v_mfma_f32_16x16x32_bf16 v[68:71], v[186:189], v[226:229], v[68:71]
	v_mfma_f32_16x16x32_bf16 v[68:71], v[178:181], v[222:225], v[68:71]
	s_barrier
	s_setprio 0
	s_add_i32 s58, s86, s63
	v_lshl_add_u64 v[182:183], v[182:183], 0, s[22:23]
	s_mov_b32 m0, s58
	ds_read_b128 v[198:201], v154 offset:49152
	v_xor_b32_e32 v253, 64, v154
	ds_read_b128 v[202:205], v253 offset:49152
	ds_read_b128 v[206:209], v154 offset:51200
	ds_read_b128 v[210:213], v253 offset:51200
	ds_read_b128 v[214:217], v154 offset:53248
	ds_read_b128 v[218:221], v253 offset:53248
	ds_read_b128 v[222:225], v154 offset:55296
	ds_read_b128 v[226:229], v253 offset:55296
	global_load_lds_dwordx4 v[182:183], off
	s_add_i32 m0, s58, 0x2000
	s_add_u32 s56, s56, 0x40080
	v_lshl_add_u64 v[182:183], v[230:231], 0, s[22:23]
	s_addc_u32 s57, s57, 0
	s_add_i32 s58, s87, s63
	global_load_lds_dwordx4 v[182:183], off
	v_lshl_add_u64 v[182:183], s[56:57], 0, v[130:131]
	s_mov_b32 m0, s58
	s_nop 0
	global_load_lds_dwordx4 v[182:183], off
	v_lshl_add_u64 v[182:183], s[56:57], 0, v[134:135]
	s_add_i32 m0, s58, 0x2000
	s_nop 0
	global_load_lds_dwordx4 v[182:183], off
	v_lshl_add_u64 v[182:183], v[232:233], 0, s[22:23]
	s_mov_b32 m0, s69
	s_nop 0
	global_load_lds_dwordx4 v[182:183], off
	v_lshl_add_u64 v[182:183], v[234:235], 0, s[22:23]
	s_mov_b32 m0, s70
	s_nop 0
	global_load_lds_dwordx4 v[182:183], off
	s_waitcnt vmcnt(8)
	s_waitcnt lgkmcnt(0)
	.p2align 3
	s_setprio 1
	s_barrier
	v_mfma_f32_16x16x32_bf16 v[60:63], v[162:165], v[198:201], v[60:63]
	v_mfma_f32_16x16x32_bf16 v[60:63], v[166:169], v[202:205], v[60:63]
	v_mfma_f32_16x16x32_bf16 v[56:59], v[174:177], v[202:205], v[56:59]
	v_mfma_f32_16x16x32_bf16 v[56:59], v[170:173], v[198:201], v[56:59]
	v_mfma_f32_16x16x32_bf16 v[40:43], v[170:173], v[206:209], v[40:43]
	v_mfma_f32_16x16x32_bf16 v[40:43], v[174:177], v[210:213], v[40:43]
	v_mfma_f32_16x16x32_bf16 v[48:51], v[166:169], v[210:213], v[48:51]
	v_mfma_f32_16x16x32_bf16 v[48:51], v[162:165], v[206:209], v[48:51]
	v_mfma_f32_16x16x32_bf16 v[32:35], v[162:165], v[214:217], v[32:35]
	v_mfma_f32_16x16x32_bf16 v[32:35], v[166:169], v[218:221], v[32:35]
	v_mfma_f32_16x16x32_bf16 v[24:27], v[174:177], v[218:221], v[24:27]
	v_mfma_f32_16x16x32_bf16 v[24:27], v[170:173], v[214:217], v[24:27]
	v_mfma_f32_16x16x32_bf16 v[8:11], v[170:173], v[222:225], v[8:11]
	v_mfma_f32_16x16x32_bf16 v[8:11], v[174:177], v[226:229], v[8:11]
	v_mfma_f32_16x16x32_bf16 v[16:19], v[166:169], v[226:229], v[16:19]
	v_mfma_f32_16x16x32_bf16 v[16:19], v[162:165], v[222:225], v[16:19]
	s_setprio 0
	s_setprio 1
	v_mfma_f32_16x16x32_bf16 v[52:55], v[178:181], v[198:201], v[52:55]
	v_mfma_f32_16x16x32_bf16 v[52:55], v[186:189], v[202:205], v[52:55]
	v_mfma_f32_16x16x32_bf16 v[44:47], v[194:197], v[202:205], v[44:47]
	v_mfma_f32_16x16x32_bf16 v[44:47], v[190:193], v[198:201], v[44:47]
	v_mfma_f32_16x16x32_bf16 v[28:31], v[190:193], v[206:209], v[28:31]
	v_mfma_f32_16x16x32_bf16 v[28:31], v[194:197], v[210:213], v[28:31]
	v_mfma_f32_16x16x32_bf16 v[36:39], v[186:189], v[210:213], v[36:39]
	v_mfma_f32_16x16x32_bf16 v[36:39], v[178:181], v[206:209], v[36:39]
	v_mfma_f32_16x16x32_bf16 v[20:23], v[178:181], v[214:217], v[20:23]
	v_mfma_f32_16x16x32_bf16 v[20:23], v[186:189], v[218:221], v[20:23]
	v_mfma_f32_16x16x32_bf16 v[12:15], v[194:197], v[218:221], v[12:15]
	v_mfma_f32_16x16x32_bf16 v[12:15], v[190:193], v[214:217], v[12:15]
	v_mfma_f32_16x16x32_bf16 v[0:3], v[190:193], v[222:225], v[0:3]
	v_mfma_f32_16x16x32_bf16 v[0:3], v[194:197], v[226:229], v[0:3]
	v_mfma_f32_16x16x32_bf16 v[4:7], v[186:189], v[226:229], v[4:7]
	v_mfma_f32_16x16x32_bf16 v[4:7], v[178:181], v[222:225], v[4:7]
	s_barrier
	s_setprio 0
	s_add_i32 s85, s85, 2
	s_add_u32 s83, s83, 0x100
	s_addc_u32 s84, s84, 0
	s_add_u32 s54, s54, 0x100
	s_addc_u32 s55, s55, 0
	s_branch .LBB0_875
.Lfa_8:
	v_add_u32_e32 v146, s73, v149
	ds_read_b128 v[162:165], v146
	v_xor_b32_e32 v253, 64, v146
	ds_read_b128 v[166:169], v253
	ds_read_b128 v[170:173], v146 offset:2048
	ds_read_b128 v[174:177], v253 offset:2048
	v_add_u32_e32 v146, s74, v149
	ds_read_b128 v[178:181], v146
	v_xor_b32_e32 v253, 64, v146
	ds_read_b128 v[186:189], v253
	ds_read_b128 v[190:193], v146 offset:2048
	ds_read_b128 v[194:197], v253 offset:2048
	s_add_u32 s58, s54, 0xfffc0080
	s_addc_u32 s59, s55, -1
	s_and_b64 s[56:57], s[56:57], exec
	s_cselect_b32 s59, s49, s59
	s_cselect_b32 s58, s80, s58
	s_cselect_b32 s57, s81, s84
	s_cselect_b32 s56, s82, s83
	v_lshl_add_u64 v[182:183], s[54:55], 0, v[138:139]
	s_add_i32 m0, s64, 0xc000
	ds_read_b128 v[198:201], v154
	v_xor_b32_e32 v253, 64, v154
	ds_read_b128 v[202:205], v253
	ds_read_b128 v[206:209], v154 offset:2048
	ds_read_b128 v[210:213], v253 offset:2048
	ds_read_b128 v[214:217], v154 offset:4096
	ds_read_b128 v[218:221], v253 offset:4096
	ds_read_b128 v[222:225], v154 offset:6144
	ds_read_b128 v[226:229], v253 offset:6144
	global_load_lds_dwordx4 v[182:183], off
	v_lshl_add_u64 v[182:183], s[54:55], 0, v[136:137]
	s_add_i32 m0, s64, 0xe000
	s_nop 0
	global_load_lds_dwordx4 v[182:183], off
	s_waitcnt vmcnt(8)
	s_waitcnt lgkmcnt(0)
	.p2align 3
	s_setprio 1
	s_barrier
	v_mfma_f32_16x16x32_bf16 v[124:127], v[162:165], v[198:201], 0
	v_mfma_f32_16x16x32_bf16 v[120:123], v[170:173], v[198:201], 0
	v_mfma_f32_16x16x32_bf16 v[112:115], v[162:165], v[206:209], 0
	v_mfma_f32_16x16x32_bf16 v[104:107], v[170:173], v[206:209], 0
	v_mfma_f32_16x16x32_bf16 v[96:99], v[162:165], v[214:217], 0
	v_mfma_f32_16x16x32_bf16 v[88:91], v[170:173], v[214:217], 0
	v_mfma_f32_16x16x32_bf16 v[80:83], v[162:165], v[222:225], 0
	v_mfma_f32_16x16x32_bf16 v[72:75], v[170:173], v[222:225], 0
	v_mfma_f32_16x16x32_bf16 v[124:127], v[166:169], v[202:205], v[124:127]
	v_mfma_f32_16x16x32_bf16 v[120:123], v[174:177], v[202:205], v[120:123]
	v_mfma_f32_16x16x32_bf16 v[112:115], v[166:169], v[210:213], v[112:115]
	v_mfma_f32_16x16x32_bf16 v[104:107], v[174:177], v[210:213], v[104:107]
	v_mfma_f32_16x16x32_bf16 v[96:99], v[166:169], v[218:221], v[96:99]
	v_mfma_f32_16x16x32_bf16 v[88:91], v[174:177], v[218:221], v[88:91]
	v_mfma_f32_16x16x32_bf16 v[80:83], v[166:169], v[226:229], v[80:83]
	v_mfma_f32_16x16x32_bf16 v[72:75], v[174:177], v[226:229], v[72:75]
	s_setprio 0
	s_setprio 1
	v_mfma_f32_16x16x32_bf16 v[116:119], v[178:181], v[198:201], 0
	v_mfma_f32_16x16x32_bf16 v[108:111], v[190:193], v[198:201], 0
	v_mfma_f32_16x16x32_bf16 v[100:103], v[178:181], v[206:209], 0
	v_mfma_f32_16x16x32_bf16 v[92:95], v[190:193], v[206:209], 0
	v_mfma_f32_16x16x32_bf16 v[84:87], v[178:181], v[214:217], 0
	v_mfma_f32_16x16x32_bf16 v[76:79], v[190:193], v[214:217], 0
	v_mfma_f32_16x16x32_bf16 v[68:71], v[178:181], v[222:225], 0
	v_mfma_f32_16x16x32_bf16 v[64:67], v[190:193], v[222:225], 0
	v_mfma_f32_16x16x32_bf16 v[116:119], v[186:189], v[202:205], v[116:119]
	v_mfma_f32_16x16x32_bf16 v[108:111], v[194:197], v[202:205], v[108:111]
	v_mfma_f32_16x16x32_bf16 v[100:103], v[186:189], v[210:213], v[100:103]
	v_mfma_f32_16x16x32_bf16 v[92:95], v[194:197], v[210:213], v[92:95]
	v_mfma_f32_16x16x32_bf16 v[84:87], v[186:189], v[218:221], v[84:87]
	v_mfma_f32_16x16x32_bf16 v[76:79], v[194:197], v[218:221], v[76:79]
	v_mfma_f32_16x16x32_bf16 v[68:71], v[186:189], v[226:229], v[68:71]
	v_mfma_f32_16x16x32_bf16 v[64:67], v[194:197], v[226:229], v[64:67]
	s_barrier
	s_setprio 0
	s_add_i32 s86, s73, s63
	v_lshl_add_u64 v[182:183], s[56:57], 0, v[130:131]
	s_mov_b32 m0, s86
	ds_read_b128 v[198:201], v154 offset:16384
	v_xor_b32_e32 v253, 64, v154
	ds_read_b128 v[202:205], v253 offset:16384
	ds_read_b128 v[206:209], v154 offset:18432
	ds_read_b128 v[210:213], v253 offset:18432
	ds_read_b128 v[214:217], v154 offset:20480
	ds_read_b128 v[218:221], v253 offset:20480
	ds_read_b128 v[222:225], v154 offset:22528
	ds_read_b128 v[226:229], v253 offset:22528
	global_load_lds_dwordx4 v[182:183], off
	s_add_i32 m0, s86, 0x2000
	s_add_u32 s86, s56, 0x40000
	v_lshl_add_u64 v[230:231], s[56:57], 0, v[134:135]
	s_addc_u32 s87, s57, 0
	s_add_i32 s88, s74, s63
	global_load_lds_dwordx4 v[230:231], off
	v_lshl_add_u64 v[232:233], s[86:87], 0, v[130:131]
	s_mov_b32 m0, s88
	v_lshl_add_u64 v[234:235], s[58:59], 0, v[132:133]
	global_load_lds_dwordx4 v[232:233], off
	v_lshl_add_u64 v[232:233], s[86:87], 0, v[134:135]
	s_add_i32 m0, s88, 0x2000
	s_nop 0
	global_load_lds_dwordx4 v[232:233], off
	v_lshl_add_u64 v[232:233], s[58:59], 0, v[128:129]
	s_mov_b32 m0, s64
	s_nop 0
	global_load_lds_dwordx4 v[232:233], off
	s_mov_b32 m0, s65
	s_nop 0
	global_load_lds_dwordx4 v[234:235], off
	s_waitcnt vmcnt(8)
	s_waitcnt lgkmcnt(0)
	.p2align 3
	s_setprio 1
	s_barrier
	v_mfma_f32_16x16x32_bf16 v[60:63], v[162:165], v[198:201], 0
	v_mfma_f32_16x16x32_bf16 v[56:59], v[170:173], v[198:201], 0
	v_mfma_f32_16x16x32_bf16 v[48:51], v[162:165], v[206:209], 0
	v_mfma_f32_16x16x32_bf16 v[40:43], v[170:173], v[206:209], 0
	v_mfma_f32_16x16x32_bf16 v[32:35], v[162:165], v[214:217], 0
	v_mfma_f32_16x16x32_bf16 v[24:27], v[170:173], v[214:217], 0
	v_mfma_f32_16x16x32_bf16 v[16:19], v[162:165], v[222:225], 0
	v_mfma_f32_16x16x32_bf16 v[8:11], v[170:173], v[222:225], 0
	v_mfma_f32_16x16x32_bf16 v[60:63], v[166:169], v[202:205], v[60:63]
	v_mfma_f32_16x16x32_bf16 v[56:59], v[174:177], v[202:205], v[56:59]
	v_mfma_f32_16x16x32_bf16 v[48:51], v[166:169], v[210:213], v[48:51]
	v_mfma_f32_16x16x32_bf16 v[40:43], v[174:177], v[210:213], v[40:43]
	v_mfma_f32_16x16x32_bf16 v[32:35], v[166:169], v[218:221], v[32:35]
	v_mfma_f32_16x16x32_bf16 v[24:27], v[174:177], v[218:221], v[24:27]
	v_mfma_f32_16x16x32_bf16 v[16:19], v[166:169], v[226:229], v[16:19]
	v_mfma_f32_16x16x32_bf16 v[8:11], v[174:177], v[226:229], v[8:11]
	s_setprio 0
	s_setprio 1
	v_mfma_f32_16x16x32_bf16 v[52:55], v[178:181], v[198:201], 0
	v_mfma_f32_16x16x32_bf16 v[44:47], v[190:193], v[198:201], 0
	v_mfma_f32_16x16x32_bf16 v[36:39], v[178:181], v[206:209], 0
	v_mfma_f32_16x16x32_bf16 v[28:31], v[190:193], v[206:209], 0
	v_mfma_f32_16x16x32_bf16 v[20:23], v[178:181], v[214:217], 0
	v_mfma_f32_16x16x32_bf16 v[12:15], v[190:193], v[214:217], 0
	v_mfma_f32_16x16x32_bf16 v[4:7], v[178:181], v[222:225], 0
	v_mfma_f32_16x16x32_bf16 v[0:3], v[190:193], v[222:225], 0
	v_mfma_f32_16x16x32_bf16 v[52:55], v[186:189], v[202:205], v[52:55]
	v_mfma_f32_16x16x32_bf16 v[44:47], v[194:197], v[202:205], v[44:47]
	v_mfma_f32_16x16x32_bf16 v[36:39], v[186:189], v[210:213], v[36:39]
	v_mfma_f32_16x16x32_bf16 v[28:31], v[194:197], v[210:213], v[28:31]
	v_mfma_f32_16x16x32_bf16 v[20:23], v[186:189], v[218:221], v[20:23]
	v_mfma_f32_16x16x32_bf16 v[12:15], v[194:197], v[218:221], v[12:15]
	v_mfma_f32_16x16x32_bf16 v[4:7], v[186:189], v[226:229], v[4:7]
	v_mfma_f32_16x16x32_bf16 v[0:3], v[194:197], v[226:229], v[0:3]
	s_barrier
	s_setprio 0
	s_add_i32 s86, 0, 0x18000
	v_add_u32_e32 v146, s86, v149
	s_add_i32 s87, 0, 0x1c000
	ds_read_b128 v[162:165], v146
	v_xor_b32_e32 v253, 64, v146
	ds_read_b128 v[166:169], v253
	ds_read_b128 v[170:173], v146 offset:2048
	ds_read_b128 v[174:177], v253 offset:2048
	v_add_u32_e32 v146, s87, v149
	ds_read_b128 v[178:181], v146
	v_xor_b32_e32 v253, 64, v146
	ds_read_b128 v[186:189], v253
	ds_read_b128 v[190:193], v146 offset:2048
	ds_read_b128 v[194:197], v253 offset:2048
	s_add_u32 s58, s58, 0x40000
	s_addc_u32 s59, s59, 0
	s_mov_b32 m0, s66
	v_lshl_add_u64 v[236:237], s[58:59], 0, v[128:129]
	ds_read_b128 v[198:201], v154 offset:32768
	v_xor_b32_e32 v253, 64, v154
	ds_read_b128 v[202:205], v253 offset:32768
	ds_read_b128 v[206:209], v154 offset:34816
	ds_read_b128 v[210:213], v253 offset:34816
	ds_read_b128 v[214:217], v154 offset:36864
	ds_read_b128 v[218:221], v253 offset:36864
	ds_read_b128 v[222:225], v154 offset:38912
	ds_read_b128 v[226:229], v253 offset:38912
	global_load_lds_dwordx4 v[236:237], off
	v_lshl_add_u64 v[236:237], s[58:59], 0, v[132:133]
	s_mov_b32 m0, s67
	s_nop 0
	global_load_lds_dwordx4 v[236:237], off
	s_waitcnt vmcnt(8)
	s_waitcnt lgkmcnt(0)
	.p2align 3
	s_setprio 1
	s_barrier
	v_mfma_f32_16x16x32_bf16 v[124:127], v[162:165], v[198:201], v[124:127]
	v_mfma_f32_16x16x32_bf16 v[124:127], v[166:169], v[202:205], v[124:127]
	v_mfma_f32_16x16x32_bf16 v[120:123], v[174:177], v[202:205], v[120:123]
	v_mfma_f32_16x16x32_bf16 v[120:123], v[170:173], v[198:201], v[120:123]
	v_mfma_f32_16x16x32_bf16 v[104:107], v[170:173], v[206:209], v[104:107]
	v_mfma_f32_16x16x32_bf16 v[104:107], v[174:177], v[210:213], v[104:107]
	v_mfma_f32_16x16x32_bf16 v[112:115], v[166:169], v[210:213], v[112:115]
	v_mfma_f32_16x16x32_bf16 v[112:115], v[162:165], v[206:209], v[112:115]
	v_mfma_f32_16x16x32_bf16 v[96:99], v[162:165], v[214:217], v[96:99]
	v_mfma_f32_16x16x32_bf16 v[96:99], v[166:169], v[218:221], v[96:99]
	v_mfma_f32_16x16x32_bf16 v[88:91], v[174:177], v[218:221], v[88:91]
	v_mfma_f32_16x16x32_bf16 v[88:91], v[170:173], v[214:217], v[88:91]
	v_mfma_f32_16x16x32_bf16 v[72:75], v[170:173], v[222:225], v[72:75]
	v_mfma_f32_16x16x32_bf16 v[72:75], v[174:177], v[226:229], v[72:75]
	v_mfma_f32_16x16x32_bf16 v[80:83], v[166:169], v[226:229], v[80:83]
	v_mfma_f32_16x16x32_bf16 v[80:83], v[162:165], v[222:225], v[80:83]
	s_setprio 0
	s_setprio 1
	v_mfma_f32_16x16x32_bf16 v[116:119], v[178:181], v[198:201], v[116:119]
	v_mfma_f32_16x16x32_bf16 v[116:119], v[186:189], v[202:205], v[116:119]
	v_mfma_f32_16x16x32_bf16 v[108:111], v[194:197], v[202:205], v[108:111]
	v_mfma_f32_16x16x32_bf16 v[108:111], v[190:193], v[198:201], v[108:111]
	v_mfma_f32_16x16x32_bf16 v[92:95], v[190:193], v[206:209], v[92:95]
	v_mfma_f32_16x16x32_bf16 v[92:95], v[194:197], v[210:213], v[92:95]
	v_mfma_f32_16x16x32_bf16 v[100:103], v[186:189], v[210:213], v[100:103]
	v_mfma_f32_16x16x32_bf16 v[100:103], v[178:181], v[206:209], v[100:103]
	v_mfma_f32_16x16x32_bf16 v[84:87], v[178:181], v[214:217], v[84:87]
	v_mfma_f32_16x16x32_bf16 v[84:87], v[186:189], v[218:221], v[84:87]
	v_mfma_f32_16x16x32_bf16 v[76:79], v[194:197], v[218:221], v[76:79]
	v_mfma_f32_16x16x32_bf16 v[76:79], v[190:193], v[214:217], v[76:79]
	v_mfma_f32_16x16x32_bf16 v[64:67], v[190:193], v[222:225], v[64:67]
	v_mfma_f32_16x16x32_bf16 v[64:67], v[194:197], v[226:229], v[64:67]
	v_mfma_f32_16x16x32_bf16 v[68:71], v[186:189], v[226:229], v[68:71]
	v_mfma_f32_16x16x32_bf16 v[68:71], v[178:181], v[222:225], v[68:71]
	s_barrier
	s_setprio 0
	s_add_i32 s58, s86, s63
	v_lshl_add_u64 v[182:183], v[182:183], 0, s[22:23]
	s_mov_b32 m0, s58
	ds_read_b128 v[198:201], v154 offset:49152
	v_xor_b32_e32 v253, 64, v154
	ds_read_b128 v[202:205], v253 offset:49152
	ds_read_b128 v[206:209], v154 offset:51200
	ds_read_b128 v[210:213], v253 offset:51200
	ds_read_b128 v[214:217], v154 offset:53248
	ds_read_b128 v[218:221], v253 offset:53248
	ds_read_b128 v[222:225], v154 offset:55296
	ds_read_b128 v[226:229], v253 offset:55296
	global_load_lds_dwordx4 v[182:183], off
	s_add_i32 m0, s58, 0x2000
	s_add_u32 s56, s56, 0x40080
	v_lshl_add_u64 v[182:183], v[230:231], 0, s[22:23]
	s_addc_u32 s57, s57, 0
	s_add_i32 s58, s87, s63
	global_load_lds_dwordx4 v[182:183], off
	v_lshl_add_u64 v[182:183], s[56:57], 0, v[130:131]
	s_mov_b32 m0, s58
	s_nop 0
	global_load_lds_dwordx4 v[182:183], off
	v_lshl_add_u64 v[182:183], s[56:57], 0, v[134:135]
	s_add_i32 m0, s58, 0x2000
	s_nop 0
	global_load_lds_dwordx4 v[182:183], off
	v_lshl_add_u64 v[182:183], v[232:233], 0, s[22:23]
	s_mov_b32 m0, s69
	s_nop 0
	global_load_lds_dwordx4 v[182:183], off
	v_lshl_add_u64 v[182:183], v[234:235], 0, s[22:23]
	s_mov_b32 m0, s70
	s_nop 0
	global_load_lds_dwordx4 v[182:183], off
	s_waitcnt vmcnt(8)
	s_waitcnt lgkmcnt(0)
	.p2align 3
	s_setprio 1
	s_barrier
	v_mfma_f32_16x16x32_bf16 v[60:63], v[162:165], v[198:201], v[60:63]
	v_mfma_f32_16x16x32_bf16 v[60:63], v[166:169], v[202:205], v[60:63]
	v_mfma_f32_16x16x32_bf16 v[56:59], v[174:177], v[202:205], v[56:59]
	v_mfma_f32_16x16x32_bf16 v[56:59], v[170:173], v[198:201], v[56:59]
	v_mfma_f32_16x16x32_bf16 v[40:43], v[170:173], v[206:209], v[40:43]
	v_mfma_f32_16x16x32_bf16 v[40:43], v[174:177], v[210:213], v[40:43]
	v_mfma_f32_16x16x32_bf16 v[48:51], v[166:169], v[210:213], v[48:51]
	v_mfma_f32_16x16x32_bf16 v[48:51], v[162:165], v[206:209], v[48:51]
	v_mfma_f32_16x16x32_bf16 v[32:35], v[162:165], v[214:217], v[32:35]
	v_mfma_f32_16x16x32_bf16 v[32:35], v[166:169], v[218:221], v[32:35]
	v_mfma_f32_16x16x32_bf16 v[24:27], v[174:177], v[218:221], v[24:27]
	v_mfma_f32_16x16x32_bf16 v[24:27], v[170:173], v[214:217], v[24:27]
	v_mfma_f32_16x16x32_bf16 v[8:11], v[170:173], v[222:225], v[8:11]
	v_mfma_f32_16x16x32_bf16 v[8:11], v[174:177], v[226:229], v[8:11]
	v_mfma_f32_16x16x32_bf16 v[16:19], v[166:169], v[226:229], v[16:19]
	v_mfma_f32_16x16x32_bf16 v[16:19], v[162:165], v[222:225], v[16:19]
	s_setprio 0
	s_setprio 1
	v_mfma_f32_16x16x32_bf16 v[52:55], v[178:181], v[198:201], v[52:55]
	v_mfma_f32_16x16x32_bf16 v[52:55], v[186:189], v[202:205], v[52:55]
	v_mfma_f32_16x16x32_bf16 v[44:47], v[194:197], v[202:205], v[44:47]
	v_mfma_f32_16x16x32_bf16 v[44:47], v[190:193], v[198:201], v[44:47]
	v_mfma_f32_16x16x32_bf16 v[28:31], v[190:193], v[206:209], v[28:31]
	v_mfma_f32_16x16x32_bf16 v[28:31], v[194:197], v[210:213], v[28:31]
	v_mfma_f32_16x16x32_bf16 v[36:39], v[186:189], v[210:213], v[36:39]
	v_mfma_f32_16x16x32_bf16 v[36:39], v[178:181], v[206:209], v[36:39]
	v_mfma_f32_16x16x32_bf16 v[20:23], v[178:181], v[214:217], v[20:23]
	v_mfma_f32_16x16x32_bf16 v[20:23], v[186:189], v[218:221], v[20:23]
	v_mfma_f32_16x16x32_bf16 v[12:15], v[194:197], v[218:221], v[12:15]
	v_mfma_f32_16x16x32_bf16 v[12:15], v[190:193], v[214:217], v[12:15]
	v_mfma_f32_16x16x32_bf16 v[0:3], v[190:193], v[222:225], v[0:3]
	v_mfma_f32_16x16x32_bf16 v[0:3], v[194:197], v[226:229], v[0:3]
	v_mfma_f32_16x16x32_bf16 v[4:7], v[186:189], v[226:229], v[4:7]
	v_mfma_f32_16x16x32_bf16 v[4:7], v[178:181], v[222:225], v[4:7]
	s_barrier
	s_setprio 0
	s_add_i32 s85, s85, 2
	s_add_u32 s83, s83, 0x100
	s_addc_u32 s84, s84, 0
	s_add_u32 s54, s54, 0x100
	s_addc_u32 s55, s55, 0
	s_branch .LBB0_875
.LBB0_874:
	v_add_u32_e32 v146, s73, v149
	ds_read_b128 v[162:165], v146
	v_xor_b32_e32 v253, 64, v146
	ds_read_b128 v[166:169], v253
	ds_read_b128 v[170:173], v146 offset:2048
	ds_read_b128 v[174:177], v253 offset:2048
	v_add_u32_e32 v146, s74, v149
	ds_read_b128 v[178:181], v146
	v_xor_b32_e32 v253, 64, v146
	ds_read_b128 v[186:189], v253
	ds_read_b128 v[190:193], v146 offset:2048
	ds_read_b128 v[194:197], v253 offset:2048
	s_add_u32 s58, s54, 0xfffc0080
	s_addc_u32 s59, s55, -1
	s_and_b64 s[56:57], s[56:57], exec
	s_cselect_b32 s59, s49, s59
	s_cselect_b32 s58, s80, s58
	s_cselect_b32 s57, s81, s84
	s_cselect_b32 s56, s82, s83
	v_lshl_add_u64 v[182:183], s[54:55], 0, v[138:139]
	s_add_i32 m0, s64, 0xc000
	ds_read_b128 v[198:201], v154
	v_xor_b32_e32 v253, 64, v154
	ds_read_b128 v[202:205], v253
	ds_read_b128 v[206:209], v154 offset:2048
	ds_read_b128 v[210:213], v253 offset:2048
	ds_read_b128 v[214:217], v154 offset:4096
	ds_read_b128 v[218:221], v253 offset:4096
	ds_read_b128 v[222:225], v154 offset:6144
	ds_read_b128 v[226:229], v253 offset:6144
	global_load_lds_dwordx4 v[182:183], off
	v_lshl_add_u64 v[182:183], s[54:55], 0, v[136:137]
	s_add_i32 m0, s64, 0xe000
	s_nop 0
	global_load_lds_dwordx4 v[182:183], off
	s_waitcnt vmcnt(8)
	s_waitcnt lgkmcnt(0)
	.p2align 3
	s_setprio 1
	s_barrier
	v_mfma_f32_16x16x32_bf16 v[124:127], v[162:165], v[198:201], v[124:127]
	v_mfma_f32_16x16x32_bf16 v[124:127], v[166:169], v[202:205], v[124:127]
	v_mfma_f32_16x16x32_bf16 v[120:123], v[174:177], v[202:205], v[120:123]
	v_mfma_f32_16x16x32_bf16 v[120:123], v[170:173], v[198:201], v[120:123]
	v_mfma_f32_16x16x32_bf16 v[104:107], v[170:173], v[206:209], v[104:107]
	v_mfma_f32_16x16x32_bf16 v[104:107], v[174:177], v[210:213], v[104:107]
	v_mfma_f32_16x16x32_bf16 v[112:115], v[166:169], v[210:213], v[112:115]
	v_mfma_f32_16x16x32_bf16 v[112:115], v[162:165], v[206:209], v[112:115]
	v_mfma_f32_16x16x32_bf16 v[96:99], v[162:165], v[214:217], v[96:99]
	v_mfma_f32_16x16x32_bf16 v[96:99], v[166:169], v[218:221], v[96:99]
	v_mfma_f32_16x16x32_bf16 v[88:91], v[174:177], v[218:221], v[88:91]
	v_mfma_f32_16x16x32_bf16 v[88:91], v[170:173], v[214:217], v[88:91]
	v_mfma_f32_16x16x32_bf16 v[72:75], v[170:173], v[222:225], v[72:75]
	v_mfma_f32_16x16x32_bf16 v[72:75], v[174:177], v[226:229], v[72:75]
	v_mfma_f32_16x16x32_bf16 v[80:83], v[166:169], v[226:229], v[80:83]
	v_mfma_f32_16x16x32_bf16 v[80:83], v[162:165], v[222:225], v[80:83]
	s_setprio 0
	s_setprio 1
	v_mfma_f32_16x16x32_bf16 v[116:119], v[178:181], v[198:201], v[116:119]
	v_mfma_f32_16x16x32_bf16 v[116:119], v[186:189], v[202:205], v[116:119]
	v_mfma_f32_16x16x32_bf16 v[108:111], v[194:197], v[202:205], v[108:111]
	v_mfma_f32_16x16x32_bf16 v[108:111], v[190:193], v[198:201], v[108:111]
	v_mfma_f32_16x16x32_bf16 v[92:95], v[190:193], v[206:209], v[92:95]
	v_mfma_f32_16x16x32_bf16 v[92:95], v[194:197], v[210:213], v[92:95]
	v_mfma_f32_16x16x32_bf16 v[100:103], v[186:189], v[210:213], v[100:103]
	v_mfma_f32_16x16x32_bf16 v[100:103], v[178:181], v[206:209], v[100:103]
	v_mfma_f32_16x16x32_bf16 v[84:87], v[178:181], v[214:217], v[84:87]
	v_mfma_f32_16x16x32_bf16 v[84:87], v[186:189], v[218:221], v[84:87]
	v_mfma_f32_16x16x32_bf16 v[76:79], v[194:197], v[218:221], v[76:79]
	v_mfma_f32_16x16x32_bf16 v[76:79], v[190:193], v[214:217], v[76:79]
	v_mfma_f32_16x16x32_bf16 v[64:67], v[190:193], v[222:225], v[64:67]
	v_mfma_f32_16x16x32_bf16 v[64:67], v[194:197], v[226:229], v[64:67]
	v_mfma_f32_16x16x32_bf16 v[68:71], v[186:189], v[226:229], v[68:71]
	v_mfma_f32_16x16x32_bf16 v[68:71], v[178:181], v[222:225], v[68:71]
	s_barrier
	s_setprio 0
	s_add_i32 s86, s73, s63
	v_lshl_add_u64 v[182:183], s[56:57], 0, v[130:131]
	s_mov_b32 m0, s86
	ds_read_b128 v[198:201], v154 offset:16384
	v_xor_b32_e32 v253, 64, v154
	ds_read_b128 v[202:205], v253 offset:16384
	ds_read_b128 v[206:209], v154 offset:18432
	ds_read_b128 v[210:213], v253 offset:18432
	ds_read_b128 v[214:217], v154 offset:20480
	ds_read_b128 v[218:221], v253 offset:20480
	ds_read_b128 v[222:225], v154 offset:22528
	ds_read_b128 v[226:229], v253 offset:22528
	global_load_lds_dwordx4 v[182:183], off
	s_add_i32 m0, s86, 0x2000
	s_add_u32 s86, s56, 0x40000
	v_lshl_add_u64 v[230:231], s[56:57], 0, v[134:135]
	s_addc_u32 s87, s57, 0
	s_add_i32 s88, s74, s63
	global_load_lds_dwordx4 v[230:231], off
	v_lshl_add_u64 v[232:233], s[86:87], 0, v[130:131]
	s_mov_b32 m0, s88
	v_lshl_add_u64 v[234:235], s[58:59], 0, v[132:133]
	global_load_lds_dwordx4 v[232:233], off
	v_lshl_add_u64 v[232:233], s[86:87], 0, v[134:135]
	s_add_i32 m0, s88, 0x2000
	s_nop 0
	global_load_lds_dwordx4 v[232:233], off
	v_lshl_add_u64 v[232:233], s[58:59], 0, v[128:129]
	s_mov_b32 m0, s64
	s_nop 0
	global_load_lds_dwordx4 v[232:233], off
	s_mov_b32 m0, s65
	s_nop 0
	global_load_lds_dwordx4 v[234:235], off
	s_waitcnt vmcnt(8)
	s_waitcnt lgkmcnt(0)
	.p2align 3
	s_setprio 1
	s_barrier
	v_mfma_f32_16x16x32_bf16 v[60:63], v[162:165], v[198:201], v[60:63]
	v_mfma_f32_16x16x32_bf16 v[60:63], v[166:169], v[202:205], v[60:63]
	v_mfma_f32_16x16x32_bf16 v[56:59], v[174:177], v[202:205], v[56:59]
	v_mfma_f32_16x16x32_bf16 v[56:59], v[170:173], v[198:201], v[56:59]
	v_mfma_f32_16x16x32_bf16 v[40:43], v[170:173], v[206:209], v[40:43]
	v_mfma_f32_16x16x32_bf16 v[40:43], v[174:177], v[210:213], v[40:43]
	v_mfma_f32_16x16x32_bf16 v[48:51], v[166:169], v[210:213], v[48:51]
	v_mfma_f32_16x16x32_bf16 v[48:51], v[162:165], v[206:209], v[48:51]
	v_mfma_f32_16x16x32_bf16 v[32:35], v[162:165], v[214:217], v[32:35]
	v_mfma_f32_16x16x32_bf16 v[32:35], v[166:169], v[218:221], v[32:35]
	v_mfma_f32_16x16x32_bf16 v[24:27], v[174:177], v[218:221], v[24:27]
	v_mfma_f32_16x16x32_bf16 v[24:27], v[170:173], v[214:217], v[24:27]
	v_mfma_f32_16x16x32_bf16 v[8:11], v[170:173], v[222:225], v[8:11]
	v_mfma_f32_16x16x32_bf16 v[8:11], v[174:177], v[226:229], v[8:11]
	v_mfma_f32_16x16x32_bf16 v[16:19], v[166:169], v[226:229], v[16:19]
	v_mfma_f32_16x16x32_bf16 v[16:19], v[162:165], v[222:225], v[16:19]
	s_setprio 0
	s_setprio 1
	v_mfma_f32_16x16x32_bf16 v[52:55], v[178:181], v[198:201], v[52:55]
	v_mfma_f32_16x16x32_bf16 v[52:55], v[186:189], v[202:205], v[52:55]
	v_mfma_f32_16x16x32_bf16 v[44:47], v[194:197], v[202:205], v[44:47]
	v_mfma_f32_16x16x32_bf16 v[44:47], v[190:193], v[198:201], v[44:47]
	v_mfma_f32_16x16x32_bf16 v[28:31], v[190:193], v[206:209], v[28:31]
	v_mfma_f32_16x16x32_bf16 v[28:31], v[194:197], v[210:213], v[28:31]
	v_mfma_f32_16x16x32_bf16 v[36:39], v[186:189], v[210:213], v[36:39]
	v_mfma_f32_16x16x32_bf16 v[36:39], v[178:181], v[206:209], v[36:39]
	v_mfma_f32_16x16x32_bf16 v[20:23], v[178:181], v[214:217], v[20:23]
	v_mfma_f32_16x16x32_bf16 v[20:23], v[186:189], v[218:221], v[20:23]
	v_mfma_f32_16x16x32_bf16 v[12:15], v[194:197], v[218:221], v[12:15]
	v_mfma_f32_16x16x32_bf16 v[12:15], v[190:193], v[214:217], v[12:15]
	v_mfma_f32_16x16x32_bf16 v[0:3], v[190:193], v[222:225], v[0:3]
	v_mfma_f32_16x16x32_bf16 v[0:3], v[194:197], v[226:229], v[0:3]
	v_mfma_f32_16x16x32_bf16 v[4:7], v[186:189], v[226:229], v[4:7]
	v_mfma_f32_16x16x32_bf16 v[4:7], v[178:181], v[222:225], v[4:7]
	s_barrier
	s_setprio 0
	s_add_i32 s86, 0, 0x18000
	v_add_u32_e32 v146, s86, v149
	s_add_i32 s87, 0, 0x1c000
	ds_read_b128 v[162:165], v146
	v_xor_b32_e32 v253, 64, v146
	ds_read_b128 v[166:169], v253
	ds_read_b128 v[170:173], v146 offset:2048
	ds_read_b128 v[174:177], v253 offset:2048
	v_add_u32_e32 v146, s87, v149
	ds_read_b128 v[178:181], v146
	v_xor_b32_e32 v253, 64, v146
	ds_read_b128 v[186:189], v253
	ds_read_b128 v[190:193], v146 offset:2048
	ds_read_b128 v[194:197], v253 offset:2048
	s_add_u32 s58, s58, 0x40000
	s_addc_u32 s59, s59, 0
	s_mov_b32 m0, s66
	v_lshl_add_u64 v[236:237], s[58:59], 0, v[128:129]
	ds_read_b128 v[198:201], v154 offset:32768
	v_xor_b32_e32 v253, 64, v154
	ds_read_b128 v[202:205], v253 offset:32768
	ds_read_b128 v[206:209], v154 offset:34816
	ds_read_b128 v[210:213], v253 offset:34816
	ds_read_b128 v[214:217], v154 offset:36864
	ds_read_b128 v[218:221], v253 offset:36864
	ds_read_b128 v[222:225], v154 offset:38912
	ds_read_b128 v[226:229], v253 offset:38912
	global_load_lds_dwordx4 v[236:237], off
	v_lshl_add_u64 v[236:237], s[58:59], 0, v[132:133]
	s_mov_b32 m0, s67
	s_nop 0
	global_load_lds_dwordx4 v[236:237], off
	s_waitcnt vmcnt(8)
	s_waitcnt lgkmcnt(0)
	.p2align 3
	s_setprio 1
	s_barrier
	v_mfma_f32_16x16x32_bf16 v[124:127], v[162:165], v[198:201], v[124:127]
	v_mfma_f32_16x16x32_bf16 v[124:127], v[166:169], v[202:205], v[124:127]
	v_mfma_f32_16x16x32_bf16 v[120:123], v[174:177], v[202:205], v[120:123]
	v_mfma_f32_16x16x32_bf16 v[120:123], v[170:173], v[198:201], v[120:123]
	v_mfma_f32_16x16x32_bf16 v[104:107], v[170:173], v[206:209], v[104:107]
	v_mfma_f32_16x16x32_bf16 v[104:107], v[174:177], v[210:213], v[104:107]
	v_mfma_f32_16x16x32_bf16 v[112:115], v[166:169], v[210:213], v[112:115]
	v_mfma_f32_16x16x32_bf16 v[112:115], v[162:165], v[206:209], v[112:115]
	v_mfma_f32_16x16x32_bf16 v[96:99], v[162:165], v[214:217], v[96:99]
	v_mfma_f32_16x16x32_bf16 v[96:99], v[166:169], v[218:221], v[96:99]
	v_mfma_f32_16x16x32_bf16 v[88:91], v[174:177], v[218:221], v[88:91]
	v_mfma_f32_16x16x32_bf16 v[88:91], v[170:173], v[214:217], v[88:91]
	v_mfma_f32_16x16x32_bf16 v[72:75], v[170:173], v[222:225], v[72:75]
	v_mfma_f32_16x16x32_bf16 v[72:75], v[174:177], v[226:229], v[72:75]
	v_mfma_f32_16x16x32_bf16 v[80:83], v[166:169], v[226:229], v[80:83]
	v_mfma_f32_16x16x32_bf16 v[80:83], v[162:165], v[222:225], v[80:83]
	s_setprio 0
	s_setprio 1
	v_mfma_f32_16x16x32_bf16 v[116:119], v[178:181], v[198:201], v[116:119]
	v_mfma_f32_16x16x32_bf16 v[116:119], v[186:189], v[202:205], v[116:119]
	v_mfma_f32_16x16x32_bf16 v[108:111], v[194:197], v[202:205], v[108:111]
	v_mfma_f32_16x16x32_bf16 v[108:111], v[190:193], v[198:201], v[108:111]
	v_mfma_f32_16x16x32_bf16 v[92:95], v[190:193], v[206:209], v[92:95]
	v_mfma_f32_16x16x32_bf16 v[92:95], v[194:197], v[210:213], v[92:95]
	v_mfma_f32_16x16x32_bf16 v[100:103], v[186:189], v[210:213], v[100:103]
	v_mfma_f32_16x16x32_bf16 v[100:103], v[178:181], v[206:209], v[100:103]
	v_mfma_f32_16x16x32_bf16 v[84:87], v[178:181], v[214:217], v[84:87]
	v_mfma_f32_16x16x32_bf16 v[84:87], v[186:189], v[218:221], v[84:87]
	v_mfma_f32_16x16x32_bf16 v[76:79], v[194:197], v[218:221], v[76:79]
	v_mfma_f32_16x16x32_bf16 v[76:79], v[190:193], v[214:217], v[76:79]
	v_mfma_f32_16x16x32_bf16 v[64:67], v[190:193], v[222:225], v[64:67]
	v_mfma_f32_16x16x32_bf16 v[64:67], v[194:197], v[226:229], v[64:67]
	v_mfma_f32_16x16x32_bf16 v[68:71], v[186:189], v[226:229], v[68:71]
	v_mfma_f32_16x16x32_bf16 v[68:71], v[178:181], v[222:225], v[68:71]
	s_barrier
	s_setprio 0
	s_add_i32 s58, s86, s63
	v_lshl_add_u64 v[182:183], v[182:183], 0, s[22:23]
	s_mov_b32 m0, s58
	ds_read_b128 v[198:201], v154 offset:49152
	v_xor_b32_e32 v253, 64, v154
	ds_read_b128 v[202:205], v253 offset:49152
	ds_read_b128 v[206:209], v154 offset:51200
	ds_read_b128 v[210:213], v253 offset:51200
	ds_read_b128 v[214:217], v154 offset:53248
	ds_read_b128 v[218:221], v253 offset:53248
	ds_read_b128 v[222:225], v154 offset:55296
	ds_read_b128 v[226:229], v253 offset:55296
	global_load_lds_dwordx4 v[182:183], off
	s_add_i32 m0, s58, 0x2000
	s_add_u32 s56, s56, 0x40080
	v_lshl_add_u64 v[182:183], v[230:231], 0, s[22:23]
	s_addc_u32 s57, s57, 0
	s_add_i32 s58, s87, s63
	global_load_lds_dwordx4 v[182:183], off
	v_lshl_add_u64 v[182:183], s[56:57], 0, v[130:131]
	s_mov_b32 m0, s58
	s_nop 0
	global_load_lds_dwordx4 v[182:183], off
	v_lshl_add_u64 v[182:183], s[56:57], 0, v[134:135]
	s_add_i32 m0, s58, 0x2000
	s_nop 0
	global_load_lds_dwordx4 v[182:183], off
	v_lshl_add_u64 v[182:183], v[232:233], 0, s[22:23]
	s_mov_b32 m0, s69
	s_nop 0
	global_load_lds_dwordx4 v[182:183], off
	v_lshl_add_u64 v[182:183], v[234:235], 0, s[22:23]
	s_mov_b32 m0, s70
	s_nop 0
	global_load_lds_dwordx4 v[182:183], off
	s_waitcnt vmcnt(8)
	s_waitcnt lgkmcnt(0)
	.p2align 3
	s_setprio 1
	s_barrier
	v_mfma_f32_16x16x32_bf16 v[60:63], v[162:165], v[198:201], v[60:63]
	v_mfma_f32_16x16x32_bf16 v[60:63], v[166:169], v[202:205], v[60:63]
	v_mfma_f32_16x16x32_bf16 v[56:59], v[174:177], v[202:205], v[56:59]
	v_mfma_f32_16x16x32_bf16 v[56:59], v[170:173], v[198:201], v[56:59]
	v_mfma_f32_16x16x32_bf16 v[40:43], v[170:173], v[206:209], v[40:43]
	v_mfma_f32_16x16x32_bf16 v[40:43], v[174:177], v[210:213], v[40:43]
	v_mfma_f32_16x16x32_bf16 v[48:51], v[166:169], v[210:213], v[48:51]
	v_mfma_f32_16x16x32_bf16 v[48:51], v[162:165], v[206:209], v[48:51]
	v_mfma_f32_16x16x32_bf16 v[32:35], v[162:165], v[214:217], v[32:35]
	v_mfma_f32_16x16x32_bf16 v[32:35], v[166:169], v[218:221], v[32:35]
	v_mfma_f32_16x16x32_bf16 v[24:27], v[174:177], v[218:221], v[24:27]
	v_mfma_f32_16x16x32_bf16 v[24:27], v[170:173], v[214:217], v[24:27]
	v_mfma_f32_16x16x32_bf16 v[8:11], v[170:173], v[222:225], v[8:11]
	v_mfma_f32_16x16x32_bf16 v[8:11], v[174:177], v[226:229], v[8:11]
	v_mfma_f32_16x16x32_bf16 v[16:19], v[166:169], v[226:229], v[16:19]
	v_mfma_f32_16x16x32_bf16 v[16:19], v[162:165], v[222:225], v[16:19]
	s_setprio 0
	s_setprio 1
	v_mfma_f32_16x16x32_bf16 v[52:55], v[178:181], v[198:201], v[52:55]
	v_mfma_f32_16x16x32_bf16 v[52:55], v[186:189], v[202:205], v[52:55]
	v_mfma_f32_16x16x32_bf16 v[44:47], v[194:197], v[202:205], v[44:47]
	v_mfma_f32_16x16x32_bf16 v[44:47], v[190:193], v[198:201], v[44:47]
	v_mfma_f32_16x16x32_bf16 v[28:31], v[190:193], v[206:209], v[28:31]
	v_mfma_f32_16x16x32_bf16 v[28:31], v[194:197], v[210:213], v[28:31]
	v_mfma_f32_16x16x32_bf16 v[36:39], v[186:189], v[210:213], v[36:39]
	v_mfma_f32_16x16x32_bf16 v[36:39], v[178:181], v[206:209], v[36:39]
	v_mfma_f32_16x16x32_bf16 v[20:23], v[178:181], v[214:217], v[20:23]
	v_mfma_f32_16x16x32_bf16 v[20:23], v[186:189], v[218:221], v[20:23]
	v_mfma_f32_16x16x32_bf16 v[12:15], v[194:197], v[218:221], v[12:15]
	v_mfma_f32_16x16x32_bf16 v[12:15], v[190:193], v[214:217], v[12:15]
	v_mfma_f32_16x16x32_bf16 v[0:3], v[190:193], v[222:225], v[0:3]
	v_mfma_f32_16x16x32_bf16 v[0:3], v[194:197], v[226:229], v[0:3]
	v_mfma_f32_16x16x32_bf16 v[4:7], v[186:189], v[226:229], v[4:7]
	v_mfma_f32_16x16x32_bf16 v[4:7], v[178:181], v[222:225], v[4:7]
	s_barrier
	s_setprio 0
	s_add_i32 s85, s85, 2
	s_add_u32 s83, s83, 0x100
	s_addc_u32 s84, s84, 0
	s_add_u32 s54, s54, 0x100
	s_addc_u32 s55, s55, 0
	s_cmp_gt_u32 s85, 13
	s_cbranch_scc1 .LBB0_877

.LBB0_1010:
	s_ashr_i32 s51, s50, 31
	s_lshl_b64 s[52:53], s[50:51], 19
	s_add_u32 s52, s33, s52
	s_addc_u32 s53, s35, s53
	s_and_b64 s[54:55], s[12:13], exec
	s_cselect_b32 s15, s53, s61
	s_cselect_b32 s51, s52, s60
	s_ashr_i32 s49, s48, 31
	s_lshl_b64 s[54:55], s[48:49], 19
	s_add_u32 s54, s64, s54
	s_addc_u32 s55, s65, s55
	s_and_b64 s[62:63], s[12:13], exec
	s_cselect_b32 s49, s55, s59
	s_cselect_b32 s57, s54, s58
	s_add_u32 s78, s58, 0x100
	s_addc_u32 s79, s59, 0
	s_add_u32 s58, s60, 0x40080
	s_addc_u32 s59, s61, 0
	s_mov_b32 s80, -2
	s_waitcnt lgkmcnt(0)
	s_cmp_eq_u32 s71, 1
	s_cbranch_scc1 .Lfa_9
	ds_read_b128 v[128:131], v188
	v_xor_b32_e32 v253, 64, v188
	ds_read_b128 v[132:135], v253
	ds_read_b128 v[136:139], v188 offset:2048
	ds_read_b128 v[140:143], v253 offset:2048
	ds_read_b128 v[144:147], v189
	v_xor_b32_e32 v253, 64, v189
	ds_read_b128 v[148:151], v253
	ds_read_b128 v[172:175], v189 offset:2048
	ds_read_b128 v[176:179], v253 offset:2048
	s_add_u32 s60, s58, 0xfffc0080
	s_addc_u32 s61, s59, -1
	s_cmp_eq_u32 s80, 12
	s_cselect_b32 s63, s15, s61
	s_cselect_b32 s62, s51, s60
	s_cselect_b32 s61, s49, s79
	s_cselect_b32 s60, s57, s78
	v_lshl_add_u64 v[220:221], s[58:59], 0, v[166:167]
	s_add_i32 m0, s67, 0xc000
	ds_read_b128 v[180:183], v190
	v_xor_b32_e32 v253, 64, v190
	ds_read_b128 v[192:195], v253
	ds_read_b128 v[196:199], v190 offset:2048
	ds_read_b128 v[200:203], v253 offset:2048
	ds_read_b128 v[204:207], v190 offset:4096
	ds_read_b128 v[208:211], v253 offset:4096
	ds_read_b128 v[212:215], v190 offset:6144
	ds_read_b128 v[216:219], v253 offset:6144
	global_load_lds_dwordx4 v[220:221], off
	v_lshl_add_u64 v[220:221], s[58:59], 0, v[164:165]
	s_add_i32 m0, s67, 0xe000
	s_nop 0
	global_load_lds_dwordx4 v[220:221], off
	s_waitcnt vmcnt(24)
	s_waitcnt lgkmcnt(0)
	.p2align 3
	s_setprio 1
	s_barrier
	v_mfma_f32_16x16x32_bf16 v[124:127], v[128:131], v[180:183], 0
	v_mfma_f32_16x16x32_bf16 v[120:123], v[136:139], v[180:183], 0
	v_mfma_f32_16x16x32_bf16 v[108:111], v[128:131], v[196:199], 0
	v_mfma_f32_16x16x32_bf16 v[104:107], v[136:139], v[196:199], 0
	v_mfma_f32_16x16x32_bf16 v[92:95], v[128:131], v[204:207], 0
	v_mfma_f32_16x16x32_bf16 v[88:91], v[136:139], v[204:207], 0
	v_mfma_f32_16x16x32_bf16 v[76:79], v[128:131], v[212:215], 0
	v_mfma_f32_16x16x32_bf16 v[72:75], v[136:139], v[212:215], 0
	v_mfma_f32_16x16x32_bf16 v[124:127], v[132:135], v[192:195], v[124:127]
	v_mfma_f32_16x16x32_bf16 v[120:123], v[140:143], v[192:195], v[120:123]
	v_mfma_f32_16x16x32_bf16 v[108:111], v[132:135], v[200:203], v[108:111]
	v_mfma_f32_16x16x32_bf16 v[104:107], v[140:143], v[200:203], v[104:107]
	v_mfma_f32_16x16x32_bf16 v[92:95], v[132:135], v[208:211], v[92:95]
	v_mfma_f32_16x16x32_bf16 v[88:91], v[140:143], v[208:211], v[88:91]
	v_mfma_f32_16x16x32_bf16 v[76:79], v[132:135], v[216:219], v[76:79]
	v_mfma_f32_16x16x32_bf16 v[72:75], v[140:143], v[216:219], v[72:75]
	s_setprio 0
	s_setprio 1
	v_mfma_f32_16x16x32_bf16 v[116:119], v[144:147], v[180:183], 0
	v_mfma_f32_16x16x32_bf16 v[112:115], v[172:175], v[180:183], 0
	v_mfma_f32_16x16x32_bf16 v[100:103], v[144:147], v[196:199], 0
	v_mfma_f32_16x16x32_bf16 v[96:99], v[172:175], v[196:199], 0
	v_mfma_f32_16x16x32_bf16 v[84:87], v[144:147], v[204:207], 0
	v_mfma_f32_16x16x32_bf16 v[80:83], v[172:175], v[204:207], 0
	v_mfma_f32_16x16x32_bf16 v[68:71], v[144:147], v[212:215], 0
	v_mfma_f32_16x16x32_bf16 v[64:67], v[172:175], v[212:215], 0
	v_mfma_f32_16x16x32_bf16 v[116:119], v[148:151], v[192:195], v[116:119]
	v_mfma_f32_16x16x32_bf16 v[112:115], v[176:179], v[192:195], v[112:115]
	v_mfma_f32_16x16x32_bf16 v[100:103], v[148:151], v[200:203], v[100:103]
	v_mfma_f32_16x16x32_bf16 v[96:99], v[176:179], v[200:203], v[96:99]
	v_mfma_f32_16x16x32_bf16 v[84:87], v[148:151], v[208:211], v[84:87]
	v_mfma_f32_16x16x32_bf16 v[80:83], v[176:179], v[208:211], v[80:83]
	v_mfma_f32_16x16x32_bf16 v[68:71], v[148:151], v[216:219], v[68:71]
	v_mfma_f32_16x16x32_bf16 v[64:67], v[176:179], v[216:219], v[64:67]
	s_barrier
	s_setprio 0
	s_add_i32 s81, s76, s66
	v_lshl_add_u64 v[220:221], s[60:61], 0, v[154:155]
	s_mov_b32 m0, s81
	ds_read_b128 v[180:183], v190 offset:16384
	v_xor_b32_e32 v253, 64, v190
	ds_read_b128 v[192:195], v253 offset:16384
	ds_read_b128 v[196:199], v190 offset:18432
	ds_read_b128 v[200:203], v253 offset:18432
	ds_read_b128 v[204:207], v190 offset:20480
	ds_read_b128 v[208:211], v253 offset:20480
	ds_read_b128 v[212:215], v190 offset:22528
	ds_read_b128 v[216:219], v253 offset:22528
	global_load_lds_dwordx4 v[220:221], off
	s_add_i32 m0, s81, 0x2000
	s_add_u32 s82, s60, 0x40000
	v_lshl_add_u64 v[222:223], s[60:61], 0, v[162:163]
	s_addc_u32 s83, s61, 0
	s_add_i32 s81, s77, s66
	global_load_lds_dwordx4 v[222:223], off
	v_lshl_add_u64 v[224:225], s[82:83], 0, v[154:155]
	s_mov_b32 m0, s81
	v_lshl_add_u64 v[226:227], s[62:63], 0, v[160:161]
	global_load_lds_dwordx4 v[224:225], off
	v_lshl_add_u64 v[224:225], s[82:83], 0, v[162:163]
	s_add_i32 m0, s81, 0x2000
	s_nop 0
	global_load_lds_dwordx4 v[224:225], off
	v_lshl_add_u64 v[224:225], s[62:63], 0, v[152:153]
	s_mov_b32 m0, s67
	s_nop 0
	global_load_lds_dwordx4 v[224:225], off
	s_mov_b32 m0, s68
	s_nop 0
	global_load_lds_dwordx4 v[226:227], off
	s_waitcnt vmcnt(24)
	s_waitcnt lgkmcnt(0)
	.p2align 3
	s_setprio 1
	s_barrier
	v_mfma_f32_16x16x32_bf16 v[60:63], v[128:131], v[180:183], 0
	v_mfma_f32_16x16x32_bf16 v[56:59], v[136:139], v[180:183], 0
	v_mfma_f32_16x16x32_bf16 v[44:47], v[128:131], v[196:199], 0
	v_mfma_f32_16x16x32_bf16 v[40:43], v[136:139], v[196:199], 0
	v_mfma_f32_16x16x32_bf16 v[28:31], v[128:131], v[204:207], 0
	v_mfma_f32_16x16x32_bf16 v[24:27], v[136:139], v[204:207], 0
	v_mfma_f32_16x16x32_bf16 v[12:15], v[128:131], v[212:215], 0
	v_mfma_f32_16x16x32_bf16 v[8:11], v[136:139], v[212:215], 0
	v_mfma_f32_16x16x32_bf16 v[60:63], v[132:135], v[192:195], v[60:63]
	v_mfma_f32_16x16x32_bf16 v[56:59], v[140:143], v[192:195], v[56:59]
	v_mfma_f32_16x16x32_bf16 v[44:47], v[132:135], v[200:203], v[44:47]
	v_mfma_f32_16x16x32_bf16 v[40:43], v[140:143], v[200:203], v[40:43]
	v_mfma_f32_16x16x32_bf16 v[28:31], v[132:135], v[208:211], v[28:31]
	v_mfma_f32_16x16x32_bf16 v[24:27], v[140:143], v[208:211], v[24:27]
	v_mfma_f32_16x16x32_bf16 v[12:15], v[132:135], v[216:219], v[12:15]
	v_mfma_f32_16x16x32_bf16 v[8:11], v[140:143], v[216:219], v[8:11]
	s_setprio 0
	s_setprio 1
	v_mfma_f32_16x16x32_bf16 v[52:55], v[144:147], v[180:183], 0
	v_mfma_f32_16x16x32_bf16 v[48:51], v[172:175], v[180:183], 0
	v_mfma_f32_16x16x32_bf16 v[36:39], v[144:147], v[196:199], 0
	v_mfma_f32_16x16x32_bf16 v[32:35], v[172:175], v[196:199], 0
	v_mfma_f32_16x16x32_bf16 v[20:23], v[144:147], v[204:207], 0
	v_mfma_f32_16x16x32_bf16 v[16:19], v[172:175], v[204:207], 0
	v_mfma_f32_16x16x32_bf16 v[4:7], v[144:147], v[212:215], 0
	v_mfma_f32_16x16x32_bf16 v[0:3], v[172:175], v[212:215], 0
	v_mfma_f32_16x16x32_bf16 v[52:55], v[148:151], v[192:195], v[52:55]
	v_mfma_f32_16x16x32_bf16 v[48:51], v[176:179], v[192:195], v[48:51]
	v_mfma_f32_16x16x32_bf16 v[36:39], v[148:151], v[200:203], v[36:39]
	v_mfma_f32_16x16x32_bf16 v[32:35], v[176:179], v[200:203], v[32:35]
	v_mfma_f32_16x16x32_bf16 v[20:23], v[148:151], v[208:211], v[20:23]
	v_mfma_f32_16x16x32_bf16 v[16:19], v[176:179], v[208:211], v[16:19]
	v_mfma_f32_16x16x32_bf16 v[4:7], v[148:151], v[216:219], v[4:7]
	v_mfma_f32_16x16x32_bf16 v[0:3], v[176:179], v[216:219], v[0:3]
	s_barrier
	s_setprio 0
	s_add_i32 s81, 0, 0x18000
	s_add_i32 s82, 0, 0x1c000
	v_add_u32_e32 v140, s81, v185
	v_add_u32_e32 v176, s82, v185
	ds_read_b128 v[128:131], v140
	v_xor_b32_e32 v253, 64, v140
	ds_read_b128 v[132:135], v253
	ds_read_b128 v[136:139], v140 offset:2048
	ds_read_b128 v[140:143], v253 offset:2048
	ds_read_b128 v[144:147], v176
	v_xor_b32_e32 v253, 64, v176
	ds_read_b128 v[148:151], v253
	ds_read_b128 v[172:175], v176 offset:2048
	ds_read_b128 v[176:179], v253 offset:2048
	s_add_u32 s62, s62, 0x40000
	s_addc_u32 s63, s63, 0
	s_mov_b32 m0, s69
	v_lshl_add_u64 v[228:229], s[62:63], 0, v[152:153]
	ds_read_b128 v[180:183], v190 offset:32768
	v_xor_b32_e32 v253, 64, v190
	ds_read_b128 v[192:195], v253 offset:32768
	ds_read_b128 v[196:199], v190 offset:34816
	ds_read_b128 v[200:203], v253 offset:34816
	ds_read_b128 v[204:207], v190 offset:36864
	ds_read_b128 v[208:211], v253 offset:36864
	ds_read_b128 v[212:215], v190 offset:38912
	ds_read_b128 v[216:219], v253 offset:38912
	global_load_lds_dwordx4 v[228:229], off
	v_lshl_add_u64 v[228:229], s[62:63], 0, v[160:161]
	s_mov_b32 m0, s70
	s_nop 0
	global_load_lds_dwordx4 v[228:229], off
	s_waitcnt vmcnt(8)
	s_waitcnt lgkmcnt(0)
	.p2align 3
	s_setprio 1
	s_barrier
	v_mfma_f32_16x16x32_bf16 v[124:127], v[128:131], v[180:183], v[124:127]
	v_mfma_f32_16x16x32_bf16 v[124:127], v[132:135], v[192:195], v[124:127]
	v_mfma_f32_16x16x32_bf16 v[120:123], v[140:143], v[192:195], v[120:123]
	v_mfma_f32_16x16x32_bf16 v[120:123], v[136:139], v[180:183], v[120:123]
	v_mfma_f32_16x16x32_bf16 v[104:107], v[136:139], v[196:199], v[104:107]
	v_mfma_f32_16x16x32_bf16 v[104:107], v[140:143], v[200:203], v[104:107]
	v_mfma_f32_16x16x32_bf16 v[108:111], v[132:135], v[200:203], v[108:111]
	v_mfma_f32_16x16x32_bf16 v[108:111], v[128:131], v[196:199], v[108:111]
	v_mfma_f32_16x16x32_bf16 v[92:95], v[128:131], v[204:207], v[92:95]
	v_mfma_f32_16x16x32_bf16 v[92:95], v[132:135], v[208:211], v[92:95]
	v_mfma_f32_16x16x32_bf16 v[88:91], v[140:143], v[208:211], v[88:91]
	v_mfma_f32_16x16x32_bf16 v[88:91], v[136:139], v[204:207], v[88:91]
	v_mfma_f32_16x16x32_bf16 v[72:75], v[136:139], v[212:215], v[72:75]
	v_mfma_f32_16x16x32_bf16 v[72:75], v[140:143], v[216:219], v[72:75]
	v_mfma_f32_16x16x32_bf16 v[76:79], v[132:135], v[216:219], v[76:79]
	v_mfma_f32_16x16x32_bf16 v[76:79], v[128:131], v[212:215], v[76:79]
	s_setprio 0
	s_setprio 1
	v_mfma_f32_16x16x32_bf16 v[116:119], v[144:147], v[180:183], v[116:119]
	v_mfma_f32_16x16x32_bf16 v[116:119], v[148:151], v[192:195], v[116:119]
	v_mfma_f32_16x16x32_bf16 v[112:115], v[176:179], v[192:195], v[112:115]
	v_mfma_f32_16x16x32_bf16 v[112:115], v[172:175], v[180:183], v[112:115]
	v_mfma_f32_16x16x32_bf16 v[96:99], v[172:175], v[196:199], v[96:99]
	v_mfma_f32_16x16x32_bf16 v[96:99], v[176:179], v[200:203], v[96:99]
	v_mfma_f32_16x16x32_bf16 v[100:103], v[148:151], v[200:203], v[100:103]
	v_mfma_f32_16x16x32_bf16 v[100:103], v[144:147], v[196:199], v[100:103]
	v_mfma_f32_16x16x32_bf16 v[84:87], v[144:147], v[204:207], v[84:87]
	v_mfma_f32_16x16x32_bf16 v[84:87], v[148:151], v[208:211], v[84:87]
	v_mfma_f32_16x16x32_bf16 v[80:83], v[176:179], v[208:211], v[80:83]
	v_mfma_f32_16x16x32_bf16 v[80:83], v[172:175], v[204:207], v[80:83]
	v_mfma_f32_16x16x32_bf16 v[64:67], v[172:175], v[212:215], v[64:67]
	v_mfma_f32_16x16x32_bf16 v[64:67], v[176:179], v[216:219], v[64:67]
	v_mfma_f32_16x16x32_bf16 v[68:71], v[148:151], v[216:219], v[68:71]
	v_mfma_f32_16x16x32_bf16 v[68:71], v[144:147], v[212:215], v[68:71]
	s_barrier
	s_setprio 0
	s_add_i32 s62, s81, s66
	v_lshl_add_u64 v[220:221], v[220:221], 0, s[26:27]
	s_mov_b32 m0, s62
	ds_read_b128 v[180:183], v190 offset:49152
	v_xor_b32_e32 v253, 64, v190
	ds_read_b128 v[192:195], v253 offset:49152
	ds_read_b128 v[196:199], v190 offset:51200
	ds_read_b128 v[200:203], v253 offset:51200
	ds_read_b128 v[204:207], v190 offset:53248
	ds_read_b128 v[208:211], v253 offset:53248
	ds_read_b128 v[212:215], v190 offset:55296
	ds_read_b128 v[216:219], v253 offset:55296
	global_load_lds_dwordx4 v[220:221], off
	s_add_i32 m0, s62, 0x2000
	s_add_u32 s60, s60, 0x40080
	v_lshl_add_u64 v[220:221], v[222:223], 0, s[26:27]
	s_addc_u32 s61, s61, 0
	s_add_i32 s62, s82, s66
	global_load_lds_dwordx4 v[220:221], off
	v_lshl_add_u64 v[220:221], s[60:61], 0, v[154:155]
	s_mov_b32 m0, s62
	s_nop 0
	global_load_lds_dwordx4 v[220:221], off
	v_lshl_add_u64 v[220:221], s[60:61], 0, v[162:163]
	s_add_i32 m0, s62, 0x2000
	s_nop 0
	global_load_lds_dwordx4 v[220:221], off
	v_lshl_add_u64 v[220:221], v[224:225], 0, s[26:27]
	s_mov_b32 m0, s3
	s_nop 0
	global_load_lds_dwordx4 v[220:221], off
	v_lshl_add_u64 v[220:221], v[226:227], 0, s[26:27]
	s_mov_b32 m0, s72
	s_nop 0
	global_load_lds_dwordx4 v[220:221], off
	s_waitcnt vmcnt(8)
	s_waitcnt lgkmcnt(0)
	.p2align 3
	s_setprio 1
	s_barrier
	v_mfma_f32_16x16x32_bf16 v[60:63], v[128:131], v[180:183], v[60:63]
	v_mfma_f32_16x16x32_bf16 v[60:63], v[132:135], v[192:195], v[60:63]
	v_mfma_f32_16x16x32_bf16 v[56:59], v[140:143], v[192:195], v[56:59]
	v_mfma_f32_16x16x32_bf16 v[56:59], v[136:139], v[180:183], v[56:59]
	v_mfma_f32_16x16x32_bf16 v[40:43], v[136:139], v[196:199], v[40:43]
	v_mfma_f32_16x16x32_bf16 v[40:43], v[140:143], v[200:203], v[40:43]
	v_mfma_f32_16x16x32_bf16 v[44:47], v[132:135], v[200:203], v[44:47]
	v_mfma_f32_16x16x32_bf16 v[44:47], v[128:131], v[196:199], v[44:47]
	v_mfma_f32_16x16x32_bf16 v[28:31], v[128:131], v[204:207], v[28:31]
	v_mfma_f32_16x16x32_bf16 v[28:31], v[132:135], v[208:211], v[28:31]
	v_mfma_f32_16x16x32_bf16 v[24:27], v[140:143], v[208:211], v[24:27]
	v_mfma_f32_16x16x32_bf16 v[24:27], v[136:139], v[204:207], v[24:27]
	v_mfma_f32_16x16x32_bf16 v[8:11], v[136:139], v[212:215], v[8:11]
	v_mfma_f32_16x16x32_bf16 v[8:11], v[140:143], v[216:219], v[8:11]
	v_mfma_f32_16x16x32_bf16 v[12:15], v[132:135], v[216:219], v[12:15]
	v_mfma_f32_16x16x32_bf16 v[12:15], v[128:131], v[212:215], v[12:15]
	s_setprio 0
	s_setprio 1
	v_mfma_f32_16x16x32_bf16 v[52:55], v[144:147], v[180:183], v[52:55]
	v_mfma_f32_16x16x32_bf16 v[52:55], v[148:151], v[192:195], v[52:55]
	v_mfma_f32_16x16x32_bf16 v[48:51], v[176:179], v[192:195], v[48:51]
	v_mfma_f32_16x16x32_bf16 v[48:51], v[172:175], v[180:183], v[48:51]
	v_mfma_f32_16x16x32_bf16 v[32:35], v[172:175], v[196:199], v[32:35]
	v_mfma_f32_16x16x32_bf16 v[32:35], v[176:179], v[200:203], v[32:35]
	v_mfma_f32_16x16x32_bf16 v[36:39], v[148:151], v[200:203], v[36:39]
	v_mfma_f32_16x16x32_bf16 v[36:39], v[144:147], v[196:199], v[36:39]
	v_mfma_f32_16x16x32_bf16 v[20:23], v[144:147], v[204:207], v[20:23]
	v_mfma_f32_16x16x32_bf16 v[20:23], v[148:151], v[208:211], v[20:23]
	v_mfma_f32_16x16x32_bf16 v[16:19], v[176:179], v[208:211], v[16:19]
	v_mfma_f32_16x16x32_bf16 v[16:19], v[172:175], v[204:207], v[16:19]
	v_mfma_f32_16x16x32_bf16 v[0:3], v[172:175], v[212:215], v[0:3]
	v_mfma_f32_16x16x32_bf16 v[0:3], v[176:179], v[216:219], v[0:3]
	v_mfma_f32_16x16x32_bf16 v[4:7], v[148:151], v[216:219], v[4:7]
	v_mfma_f32_16x16x32_bf16 v[4:7], v[144:147], v[212:215], v[4:7]
	s_barrier
	s_setprio 0
	s_add_i32 s80, s80, 2
	s_add_u32 s78, s78, 0x100
	s_addc_u32 s79, s79, 0
	s_add_u32 s58, s58, 0x100
	s_addc_u32 s59, s59, 0
	s_cmp_gt_u32 s80, 13
	s_branch .LBB0_1011
.Lfa_9:
	ds_read_b128 v[128:131], v188
	v_xor_b32_e32 v253, 64, v188
	ds_read_b128 v[132:135], v253
	ds_read_b128 v[136:139], v188 offset:2048
	ds_read_b128 v[140:143], v253 offset:2048
	ds_read_b128 v[144:147], v189
	v_xor_b32_e32 v253, 64, v189
	ds_read_b128 v[148:151], v253
	ds_read_b128 v[172:175], v189 offset:2048
	ds_read_b128 v[176:179], v253 offset:2048
	s_add_u32 s60, s58, 0xfffc0080
	s_addc_u32 s61, s59, -1
	s_cmp_eq_u32 s80, 12
	s_cselect_b32 s63, s15, s61
	s_cselect_b32 s62, s51, s60
	s_cselect_b32 s61, s49, s79
	s_cselect_b32 s60, s57, s78
	v_lshl_add_u64 v[220:221], s[58:59], 0, v[166:167]
	s_add_i32 m0, s67, 0xc000
	ds_read_b128 v[180:183], v190
	v_xor_b32_e32 v253, 64, v190
	ds_read_b128 v[192:195], v253
	ds_read_b128 v[196:199], v190 offset:2048
	ds_read_b128 v[200:203], v253 offset:2048
	ds_read_b128 v[204:207], v190 offset:4096
	ds_read_b128 v[208:211], v253 offset:4096
	ds_read_b128 v[212:215], v190 offset:6144
	ds_read_b128 v[216:219], v253 offset:6144
	global_load_lds_dwordx4 v[220:221], off
	v_lshl_add_u64 v[220:221], s[58:59], 0, v[164:165]
	s_add_i32 m0, s67, 0xe000
	s_nop 0
	global_load_lds_dwordx4 v[220:221], off
	s_waitcnt vmcnt(8)
	s_waitcnt lgkmcnt(0)
	.p2align 3
	s_setprio 1
	s_barrier
	v_mfma_f32_16x16x32_bf16 v[124:127], v[128:131], v[180:183], 0
	v_mfma_f32_16x16x32_bf16 v[120:123], v[136:139], v[180:183], 0
	v_mfma_f32_16x16x32_bf16 v[108:111], v[128:131], v[196:199], 0
	v_mfma_f32_16x16x32_bf16 v[104:107], v[136:139], v[196:199], 0
	v_mfma_f32_16x16x32_bf16 v[92:95], v[128:131], v[204:207], 0
	v_mfma_f32_16x16x32_bf16 v[88:91], v[136:139], v[204:207], 0
	v_mfma_f32_16x16x32_bf16 v[76:79], v[128:131], v[212:215], 0
	v_mfma_f32_16x16x32_bf16 v[72:75], v[136:139], v[212:215], 0
	v_mfma_f32_16x16x32_bf16 v[124:127], v[132:135], v[192:195], v[124:127]
	v_mfma_f32_16x16x32_bf16 v[120:123], v[140:143], v[192:195], v[120:123]
	v_mfma_f32_16x16x32_bf16 v[108:111], v[132:135], v[200:203], v[108:111]
	v_mfma_f32_16x16x32_bf16 v[104:107], v[140:143], v[200:203], v[104:107]
	v_mfma_f32_16x16x32_bf16 v[92:95], v[132:135], v[208:211], v[92:95]
	v_mfma_f32_16x16x32_bf16 v[88:91], v[140:143], v[208:211], v[88:91]
	v_mfma_f32_16x16x32_bf16 v[76:79], v[132:135], v[216:219], v[76:79]
	v_mfma_f32_16x16x32_bf16 v[72:75], v[140:143], v[216:219], v[72:75]
	s_setprio 0
	s_setprio 1
	v_mfma_f32_16x16x32_bf16 v[116:119], v[144:147], v[180:183], 0
	v_mfma_f32_16x16x32_bf16 v[112:115], v[172:175], v[180:183], 0
	v_mfma_f32_16x16x32_bf16 v[100:103], v[144:147], v[196:199], 0
	v_mfma_f32_16x16x32_bf16 v[96:99], v[172:175], v[196:199], 0
	v_mfma_f32_16x16x32_bf16 v[84:87], v[144:147], v[204:207], 0
	v_mfma_f32_16x16x32_bf16 v[80:83], v[172:175], v[204:207], 0
	v_mfma_f32_16x16x32_bf16 v[68:71], v[144:147], v[212:215], 0
	v_mfma_f32_16x16x32_bf16 v[64:67], v[172:175], v[212:215], 0
	v_mfma_f32_16x16x32_bf16 v[116:119], v[148:151], v[192:195], v[116:119]
	v_mfma_f32_16x16x32_bf16 v[112:115], v[176:179], v[192:195], v[112:115]
	v_mfma_f32_16x16x32_bf16 v[100:103], v[148:151], v[200:203], v[100:103]
	v_mfma_f32_16x16x32_bf16 v[96:99], v[176:179], v[200:203], v[96:99]
	v_mfma_f32_16x16x32_bf16 v[84:87], v[148:151], v[208:211], v[84:87]
	v_mfma_f32_16x16x32_bf16 v[80:83], v[176:179], v[208:211], v[80:83]
	v_mfma_f32_16x16x32_bf16 v[68:71], v[148:151], v[216:219], v[68:71]
	v_mfma_f32_16x16x32_bf16 v[64:67], v[176:179], v[216:219], v[64:67]
	s_barrier
	s_setprio 0
	s_add_i32 s81, s76, s66
	v_lshl_add_u64 v[220:221], s[60:61], 0, v[154:155]
	s_mov_b32 m0, s81
	ds_read_b128 v[180:183], v190 offset:16384
	v_xor_b32_e32 v253, 64, v190
	ds_read_b128 v[192:195], v253 offset:16384
	ds_read_b128 v[196:199], v190 offset:18432
	ds_read_b128 v[200:203], v253 offset:18432
	ds_read_b128 v[204:207], v190 offset:20480
	ds_read_b128 v[208:211], v253 offset:20480
	ds_read_b128 v[212:215], v190 offset:22528
	ds_read_b128 v[216:219], v253 offset:22528
	global_load_lds_dwordx4 v[220:221], off
	s_add_i32 m0, s81, 0x2000
	s_add_u32 s82, s60, 0x40000
	v_lshl_add_u64 v[222:223], s[60:61], 0, v[162:163]
	s_addc_u32 s83, s61, 0
	s_add_i32 s81, s77, s66
	global_load_lds_dwordx4 v[222:223], off
	v_lshl_add_u64 v[224:225], s[82:83], 0, v[154:155]
	s_mov_b32 m0, s81
	v_lshl_add_u64 v[226:227], s[62:63], 0, v[160:161]
	global_load_lds_dwordx4 v[224:225], off
	v_lshl_add_u64 v[224:225], s[82:83], 0, v[162:163]
	s_add_i32 m0, s81, 0x2000
	s_nop 0
	global_load_lds_dwordx4 v[224:225], off
	v_lshl_add_u64 v[224:225], s[62:63], 0, v[152:153]
	s_mov_b32 m0, s67
	s_nop 0
	global_load_lds_dwordx4 v[224:225], off
	s_mov_b32 m0, s68
	s_nop 0
	global_load_lds_dwordx4 v[226:227], off
	s_waitcnt vmcnt(8)
	s_waitcnt lgkmcnt(0)
	.p2align 3
	s_setprio 1
	s_barrier
	v_mfma_f32_16x16x32_bf16 v[60:63], v[128:131], v[180:183], 0
	v_mfma_f32_16x16x32_bf16 v[56:59], v[136:139], v[180:183], 0
	v_mfma_f32_16x16x32_bf16 v[44:47], v[128:131], v[196:199], 0
	v_mfma_f32_16x16x32_bf16 v[40:43], v[136:139], v[196:199], 0
	v_mfma_f32_16x16x32_bf16 v[28:31], v[128:131], v[204:207], 0
	v_mfma_f32_16x16x32_bf16 v[24:27], v[136:139], v[204:207], 0
	v_mfma_f32_16x16x32_bf16 v[12:15], v[128:131], v[212:215], 0
	v_mfma_f32_16x16x32_bf16 v[8:11], v[136:139], v[212:215], 0
	v_mfma_f32_16x16x32_bf16 v[60:63], v[132:135], v[192:195], v[60:63]
	v_mfma_f32_16x16x32_bf16 v[56:59], v[140:143], v[192:195], v[56:59]
	v_mfma_f32_16x16x32_bf16 v[44:47], v[132:135], v[200:203], v[44:47]
	v_mfma_f32_16x16x32_bf16 v[40:43], v[140:143], v[200:203], v[40:43]
	v_mfma_f32_16x16x32_bf16 v[28:31], v[132:135], v[208:211], v[28:31]
	v_mfma_f32_16x16x32_bf16 v[24:27], v[140:143], v[208:211], v[24:27]
	v_mfma_f32_16x16x32_bf16 v[12:15], v[132:135], v[216:219], v[12:15]
	v_mfma_f32_16x16x32_bf16 v[8:11], v[140:143], v[216:219], v[8:11]
	s_setprio 0
	s_setprio 1
	v_mfma_f32_16x16x32_bf16 v[52:55], v[144:147], v[180:183], 0
	v_mfma_f32_16x16x32_bf16 v[48:51], v[172:175], v[180:183], 0
	v_mfma_f32_16x16x32_bf16 v[36:39], v[144:147], v[196:199], 0
	v_mfma_f32_16x16x32_bf16 v[32:35], v[172:175], v[196:199], 0
	v_mfma_f32_16x16x32_bf16 v[20:23], v[144:147], v[204:207], 0
	v_mfma_f32_16x16x32_bf16 v[16:19], v[172:175], v[204:207], 0
	v_mfma_f32_16x16x32_bf16 v[4:7], v[144:147], v[212:215], 0
	v_mfma_f32_16x16x32_bf16 v[0:3], v[172:175], v[212:215], 0
	v_mfma_f32_16x16x32_bf16 v[52:55], v[148:151], v[192:195], v[52:55]
	v_mfma_f32_16x16x32_bf16 v[48:51], v[176:179], v[192:195], v[48:51]
	v_mfma_f32_16x16x32_bf16 v[36:39], v[148:151], v[200:203], v[36:39]
	v_mfma_f32_16x16x32_bf16 v[32:35], v[176:179], v[200:203], v[32:35]
	v_mfma_f32_16x16x32_bf16 v[20:23], v[148:151], v[208:211], v[20:23]
	v_mfma_f32_16x16x32_bf16 v[16:19], v[176:179], v[208:211], v[16:19]
	v_mfma_f32_16x16x32_bf16 v[4:7], v[148:151], v[216:219], v[4:7]
	v_mfma_f32_16x16x32_bf16 v[0:3], v[176:179], v[216:219], v[0:3]
	s_barrier
	s_setprio 0
	s_add_i32 s81, 0, 0x18000
	s_add_i32 s82, 0, 0x1c000
	v_add_u32_e32 v140, s81, v185
	v_add_u32_e32 v176, s82, v185
	ds_read_b128 v[128:131], v140
	v_xor_b32_e32 v253, 64, v140
	ds_read_b128 v[132:135], v253
	ds_read_b128 v[136:139], v140 offset:2048
	ds_read_b128 v[140:143], v253 offset:2048
	ds_read_b128 v[144:147], v176
	v_xor_b32_e32 v253, 64, v176
	ds_read_b128 v[148:151], v253
	ds_read_b128 v[172:175], v176 offset:2048
	ds_read_b128 v[176:179], v253 offset:2048
	s_add_u32 s62, s62, 0x40000
	s_addc_u32 s63, s63, 0
	s_mov_b32 m0, s69
	v_lshl_add_u64 v[228:229], s[62:63], 0, v[152:153]
	ds_read_b128 v[180:183], v190 offset:32768
	v_xor_b32_e32 v253, 64, v190
	ds_read_b128 v[192:195], v253 offset:32768
	ds_read_b128 v[196:199], v190 offset:34816
	ds_read_b128 v[200:203], v253 offset:34816
	ds_read_b128 v[204:207], v190 offset:36864
	ds_read_b128 v[208:211], v253 offset:36864
	ds_read_b128 v[212:215], v190 offset:38912
	ds_read_b128 v[216:219], v253 offset:38912
	global_load_lds_dwordx4 v[228:229], off
	v_lshl_add_u64 v[228:229], s[62:63], 0, v[160:161]
	s_mov_b32 m0, s70
	s_nop 0
	global_load_lds_dwordx4 v[228:229], off
	s_waitcnt vmcnt(8)
	s_waitcnt lgkmcnt(0)
	.p2align 3
	s_setprio 1
	s_barrier
	v_mfma_f32_16x16x32_bf16 v[124:127], v[128:131], v[180:183], v[124:127]
	v_mfma_f32_16x16x32_bf16 v[124:127], v[132:135], v[192:195], v[124:127]
	v_mfma_f32_16x16x32_bf16 v[120:123], v[140:143], v[192:195], v[120:123]
	v_mfma_f32_16x16x32_bf16 v[120:123], v[136:139], v[180:183], v[120:123]
	v_mfma_f32_16x16x32_bf16 v[104:107], v[136:139], v[196:199], v[104:107]
	v_mfma_f32_16x16x32_bf16 v[104:107], v[140:143], v[200:203], v[104:107]
	v_mfma_f32_16x16x32_bf16 v[108:111], v[132:135], v[200:203], v[108:111]
	v_mfma_f32_16x16x32_bf16 v[108:111], v[128:131], v[196:199], v[108:111]
	v_mfma_f32_16x16x32_bf16 v[92:95], v[128:131], v[204:207], v[92:95]
	v_mfma_f32_16x16x32_bf16 v[92:95], v[132:135], v[208:211], v[92:95]
	v_mfma_f32_16x16x32_bf16 v[88:91], v[140:143], v[208:211], v[88:91]
	v_mfma_f32_16x16x32_bf16 v[88:91], v[136:139], v[204:207], v[88:91]
	v_mfma_f32_16x16x32_bf16 v[72:75], v[136:139], v[212:215], v[72:75]
	v_mfma_f32_16x16x32_bf16 v[72:75], v[140:143], v[216:219], v[72:75]
	v_mfma_f32_16x16x32_bf16 v[76:79], v[132:135], v[216:219], v[76:79]
	v_mfma_f32_16x16x32_bf16 v[76:79], v[128:131], v[212:215], v[76:79]
	s_setprio 0
	s_setprio 1
	v_mfma_f32_16x16x32_bf16 v[116:119], v[144:147], v[180:183], v[116:119]
	v_mfma_f32_16x16x32_bf16 v[116:119], v[148:151], v[192:195], v[116:119]
	v_mfma_f32_16x16x32_bf16 v[112:115], v[176:179], v[192:195], v[112:115]
	v_mfma_f32_16x16x32_bf16 v[112:115], v[172:175], v[180:183], v[112:115]
	v_mfma_f32_16x16x32_bf16 v[96:99], v[172:175], v[196:199], v[96:99]
	v_mfma_f32_16x16x32_bf16 v[96:99], v[176:179], v[200:203], v[96:99]
	v_mfma_f32_16x16x32_bf16 v[100:103], v[148:151], v[200:203], v[100:103]
	v_mfma_f32_16x16x32_bf16 v[100:103], v[144:147], v[196:199], v[100:103]
	v_mfma_f32_16x16x32_bf16 v[84:87], v[144:147], v[204:207], v[84:87]
	v_mfma_f32_16x16x32_bf16 v[84:87], v[148:151], v[208:211], v[84:87]
	v_mfma_f32_16x16x32_bf16 v[80:83], v[176:179], v[208:211], v[80:83]
	v_mfma_f32_16x16x32_bf16 v[80:83], v[172:175], v[204:207], v[80:83]
	v_mfma_f32_16x16x32_bf16 v[64:67], v[172:175], v[212:215], v[64:67]
	v_mfma_f32_16x16x32_bf16 v[64:67], v[176:179], v[216:219], v[64:67]
	v_mfma_f32_16x16x32_bf16 v[68:71], v[148:151], v[216:219], v[68:71]
	v_mfma_f32_16x16x32_bf16 v[68:71], v[144:147], v[212:215], v[68:71]
	s_barrier
	s_setprio 0
	s_add_i32 s62, s81, s66
	v_lshl_add_u64 v[220:221], v[220:221], 0, s[26:27]
	s_mov_b32 m0, s62
	ds_read_b128 v[180:183], v190 offset:49152
	v_xor_b32_e32 v253, 64, v190
	ds_read_b128 v[192:195], v253 offset:49152
	ds_read_b128 v[196:199], v190 offset:51200
	ds_read_b128 v[200:203], v253 offset:51200
	ds_read_b128 v[204:207], v190 offset:53248
	ds_read_b128 v[208:211], v253 offset:53248
	ds_read_b128 v[212:215], v190 offset:55296
	ds_read_b128 v[216:219], v253 offset:55296
	global_load_lds_dwordx4 v[220:221], off
	s_add_i32 m0, s62, 0x2000
	s_add_u32 s60, s60, 0x40080
	v_lshl_add_u64 v[220:221], v[222:223], 0, s[26:27]
	s_addc_u32 s61, s61, 0
	s_add_i32 s62, s82, s66
	global_load_lds_dwordx4 v[220:221], off
	v_lshl_add_u64 v[220:221], s[60:61], 0, v[154:155]
	s_mov_b32 m0, s62
	s_nop 0
	global_load_lds_dwordx4 v[220:221], off
	v_lshl_add_u64 v[220:221], s[60:61], 0, v[162:163]
	s_add_i32 m0, s62, 0x2000
	s_nop 0
	global_load_lds_dwordx4 v[220:221], off
	v_lshl_add_u64 v[220:221], v[224:225], 0, s[26:27]
	s_mov_b32 m0, s3
	s_nop 0
	global_load_lds_dwordx4 v[220:221], off
	v_lshl_add_u64 v[220:221], v[226:227], 0, s[26:27]
	s_mov_b32 m0, s72
	s_nop 0
	global_load_lds_dwordx4 v[220:221], off
	s_waitcnt vmcnt(8)
	s_waitcnt lgkmcnt(0)
	.p2align 3
	s_setprio 1
	s_barrier
	v_mfma_f32_16x16x32_bf16 v[60:63], v[128:131], v[180:183], v[60:63]
	v_mfma_f32_16x16x32_bf16 v[60:63], v[132:135], v[192:195], v[60:63]
	v_mfma_f32_16x16x32_bf16 v[56:59], v[140:143], v[192:195], v[56:59]
	v_mfma_f32_16x16x32_bf16 v[56:59], v[136:139], v[180:183], v[56:59]
	v_mfma_f32_16x16x32_bf16 v[40:43], v[136:139], v[196:199], v[40:43]
	v_mfma_f32_16x16x32_bf16 v[40:43], v[140:143], v[200:203], v[40:43]
	v_mfma_f32_16x16x32_bf16 v[44:47], v[132:135], v[200:203], v[44:47]
	v_mfma_f32_16x16x32_bf16 v[44:47], v[128:131], v[196:199], v[44:47]
	v_mfma_f32_16x16x32_bf16 v[28:31], v[128:131], v[204:207], v[28:31]
	v_mfma_f32_16x16x32_bf16 v[28:31], v[132:135], v[208:211], v[28:31]
	v_mfma_f32_16x16x32_bf16 v[24:27], v[140:143], v[208:211], v[24:27]
	v_mfma_f32_16x16x32_bf16 v[24:27], v[136:139], v[204:207], v[24:27]
	v_mfma_f32_16x16x32_bf16 v[8:11], v[136:139], v[212:215], v[8:11]
	v_mfma_f32_16x16x32_bf16 v[8:11], v[140:143], v[216:219], v[8:11]
	v_mfma_f32_16x16x32_bf16 v[12:15], v[132:135], v[216:219], v[12:15]
	v_mfma_f32_16x16x32_bf16 v[12:15], v[128:131], v[212:215], v[12:15]
	s_setprio 0
	s_setprio 1
	v_mfma_f32_16x16x32_bf16 v[52:55], v[144:147], v[180:183], v[52:55]
	v_mfma_f32_16x16x32_bf16 v[52:55], v[148:151], v[192:195], v[52:55]
	v_mfma_f32_16x16x32_bf16 v[48:51], v[176:179], v[192:195], v[48:51]
	v_mfma_f32_16x16x32_bf16 v[48:51], v[172:175], v[180:183], v[48:51]
	v_mfma_f32_16x16x32_bf16 v[32:35], v[172:175], v[196:199], v[32:35]
	v_mfma_f32_16x16x32_bf16 v[32:35], v[176:179], v[200:203], v[32:35]
	v_mfma_f32_16x16x32_bf16 v[36:39], v[148:151], v[200:203], v[36:39]
	v_mfma_f32_16x16x32_bf16 v[36:39], v[144:147], v[196:199], v[36:39]
	v_mfma_f32_16x16x32_bf16 v[20:23], v[144:147], v[204:207], v[20:23]
	v_mfma_f32_16x16x32_bf16 v[20:23], v[148:151], v[208:211], v[20:23]
	v_mfma_f32_16x16x32_bf16 v[16:19], v[176:179], v[208:211], v[16:19]
	v_mfma_f32_16x16x32_bf16 v[16:19], v[172:175], v[204:207], v[16:19]
	v_mfma_f32_16x16x32_bf16 v[0:3], v[172:175], v[212:215], v[0:3]
	v_mfma_f32_16x16x32_bf16 v[0:3], v[176:179], v[216:219], v[0:3]
	v_mfma_f32_16x16x32_bf16 v[4:7], v[148:151], v[216:219], v[4:7]
	v_mfma_f32_16x16x32_bf16 v[4:7], v[144:147], v[212:215], v[4:7]
	s_barrier
	s_setprio 0
	s_add_i32 s80, s80, 2
	s_add_u32 s78, s78, 0x100
	s_addc_u32 s79, s79, 0
	s_add_u32 s58, s58, 0x100
	s_addc_u32 s59, s59, 0
	s_cmp_gt_u32 s80, 13
.LBB0_1011:
	ds_read_b128 v[128:131], v188
	v_xor_b32_e32 v253, 64, v188
	ds_read_b128 v[132:135], v253
	ds_read_b128 v[136:139], v188 offset:2048
	ds_read_b128 v[140:143], v253 offset:2048
	ds_read_b128 v[144:147], v189
	v_xor_b32_e32 v253, 64, v189
	ds_read_b128 v[148:151], v253
	ds_read_b128 v[172:175], v189 offset:2048
	ds_read_b128 v[176:179], v253 offset:2048
	s_add_u32 s60, s58, 0xfffc0080
	s_addc_u32 s61, s59, -1
	s_cmp_eq_u32 s80, 12
	s_cselect_b32 s63, s15, s61
	s_cselect_b32 s62, s51, s60
	s_cselect_b32 s61, s49, s79
	s_cselect_b32 s60, s57, s78
	v_lshl_add_u64 v[220:221], s[58:59], 0, v[166:167]
	s_add_i32 m0, s67, 0xc000
	ds_read_b128 v[180:183], v190
	v_xor_b32_e32 v253, 64, v190
	ds_read_b128 v[192:195], v253
	ds_read_b128 v[196:199], v190 offset:2048
	ds_read_b128 v[200:203], v253 offset:2048
	ds_read_b128 v[204:207], v190 offset:4096
	ds_read_b128 v[208:211], v253 offset:4096
	ds_read_b128 v[212:215], v190 offset:6144
	ds_read_b128 v[216:219], v253 offset:6144
	global_load_lds_dwordx4 v[220:221], off
	v_lshl_add_u64 v[220:221], s[58:59], 0, v[164:165]
	s_add_i32 m0, s67, 0xe000
	s_nop 0
	global_load_lds_dwordx4 v[220:221], off
	s_waitcnt vmcnt(8)
	s_waitcnt lgkmcnt(0)
	.p2align 3
	s_setprio 1
	s_barrier
	v_mfma_f32_16x16x32_bf16 v[124:127], v[128:131], v[180:183], v[124:127]
	v_mfma_f32_16x16x32_bf16 v[124:127], v[132:135], v[192:195], v[124:127]
	v_mfma_f32_16x16x32_bf16 v[120:123], v[140:143], v[192:195], v[120:123]
	v_mfma_f32_16x16x32_bf16 v[120:123], v[136:139], v[180:183], v[120:123]
	v_mfma_f32_16x16x32_bf16 v[104:107], v[136:139], v[196:199], v[104:107]
	v_mfma_f32_16x16x32_bf16 v[104:107], v[140:143], v[200:203], v[104:107]
	v_mfma_f32_16x16x32_bf16 v[108:111], v[132:135], v[200:203], v[108:111]
	v_mfma_f32_16x16x32_bf16 v[108:111], v[128:131], v[196:199], v[108:111]
	v_mfma_f32_16x16x32_bf16 v[92:95], v[128:131], v[204:207], v[92:95]
	v_mfma_f32_16x16x32_bf16 v[92:95], v[132:135], v[208:211], v[92:95]
	v_mfma_f32_16x16x32_bf16 v[88:91], v[140:143], v[208:211], v[88:91]
	v_mfma_f32_16x16x32_bf16 v[88:91], v[136:139], v[204:207], v[88:91]
	v_mfma_f32_16x16x32_bf16 v[72:75], v[136:139], v[212:215], v[72:75]
	v_mfma_f32_16x16x32_bf16 v[72:75], v[140:143], v[216:219], v[72:75]
	v_mfma_f32_16x16x32_bf16 v[76:79], v[132:135], v[216:219], v[76:79]
	v_mfma_f32_16x16x32_bf16 v[76:79], v[128:131], v[212:215], v[76:79]
	s_setprio 0
	s_setprio 1
	v_mfma_f32_16x16x32_bf16 v[116:119], v[144:147], v[180:183], v[116:119]
	v_mfma_f32_16x16x32_bf16 v[116:119], v[148:151], v[192:195], v[116:119]
	v_mfma_f32_16x16x32_bf16 v[112:115], v[176:179], v[192:195], v[112:115]
	v_mfma_f32_16x16x32_bf16 v[112:115], v[172:175], v[180:183], v[112:115]
	v_mfma_f32_16x16x32_bf16 v[96:99], v[172:175], v[196:199], v[96:99]
	v_mfma_f32_16x16x32_bf16 v[96:99], v[176:179], v[200:203], v[96:99]
	v_mfma_f32_16x16x32_bf16 v[100:103], v[148:151], v[200:203], v[100:103]
	v_mfma_f32_16x16x32_bf16 v[100:103], v[144:147], v[196:199], v[100:103]
	v_mfma_f32_16x16x32_bf16 v[84:87], v[144:147], v[204:207], v[84:87]
	v_mfma_f32_16x16x32_bf16 v[84:87], v[148:151], v[208:211], v[84:87]
	v_mfma_f32_16x16x32_bf16 v[80:83], v[176:179], v[208:211], v[80:83]
	v_mfma_f32_16x16x32_bf16 v[80:83], v[172:175], v[204:207], v[80:83]
	v_mfma_f32_16x16x32_bf16 v[64:67], v[172:175], v[212:215], v[64:67]
	v_mfma_f32_16x16x32_bf16 v[64:67], v[176:179], v[216:219], v[64:67]
	v_mfma_f32_16x16x32_bf16 v[68:71], v[148:151], v[216:219], v[68:71]
	v_mfma_f32_16x16x32_bf16 v[68:71], v[144:147], v[212:215], v[68:71]
	s_barrier
	s_setprio 0
	s_add_i32 s81, s76, s66
	v_lshl_add_u64 v[220:221], s[60:61], 0, v[154:155]
	s_mov_b32 m0, s81
	ds_read_b128 v[180:183], v190 offset:16384
	v_xor_b32_e32 v253, 64, v190
	ds_read_b128 v[192:195], v253 offset:16384
	ds_read_b128 v[196:199], v190 offset:18432
	ds_read_b128 v[200:203], v253 offset:18432
	ds_read_b128 v[204:207], v190 offset:20480
	ds_read_b128 v[208:211], v253 offset:20480
	ds_read_b128 v[212:215], v190 offset:22528
	ds_read_b128 v[216:219], v253 offset:22528
	global_load_lds_dwordx4 v[220:221], off
	s_add_i32 m0, s81, 0x2000
	s_add_u32 s82, s60, 0x40000
	v_lshl_add_u64 v[222:223], s[60:61], 0, v[162:163]
	s_addc_u32 s83, s61, 0
	s_add_i32 s81, s77, s66
	global_load_lds_dwordx4 v[222:223], off
	v_lshl_add_u64 v[224:225], s[82:83], 0, v[154:155]
	s_mov_b32 m0, s81
	v_lshl_add_u64 v[226:227], s[62:63], 0, v[160:161]
	global_load_lds_dwordx4 v[224:225], off
	v_lshl_add_u64 v[224:225], s[82:83], 0, v[162:163]
	s_add_i32 m0, s81, 0x2000
	s_nop 0
	global_load_lds_dwordx4 v[224:225], off
	v_lshl_add_u64 v[224:225], s[62:63], 0, v[152:153]
	s_mov_b32 m0, s67
	s_nop 0
	global_load_lds_dwordx4 v[224:225], off
	s_mov_b32 m0, s68
	s_nop 0
	global_load_lds_dwordx4 v[226:227], off
	s_waitcnt vmcnt(8)
	s_waitcnt lgkmcnt(0)
	.p2align 3
	s_setprio 1
	s_barrier
	v_mfma_f32_16x16x32_bf16 v[60:63], v[128:131], v[180:183], v[60:63]
	v_mfma_f32_16x16x32_bf16 v[60:63], v[132:135], v[192:195], v[60:63]
	v_mfma_f32_16x16x32_bf16 v[56:59], v[140:143], v[192:195], v[56:59]
	v_mfma_f32_16x16x32_bf16 v[56:59], v[136:139], v[180:183], v[56:59]
	v_mfma_f32_16x16x32_bf16 v[40:43], v[136:139], v[196:199], v[40:43]
	v_mfma_f32_16x16x32_bf16 v[40:43], v[140:143], v[200:203], v[40:43]
	v_mfma_f32_16x16x32_bf16 v[44:47], v[132:135], v[200:203], v[44:47]
	v_mfma_f32_16x16x32_bf16 v[44:47], v[128:131], v[196:199], v[44:47]
	v_mfma_f32_16x16x32_bf16 v[28:31], v[128:131], v[204:207], v[28:31]
	v_mfma_f32_16x16x32_bf16 v[28:31], v[132:135], v[208:211], v[28:31]
	v_mfma_f32_16x16x32_bf16 v[24:27], v[140:143], v[208:211], v[24:27]
	v_mfma_f32_16x16x32_bf16 v[24:27], v[136:139], v[204:207], v[24:27]
	v_mfma_f32_16x16x32_bf16 v[8:11], v[136:139], v[212:215], v[8:11]
	v_mfma_f32_16x16x32_bf16 v[8:11], v[140:143], v[216:219], v[8:11]
	v_mfma_f32_16x16x32_bf16 v[12:15], v[132:135], v[216:219], v[12:15]
	v_mfma_f32_16x16x32_bf16 v[12:15], v[128:131], v[212:215], v[12:15]
	s_setprio 0
	s_setprio 1
	v_mfma_f32_16x16x32_bf16 v[52:55], v[144:147], v[180:183], v[52:55]
	v_mfma_f32_16x16x32_bf16 v[52:55], v[148:151], v[192:195], v[52:55]
	v_mfma_f32_16x16x32_bf16 v[48:51], v[176:179], v[192:195], v[48:51]
	v_mfma_f32_16x16x32_bf16 v[48:51], v[172:175], v[180:183], v[48:51]
	v_mfma_f32_16x16x32_bf16 v[32:35], v[172:175], v[196:199], v[32:35]
	v_mfma_f32_16x16x32_bf16 v[32:35], v[176:179], v[200:203], v[32:35]
	v_mfma_f32_16x16x32_bf16 v[36:39], v[148:151], v[200:203], v[36:39]
	v_mfma_f32_16x16x32_bf16 v[36:39], v[144:147], v[196:199], v[36:39]
	v_mfma_f32_16x16x32_bf16 v[20:23], v[144:147], v[204:207], v[20:23]
	v_mfma_f32_16x16x32_bf16 v[20:23], v[148:151], v[208:211], v[20:23]
	v_mfma_f32_16x16x32_bf16 v[16:19], v[176:179], v[208:211], v[16:19]
	v_mfma_f32_16x16x32_bf16 v[16:19], v[172:175], v[204:207], v[16:19]
	v_mfma_f32_16x16x32_bf16 v[0:3], v[172:175], v[212:215], v[0:3]
	v_mfma_f32_16x16x32_bf16 v[0:3], v[176:179], v[216:219], v[0:3]
	v_mfma_f32_16x16x32_bf16 v[4:7], v[148:151], v[216:219], v[4:7]
	v_mfma_f32_16x16x32_bf16 v[4:7], v[144:147], v[212:215], v[4:7]
	s_barrier
	s_setprio 0
	s_add_i32 s81, 0, 0x18000
	s_add_i32 s82, 0, 0x1c000
	v_add_u32_e32 v140, s81, v185
	v_add_u32_e32 v176, s82, v185
	ds_read_b128 v[128:131], v140
	v_xor_b32_e32 v253, 64, v140
	ds_read_b128 v[132:135], v253
	ds_read_b128 v[136:139], v140 offset:2048
	ds_read_b128 v[140:143], v253 offset:2048
	ds_read_b128 v[144:147], v176
	v_xor_b32_e32 v253, 64, v176
	ds_read_b128 v[148:151], v253
	ds_read_b128 v[172:175], v176 offset:2048
	ds_read_b128 v[176:179], v253 offset:2048
	s_add_u32 s62, s62, 0x40000
	s_addc_u32 s63, s63, 0
	s_mov_b32 m0, s69
	v_lshl_add_u64 v[228:229], s[62:63], 0, v[152:153]
	ds_read_b128 v[180:183], v190 offset:32768
	v_xor_b32_e32 v253, 64, v190
	ds_read_b128 v[192:195], v253 offset:32768
	ds_read_b128 v[196:199], v190 offset:34816
	ds_read_b128 v[200:203], v253 offset:34816
	ds_read_b128 v[204:207], v190 offset:36864
	ds_read_b128 v[208:211], v253 offset:36864
	ds_read_b128 v[212:215], v190 offset:38912
	ds_read_b128 v[216:219], v253 offset:38912
	global_load_lds_dwordx4 v[228:229], off
	v_lshl_add_u64 v[228:229], s[62:63], 0, v[160:161]
	s_mov_b32 m0, s70
	s_nop 0
	global_load_lds_dwordx4 v[228:229], off
	s_waitcnt vmcnt(8)
	s_waitcnt lgkmcnt(0)
	.p2align 3
	s_setprio 1
	s_barrier
	v_mfma_f32_16x16x32_bf16 v[124:127], v[128:131], v[180:183], v[124:127]
	v_mfma_f32_16x16x32_bf16 v[124:127], v[132:135], v[192:195], v[124:127]
	v_mfma_f32_16x16x32_bf16 v[120:123], v[140:143], v[192:195], v[120:123]
	v_mfma_f32_16x16x32_bf16 v[120:123], v[136:139], v[180:183], v[120:123]
	v_mfma_f32_16x16x32_bf16 v[104:107], v[136:139], v[196:199], v[104:107]
	v_mfma_f32_16x16x32_bf16 v[104:107], v[140:143], v[200:203], v[104:107]
	v_mfma_f32_16x16x32_bf16 v[108:111], v[132:135], v[200:203], v[108:111]
	v_mfma_f32_16x16x32_bf16 v[108:111], v[128:131], v[196:199], v[108:111]
	v_mfma_f32_16x16x32_bf16 v[92:95], v[128:131], v[204:207], v[92:95]
	v_mfma_f32_16x16x32_bf16 v[92:95], v[132:135], v[208:211], v[92:95]
	v_mfma_f32_16x16x32_bf16 v[88:91], v[140:143], v[208:211], v[88:91]
	v_mfma_f32_16x16x32_bf16 v[88:91], v[136:139], v[204:207], v[88:91]
	v_mfma_f32_16x16x32_bf16 v[72:75], v[136:139], v[212:215], v[72:75]
	v_mfma_f32_16x16x32_bf16 v[72:75], v[140:143], v[216:219], v[72:75]
	v_mfma_f32_16x16x32_bf16 v[76:79], v[132:135], v[216:219], v[76:79]
	v_mfma_f32_16x16x32_bf16 v[76:79], v[128:131], v[212:215], v[76:79]
	s_setprio 0
	s_setprio 1
	v_mfma_f32_16x16x32_bf16 v[116:119], v[144:147], v[180:183], v[116:119]
	v_mfma_f32_16x16x32_bf16 v[116:119], v[148:151], v[192:195], v[116:119]
	v_mfma_f32_16x16x32_bf16 v[112:115], v[176:179], v[192:195], v[112:115]
	v_mfma_f32_16x16x32_bf16 v[112:115], v[172:175], v[180:183], v[112:115]
	v_mfma_f32_16x16x32_bf16 v[96:99], v[172:175], v[196:199], v[96:99]
	v_mfma_f32_16x16x32_bf16 v[96:99], v[176:179], v[200:203], v[96:99]
	v_mfma_f32_16x16x32_bf16 v[100:103], v[148:151], v[200:203], v[100:103]
	v_mfma_f32_16x16x32_bf16 v[100:103], v[144:147], v[196:199], v[100:103]
	v_mfma_f32_16x16x32_bf16 v[84:87], v[144:147], v[204:207], v[84:87]
	v_mfma_f32_16x16x32_bf16 v[84:87], v[148:151], v[208:211], v[84:87]
	v_mfma_f32_16x16x32_bf16 v[80:83], v[176:179], v[208:211], v[80:83]
	v_mfma_f32_16x16x32_bf16 v[80:83], v[172:175], v[204:207], v[80:83]
	v_mfma_f32_16x16x32_bf16 v[64:67], v[172:175], v[212:215], v[64:67]
	v_mfma_f32_16x16x32_bf16 v[64:67], v[176:179], v[216:219], v[64:67]
	v_mfma_f32_16x16x32_bf16 v[68:71], v[148:151], v[216:219], v[68:71]
	v_mfma_f32_16x16x32_bf16 v[68:71], v[144:147], v[212:215], v[68:71]
	s_barrier
	s_setprio 0
	s_add_i32 s62, s81, s66
	v_lshl_add_u64 v[220:221], v[220:221], 0, s[26:27]
	s_mov_b32 m0, s62
	ds_read_b128 v[180:183], v190 offset:49152
	v_xor_b32_e32 v253, 64, v190
	ds_read_b128 v[192:195], v253 offset:49152
	ds_read_b128 v[196:199], v190 offset:51200
	ds_read_b128 v[200:203], v253 offset:51200
	ds_read_b128 v[204:207], v190 offset:53248
	ds_read_b128 v[208:211], v253 offset:53248
	ds_read_b128 v[212:215], v190 offset:55296
	ds_read_b128 v[216:219], v253 offset:55296
	global_load_lds_dwordx4 v[220:221], off
	s_add_i32 m0, s62, 0x2000
	s_add_u32 s60, s60, 0x40080
	v_lshl_add_u64 v[220:221], v[222:223], 0, s[26:27]
	s_addc_u32 s61, s61, 0
	s_add_i32 s62, s82, s66
	global_load_lds_dwordx4 v[220:221], off
	v_lshl_add_u64 v[220:221], s[60:61], 0, v[154:155]
	s_mov_b32 m0, s62
	s_nop 0
	global_load_lds_dwordx4 v[220:221], off
	v_lshl_add_u64 v[220:221], s[60:61], 0, v[162:163]
	s_add_i32 m0, s62, 0x2000
	s_nop 0
	global_load_lds_dwordx4 v[220:221], off
	v_lshl_add_u64 v[220:221], v[224:225], 0, s[26:27]
	s_mov_b32 m0, s3
	s_nop 0
	global_load_lds_dwordx4 v[220:221], off
	v_lshl_add_u64 v[220:221], v[226:227], 0, s[26:27]
	s_mov_b32 m0, s72
	s_nop 0
	global_load_lds_dwordx4 v[220:221], off
	s_waitcnt vmcnt(8)
	s_waitcnt lgkmcnt(0)
	.p2align 3
	s_setprio 1
	s_barrier
	v_mfma_f32_16x16x32_bf16 v[60:63], v[128:131], v[180:183], v[60:63]
	v_mfma_f32_16x16x32_bf16 v[60:63], v[132:135], v[192:195], v[60:63]
	v_mfma_f32_16x16x32_bf16 v[56:59], v[140:143], v[192:195], v[56:59]
	v_mfma_f32_16x16x32_bf16 v[56:59], v[136:139], v[180:183], v[56:59]
	v_mfma_f32_16x16x32_bf16 v[40:43], v[136:139], v[196:199], v[40:43]
	v_mfma_f32_16x16x32_bf16 v[40:43], v[140:143], v[200:203], v[40:43]
	v_mfma_f32_16x16x32_bf16 v[44:47], v[132:135], v[200:203], v[44:47]
	v_mfma_f32_16x16x32_bf16 v[44:47], v[128:131], v[196:199], v[44:47]
	v_mfma_f32_16x16x32_bf16 v[28:31], v[128:131], v[204:207], v[28:31]
	v_mfma_f32_16x16x32_bf16 v[28:31], v[132:135], v[208:211], v[28:31]
	v_mfma_f32_16x16x32_bf16 v[24:27], v[140:143], v[208:211], v[24:27]
	v_mfma_f32_16x16x32_bf16 v[24:27], v[136:139], v[204:207], v[24:27]
	v_mfma_f32_16x16x32_bf16 v[8:11], v[136:139], v[212:215], v[8:11]
	v_mfma_f32_16x16x32_bf16 v[8:11], v[140:143], v[216:219], v[8:11]
	v_mfma_f32_16x16x32_bf16 v[12:15], v[132:135], v[216:219], v[12:15]
	v_mfma_f32_16x16x32_bf16 v[12:15], v[128:131], v[212:215], v[12:15]
	s_setprio 0
	s_setprio 1
	v_mfma_f32_16x16x32_bf16 v[52:55], v[144:147], v[180:183], v[52:55]
	v_mfma_f32_16x16x32_bf16 v[52:55], v[148:151], v[192:195], v[52:55]
	v_mfma_f32_16x16x32_bf16 v[48:51], v[176:179], v[192:195], v[48:51]
	v_mfma_f32_16x16x32_bf16 v[48:51], v[172:175], v[180:183], v[48:51]
	v_mfma_f32_16x16x32_bf16 v[32:35], v[172:175], v[196:199], v[32:35]
	v_mfma_f32_16x16x32_bf16 v[32:35], v[176:179], v[200:203], v[32:35]
	v_mfma_f32_16x16x32_bf16 v[36:39], v[148:151], v[200:203], v[36:39]
	v_mfma_f32_16x16x32_bf16 v[36:39], v[144:147], v[196:199], v[36:39]
	v_mfma_f32_16x16x32_bf16 v[20:23], v[144:147], v[204:207], v[20:23]
	v_mfma_f32_16x16x32_bf16 v[20:23], v[148:151], v[208:211], v[20:23]
	v_mfma_f32_16x16x32_bf16 v[16:19], v[176:179], v[208:211], v[16:19]
	v_mfma_f32_16x16x32_bf16 v[16:19], v[172:175], v[204:207], v[16:19]
	v_mfma_f32_16x16x32_bf16 v[0:3], v[172:175], v[212:215], v[0:3]
	v_mfma_f32_16x16x32_bf16 v[0:3], v[176:179], v[216:219], v[0:3]
	v_mfma_f32_16x16x32_bf16 v[4:7], v[148:151], v[216:219], v[4:7]
	v_mfma_f32_16x16x32_bf16 v[4:7], v[144:147], v[212:215], v[4:7]
	s_barrier
	s_setprio 0
	s_add_i32 s80, s80, 2
	s_add_u32 s78, s78, 0x100
	s_addc_u32 s79, s79, 0
	s_add_u32 s58, s58, 0x100
	s_addc_u32 s59, s59, 0
	s_cmp_gt_u32 s80, 13
	s_cbranch_scc0 .LBB0_1011
	s_and_b64 vcc, exec, s[28:29]
	s_cbranch_vccz .LBB0_1014
	s_barrier

.LBB0_1096:
	s_ashr_i32 s25, s24, 31
	s_lshl_b64 s[26:27], s[24:25], 19
	s_add_u32 s26, s3, s26
	s_addc_u32 s27, s33, s27
	s_and_b64 s[28:29], s[6:7], exec
	s_cselect_b32 s25, s27, s47
	s_cselect_b32 s65, s26, s46
	s_ashr_i32 s23, s22, 31
	s_lshl_b64 s[28:29], s[22:23], 19
	s_add_u32 s28, s35, s28
	s_addc_u32 s29, s48, s29
	s_and_b64 s[66:67], s[6:7], exec
	s_cselect_b32 s66, s29, s45
	s_cselect_b32 s67, s28, s44
	s_lshl_b32 s23, s30, 8
	v_add_u32_e32 v0, s23, v148
	s_add_u32 s68, s44, 0x100
	v_ashrrev_i32_e32 v1, 31, v0
	s_addc_u32 s69, s45, 0
	v_lshl_add_u64 v[144:145], v[0:1], 4, s[12:13]
	s_add_u32 s30, s46, 0x40080
	s_addc_u32 s31, s47, 0
	s_mov_b32 s70, -2
	s_mov_b64 s[44:45], 0
	s_cmp_eq_u32 s56, 1
	s_cbranch_scc1 .Lfa_10
	v_add_u32_e32 v153, s61, v147
	ds_read_b128 v[160:163], v153
	v_xor_b32_e32 v253, 64, v153
	ds_read_b128 v[164:167], v253
	ds_read_b128 v[168:171], v153 offset:2048
	ds_read_b128 v[172:175], v253 offset:2048
	v_add_u32_e32 v153, s62, v147
	ds_read_b128 v[176:179], v153
	v_xor_b32_e32 v253, 64, v153
	ds_read_b128 v[180:183], v253
	ds_read_b128 v[184:187], v153 offset:2048
	ds_read_b128 v[188:191], v253 offset:2048
	s_add_u32 s46, s30, 0xfffc0080
	s_addc_u32 s47, s31, -1
	s_and_b64 s[44:45], s[44:45], exec
	s_cselect_b32 s47, s25, s47
	s_cselect_b32 s46, s65, s46
	s_cselect_b32 s45, s66, s69
	s_cselect_b32 s44, s67, s68
	v_lshl_add_u64 v[154:155], s[30:31], 0, v[138:139]
	s_add_i32 m0, s52, 0xc000
	ds_read_b128 v[192:195], v150
	v_xor_b32_e32 v253, 64, v150
	ds_read_b128 v[196:199], v253
	ds_read_b128 v[200:203], v150 offset:2048
	ds_read_b128 v[204:207], v253 offset:2048
	ds_read_b128 v[208:211], v150 offset:4096
	ds_read_b128 v[212:215], v253 offset:4096
	ds_read_b128 v[216:219], v150 offset:6144
	ds_read_b128 v[220:223], v253 offset:6144
	global_load_lds_dwordx4 v[154:155], off
	v_lshl_add_u64 v[154:155], s[30:31], 0, v[136:137]
	s_add_i32 m0, s52, 0xe000
	s_nop 0
	global_load_lds_dwordx4 v[154:155], off
	s_waitcnt vmcnt(16)
	s_waitcnt lgkmcnt(0)
	.p2align 3
	s_setprio 1
	s_barrier
	v_mfma_f32_16x16x32_bf16 v[124:127], v[160:163], v[192:195], 0
	v_mfma_f32_16x16x32_bf16 v[116:119], v[168:171], v[192:195], 0
	v_mfma_f32_16x16x32_bf16 v[108:111], v[160:163], v[200:203], 0
	v_mfma_f32_16x16x32_bf16 v[100:103], v[168:171], v[200:203], 0
	v_mfma_f32_16x16x32_bf16 v[92:95], v[160:163], v[208:211], 0
	v_mfma_f32_16x16x32_bf16 v[84:87], v[168:171], v[208:211], 0
	v_mfma_f32_16x16x32_bf16 v[76:79], v[160:163], v[216:219], 0
	v_mfma_f32_16x16x32_bf16 v[68:71], v[168:171], v[216:219], 0
	v_mfma_f32_16x16x32_bf16 v[124:127], v[164:167], v[196:199], v[124:127]
	v_mfma_f32_16x16x32_bf16 v[116:119], v[172:175], v[196:199], v[116:119]
	v_mfma_f32_16x16x32_bf16 v[108:111], v[164:167], v[204:207], v[108:111]
	v_mfma_f32_16x16x32_bf16 v[100:103], v[172:175], v[204:207], v[100:103]
	v_mfma_f32_16x16x32_bf16 v[92:95], v[164:167], v[212:215], v[92:95]
	v_mfma_f32_16x16x32_bf16 v[84:87], v[172:175], v[212:215], v[84:87]
	v_mfma_f32_16x16x32_bf16 v[76:79], v[164:167], v[220:223], v[76:79]
	v_mfma_f32_16x16x32_bf16 v[68:71], v[172:175], v[220:223], v[68:71]
	s_setprio 0
	s_setprio 1
	v_mfma_f32_16x16x32_bf16 v[120:123], v[176:179], v[192:195], 0
	v_mfma_f32_16x16x32_bf16 v[112:115], v[184:187], v[192:195], 0
	v_mfma_f32_16x16x32_bf16 v[104:107], v[176:179], v[200:203], 0
	v_mfma_f32_16x16x32_bf16 v[96:99], v[184:187], v[200:203], 0
	v_mfma_f32_16x16x32_bf16 v[88:91], v[176:179], v[208:211], 0
	v_mfma_f32_16x16x32_bf16 v[80:83], v[184:187], v[208:211], 0
	v_mfma_f32_16x16x32_bf16 v[72:75], v[176:179], v[216:219], 0
	v_mfma_f32_16x16x32_bf16 v[64:67], v[184:187], v[216:219], 0
	v_mfma_f32_16x16x32_bf16 v[120:123], v[180:183], v[196:199], v[120:123]
	v_mfma_f32_16x16x32_bf16 v[112:115], v[188:191], v[196:199], v[112:115]
	v_mfma_f32_16x16x32_bf16 v[104:107], v[180:183], v[204:207], v[104:107]
	v_mfma_f32_16x16x32_bf16 v[96:99], v[188:191], v[204:207], v[96:99]
	v_mfma_f32_16x16x32_bf16 v[88:91], v[180:183], v[212:215], v[88:91]
	v_mfma_f32_16x16x32_bf16 v[80:83], v[188:191], v[212:215], v[80:83]
	v_mfma_f32_16x16x32_bf16 v[72:75], v[180:183], v[220:223], v[72:75]
	v_mfma_f32_16x16x32_bf16 v[64:67], v[188:191], v[220:223], v[64:67]
	s_barrier
	s_setprio 0
	s_add_i32 s71, s61, s49
	v_lshl_add_u64 v[154:155], s[44:45], 0, v[132:133]
	s_mov_b32 m0, s71
	ds_read_b128 v[192:195], v150 offset:16384
	v_xor_b32_e32 v253, 64, v150
	ds_read_b128 v[196:199], v253 offset:16384
	ds_read_b128 v[200:203], v150 offset:18432
	ds_read_b128 v[204:207], v253 offset:18432
	ds_read_b128 v[208:211], v150 offset:20480
	ds_read_b128 v[212:215], v253 offset:20480
	ds_read_b128 v[216:219], v150 offset:22528
	ds_read_b128 v[220:223], v253 offset:22528
	global_load_lds_dwordx4 v[154:155], off
	s_add_i32 m0, s71, 0x2000
	s_add_u32 s72, s44, 0x40000
	v_lshl_add_u64 v[224:225], s[44:45], 0, v[128:129]
	s_addc_u32 s73, s45, 0
	s_add_i32 s71, s62, s49
	global_load_lds_dwordx4 v[224:225], off
	v_lshl_add_u64 v[226:227], s[72:73], 0, v[132:133]
	s_mov_b32 m0, s71
	v_lshl_add_u64 v[228:229], s[46:47], 0, v[130:131]
	global_load_lds_dwordx4 v[226:227], off
	v_lshl_add_u64 v[226:227], s[72:73], 0, v[128:129]
	s_add_i32 m0, s71, 0x2000
	s_nop 0
	global_load_lds_dwordx4 v[226:227], off
	v_lshl_add_u64 v[226:227], s[46:47], 0, v[134:135]
	s_mov_b32 m0, s52
	s_nop 0
	global_load_lds_dwordx4 v[226:227], off
	s_mov_b32 m0, s53
	s_nop 0
	global_load_lds_dwordx4 v[228:229], off
	s_waitcnt vmcnt(16)
	s_waitcnt lgkmcnt(0)
	.p2align 3
	s_setprio 1
	s_barrier
	v_mfma_f32_16x16x32_bf16 v[60:63], v[160:163], v[192:195], 0
	v_mfma_f32_16x16x32_bf16 v[52:55], v[168:171], v[192:195], 0
	v_mfma_f32_16x16x32_bf16 v[44:47], v[160:163], v[200:203], 0
	v_mfma_f32_16x16x32_bf16 v[36:39], v[168:171], v[200:203], 0
	v_mfma_f32_16x16x32_bf16 v[28:31], v[160:163], v[208:211], 0
	v_mfma_f32_16x16x32_bf16 v[20:23], v[168:171], v[208:211], 0
	v_mfma_f32_16x16x32_bf16 v[12:15], v[160:163], v[216:219], 0
	v_mfma_f32_16x16x32_bf16 v[4:7], v[168:171], v[216:219], 0
	v_mfma_f32_16x16x32_bf16 v[60:63], v[164:167], v[196:199], v[60:63]
	v_mfma_f32_16x16x32_bf16 v[52:55], v[172:175], v[196:199], v[52:55]
	v_mfma_f32_16x16x32_bf16 v[44:47], v[164:167], v[204:207], v[44:47]
	v_mfma_f32_16x16x32_bf16 v[36:39], v[172:175], v[204:207], v[36:39]
	v_mfma_f32_16x16x32_bf16 v[28:31], v[164:167], v[212:215], v[28:31]
	v_mfma_f32_16x16x32_bf16 v[20:23], v[172:175], v[212:215], v[20:23]
	v_mfma_f32_16x16x32_bf16 v[12:15], v[164:167], v[220:223], v[12:15]
	v_mfma_f32_16x16x32_bf16 v[4:7], v[172:175], v[220:223], v[4:7]
	s_setprio 0
	s_setprio 1
	v_mfma_f32_16x16x32_bf16 v[56:59], v[176:179], v[192:195], 0
	v_mfma_f32_16x16x32_bf16 v[48:51], v[184:187], v[192:195], 0
	v_mfma_f32_16x16x32_bf16 v[40:43], v[176:179], v[200:203], 0
	v_mfma_f32_16x16x32_bf16 v[32:35], v[184:187], v[200:203], 0
	v_mfma_f32_16x16x32_bf16 v[24:27], v[176:179], v[208:211], 0
	v_mfma_f32_16x16x32_bf16 v[16:19], v[184:187], v[208:211], 0
	v_mfma_f32_16x16x32_bf16 v[8:11], v[176:179], v[216:219], 0
	v_mfma_f32_16x16x32_bf16 v[0:3], v[184:187], v[216:219], 0
	v_mfma_f32_16x16x32_bf16 v[56:59], v[180:183], v[196:199], v[56:59]
	v_mfma_f32_16x16x32_bf16 v[48:51], v[188:191], v[196:199], v[48:51]
	v_mfma_f32_16x16x32_bf16 v[40:43], v[180:183], v[204:207], v[40:43]
	v_mfma_f32_16x16x32_bf16 v[32:35], v[188:191], v[204:207], v[32:35]
	v_mfma_f32_16x16x32_bf16 v[24:27], v[180:183], v[212:215], v[24:27]
	v_mfma_f32_16x16x32_bf16 v[16:19], v[188:191], v[212:215], v[16:19]
	v_mfma_f32_16x16x32_bf16 v[8:11], v[180:183], v[220:223], v[8:11]
	v_mfma_f32_16x16x32_bf16 v[0:3], v[188:191], v[220:223], v[0:3]
	s_barrier
	s_setprio 0
	s_add_i32 s71, 0, 0x18000
	v_add_u32_e32 v153, s71, v147
	s_add_i32 s72, 0, 0x1c000
	ds_read_b128 v[160:163], v153
	v_xor_b32_e32 v253, 64, v153
	ds_read_b128 v[164:167], v253
	ds_read_b128 v[168:171], v153 offset:2048
	ds_read_b128 v[172:175], v253 offset:2048
	v_add_u32_e32 v153, s72, v147
	ds_read_b128 v[176:179], v153
	v_xor_b32_e32 v253, 64, v153
	ds_read_b128 v[180:183], v253
	ds_read_b128 v[184:187], v153 offset:2048
	ds_read_b128 v[188:191], v253 offset:2048
	s_add_u32 s46, s46, 0x40000
	s_addc_u32 s47, s47, 0
	s_mov_b32 m0, s54
	v_lshl_add_u64 v[230:231], s[46:47], 0, v[134:135]
	ds_read_b128 v[192:195], v150 offset:32768
	v_xor_b32_e32 v253, 64, v150
	ds_read_b128 v[196:199], v253 offset:32768
	ds_read_b128 v[200:203], v150 offset:34816
	ds_read_b128 v[204:207], v253 offset:34816
	ds_read_b128 v[208:211], v150 offset:36864
	ds_read_b128 v[212:215], v253 offset:36864
	ds_read_b128 v[216:219], v150 offset:38912
	ds_read_b128 v[220:223], v253 offset:38912
	global_load_lds_dwordx4 v[230:231], off
	v_lshl_add_u64 v[230:231], s[46:47], 0, v[130:131]
	s_mov_b32 m0, s55
	s_nop 0
	global_load_lds_dwordx4 v[230:231], off
	s_waitcnt vmcnt(8)
	s_waitcnt lgkmcnt(0)
	.p2align 3
	s_setprio 1
	s_barrier
	v_mfma_f32_16x16x32_bf16 v[124:127], v[160:163], v[192:195], v[124:127]
	v_mfma_f32_16x16x32_bf16 v[124:127], v[164:167], v[196:199], v[124:127]
	v_mfma_f32_16x16x32_bf16 v[116:119], v[172:175], v[196:199], v[116:119]
	v_mfma_f32_16x16x32_bf16 v[116:119], v[168:171], v[192:195], v[116:119]
	v_mfma_f32_16x16x32_bf16 v[100:103], v[168:171], v[200:203], v[100:103]
	v_mfma_f32_16x16x32_bf16 v[100:103], v[172:175], v[204:207], v[100:103]
	v_mfma_f32_16x16x32_bf16 v[108:111], v[164:167], v[204:207], v[108:111]
	v_mfma_f32_16x16x32_bf16 v[108:111], v[160:163], v[200:203], v[108:111]
	v_mfma_f32_16x16x32_bf16 v[92:95], v[160:163], v[208:211], v[92:95]
	v_mfma_f32_16x16x32_bf16 v[92:95], v[164:167], v[212:215], v[92:95]
	v_mfma_f32_16x16x32_bf16 v[84:87], v[172:175], v[212:215], v[84:87]
	v_mfma_f32_16x16x32_bf16 v[84:87], v[168:171], v[208:211], v[84:87]
	v_mfma_f32_16x16x32_bf16 v[68:71], v[168:171], v[216:219], v[68:71]
	v_mfma_f32_16x16x32_bf16 v[68:71], v[172:175], v[220:223], v[68:71]
	v_mfma_f32_16x16x32_bf16 v[76:79], v[164:167], v[220:223], v[76:79]
	v_mfma_f32_16x16x32_bf16 v[76:79], v[160:163], v[216:219], v[76:79]
	s_setprio 0
	s_setprio 1
	v_mfma_f32_16x16x32_bf16 v[120:123], v[176:179], v[192:195], v[120:123]
	v_mfma_f32_16x16x32_bf16 v[120:123], v[180:183], v[196:199], v[120:123]
	v_mfma_f32_16x16x32_bf16 v[112:115], v[188:191], v[196:199], v[112:115]
	v_mfma_f32_16x16x32_bf16 v[112:115], v[184:187], v[192:195], v[112:115]
	v_mfma_f32_16x16x32_bf16 v[96:99], v[184:187], v[200:203], v[96:99]
	v_mfma_f32_16x16x32_bf16 v[96:99], v[188:191], v[204:207], v[96:99]
	v_mfma_f32_16x16x32_bf16 v[104:107], v[180:183], v[204:207], v[104:107]
	v_mfma_f32_16x16x32_bf16 v[104:107], v[176:179], v[200:203], v[104:107]
	v_mfma_f32_16x16x32_bf16 v[88:91], v[176:179], v[208:211], v[88:91]
	v_mfma_f32_16x16x32_bf16 v[88:91], v[180:183], v[212:215], v[88:91]
	v_mfma_f32_16x16x32_bf16 v[80:83], v[188:191], v[212:215], v[80:83]
	v_mfma_f32_16x16x32_bf16 v[80:83], v[184:187], v[208:211], v[80:83]
	v_mfma_f32_16x16x32_bf16 v[64:67], v[184:187], v[216:219], v[64:67]
	v_mfma_f32_16x16x32_bf16 v[64:67], v[188:191], v[220:223], v[64:67]
	v_mfma_f32_16x16x32_bf16 v[72:75], v[180:183], v[220:223], v[72:75]
	v_mfma_f32_16x16x32_bf16 v[72:75], v[176:179], v[216:219], v[72:75]
	s_barrier
	s_setprio 0
	s_add_i32 s46, s71, s49
	v_lshl_add_u64 v[154:155], v[154:155], 0, s[14:15]
	s_mov_b32 m0, s46
	ds_read_b128 v[192:195], v150 offset:49152
	v_xor_b32_e32 v253, 64, v150
	ds_read_b128 v[196:199], v253 offset:49152
	ds_read_b128 v[200:203], v150 offset:51200
	ds_read_b128 v[204:207], v253 offset:51200
	ds_read_b128 v[208:211], v150 offset:53248
	ds_read_b128 v[212:215], v253 offset:53248
	ds_read_b128 v[216:219], v150 offset:55296
	ds_read_b128 v[220:223], v253 offset:55296
	global_load_lds_dwordx4 v[154:155], off
	s_add_i32 m0, s46, 0x2000
	s_add_u32 s44, s44, 0x40080
	v_lshl_add_u64 v[154:155], v[224:225], 0, s[14:15]
	s_addc_u32 s45, s45, 0
	s_add_i32 s46, s72, s49
	global_load_lds_dwordx4 v[154:155], off
	v_lshl_add_u64 v[154:155], s[44:45], 0, v[132:133]
	s_mov_b32 m0, s46
	s_nop 0
	global_load_lds_dwordx4 v[154:155], off
	v_lshl_add_u64 v[154:155], s[44:45], 0, v[128:129]
	s_add_i32 m0, s46, 0x2000
	s_nop 0
	global_load_lds_dwordx4 v[154:155], off
	v_lshl_add_u64 v[154:155], v[226:227], 0, s[14:15]
	s_mov_b32 m0, s57
	s_nop 0
	global_load_lds_dwordx4 v[154:155], off
	v_lshl_add_u64 v[154:155], v[228:229], 0, s[14:15]
	s_mov_b32 m0, s58
	s_nop 0
	global_load_lds_dwordx4 v[154:155], off
	s_waitcnt vmcnt(8)
	s_waitcnt lgkmcnt(0)
	.p2align 3
	s_setprio 1
	s_barrier
	v_mfma_f32_16x16x32_bf16 v[60:63], v[160:163], v[192:195], v[60:63]
	v_mfma_f32_16x16x32_bf16 v[60:63], v[164:167], v[196:199], v[60:63]
	v_mfma_f32_16x16x32_bf16 v[52:55], v[172:175], v[196:199], v[52:55]
	v_mfma_f32_16x16x32_bf16 v[52:55], v[168:171], v[192:195], v[52:55]
	v_mfma_f32_16x16x32_bf16 v[36:39], v[168:171], v[200:203], v[36:39]
	v_mfma_f32_16x16x32_bf16 v[36:39], v[172:175], v[204:207], v[36:39]
	v_mfma_f32_16x16x32_bf16 v[44:47], v[164:167], v[204:207], v[44:47]
	v_mfma_f32_16x16x32_bf16 v[44:47], v[160:163], v[200:203], v[44:47]
	v_mfma_f32_16x16x32_bf16 v[28:31], v[160:163], v[208:211], v[28:31]
	v_mfma_f32_16x16x32_bf16 v[28:31], v[164:167], v[212:215], v[28:31]
	v_mfma_f32_16x16x32_bf16 v[20:23], v[172:175], v[212:215], v[20:23]
	v_mfma_f32_16x16x32_bf16 v[20:23], v[168:171], v[208:211], v[20:23]
	v_mfma_f32_16x16x32_bf16 v[4:7], v[168:171], v[216:219], v[4:7]
	v_mfma_f32_16x16x32_bf16 v[4:7], v[172:175], v[220:223], v[4:7]
	v_mfma_f32_16x16x32_bf16 v[12:15], v[164:167], v[220:223], v[12:15]
	v_mfma_f32_16x16x32_bf16 v[12:15], v[160:163], v[216:219], v[12:15]
	s_setprio 0
	s_setprio 1
	v_mfma_f32_16x16x32_bf16 v[56:59], v[176:179], v[192:195], v[56:59]
	v_mfma_f32_16x16x32_bf16 v[56:59], v[180:183], v[196:199], v[56:59]
	v_mfma_f32_16x16x32_bf16 v[48:51], v[188:191], v[196:199], v[48:51]
	v_mfma_f32_16x16x32_bf16 v[48:51], v[184:187], v[192:195], v[48:51]
	v_mfma_f32_16x16x32_bf16 v[32:35], v[184:187], v[200:203], v[32:35]
	v_mfma_f32_16x16x32_bf16 v[32:35], v[188:191], v[204:207], v[32:35]
	v_mfma_f32_16x16x32_bf16 v[40:43], v[180:183], v[204:207], v[40:43]
	v_mfma_f32_16x16x32_bf16 v[40:43], v[176:179], v[200:203], v[40:43]
	v_mfma_f32_16x16x32_bf16 v[24:27], v[176:179], v[208:211], v[24:27]
	v_mfma_f32_16x16x32_bf16 v[24:27], v[180:183], v[212:215], v[24:27]
	v_mfma_f32_16x16x32_bf16 v[16:19], v[188:191], v[212:215], v[16:19]
	v_mfma_f32_16x16x32_bf16 v[16:19], v[184:187], v[208:211], v[16:19]
	v_mfma_f32_16x16x32_bf16 v[0:3], v[184:187], v[216:219], v[0:3]
	v_mfma_f32_16x16x32_bf16 v[0:3], v[188:191], v[220:223], v[0:3]
	v_mfma_f32_16x16x32_bf16 v[8:11], v[180:183], v[220:223], v[8:11]
	v_mfma_f32_16x16x32_bf16 v[8:11], v[176:179], v[216:219], v[8:11]
	s_barrier
	s_setprio 0
	s_add_i32 s70, s70, 2
	s_add_u32 s68, s68, 0x100
	s_addc_u32 s69, s69, 0
	s_add_u32 s30, s30, 0x100
	s_addc_u32 s31, s31, 0
	s_branch .LBB0_1098
.Lfa_10:
	v_add_u32_e32 v153, s61, v147
	ds_read_b128 v[160:163], v153
	v_xor_b32_e32 v253, 64, v153
	ds_read_b128 v[164:167], v253
	ds_read_b128 v[168:171], v153 offset:2048
	ds_read_b128 v[172:175], v253 offset:2048
	v_add_u32_e32 v153, s62, v147
	ds_read_b128 v[176:179], v153
	v_xor_b32_e32 v253, 64, v153
	ds_read_b128 v[180:183], v253
	ds_read_b128 v[184:187], v153 offset:2048
	ds_read_b128 v[188:191], v253 offset:2048
	s_add_u32 s46, s30, 0xfffc0080
	s_addc_u32 s47, s31, -1
	s_and_b64 s[44:45], s[44:45], exec
	s_cselect_b32 s47, s25, s47
	s_cselect_b32 s46, s65, s46
	s_cselect_b32 s45, s66, s69
	s_cselect_b32 s44, s67, s68
	v_lshl_add_u64 v[154:155], s[30:31], 0, v[138:139]
	s_add_i32 m0, s52, 0xc000
	ds_read_b128 v[192:195], v150
	v_xor_b32_e32 v253, 64, v150
	ds_read_b128 v[196:199], v253
	ds_read_b128 v[200:203], v150 offset:2048
	ds_read_b128 v[204:207], v253 offset:2048
	ds_read_b128 v[208:211], v150 offset:4096
	ds_read_b128 v[212:215], v253 offset:4096
	ds_read_b128 v[216:219], v150 offset:6144
	ds_read_b128 v[220:223], v253 offset:6144
	global_load_lds_dwordx4 v[154:155], off
	v_lshl_add_u64 v[154:155], s[30:31], 0, v[136:137]
	s_add_i32 m0, s52, 0xe000
	s_nop 0
	global_load_lds_dwordx4 v[154:155], off
	s_waitcnt vmcnt(8)
	s_waitcnt lgkmcnt(0)
	.p2align 3
	s_setprio 1
	s_barrier
	v_mfma_f32_16x16x32_bf16 v[124:127], v[160:163], v[192:195], 0
	v_mfma_f32_16x16x32_bf16 v[116:119], v[168:171], v[192:195], 0
	v_mfma_f32_16x16x32_bf16 v[108:111], v[160:163], v[200:203], 0
	v_mfma_f32_16x16x32_bf16 v[100:103], v[168:171], v[200:203], 0
	v_mfma_f32_16x16x32_bf16 v[92:95], v[160:163], v[208:211], 0
	v_mfma_f32_16x16x32_bf16 v[84:87], v[168:171], v[208:211], 0
	v_mfma_f32_16x16x32_bf16 v[76:79], v[160:163], v[216:219], 0
	v_mfma_f32_16x16x32_bf16 v[68:71], v[168:171], v[216:219], 0
	v_mfma_f32_16x16x32_bf16 v[124:127], v[164:167], v[196:199], v[124:127]
	v_mfma_f32_16x16x32_bf16 v[116:119], v[172:175], v[196:199], v[116:119]
	v_mfma_f32_16x16x32_bf16 v[108:111], v[164:167], v[204:207], v[108:111]
	v_mfma_f32_16x16x32_bf16 v[100:103], v[172:175], v[204:207], v[100:103]
	v_mfma_f32_16x16x32_bf16 v[92:95], v[164:167], v[212:215], v[92:95]
	v_mfma_f32_16x16x32_bf16 v[84:87], v[172:175], v[212:215], v[84:87]
	v_mfma_f32_16x16x32_bf16 v[76:79], v[164:167], v[220:223], v[76:79]
	v_mfma_f32_16x16x32_bf16 v[68:71], v[172:175], v[220:223], v[68:71]
	s_setprio 0
	s_setprio 1
	v_mfma_f32_16x16x32_bf16 v[120:123], v[176:179], v[192:195], 0
	v_mfma_f32_16x16x32_bf16 v[112:115], v[184:187], v[192:195], 0
	v_mfma_f32_16x16x32_bf16 v[104:107], v[176:179], v[200:203], 0
	v_mfma_f32_16x16x32_bf16 v[96:99], v[184:187], v[200:203], 0
	v_mfma_f32_16x16x32_bf16 v[88:91], v[176:179], v[208:211], 0
	v_mfma_f32_16x16x32_bf16 v[80:83], v[184:187], v[208:211], 0
	v_mfma_f32_16x16x32_bf16 v[72:75], v[176:179], v[216:219], 0
	v_mfma_f32_16x16x32_bf16 v[64:67], v[184:187], v[216:219], 0
	v_mfma_f32_16x16x32_bf16 v[120:123], v[180:183], v[196:199], v[120:123]
	v_mfma_f32_16x16x32_bf16 v[112:115], v[188:191], v[196:199], v[112:115]
	v_mfma_f32_16x16x32_bf16 v[104:107], v[180:183], v[204:207], v[104:107]
	v_mfma_f32_16x16x32_bf16 v[96:99], v[188:191], v[204:207], v[96:99]
	v_mfma_f32_16x16x32_bf16 v[88:91], v[180:183], v[212:215], v[88:91]
	v_mfma_f32_16x16x32_bf16 v[80:83], v[188:191], v[212:215], v[80:83]
	v_mfma_f32_16x16x32_bf16 v[72:75], v[180:183], v[220:223], v[72:75]
	v_mfma_f32_16x16x32_bf16 v[64:67], v[188:191], v[220:223], v[64:67]
	s_barrier
	s_setprio 0
	s_add_i32 s71, s61, s49
	v_lshl_add_u64 v[154:155], s[44:45], 0, v[132:133]
	s_mov_b32 m0, s71
	ds_read_b128 v[192:195], v150 offset:16384
	v_xor_b32_e32 v253, 64, v150
	ds_read_b128 v[196:199], v253 offset:16384
	ds_read_b128 v[200:203], v150 offset:18432
	ds_read_b128 v[204:207], v253 offset:18432
	ds_read_b128 v[208:211], v150 offset:20480
	ds_read_b128 v[212:215], v253 offset:20480
	ds_read_b128 v[216:219], v150 offset:22528
	ds_read_b128 v[220:223], v253 offset:22528
	global_load_lds_dwordx4 v[154:155], off
	s_add_i32 m0, s71, 0x2000
	s_add_u32 s72, s44, 0x40000
	v_lshl_add_u64 v[224:225], s[44:45], 0, v[128:129]
	s_addc_u32 s73, s45, 0
	s_add_i32 s71, s62, s49
	global_load_lds_dwordx4 v[224:225], off
	v_lshl_add_u64 v[226:227], s[72:73], 0, v[132:133]
	s_mov_b32 m0, s71
	v_lshl_add_u64 v[228:229], s[46:47], 0, v[130:131]
	global_load_lds_dwordx4 v[226:227], off
	v_lshl_add_u64 v[226:227], s[72:73], 0, v[128:129]
	s_add_i32 m0, s71, 0x2000
	s_nop 0
	global_load_lds_dwordx4 v[226:227], off
	v_lshl_add_u64 v[226:227], s[46:47], 0, v[134:135]
	s_mov_b32 m0, s52
	s_nop 0
	global_load_lds_dwordx4 v[226:227], off
	s_mov_b32 m0, s53
	s_nop 0
	global_load_lds_dwordx4 v[228:229], off
	s_waitcnt vmcnt(8)
	s_waitcnt lgkmcnt(0)
	.p2align 3
	s_setprio 1
	s_barrier
	v_mfma_f32_16x16x32_bf16 v[60:63], v[160:163], v[192:195], 0
	v_mfma_f32_16x16x32_bf16 v[52:55], v[168:171], v[192:195], 0
	v_mfma_f32_16x16x32_bf16 v[44:47], v[160:163], v[200:203], 0
	v_mfma_f32_16x16x32_bf16 v[36:39], v[168:171], v[200:203], 0
	v_mfma_f32_16x16x32_bf16 v[28:31], v[160:163], v[208:211], 0
	v_mfma_f32_16x16x32_bf16 v[20:23], v[168:171], v[208:211], 0
	v_mfma_f32_16x16x32_bf16 v[12:15], v[160:163], v[216:219], 0
	v_mfma_f32_16x16x32_bf16 v[4:7], v[168:171], v[216:219], 0
	v_mfma_f32_16x16x32_bf16 v[60:63], v[164:167], v[196:199], v[60:63]
	v_mfma_f32_16x16x32_bf16 v[52:55], v[172:175], v[196:199], v[52:55]
	v_mfma_f32_16x16x32_bf16 v[44:47], v[164:167], v[204:207], v[44:47]
	v_mfma_f32_16x16x32_bf16 v[36:39], v[172:175], v[204:207], v[36:39]
	v_mfma_f32_16x16x32_bf16 v[28:31], v[164:167], v[212:215], v[28:31]
	v_mfma_f32_16x16x32_bf16 v[20:23], v[172:175], v[212:215], v[20:23]
	v_mfma_f32_16x16x32_bf16 v[12:15], v[164:167], v[220:223], v[12:15]
	v_mfma_f32_16x16x32_bf16 v[4:7], v[172:175], v[220:223], v[4:7]
	s_setprio 0
	s_setprio 1
	v_mfma_f32_16x16x32_bf16 v[56:59], v[176:179], v[192:195], 0
	v_mfma_f32_16x16x32_bf16 v[48:51], v[184:187], v[192:195], 0
	v_mfma_f32_16x16x32_bf16 v[40:43], v[176:179], v[200:203], 0
	v_mfma_f32_16x16x32_bf16 v[32:35], v[184:187], v[200:203], 0
	v_mfma_f32_16x16x32_bf16 v[24:27], v[176:179], v[208:211], 0
	v_mfma_f32_16x16x32_bf16 v[16:19], v[184:187], v[208:211], 0
	v_mfma_f32_16x16x32_bf16 v[8:11], v[176:179], v[216:219], 0
	v_mfma_f32_16x16x32_bf16 v[0:3], v[184:187], v[216:219], 0
	v_mfma_f32_16x16x32_bf16 v[56:59], v[180:183], v[196:199], v[56:59]
	v_mfma_f32_16x16x32_bf16 v[48:51], v[188:191], v[196:199], v[48:51]
	v_mfma_f32_16x16x32_bf16 v[40:43], v[180:183], v[204:207], v[40:43]
	v_mfma_f32_16x16x32_bf16 v[32:35], v[188:191], v[204:207], v[32:35]
	v_mfma_f32_16x16x32_bf16 v[24:27], v[180:183], v[212:215], v[24:27]
	v_mfma_f32_16x16x32_bf16 v[16:19], v[188:191], v[212:215], v[16:19]
	v_mfma_f32_16x16x32_bf16 v[8:11], v[180:183], v[220:223], v[8:11]
	v_mfma_f32_16x16x32_bf16 v[0:3], v[188:191], v[220:223], v[0:3]
	s_barrier
	s_setprio 0
	s_add_i32 s71, 0, 0x18000
	v_add_u32_e32 v153, s71, v147
	s_add_i32 s72, 0, 0x1c000
	ds_read_b128 v[160:163], v153
	v_xor_b32_e32 v253, 64, v153
	ds_read_b128 v[164:167], v253
	ds_read_b128 v[168:171], v153 offset:2048
	ds_read_b128 v[172:175], v253 offset:2048
	v_add_u32_e32 v153, s72, v147
	ds_read_b128 v[176:179], v153
	v_xor_b32_e32 v253, 64, v153
	ds_read_b128 v[180:183], v253
	ds_read_b128 v[184:187], v153 offset:2048
	ds_read_b128 v[188:191], v253 offset:2048
	s_add_u32 s46, s46, 0x40000
	s_addc_u32 s47, s47, 0
	s_mov_b32 m0, s54
	v_lshl_add_u64 v[230:231], s[46:47], 0, v[134:135]
	ds_read_b128 v[192:195], v150 offset:32768
	v_xor_b32_e32 v253, 64, v150
	ds_read_b128 v[196:199], v253 offset:32768
	ds_read_b128 v[200:203], v150 offset:34816
	ds_read_b128 v[204:207], v253 offset:34816
	ds_read_b128 v[208:211], v150 offset:36864
	ds_read_b128 v[212:215], v253 offset:36864
	ds_read_b128 v[216:219], v150 offset:38912
	ds_read_b128 v[220:223], v253 offset:38912
	global_load_lds_dwordx4 v[230:231], off
	v_lshl_add_u64 v[230:231], s[46:47], 0, v[130:131]
	s_mov_b32 m0, s55
	s_nop 0
	global_load_lds_dwordx4 v[230:231], off
	s_waitcnt vmcnt(8)
	s_waitcnt lgkmcnt(0)
	.p2align 3
	s_setprio 1
	s_barrier
	v_mfma_f32_16x16x32_bf16 v[124:127], v[160:163], v[192:195], v[124:127]
	v_mfma_f32_16x16x32_bf16 v[124:127], v[164:167], v[196:199], v[124:127]
	v_mfma_f32_16x16x32_bf16 v[116:119], v[172:175], v[196:199], v[116:119]
	v_mfma_f32_16x16x32_bf16 v[116:119], v[168:171], v[192:195], v[116:119]
	v_mfma_f32_16x16x32_bf16 v[100:103], v[168:171], v[200:203], v[100:103]
	v_mfma_f32_16x16x32_bf16 v[100:103], v[172:175], v[204:207], v[100:103]
	v_mfma_f32_16x16x32_bf16 v[108:111], v[164:167], v[204:207], v[108:111]
	v_mfma_f32_16x16x32_bf16 v[108:111], v[160:163], v[200:203], v[108:111]
	v_mfma_f32_16x16x32_bf16 v[92:95], v[160:163], v[208:211], v[92:95]
	v_mfma_f32_16x16x32_bf16 v[92:95], v[164:167], v[212:215], v[92:95]
	v_mfma_f32_16x16x32_bf16 v[84:87], v[172:175], v[212:215], v[84:87]
	v_mfma_f32_16x16x32_bf16 v[84:87], v[168:171], v[208:211], v[84:87]
	v_mfma_f32_16x16x32_bf16 v[68:71], v[168:171], v[216:219], v[68:71]
	v_mfma_f32_16x16x32_bf16 v[68:71], v[172:175], v[220:223], v[68:71]
	v_mfma_f32_16x16x32_bf16 v[76:79], v[164:167], v[220:223], v[76:79]
	v_mfma_f32_16x16x32_bf16 v[76:79], v[160:163], v[216:219], v[76:79]
	s_setprio 0
	s_setprio 1
	v_mfma_f32_16x16x32_bf16 v[120:123], v[176:179], v[192:195], v[120:123]
	v_mfma_f32_16x16x32_bf16 v[120:123], v[180:183], v[196:199], v[120:123]
	v_mfma_f32_16x16x32_bf16 v[112:115], v[188:191], v[196:199], v[112:115]
	v_mfma_f32_16x16x32_bf16 v[112:115], v[184:187], v[192:195], v[112:115]
	v_mfma_f32_16x16x32_bf16 v[96:99], v[184:187], v[200:203], v[96:99]
	v_mfma_f32_16x16x32_bf16 v[96:99], v[188:191], v[204:207], v[96:99]
	v_mfma_f32_16x16x32_bf16 v[104:107], v[180:183], v[204:207], v[104:107]
	v_mfma_f32_16x16x32_bf16 v[104:107], v[176:179], v[200:203], v[104:107]
	v_mfma_f32_16x16x32_bf16 v[88:91], v[176:179], v[208:211], v[88:91]
	v_mfma_f32_16x16x32_bf16 v[88:91], v[180:183], v[212:215], v[88:91]
	v_mfma_f32_16x16x32_bf16 v[80:83], v[188:191], v[212:215], v[80:83]
	v_mfma_f32_16x16x32_bf16 v[80:83], v[184:187], v[208:211], v[80:83]
	v_mfma_f32_16x16x32_bf16 v[64:67], v[184:187], v[216:219], v[64:67]
	v_mfma_f32_16x16x32_bf16 v[64:67], v[188:191], v[220:223], v[64:67]
	v_mfma_f32_16x16x32_bf16 v[72:75], v[180:183], v[220:223], v[72:75]
	v_mfma_f32_16x16x32_bf16 v[72:75], v[176:179], v[216:219], v[72:75]
	s_barrier
	s_setprio 0
	s_add_i32 s46, s71, s49
	v_lshl_add_u64 v[154:155], v[154:155], 0, s[14:15]
	s_mov_b32 m0, s46
	ds_read_b128 v[192:195], v150 offset:49152
	v_xor_b32_e32 v253, 64, v150
	ds_read_b128 v[196:199], v253 offset:49152
	ds_read_b128 v[200:203], v150 offset:51200
	ds_read_b128 v[204:207], v253 offset:51200
	ds_read_b128 v[208:211], v150 offset:53248
	ds_read_b128 v[212:215], v253 offset:53248
	ds_read_b128 v[216:219], v150 offset:55296
	ds_read_b128 v[220:223], v253 offset:55296
	global_load_lds_dwordx4 v[154:155], off
	s_add_i32 m0, s46, 0x2000
	s_add_u32 s44, s44, 0x40080
	v_lshl_add_u64 v[154:155], v[224:225], 0, s[14:15]
	s_addc_u32 s45, s45, 0
	s_add_i32 s46, s72, s49
	global_load_lds_dwordx4 v[154:155], off
	v_lshl_add_u64 v[154:155], s[44:45], 0, v[132:133]
	s_mov_b32 m0, s46
	s_nop 0
	global_load_lds_dwordx4 v[154:155], off
	v_lshl_add_u64 v[154:155], s[44:45], 0, v[128:129]
	s_add_i32 m0, s46, 0x2000
	s_nop 0
	global_load_lds_dwordx4 v[154:155], off
	v_lshl_add_u64 v[154:155], v[226:227], 0, s[14:15]
	s_mov_b32 m0, s57
	s_nop 0
	global_load_lds_dwordx4 v[154:155], off
	v_lshl_add_u64 v[154:155], v[228:229], 0, s[14:15]
	s_mov_b32 m0, s58
	s_nop 0
	global_load_lds_dwordx4 v[154:155], off
	s_waitcnt vmcnt(8)
	s_waitcnt lgkmcnt(0)
	.p2align 3
	s_setprio 1
	s_barrier
	v_mfma_f32_16x16x32_bf16 v[60:63], v[160:163], v[192:195], v[60:63]
	v_mfma_f32_16x16x32_bf16 v[60:63], v[164:167], v[196:199], v[60:63]
	v_mfma_f32_16x16x32_bf16 v[52:55], v[172:175], v[196:199], v[52:55]
	v_mfma_f32_16x16x32_bf16 v[52:55], v[168:171], v[192:195], v[52:55]
	v_mfma_f32_16x16x32_bf16 v[36:39], v[168:171], v[200:203], v[36:39]
	v_mfma_f32_16x16x32_bf16 v[36:39], v[172:175], v[204:207], v[36:39]
	v_mfma_f32_16x16x32_bf16 v[44:47], v[164:167], v[204:207], v[44:47]
	v_mfma_f32_16x16x32_bf16 v[44:47], v[160:163], v[200:203], v[44:47]
	v_mfma_f32_16x16x32_bf16 v[28:31], v[160:163], v[208:211], v[28:31]
	v_mfma_f32_16x16x32_bf16 v[28:31], v[164:167], v[212:215], v[28:31]
	v_mfma_f32_16x16x32_bf16 v[20:23], v[172:175], v[212:215], v[20:23]
	v_mfma_f32_16x16x32_bf16 v[20:23], v[168:171], v[208:211], v[20:23]
	v_mfma_f32_16x16x32_bf16 v[4:7], v[168:171], v[216:219], v[4:7]
	v_mfma_f32_16x16x32_bf16 v[4:7], v[172:175], v[220:223], v[4:7]
	v_mfma_f32_16x16x32_bf16 v[12:15], v[164:167], v[220:223], v[12:15]
	v_mfma_f32_16x16x32_bf16 v[12:15], v[160:163], v[216:219], v[12:15]
	s_setprio 0
	s_setprio 1
	v_mfma_f32_16x16x32_bf16 v[56:59], v[176:179], v[192:195], v[56:59]
	v_mfma_f32_16x16x32_bf16 v[56:59], v[180:183], v[196:199], v[56:59]
	v_mfma_f32_16x16x32_bf16 v[48:51], v[188:191], v[196:199], v[48:51]
	v_mfma_f32_16x16x32_bf16 v[48:51], v[184:187], v[192:195], v[48:51]
	v_mfma_f32_16x16x32_bf16 v[32:35], v[184:187], v[200:203], v[32:35]
	v_mfma_f32_16x16x32_bf16 v[32:35], v[188:191], v[204:207], v[32:35]
	v_mfma_f32_16x16x32_bf16 v[40:43], v[180:183], v[204:207], v[40:43]
	v_mfma_f32_16x16x32_bf16 v[40:43], v[176:179], v[200:203], v[40:43]
	v_mfma_f32_16x16x32_bf16 v[24:27], v[176:179], v[208:211], v[24:27]
	v_mfma_f32_16x16x32_bf16 v[24:27], v[180:183], v[212:215], v[24:27]
	v_mfma_f32_16x16x32_bf16 v[16:19], v[188:191], v[212:215], v[16:19]
	v_mfma_f32_16x16x32_bf16 v[16:19], v[184:187], v[208:211], v[16:19]
	v_mfma_f32_16x16x32_bf16 v[0:3], v[184:187], v[216:219], v[0:3]
	v_mfma_f32_16x16x32_bf16 v[0:3], v[188:191], v[220:223], v[0:3]
	v_mfma_f32_16x16x32_bf16 v[8:11], v[180:183], v[220:223], v[8:11]
	v_mfma_f32_16x16x32_bf16 v[8:11], v[176:179], v[216:219], v[8:11]
	s_barrier
	s_setprio 0
	s_add_i32 s70, s70, 2
	s_add_u32 s68, s68, 0x100
	s_addc_u32 s69, s69, 0
	s_add_u32 s30, s30, 0x100
	s_addc_u32 s31, s31, 0
	s_branch .LBB0_1098
.LBB0_1097:
	v_add_u32_e32 v153, s61, v147
	ds_read_b128 v[160:163], v153
	v_xor_b32_e32 v253, 64, v153
	ds_read_b128 v[164:167], v253
	ds_read_b128 v[168:171], v153 offset:2048
	ds_read_b128 v[172:175], v253 offset:2048
	v_add_u32_e32 v153, s62, v147
	ds_read_b128 v[176:179], v153
	v_xor_b32_e32 v253, 64, v153
	ds_read_b128 v[180:183], v253
	ds_read_b128 v[184:187], v153 offset:2048
	ds_read_b128 v[188:191], v253 offset:2048
	s_add_u32 s46, s30, 0xfffc0080
	s_addc_u32 s47, s31, -1
	s_and_b64 s[44:45], s[44:45], exec
	s_cselect_b32 s47, s25, s47
	s_cselect_b32 s46, s65, s46
	s_cselect_b32 s45, s66, s69
	s_cselect_b32 s44, s67, s68
	v_lshl_add_u64 v[154:155], s[30:31], 0, v[138:139]
	s_add_i32 m0, s52, 0xc000
	ds_read_b128 v[192:195], v150
	v_xor_b32_e32 v253, 64, v150
	ds_read_b128 v[196:199], v253
	ds_read_b128 v[200:203], v150 offset:2048
	ds_read_b128 v[204:207], v253 offset:2048
	ds_read_b128 v[208:211], v150 offset:4096
	ds_read_b128 v[212:215], v253 offset:4096
	ds_read_b128 v[216:219], v150 offset:6144
	ds_read_b128 v[220:223], v253 offset:6144
	global_load_lds_dwordx4 v[154:155], off
	v_lshl_add_u64 v[154:155], s[30:31], 0, v[136:137]
	s_add_i32 m0, s52, 0xe000
	s_nop 0
	global_load_lds_dwordx4 v[154:155], off
	s_waitcnt vmcnt(8)
	s_waitcnt lgkmcnt(0)
	.p2align 3
	s_setprio 1
	s_barrier
	v_mfma_f32_16x16x32_bf16 v[124:127], v[160:163], v[192:195], v[124:127]
	v_mfma_f32_16x16x32_bf16 v[124:127], v[164:167], v[196:199], v[124:127]
	v_mfma_f32_16x16x32_bf16 v[116:119], v[172:175], v[196:199], v[116:119]
	v_mfma_f32_16x16x32_bf16 v[116:119], v[168:171], v[192:195], v[116:119]
	v_mfma_f32_16x16x32_bf16 v[100:103], v[168:171], v[200:203], v[100:103]
	v_mfma_f32_16x16x32_bf16 v[100:103], v[172:175], v[204:207], v[100:103]
	v_mfma_f32_16x16x32_bf16 v[108:111], v[164:167], v[204:207], v[108:111]
	v_mfma_f32_16x16x32_bf16 v[108:111], v[160:163], v[200:203], v[108:111]
	v_mfma_f32_16x16x32_bf16 v[92:95], v[160:163], v[208:211], v[92:95]
	v_mfma_f32_16x16x32_bf16 v[92:95], v[164:167], v[212:215], v[92:95]
	v_mfma_f32_16x16x32_bf16 v[84:87], v[172:175], v[212:215], v[84:87]
	v_mfma_f32_16x16x32_bf16 v[84:87], v[168:171], v[208:211], v[84:87]
	v_mfma_f32_16x16x32_bf16 v[68:71], v[168:171], v[216:219], v[68:71]
	v_mfma_f32_16x16x32_bf16 v[68:71], v[172:175], v[220:223], v[68:71]
	v_mfma_f32_16x16x32_bf16 v[76:79], v[164:167], v[220:223], v[76:79]
	v_mfma_f32_16x16x32_bf16 v[76:79], v[160:163], v[216:219], v[76:79]
	s_setprio 0
	s_setprio 1
	v_mfma_f32_16x16x32_bf16 v[120:123], v[176:179], v[192:195], v[120:123]
	v_mfma_f32_16x16x32_bf16 v[120:123], v[180:183], v[196:199], v[120:123]
	v_mfma_f32_16x16x32_bf16 v[112:115], v[188:191], v[196:199], v[112:115]
	v_mfma_f32_16x16x32_bf16 v[112:115], v[184:187], v[192:195], v[112:115]
	v_mfma_f32_16x16x32_bf16 v[96:99], v[184:187], v[200:203], v[96:99]
	v_mfma_f32_16x16x32_bf16 v[96:99], v[188:191], v[204:207], v[96:99]
	v_mfma_f32_16x16x32_bf16 v[104:107], v[180:183], v[204:207], v[104:107]
	v_mfma_f32_16x16x32_bf16 v[104:107], v[176:179], v[200:203], v[104:107]
	v_mfma_f32_16x16x32_bf16 v[88:91], v[176:179], v[208:211], v[88:91]
	v_mfma_f32_16x16x32_bf16 v[88:91], v[180:183], v[212:215], v[88:91]
	v_mfma_f32_16x16x32_bf16 v[80:83], v[188:191], v[212:215], v[80:83]
	v_mfma_f32_16x16x32_bf16 v[80:83], v[184:187], v[208:211], v[80:83]
	v_mfma_f32_16x16x32_bf16 v[64:67], v[184:187], v[216:219], v[64:67]
	v_mfma_f32_16x16x32_bf16 v[64:67], v[188:191], v[220:223], v[64:67]
	v_mfma_f32_16x16x32_bf16 v[72:75], v[180:183], v[220:223], v[72:75]
	v_mfma_f32_16x16x32_bf16 v[72:75], v[176:179], v[216:219], v[72:75]
	s_barrier
	s_setprio 0
	s_add_i32 s71, s61, s49
	v_lshl_add_u64 v[154:155], s[44:45], 0, v[132:133]
	s_mov_b32 m0, s71
	ds_read_b128 v[192:195], v150 offset:16384
	v_xor_b32_e32 v253, 64, v150
	ds_read_b128 v[196:199], v253 offset:16384
	ds_read_b128 v[200:203], v150 offset:18432
	ds_read_b128 v[204:207], v253 offset:18432
	ds_read_b128 v[208:211], v150 offset:20480
	ds_read_b128 v[212:215], v253 offset:20480
	ds_read_b128 v[216:219], v150 offset:22528
	ds_read_b128 v[220:223], v253 offset:22528
	global_load_lds_dwordx4 v[154:155], off
	s_add_i32 m0, s71, 0x2000
	s_add_u32 s72, s44, 0x40000
	v_lshl_add_u64 v[224:225], s[44:45], 0, v[128:129]
	s_addc_u32 s73, s45, 0
	s_add_i32 s71, s62, s49
	global_load_lds_dwordx4 v[224:225], off
	v_lshl_add_u64 v[226:227], s[72:73], 0, v[132:133]
	s_mov_b32 m0, s71
	v_lshl_add_u64 v[228:229], s[46:47], 0, v[130:131]
	global_load_lds_dwordx4 v[226:227], off
	v_lshl_add_u64 v[226:227], s[72:73], 0, v[128:129]
	s_add_i32 m0, s71, 0x2000
	s_nop 0
	global_load_lds_dwordx4 v[226:227], off
	v_lshl_add_u64 v[226:227], s[46:47], 0, v[134:135]
	s_mov_b32 m0, s52
	s_nop 0
	global_load_lds_dwordx4 v[226:227], off
	s_mov_b32 m0, s53
	s_nop 0
	global_load_lds_dwordx4 v[228:229], off
	s_waitcnt vmcnt(8)
	s_waitcnt lgkmcnt(0)
	.p2align 3
	s_setprio 1
	s_barrier
	v_mfma_f32_16x16x32_bf16 v[60:63], v[160:163], v[192:195], v[60:63]
	v_mfma_f32_16x16x32_bf16 v[60:63], v[164:167], v[196:199], v[60:63]
	v_mfma_f32_16x16x32_bf16 v[52:55], v[172:175], v[196:199], v[52:55]
	v_mfma_f32_16x16x32_bf16 v[52:55], v[168:171], v[192:195], v[52:55]
	v_mfma_f32_16x16x32_bf16 v[36:39], v[168:171], v[200:203], v[36:39]
	v_mfma_f32_16x16x32_bf16 v[36:39], v[172:175], v[204:207], v[36:39]
	v_mfma_f32_16x16x32_bf16 v[44:47], v[164:167], v[204:207], v[44:47]
	v_mfma_f32_16x16x32_bf16 v[44:47], v[160:163], v[200:203], v[44:47]
	v_mfma_f32_16x16x32_bf16 v[28:31], v[160:163], v[208:211], v[28:31]
	v_mfma_f32_16x16x32_bf16 v[28:31], v[164:167], v[212:215], v[28:31]
	v_mfma_f32_16x16x32_bf16 v[20:23], v[172:175], v[212:215], v[20:23]
	v_mfma_f32_16x16x32_bf16 v[20:23], v[168:171], v[208:211], v[20:23]
	v_mfma_f32_16x16x32_bf16 v[4:7], v[168:171], v[216:219], v[4:7]
	v_mfma_f32_16x16x32_bf16 v[4:7], v[172:175], v[220:223], v[4:7]
	v_mfma_f32_16x16x32_bf16 v[12:15], v[164:167], v[220:223], v[12:15]
	v_mfma_f32_16x16x32_bf16 v[12:15], v[160:163], v[216:219], v[12:15]
	s_setprio 0
	s_setprio 1
	v_mfma_f32_16x16x32_bf16 v[56:59], v[176:179], v[192:195], v[56:59]
	v_mfma_f32_16x16x32_bf16 v[56:59], v[180:183], v[196:199], v[56:59]
	v_mfma_f32_16x16x32_bf16 v[48:51], v[188:191], v[196:199], v[48:51]
	v_mfma_f32_16x16x32_bf16 v[48:51], v[184:187], v[192:195], v[48:51]
	v_mfma_f32_16x16x32_bf16 v[32:35], v[184:187], v[200:203], v[32:35]
	v_mfma_f32_16x16x32_bf16 v[32:35], v[188:191], v[204:207], v[32:35]
	v_mfma_f32_16x16x32_bf16 v[40:43], v[180:183], v[204:207], v[40:43]
	v_mfma_f32_16x16x32_bf16 v[40:43], v[176:179], v[200:203], v[40:43]
	v_mfma_f32_16x16x32_bf16 v[24:27], v[176:179], v[208:211], v[24:27]
	v_mfma_f32_16x16x32_bf16 v[24:27], v[180:183], v[212:215], v[24:27]
	v_mfma_f32_16x16x32_bf16 v[16:19], v[188:191], v[212:215], v[16:19]
	v_mfma_f32_16x16x32_bf16 v[16:19], v[184:187], v[208:211], v[16:19]
	v_mfma_f32_16x16x32_bf16 v[0:3], v[184:187], v[216:219], v[0:3]
	v_mfma_f32_16x16x32_bf16 v[0:3], v[188:191], v[220:223], v[0:3]
	v_mfma_f32_16x16x32_bf16 v[8:11], v[180:183], v[220:223], v[8:11]
	v_mfma_f32_16x16x32_bf16 v[8:11], v[176:179], v[216:219], v[8:11]
	s_barrier
	s_setprio 0
	s_add_i32 s71, 0, 0x18000
	v_add_u32_e32 v153, s71, v147
	s_add_i32 s72, 0, 0x1c000
	ds_read_b128 v[160:163], v153
	v_xor_b32_e32 v253, 64, v153
	ds_read_b128 v[164:167], v253
	ds_read_b128 v[168:171], v153 offset:2048
	ds_read_b128 v[172:175], v253 offset:2048
	v_add_u32_e32 v153, s72, v147
	ds_read_b128 v[176:179], v153
	v_xor_b32_e32 v253, 64, v153
	ds_read_b128 v[180:183], v253
	ds_read_b128 v[184:187], v153 offset:2048
	ds_read_b128 v[188:191], v253 offset:2048
	s_add_u32 s46, s46, 0x40000
	s_addc_u32 s47, s47, 0
	s_mov_b32 m0, s54
	v_lshl_add_u64 v[230:231], s[46:47], 0, v[134:135]
	ds_read_b128 v[192:195], v150 offset:32768
	v_xor_b32_e32 v253, 64, v150
	ds_read_b128 v[196:199], v253 offset:32768
	ds_read_b128 v[200:203], v150 offset:34816
	ds_read_b128 v[204:207], v253 offset:34816
	ds_read_b128 v[208:211], v150 offset:36864
	ds_read_b128 v[212:215], v253 offset:36864
	ds_read_b128 v[216:219], v150 offset:38912
	ds_read_b128 v[220:223], v253 offset:38912
	global_load_lds_dwordx4 v[230:231], off
	v_lshl_add_u64 v[230:231], s[46:47], 0, v[130:131]
	s_mov_b32 m0, s55
	s_nop 0
	global_load_lds_dwordx4 v[230:231], off
	s_waitcnt vmcnt(8)
	s_waitcnt lgkmcnt(0)
	.p2align 3
	s_setprio 1
	s_barrier
	v_mfma_f32_16x16x32_bf16 v[124:127], v[160:163], v[192:195], v[124:127]
	v_mfma_f32_16x16x32_bf16 v[124:127], v[164:167], v[196:199], v[124:127]
	v_mfma_f32_16x16x32_bf16 v[116:119], v[172:175], v[196:199], v[116:119]
	v_mfma_f32_16x16x32_bf16 v[116:119], v[168:171], v[192:195], v[116:119]
	v_mfma_f32_16x16x32_bf16 v[100:103], v[168:171], v[200:203], v[100:103]
	v_mfma_f32_16x16x32_bf16 v[100:103], v[172:175], v[204:207], v[100:103]
	v_mfma_f32_16x16x32_bf16 v[108:111], v[164:167], v[204:207], v[108:111]
	v_mfma_f32_16x16x32_bf16 v[108:111], v[160:163], v[200:203], v[108:111]
	v_mfma_f32_16x16x32_bf16 v[92:95], v[160:163], v[208:211], v[92:95]
	v_mfma_f32_16x16x32_bf16 v[92:95], v[164:167], v[212:215], v[92:95]
	v_mfma_f32_16x16x32_bf16 v[84:87], v[172:175], v[212:215], v[84:87]
	v_mfma_f32_16x16x32_bf16 v[84:87], v[168:171], v[208:211], v[84:87]
	v_mfma_f32_16x16x32_bf16 v[68:71], v[168:171], v[216:219], v[68:71]
	v_mfma_f32_16x16x32_bf16 v[68:71], v[172:175], v[220:223], v[68:71]
	v_mfma_f32_16x16x32_bf16 v[76:79], v[164:167], v[220:223], v[76:79]
	v_mfma_f32_16x16x32_bf16 v[76:79], v[160:163], v[216:219], v[76:79]
	s_setprio 0
	s_setprio 1
	v_mfma_f32_16x16x32_bf16 v[120:123], v[176:179], v[192:195], v[120:123]
	v_mfma_f32_16x16x32_bf16 v[120:123], v[180:183], v[196:199], v[120:123]
	v_mfma_f32_16x16x32_bf16 v[112:115], v[188:191], v[196:199], v[112:115]
	v_mfma_f32_16x16x32_bf16 v[112:115], v[184:187], v[192:195], v[112:115]
	v_mfma_f32_16x16x32_bf16 v[96:99], v[184:187], v[200:203], v[96:99]
	v_mfma_f32_16x16x32_bf16 v[96:99], v[188:191], v[204:207], v[96:99]
	v_mfma_f32_16x16x32_bf16 v[104:107], v[180:183], v[204:207], v[104:107]
	v_mfma_f32_16x16x32_bf16 v[104:107], v[176:179], v[200:203], v[104:107]
	v_mfma_f32_16x16x32_bf16 v[88:91], v[176:179], v[208:211], v[88:91]
	v_mfma_f32_16x16x32_bf16 v[88:91], v[180:183], v[212:215], v[88:91]
	v_mfma_f32_16x16x32_bf16 v[80:83], v[188:191], v[212:215], v[80:83]
	v_mfma_f32_16x16x32_bf16 v[80:83], v[184:187], v[208:211], v[80:83]
	v_mfma_f32_16x16x32_bf16 v[64:67], v[184:187], v[216:219], v[64:67]
	v_mfma_f32_16x16x32_bf16 v[64:67], v[188:191], v[220:223], v[64:67]
	v_mfma_f32_16x16x32_bf16 v[72:75], v[180:183], v[220:223], v[72:75]
	v_mfma_f32_16x16x32_bf16 v[72:75], v[176:179], v[216:219], v[72:75]
	s_barrier
	s_setprio 0
	s_add_i32 s46, s71, s49
	v_lshl_add_u64 v[154:155], v[154:155], 0, s[14:15]
	s_mov_b32 m0, s46
	ds_read_b128 v[192:195], v150 offset:49152
	v_xor_b32_e32 v253, 64, v150
	ds_read_b128 v[196:199], v253 offset:49152
	ds_read_b128 v[200:203], v150 offset:51200
	ds_read_b128 v[204:207], v253 offset:51200
	ds_read_b128 v[208:211], v150 offset:53248
	ds_read_b128 v[212:215], v253 offset:53248
	ds_read_b128 v[216:219], v150 offset:55296
	ds_read_b128 v[220:223], v253 offset:55296
	global_load_lds_dwordx4 v[154:155], off
	s_add_i32 m0, s46, 0x2000
	s_add_u32 s44, s44, 0x40080
	v_lshl_add_u64 v[154:155], v[224:225], 0, s[14:15]
	s_addc_u32 s45, s45, 0
	s_add_i32 s46, s72, s49
	global_load_lds_dwordx4 v[154:155], off
	v_lshl_add_u64 v[154:155], s[44:45], 0, v[132:133]
	s_mov_b32 m0, s46
	s_nop 0
	global_load_lds_dwordx4 v[154:155], off
	v_lshl_add_u64 v[154:155], s[44:45], 0, v[128:129]
	s_add_i32 m0, s46, 0x2000
	s_nop 0
	global_load_lds_dwordx4 v[154:155], off
	v_lshl_add_u64 v[154:155], v[226:227], 0, s[14:15]
	s_mov_b32 m0, s57
	s_nop 0
	global_load_lds_dwordx4 v[154:155], off
	v_lshl_add_u64 v[154:155], v[228:229], 0, s[14:15]
	s_mov_b32 m0, s58
	s_nop 0
	global_load_lds_dwordx4 v[154:155], off
	s_waitcnt vmcnt(8)
	s_waitcnt lgkmcnt(0)
	.p2align 3
	s_setprio 1
	s_barrier
	v_mfma_f32_16x16x32_bf16 v[60:63], v[160:163], v[192:195], v[60:63]
	v_mfma_f32_16x16x32_bf16 v[60:63], v[164:167], v[196:199], v[60:63]
	v_mfma_f32_16x16x32_bf16 v[52:55], v[172:175], v[196:199], v[52:55]
	v_mfma_f32_16x16x32_bf16 v[52:55], v[168:171], v[192:195], v[52:55]
	v_mfma_f32_16x16x32_bf16 v[36:39], v[168:171], v[200:203], v[36:39]
	v_mfma_f32_16x16x32_bf16 v[36:39], v[172:175], v[204:207], v[36:39]
	v_mfma_f32_16x16x32_bf16 v[44:47], v[164:167], v[204:207], v[44:47]
	v_mfma_f32_16x16x32_bf16 v[44:47], v[160:163], v[200:203], v[44:47]
	v_mfma_f32_16x16x32_bf16 v[28:31], v[160:163], v[208:211], v[28:31]
	v_mfma_f32_16x16x32_bf16 v[28:31], v[164:167], v[212:215], v[28:31]
	v_mfma_f32_16x16x32_bf16 v[20:23], v[172:175], v[212:215], v[20:23]
	v_mfma_f32_16x16x32_bf16 v[20:23], v[168:171], v[208:211], v[20:23]
	v_mfma_f32_16x16x32_bf16 v[4:7], v[168:171], v[216:219], v[4:7]
	v_mfma_f32_16x16x32_bf16 v[4:7], v[172:175], v[220:223], v[4:7]
	v_mfma_f32_16x16x32_bf16 v[12:15], v[164:167], v[220:223], v[12:15]
	v_mfma_f32_16x16x32_bf16 v[12:15], v[160:163], v[216:219], v[12:15]
	s_setprio 0
	s_setprio 1
	v_mfma_f32_16x16x32_bf16 v[56:59], v[176:179], v[192:195], v[56:59]
	v_mfma_f32_16x16x32_bf16 v[56:59], v[180:183], v[196:199], v[56:59]
	v_mfma_f32_16x16x32_bf16 v[48:51], v[188:191], v[196:199], v[48:51]
	v_mfma_f32_16x16x32_bf16 v[48:51], v[184:187], v[192:195], v[48:51]
	v_mfma_f32_16x16x32_bf16 v[32:35], v[184:187], v[200:203], v[32:35]
	v_mfma_f32_16x16x32_bf16 v[32:35], v[188:191], v[204:207], v[32:35]
	v_mfma_f32_16x16x32_bf16 v[40:43], v[180:183], v[204:207], v[40:43]
	v_mfma_f32_16x16x32_bf16 v[40:43], v[176:179], v[200:203], v[40:43]
	v_mfma_f32_16x16x32_bf16 v[24:27], v[176:179], v[208:211], v[24:27]
	v_mfma_f32_16x16x32_bf16 v[24:27], v[180:183], v[212:215], v[24:27]
	v_mfma_f32_16x16x32_bf16 v[16:19], v[188:191], v[212:215], v[16:19]
	v_mfma_f32_16x16x32_bf16 v[16:19], v[184:187], v[208:211], v[16:19]
	v_mfma_f32_16x16x32_bf16 v[0:3], v[184:187], v[216:219], v[0:3]
	v_mfma_f32_16x16x32_bf16 v[0:3], v[188:191], v[220:223], v[0:3]
	v_mfma_f32_16x16x32_bf16 v[8:11], v[180:183], v[220:223], v[8:11]
	v_mfma_f32_16x16x32_bf16 v[8:11], v[176:179], v[216:219], v[8:11]
	s_barrier
	s_setprio 0
	s_add_i32 s70, s70, 2
	s_add_u32 s68, s68, 0x100
	s_addc_u32 s69, s69, 0
	s_add_u32 s30, s30, 0x100
	s_addc_u32 s31, s31, 0
	s_cmp_gt_u32 s70, 13
	s_cbranch_scc1 .LBB0_1100

.Llast_10:
	v_add_u32_e32 v153, s61, v147
	ds_read_b128 v[160:163], v153
	v_xor_b32_e32 v253, 64, v153
	ds_read_b128 v[164:167], v253
	ds_read_b128 v[168:171], v153 offset:2048
	ds_read_b128 v[172:175], v253 offset:2048
	v_add_u32_e32 v153, s62, v147
	ds_read_b128 v[176:179], v153
	v_xor_b32_e32 v253, 64, v153
	ds_read_b128 v[180:183], v253
	ds_read_b128 v[184:187], v153 offset:2048
	ds_read_b128 v[188:191], v253 offset:2048
	s_add_u32 s46, s30, 0xfffc0080
	s_addc_u32 s47, s31, -1
	s_and_b64 s[44:45], s[44:45], exec
	s_cselect_b32 s47, s25, s47
	s_cselect_b32 s46, s65, s46
	s_cselect_b32 s45, s66, s69
	s_cselect_b32 s44, s67, s68
	v_lshl_add_u64 v[154:155], s[30:31], 0, v[138:139]
	s_add_i32 m0, s52, 0xc000
	ds_read_b128 v[192:195], v150
	v_xor_b32_e32 v253, 64, v150
	ds_read_b128 v[196:199], v253
	ds_read_b128 v[200:203], v150 offset:2048
	ds_read_b128 v[204:207], v253 offset:2048
	ds_read_b128 v[208:211], v150 offset:4096
	ds_read_b128 v[212:215], v253 offset:4096
	ds_read_b128 v[216:219], v150 offset:6144
	ds_read_b128 v[220:223], v253 offset:6144
	global_load_lds_dwordx4 v[154:155], off
	v_lshl_add_u64 v[154:155], s[30:31], 0, v[136:137]
	s_add_i32 m0, s52, 0xe000
	s_nop 0
	global_load_lds_dwordx4 v[154:155], off
	s_waitcnt vmcnt(8)
	s_waitcnt lgkmcnt(0)
	.p2align 3
	s_setprio 1
	s_barrier
	v_mfma_f32_16x16x32_bf16 v[124:127], v[160:163], v[192:195], v[124:127]
	v_mfma_f32_16x16x32_bf16 v[124:127], v[164:167], v[196:199], v[124:127]
	v_mfma_f32_16x16x32_bf16 v[116:119], v[172:175], v[196:199], v[116:119]
	v_mfma_f32_16x16x32_bf16 v[116:119], v[168:171], v[192:195], v[116:119]
	v_mfma_f32_16x16x32_bf16 v[100:103], v[168:171], v[200:203], v[100:103]
	v_mfma_f32_16x16x32_bf16 v[100:103], v[172:175], v[204:207], v[100:103]
	v_mfma_f32_16x16x32_bf16 v[108:111], v[164:167], v[204:207], v[108:111]
	v_mfma_f32_16x16x32_bf16 v[108:111], v[160:163], v[200:203], v[108:111]
	v_mfma_f32_16x16x32_bf16 v[92:95], v[160:163], v[208:211], v[92:95]
	v_mfma_f32_16x16x32_bf16 v[92:95], v[164:167], v[212:215], v[92:95]
	v_mfma_f32_16x16x32_bf16 v[84:87], v[172:175], v[212:215], v[84:87]
	v_mfma_f32_16x16x32_bf16 v[84:87], v[168:171], v[208:211], v[84:87]
	v_mfma_f32_16x16x32_bf16 v[68:71], v[168:171], v[216:219], v[68:71]
	v_mfma_f32_16x16x32_bf16 v[68:71], v[172:175], v[220:223], v[68:71]
	v_mfma_f32_16x16x32_bf16 v[76:79], v[164:167], v[220:223], v[76:79]
	v_mfma_f32_16x16x32_bf16 v[76:79], v[160:163], v[216:219], v[76:79]
	s_setprio 0
	s_setprio 1
	v_mfma_f32_16x16x32_bf16 v[120:123], v[176:179], v[192:195], v[120:123]
	v_mfma_f32_16x16x32_bf16 v[120:123], v[180:183], v[196:199], v[120:123]
	v_mfma_f32_16x16x32_bf16 v[112:115], v[188:191], v[196:199], v[112:115]
	v_mfma_f32_16x16x32_bf16 v[112:115], v[184:187], v[192:195], v[112:115]
	v_mfma_f32_16x16x32_bf16 v[96:99], v[184:187], v[200:203], v[96:99]
	v_mfma_f32_16x16x32_bf16 v[96:99], v[188:191], v[204:207], v[96:99]
	v_mfma_f32_16x16x32_bf16 v[104:107], v[180:183], v[204:207], v[104:107]
	v_mfma_f32_16x16x32_bf16 v[104:107], v[176:179], v[200:203], v[104:107]
	v_mfma_f32_16x16x32_bf16 v[88:91], v[176:179], v[208:211], v[88:91]
	v_mfma_f32_16x16x32_bf16 v[88:91], v[180:183], v[212:215], v[88:91]
	v_mfma_f32_16x16x32_bf16 v[80:83], v[188:191], v[212:215], v[80:83]
	v_mfma_f32_16x16x32_bf16 v[80:83], v[184:187], v[208:211], v[80:83]
	v_mfma_f32_16x16x32_bf16 v[64:67], v[184:187], v[216:219], v[64:67]
	v_mfma_f32_16x16x32_bf16 v[64:67], v[188:191], v[220:223], v[64:67]
	v_mfma_f32_16x16x32_bf16 v[72:75], v[180:183], v[220:223], v[72:75]
	v_mfma_f32_16x16x32_bf16 v[72:75], v[176:179], v[216:219], v[72:75]
	s_barrier
	s_setprio 0
	s_add_i32 s71, s61, s49
	v_lshl_add_u64 v[154:155], s[44:45], 0, v[132:133]
	s_mov_b32 m0, s71
	ds_read_b128 v[192:195], v150 offset:16384
	v_xor_b32_e32 v253, 64, v150
	ds_read_b128 v[196:199], v253 offset:16384
	ds_read_b128 v[200:203], v150 offset:18432
	ds_read_b128 v[204:207], v253 offset:18432
	ds_read_b128 v[208:211], v150 offset:20480
	ds_read_b128 v[212:215], v253 offset:20480
	ds_read_b128 v[216:219], v150 offset:22528
	ds_read_b128 v[220:223], v253 offset:22528
	global_load_lds_dwordx4 v[154:155], off
	s_add_i32 m0, s71, 0x2000
	s_add_u32 s72, s44, 0x40000
	v_lshl_add_u64 v[224:225], s[44:45], 0, v[128:129]
	s_addc_u32 s73, s45, 0
	s_add_i32 s71, s62, s49
	global_load_lds_dwordx4 v[224:225], off
	v_lshl_add_u64 v[226:227], s[72:73], 0, v[132:133]
	s_mov_b32 m0, s71
	v_lshl_add_u64 v[228:229], s[46:47], 0, v[130:131]
	global_load_lds_dwordx4 v[226:227], off
	v_lshl_add_u64 v[226:227], s[72:73], 0, v[128:129]
	s_add_i32 m0, s71, 0x2000
	s_nop 0
	global_load_lds_dwordx4 v[226:227], off
	v_lshl_add_u64 v[226:227], s[46:47], 0, v[134:135]
	s_mov_b32 m0, s52
	s_nop 0
	global_load_lds_dwordx4 v[226:227], off
	s_mov_b32 m0, s53
	s_nop 0
	global_load_lds_dwordx4 v[228:229], off
	s_waitcnt vmcnt(8)
	s_waitcnt lgkmcnt(0)
	.p2align 3
	s_setprio 1
	s_barrier
	v_mfma_f32_16x16x32_bf16 v[60:63], v[160:163], v[192:195], v[60:63]
	v_mfma_f32_16x16x32_bf16 v[60:63], v[164:167], v[196:199], v[60:63]
	v_mfma_f32_16x16x32_bf16 v[52:55], v[172:175], v[196:199], v[52:55]
	v_mfma_f32_16x16x32_bf16 v[52:55], v[168:171], v[192:195], v[52:55]
	v_mfma_f32_16x16x32_bf16 v[36:39], v[168:171], v[200:203], v[36:39]
	v_mfma_f32_16x16x32_bf16 v[36:39], v[172:175], v[204:207], v[36:39]
	v_mfma_f32_16x16x32_bf16 v[44:47], v[164:167], v[204:207], v[44:47]
	v_mfma_f32_16x16x32_bf16 v[44:47], v[160:163], v[200:203], v[44:47]
	v_mfma_f32_16x16x32_bf16 v[28:31], v[160:163], v[208:211], v[28:31]
	v_mfma_f32_16x16x32_bf16 v[28:31], v[164:167], v[212:215], v[28:31]
	v_mfma_f32_16x16x32_bf16 v[20:23], v[172:175], v[212:215], v[20:23]
	v_mfma_f32_16x16x32_bf16 v[20:23], v[168:171], v[208:211], v[20:23]
	v_mfma_f32_16x16x32_bf16 v[4:7], v[168:171], v[216:219], v[4:7]
	v_mfma_f32_16x16x32_bf16 v[4:7], v[172:175], v[220:223], v[4:7]
	v_mfma_f32_16x16x32_bf16 v[12:15], v[164:167], v[220:223], v[12:15]
	v_mfma_f32_16x16x32_bf16 v[12:15], v[160:163], v[216:219], v[12:15]
	s_setprio 0
	s_setprio 1
	v_mfma_f32_16x16x32_bf16 v[56:59], v[176:179], v[192:195], v[56:59]
	v_mfma_f32_16x16x32_bf16 v[56:59], v[180:183], v[196:199], v[56:59]
	v_mfma_f32_16x16x32_bf16 v[48:51], v[188:191], v[196:199], v[48:51]
	v_mfma_f32_16x16x32_bf16 v[48:51], v[184:187], v[192:195], v[48:51]
	v_mfma_f32_16x16x32_bf16 v[32:35], v[184:187], v[200:203], v[32:35]
	v_mfma_f32_16x16x32_bf16 v[32:35], v[188:191], v[204:207], v[32:35]
	v_mfma_f32_16x16x32_bf16 v[40:43], v[180:183], v[204:207], v[40:43]
	v_mfma_f32_16x16x32_bf16 v[40:43], v[176:179], v[200:203], v[40:43]
	v_mfma_f32_16x16x32_bf16 v[24:27], v[176:179], v[208:211], v[24:27]
	v_mfma_f32_16x16x32_bf16 v[24:27], v[180:183], v[212:215], v[24:27]
	v_mfma_f32_16x16x32_bf16 v[16:19], v[188:191], v[212:215], v[16:19]
	v_mfma_f32_16x16x32_bf16 v[16:19], v[184:187], v[208:211], v[16:19]
	v_mfma_f32_16x16x32_bf16 v[0:3], v[184:187], v[216:219], v[0:3]
	v_mfma_f32_16x16x32_bf16 v[0:3], v[188:191], v[220:223], v[0:3]
	v_mfma_f32_16x16x32_bf16 v[8:11], v[180:183], v[220:223], v[8:11]
	v_mfma_f32_16x16x32_bf16 v[8:11], v[176:179], v[216:219], v[8:11]
	s_barrier
	s_setprio 0
	s_add_i32 s71, 0, 0x18000
	v_add_u32_e32 v153, s71, v147
	s_add_i32 s72, 0, 0x1c000
	ds_read_b128 v[160:163], v153
	v_xor_b32_e32 v253, 64, v153
	ds_read_b128 v[164:167], v253
	ds_read_b128 v[168:171], v153 offset:2048
	ds_read_b128 v[172:175], v253 offset:2048
	v_add_u32_e32 v153, s72, v147
	ds_read_b128 v[176:179], v153
	v_xor_b32_e32 v253, 64, v153
	ds_read_b128 v[180:183], v253
	ds_read_b128 v[184:187], v153 offset:2048
	ds_read_b128 v[188:191], v253 offset:2048
	s_add_u32 s46, s46, 0x40000
	s_addc_u32 s47, s47, 0
	s_mov_b32 m0, s54
	v_lshl_add_u64 v[230:231], s[46:47], 0, v[134:135]
	ds_read_b128 v[192:195], v150 offset:32768
	v_xor_b32_e32 v253, 64, v150
	ds_read_b128 v[196:199], v253 offset:32768
	ds_read_b128 v[200:203], v150 offset:34816
	ds_read_b128 v[204:207], v253 offset:34816
	ds_read_b128 v[208:211], v150 offset:36864
	ds_read_b128 v[212:215], v253 offset:36864
	ds_read_b128 v[216:219], v150 offset:38912
	ds_read_b128 v[220:223], v253 offset:38912
	global_load_lds_dwordx4 v[230:231], off
	v_lshl_add_u64 v[230:231], s[46:47], 0, v[130:131]
	s_mov_b32 m0, s55
	s_nop 0
	global_load_lds_dwordx4 v[230:231], off
	s_waitcnt vmcnt(8)
	s_waitcnt lgkmcnt(0)
	.p2align 3
	s_setprio 1
	s_barrier
	v_mfma_f32_16x16x32_bf16 v[124:127], v[160:163], v[192:195], v[124:127]
	v_mfma_f32_16x16x32_bf16 v[124:127], v[164:167], v[196:199], v[124:127]
	v_mfma_f32_16x16x32_bf16 v[116:119], v[172:175], v[196:199], v[116:119]
	v_mfma_f32_16x16x32_bf16 v[116:119], v[168:171], v[192:195], v[116:119]
	v_mfma_f32_16x16x32_bf16 v[100:103], v[168:171], v[200:203], v[100:103]
	v_mfma_f32_16x16x32_bf16 v[100:103], v[172:175], v[204:207], v[100:103]
	v_mfma_f32_16x16x32_bf16 v[108:111], v[164:167], v[204:207], v[108:111]
	v_mfma_f32_16x16x32_bf16 v[108:111], v[160:163], v[200:203], v[108:111]
	v_mfma_f32_16x16x32_bf16 v[92:95], v[160:163], v[208:211], v[92:95]
	v_mfma_f32_16x16x32_bf16 v[92:95], v[164:167], v[212:215], v[92:95]
	v_mfma_f32_16x16x32_bf16 v[84:87], v[172:175], v[212:215], v[84:87]
	v_mfma_f32_16x16x32_bf16 v[84:87], v[168:171], v[208:211], v[84:87]
	v_mfma_f32_16x16x32_bf16 v[68:71], v[168:171], v[216:219], v[68:71]
	v_mfma_f32_16x16x32_bf16 v[68:71], v[172:175], v[220:223], v[68:71]
	v_mfma_f32_16x16x32_bf16 v[76:79], v[164:167], v[220:223], v[76:79]
	v_mfma_f32_16x16x32_bf16 v[76:79], v[160:163], v[216:219], v[76:79]
	s_setprio 0
	s_setprio 1
	v_mfma_f32_16x16x32_bf16 v[120:123], v[176:179], v[192:195], v[120:123]
	v_mfma_f32_16x16x32_bf16 v[120:123], v[180:183], v[196:199], v[120:123]
	v_mfma_f32_16x16x32_bf16 v[112:115], v[188:191], v[196:199], v[112:115]
	v_mfma_f32_16x16x32_bf16 v[112:115], v[184:187], v[192:195], v[112:115]
	v_mfma_f32_16x16x32_bf16 v[96:99], v[184:187], v[200:203], v[96:99]
	v_mfma_f32_16x16x32_bf16 v[96:99], v[188:191], v[204:207], v[96:99]
	v_mfma_f32_16x16x32_bf16 v[104:107], v[180:183], v[204:207], v[104:107]
	v_mfma_f32_16x16x32_bf16 v[104:107], v[176:179], v[200:203], v[104:107]
	v_mfma_f32_16x16x32_bf16 v[88:91], v[176:179], v[208:211], v[88:91]
	v_mfma_f32_16x16x32_bf16 v[88:91], v[180:183], v[212:215], v[88:91]
	v_mfma_f32_16x16x32_bf16 v[80:83], v[188:191], v[212:215], v[80:83]
	v_mfma_f32_16x16x32_bf16 v[80:83], v[184:187], v[208:211], v[80:83]
	v_mfma_f32_16x16x32_bf16 v[64:67], v[184:187], v[216:219], v[64:67]
	v_mfma_f32_16x16x32_bf16 v[64:67], v[188:191], v[220:223], v[64:67]
	v_mfma_f32_16x16x32_bf16 v[72:75], v[180:183], v[220:223], v[72:75]
	v_mfma_f32_16x16x32_bf16 v[72:75], v[176:179], v[216:219], v[72:75]
	s_barrier
	s_setprio 0
	v_add_u32_e32 v234, 0x21000, v151
	ds_read_b128 v[236:239], v234
	ds_read_b128 v[240:243], v234 offset:256
	ds_read_b128 v[244:247], v234 offset:512
	ds_read_b128 v[248:251], v234 offset:768
	v_add_u32_e32 v235, s23, v146
	v_mul_u32_u24_e32 v235, 0x1600, v235
	v_lshl_or_b32 v234, s64, 7, v149
	v_lshl_add_u32 v235, v234, 1, v235
	s_add_i32 s46, s71, s49
	v_lshl_add_u64 v[154:155], v[154:155], 0, s[14:15]
	s_mov_b32 m0, s46
	ds_read_b128 v[192:195], v150 offset:49152
	v_xor_b32_e32 v253, 64, v150
	ds_read_b128 v[196:199], v253 offset:49152
	ds_read_b128 v[200:203], v150 offset:51200
	ds_read_b128 v[204:207], v253 offset:51200
	ds_read_b128 v[208:211], v150 offset:53248
	ds_read_b128 v[212:215], v253 offset:53248
	ds_read_b128 v[216:219], v150 offset:55296
	ds_read_b128 v[220:223], v253 offset:55296
	global_load_lds_dwordx4 v[154:155], off
	s_add_i32 m0, s46, 0x2000
	s_add_u32 s44, s44, 0x40080
	v_lshl_add_u64 v[154:155], v[224:225], 0, s[14:15]
	s_addc_u32 s45, s45, 0
	s_add_i32 s46, s72, s49
	global_load_lds_dwordx4 v[154:155], off
	v_lshl_add_u64 v[154:155], s[44:45], 0, v[132:133]
	s_mov_b32 m0, s46
	s_nop 0
	global_load_lds_dwordx4 v[154:155], off
	v_lshl_add_u64 v[154:155], s[44:45], 0, v[128:129]
	s_add_i32 m0, s46, 0x2000
	s_nop 0
	global_load_lds_dwordx4 v[154:155], off
	v_lshl_add_u64 v[154:155], v[226:227], 0, s[14:15]
	s_mov_b32 m0, s57
	s_nop 0
	global_load_lds_dwordx4 v[154:155], off
	v_lshl_add_u64 v[154:155], v[228:229], 0, s[14:15]
	s_mov_b32 m0, s58
	s_nop 0
	global_load_lds_dwordx4 v[154:155], off
	s_waitcnt lgkmcnt(8)
	v_add_f32_e32 v236, v236, v237
	v_add_f32_e32 v238, v238, v239
	v_add_f32_e32 v240, v240, v241
	v_add_f32_e32 v242, v242, v243
	v_add_f32_e32 v244, v244, v245
	v_add_f32_e32 v246, v246, v247
	v_add_f32_e32 v248, v248, v249
	v_add_f32_e32 v250, v250, v251
	v_add_f32_e32 v236, v236, v238
	v_add_f32_e32 v240, v240, v242
	v_add_f32_e32 v244, v244, v246
	v_add_f32_e32 v248, v248, v250
	v_fmamk_f32 v236, v236, 0x3a800000, v152
	v_fmamk_f32 v240, v240, 0x3a800000, v152
	v_fmamk_f32 v244, v244, 0x3a800000, v152
	v_fmamk_f32 v248, v248, 0x3a800000, v152
	v_rsq_f32_e32 v236, v236
	v_rsq_f32_e32 v240, v240
	v_rsq_f32_e32 v244, v244
	v_rsq_f32_e32 v248, v248
	v_mul_f32_e32 v252, 0xbfb8aa3b, v236
	v_mul_f32_e32 v254, v236, v236
	v_rcp_f32_e32 v254, v254
	v_pk_mul_f32 v[120:121], v[124:125], v[120:121]
	v_pk_mul_f32 v[122:123], v[126:127], v[122:123]
	v_pk_mul_f32 v[112:113], v[116:117], v[112:113]
	v_pk_mul_f32 v[114:115], v[118:119], v[114:115]
	v_pk_mul_f32 v[124:125], v[124:125], v[252:253] op_sel_hi:[1,0]
	v_pk_mul_f32 v[126:127], v[126:127], v[252:253] op_sel_hi:[1,0]
	v_pk_mul_f32 v[116:117], v[116:117], v[252:253] op_sel_hi:[1,0]
	v_pk_mul_f32 v[118:119], v[118:119], v[252:253] op_sel_hi:[1,0]
	v_exp_f32_e32 v124, v124
	v_exp_f32_e32 v125, v125
	v_exp_f32_e32 v126, v126
	v_exp_f32_e32 v127, v127
	v_exp_f32_e32 v116, v116
	v_exp_f32_e32 v117, v117
	v_exp_f32_e32 v118, v118
	v_exp_f32_e32 v119, v119
	v_pk_fma_f32 v[124:125], v[124:125], v[254:255], v[254:255] op_sel_hi:[1,0,0]
	v_pk_fma_f32 v[126:127], v[126:127], v[254:255], v[254:255] op_sel_hi:[1,0,0]
	v_pk_fma_f32 v[116:117], v[116:117], v[254:255], v[254:255] op_sel_hi:[1,0,0]
	v_pk_fma_f32 v[118:119], v[118:119], v[254:255], v[254:255] op_sel_hi:[1,0,0]
	v_rcp_f32_e32 v124, v124
	v_rcp_f32_e32 v125, v125
	v_rcp_f32_e32 v126, v126
	v_rcp_f32_e32 v127, v127
	v_rcp_f32_e32 v116, v116
	v_rcp_f32_e32 v117, v117
	v_rcp_f32_e32 v118, v118
	v_rcp_f32_e32 v119, v119
	v_pk_mul_f32 v[120:121], v[120:121], v[124:125]
	v_pk_mul_f32 v[122:123], v[122:123], v[126:127]
	v_pk_mul_f32 v[112:113], v[112:113], v[116:117]
	v_pk_mul_f32 v[114:115], v[114:115], v[118:119]
	v_cvt_pk_bf16_f32 v120, v120, v121
	v_cvt_pk_bf16_f32 v121, v122, v123
	v_cvt_pk_bf16_f32 v122, v112, v113
	v_cvt_pk_bf16_f32 v123, v114, v115
	global_store_dwordx4 v235, v[120:123], s[10:11]
	v_add_u32_e32 v234, 0x16000, v235
	v_mul_f32_e32 v252, 0xbfb8aa3b, v240
	v_mul_f32_e32 v254, v240, v240
	v_rcp_f32_e32 v254, v254
	v_pk_mul_f32 v[104:105], v[108:109], v[104:105]
	v_pk_mul_f32 v[106:107], v[110:111], v[106:107]
	v_pk_mul_f32 v[96:97], v[100:101], v[96:97]
	v_pk_mul_f32 v[98:99], v[102:103], v[98:99]
	v_pk_mul_f32 v[108:109], v[108:109], v[252:253] op_sel_hi:[1,0]
	v_pk_mul_f32 v[110:111], v[110:111], v[252:253] op_sel_hi:[1,0]
	v_pk_mul_f32 v[100:101], v[100:101], v[252:253] op_sel_hi:[1,0]
	v_pk_mul_f32 v[102:103], v[102:103], v[252:253] op_sel_hi:[1,0]
	v_exp_f32_e32 v108, v108
	v_exp_f32_e32 v109, v109
	v_exp_f32_e32 v110, v110
	v_exp_f32_e32 v111, v111
	v_exp_f32_e32 v100, v100
	v_exp_f32_e32 v101, v101
	v_exp_f32_e32 v102, v102
	v_exp_f32_e32 v103, v103
	v_pk_fma_f32 v[108:109], v[108:109], v[254:255], v[254:255] op_sel_hi:[1,0,0]
	v_pk_fma_f32 v[110:111], v[110:111], v[254:255], v[254:255] op_sel_hi:[1,0,0]
	v_pk_fma_f32 v[100:101], v[100:101], v[254:255], v[254:255] op_sel_hi:[1,0,0]
	v_pk_fma_f32 v[102:103], v[102:103], v[254:255], v[254:255] op_sel_hi:[1,0,0]
	v_rcp_f32_e32 v108, v108
	v_rcp_f32_e32 v109, v109
	v_rcp_f32_e32 v110, v110
	v_rcp_f32_e32 v111, v111
	v_rcp_f32_e32 v100, v100
	v_rcp_f32_e32 v101, v101
	v_rcp_f32_e32 v102, v102
	v_rcp_f32_e32 v103, v103
	v_pk_mul_f32 v[104:105], v[104:105], v[108:109]
	v_pk_mul_f32 v[106:107], v[106:107], v[110:111]
	v_pk_mul_f32 v[96:97], v[96:97], v[100:101]
	v_pk_mul_f32 v[98:99], v[98:99], v[102:103]
	v_cvt_pk_bf16_f32 v104, v104, v105
	v_cvt_pk_bf16_f32 v105, v106, v107
	v_cvt_pk_bf16_f32 v106, v96, v97
	v_cvt_pk_bf16_f32 v107, v98, v99
	global_store_dwordx4 v234, v[104:107], s[10:11]
	v_add_u32_e32 v235, 0x16000, v234
	v_mul_f32_e32 v252, 0xbfb8aa3b, v244
	v_mul_f32_e32 v254, v244, v244
	v_rcp_f32_e32 v254, v254
	v_pk_mul_f32 v[88:89], v[92:93], v[88:89]
	v_pk_mul_f32 v[90:91], v[94:95], v[90:91]
	v_pk_mul_f32 v[80:81], v[84:85], v[80:81]
	v_pk_mul_f32 v[82:83], v[86:87], v[82:83]
	v_pk_mul_f32 v[92:93], v[92:93], v[252:253] op_sel_hi:[1,0]
	v_pk_mul_f32 v[94:95], v[94:95], v[252:253] op_sel_hi:[1,0]
	v_pk_mul_f32 v[84:85], v[84:85], v[252:253] op_sel_hi:[1,0]
	v_pk_mul_f32 v[86:87], v[86:87], v[252:253] op_sel_hi:[1,0]
	v_exp_f32_e32 v92, v92
	v_exp_f32_e32 v93, v93
	v_exp_f32_e32 v94, v94
	v_exp_f32_e32 v95, v95
	v_exp_f32_e32 v84, v84
	v_exp_f32_e32 v85, v85
	v_exp_f32_e32 v86, v86
	v_exp_f32_e32 v87, v87
	v_pk_fma_f32 v[92:93], v[92:93], v[254:255], v[254:255] op_sel_hi:[1,0,0]
	v_pk_fma_f32 v[94:95], v[94:95], v[254:255], v[254:255] op_sel_hi:[1,0,0]
	v_pk_fma_f32 v[84:85], v[84:85], v[254:255], v[254:255] op_sel_hi:[1,0,0]
	v_pk_fma_f32 v[86:87], v[86:87], v[254:255], v[254:255] op_sel_hi:[1,0,0]
	v_rcp_f32_e32 v92, v92
	v_rcp_f32_e32 v93, v93
	v_rcp_f32_e32 v94, v94
	v_rcp_f32_e32 v95, v95
	v_rcp_f32_e32 v84, v84
	v_rcp_f32_e32 v85, v85
	v_rcp_f32_e32 v86, v86
	v_rcp_f32_e32 v87, v87
	v_pk_mul_f32 v[88:89], v[88:89], v[92:93]
	v_pk_mul_f32 v[90:91], v[90:91], v[94:95]
	v_pk_mul_f32 v[80:81], v[80:81], v[84:85]
	v_pk_mul_f32 v[82:83], v[82:83], v[86:87]
	v_cvt_pk_bf16_f32 v88, v88, v89
	v_cvt_pk_bf16_f32 v89, v90, v91
	v_cvt_pk_bf16_f32 v90, v80, v81
	v_cvt_pk_bf16_f32 v91, v82, v83
	global_store_dwordx4 v235, v[88:91], s[10:11]
	v_add_u32_e32 v234, 0x16000, v235
	v_mul_f32_e32 v252, 0xbfb8aa3b, v248
	v_mul_f32_e32 v254, v248, v248
	v_rcp_f32_e32 v254, v254
	v_pk_mul_f32 v[72:73], v[76:77], v[72:73]
	v_pk_mul_f32 v[74:75], v[78:79], v[74:75]
	v_pk_mul_f32 v[64:65], v[68:69], v[64:65]
	v_pk_mul_f32 v[66:67], v[70:71], v[66:67]
	v_pk_mul_f32 v[76:77], v[76:77], v[252:253] op_sel_hi:[1,0]
	v_pk_mul_f32 v[78:79], v[78:79], v[252:253] op_sel_hi:[1,0]
	v_pk_mul_f32 v[68:69], v[68:69], v[252:253] op_sel_hi:[1,0]
	v_pk_mul_f32 v[70:71], v[70:71], v[252:253] op_sel_hi:[1,0]
	v_exp_f32_e32 v76, v76
	v_exp_f32_e32 v77, v77
	v_exp_f32_e32 v78, v78
	v_exp_f32_e32 v79, v79
	v_exp_f32_e32 v68, v68
	v_exp_f32_e32 v69, v69
	v_exp_f32_e32 v70, v70
	v_exp_f32_e32 v71, v71
	v_pk_fma_f32 v[76:77], v[76:77], v[254:255], v[254:255] op_sel_hi:[1,0,0]
	v_pk_fma_f32 v[78:79], v[78:79], v[254:255], v[254:255] op_sel_hi:[1,0,0]
	v_pk_fma_f32 v[68:69], v[68:69], v[254:255], v[254:255] op_sel_hi:[1,0,0]
	v_pk_fma_f32 v[70:71], v[70:71], v[254:255], v[254:255] op_sel_hi:[1,0,0]
	v_rcp_f32_e32 v76, v76
	v_rcp_f32_e32 v77, v77
	v_rcp_f32_e32 v78, v78
	v_rcp_f32_e32 v79, v79
	v_rcp_f32_e32 v68, v68
	v_rcp_f32_e32 v69, v69
	v_rcp_f32_e32 v70, v70
	v_rcp_f32_e32 v71, v71
	v_pk_mul_f32 v[72:73], v[72:73], v[76:77]
	v_pk_mul_f32 v[74:75], v[74:75], v[78:79]
	v_pk_mul_f32 v[64:65], v[64:65], v[68:69]
	v_pk_mul_f32 v[66:67], v[66:67], v[70:71]
	v_cvt_pk_bf16_f32 v72, v72, v73
	v_cvt_pk_bf16_f32 v73, v74, v75
	v_cvt_pk_bf16_f32 v74, v64, v65
	v_cvt_pk_bf16_f32 v75, v66, v67
	global_store_dwordx4 v234, v[72:75], s[10:11]
	s_waitcnt vmcnt(12)
	s_waitcnt lgkmcnt(0)
	.p2align 3
	s_setprio 1
	s_barrier
	v_mfma_f32_16x16x32_bf16 v[60:63], v[160:163], v[192:195], v[60:63]
	v_mfma_f32_16x16x32_bf16 v[60:63], v[164:167], v[196:199], v[60:63]
	v_mfma_f32_16x16x32_bf16 v[52:55], v[172:175], v[196:199], v[52:55]
	v_mfma_f32_16x16x32_bf16 v[52:55], v[168:171], v[192:195], v[52:55]
	v_mfma_f32_16x16x32_bf16 v[36:39], v[168:171], v[200:203], v[36:39]
	v_mfma_f32_16x16x32_bf16 v[36:39], v[172:175], v[204:207], v[36:39]
	v_mfma_f32_16x16x32_bf16 v[44:47], v[164:167], v[204:207], v[44:47]
	v_mfma_f32_16x16x32_bf16 v[44:47], v[160:163], v[200:203], v[44:47]
	v_mfma_f32_16x16x32_bf16 v[28:31], v[160:163], v[208:211], v[28:31]
	v_mfma_f32_16x16x32_bf16 v[28:31], v[164:167], v[212:215], v[28:31]
	v_mfma_f32_16x16x32_bf16 v[20:23], v[172:175], v[212:215], v[20:23]
	v_mfma_f32_16x16x32_bf16 v[20:23], v[168:171], v[208:211], v[20:23]
	v_mfma_f32_16x16x32_bf16 v[4:7], v[168:171], v[216:219], v[4:7]
	v_mfma_f32_16x16x32_bf16 v[4:7], v[172:175], v[220:223], v[4:7]
	v_mfma_f32_16x16x32_bf16 v[12:15], v[164:167], v[220:223], v[12:15]
	v_mfma_f32_16x16x32_bf16 v[12:15], v[160:163], v[216:219], v[12:15]
	s_setprio 0
	s_setprio 1
	v_mfma_f32_16x16x32_bf16 v[56:59], v[176:179], v[192:195], v[56:59]
	v_mfma_f32_16x16x32_bf16 v[56:59], v[180:183], v[196:199], v[56:59]
	v_mfma_f32_16x16x32_bf16 v[48:51], v[188:191], v[196:199], v[48:51]
	v_mfma_f32_16x16x32_bf16 v[48:51], v[184:187], v[192:195], v[48:51]
	v_mfma_f32_16x16x32_bf16 v[32:35], v[184:187], v[200:203], v[32:35]
	v_mfma_f32_16x16x32_bf16 v[32:35], v[188:191], v[204:207], v[32:35]
	v_mfma_f32_16x16x32_bf16 v[40:43], v[180:183], v[204:207], v[40:43]
	v_mfma_f32_16x16x32_bf16 v[40:43], v[176:179], v[200:203], v[40:43]
	v_mfma_f32_16x16x32_bf16 v[24:27], v[176:179], v[208:211], v[24:27]
	v_mfma_f32_16x16x32_bf16 v[24:27], v[180:183], v[212:215], v[24:27]
	v_mfma_f32_16x16x32_bf16 v[16:19], v[188:191], v[212:215], v[16:19]
	v_mfma_f32_16x16x32_bf16 v[16:19], v[184:187], v[208:211], v[16:19]
	v_mfma_f32_16x16x32_bf16 v[0:3], v[184:187], v[216:219], v[0:3]
	v_mfma_f32_16x16x32_bf16 v[0:3], v[188:191], v[220:223], v[0:3]
	v_mfma_f32_16x16x32_bf16 v[8:11], v[180:183], v[220:223], v[8:11]
	v_mfma_f32_16x16x32_bf16 v[8:11], v[176:179], v[216:219], v[8:11]
	s_barrier
	s_setprio 0
	s_add_i32 s70, s70, 2
	s_add_u32 s68, s68, 0x100
	s_addc_u32 s69, s69, 0
	s_add_u32 s30, s30, 0x100
	s_addc_u32 s31, s31, 0

.LBB0_1180:
	s_add_u32 s72, s50, 0x100
	s_addc_u32 s73, s51, 0
	s_mov_b32 s74, -2
	s_waitcnt lgkmcnt(0)
	s_cmp_eq_u32 s63, 1
	s_cbranch_scc1 .Lfa_11
	ds_read_b128 v[128:131], v188
	v_xor_b32_e32 v253, 64, v188
	ds_read_b128 v[132:135], v253
	ds_read_b128 v[136:139], v188 offset:2048
	ds_read_b128 v[140:143], v253 offset:2048
	ds_read_b128 v[144:147], v189
	v_xor_b32_e32 v253, 64, v189
	ds_read_b128 v[148:151], v253
	ds_read_b128 v[172:175], v189 offset:2048
	ds_read_b128 v[176:179], v253 offset:2048
	s_add_u32 s50, s48, 0x100
	s_addc_u32 s51, s49, 0
	s_cmp_eq_u32 s74, 40
	s_cselect_b32 s55, s11, s51
	s_cselect_b32 s54, s10, s50
	s_cselect_b32 s53, s47, s73
	s_cselect_b32 s52, s46, s72
	v_lshl_add_u64 v[220:221], s[48:49], 0, v[166:167]
	s_add_i32 m0, s59, 0xc000
	ds_read_b128 v[180:183], v190
	v_xor_b32_e32 v253, 64, v190
	ds_read_b128 v[192:195], v253
	ds_read_b128 v[196:199], v190 offset:2048
	ds_read_b128 v[200:203], v253 offset:2048
	ds_read_b128 v[204:207], v190 offset:4096
	ds_read_b128 v[208:211], v253 offset:4096
	ds_read_b128 v[212:215], v190 offset:6144
	ds_read_b128 v[216:219], v253 offset:6144
	global_load_lds_dwordx4 v[220:221], off
	v_lshl_add_u64 v[220:221], s[48:49], 0, v[164:165]
	s_add_i32 m0, s59, 0xe000
	s_nop 0
	global_load_lds_dwordx4 v[220:221], off
	s_waitcnt vmcnt(24)
	s_waitcnt lgkmcnt(0)
	.p2align 3
	s_setprio 1
	s_barrier
	v_mfma_f32_16x16x32_bf16 v[124:127], v[128:131], v[180:183], 0
	v_mfma_f32_16x16x32_bf16 v[120:123], v[136:139], v[180:183], 0
	v_mfma_f32_16x16x32_bf16 v[108:111], v[128:131], v[196:199], 0
	v_mfma_f32_16x16x32_bf16 v[104:107], v[136:139], v[196:199], 0
	v_mfma_f32_16x16x32_bf16 v[92:95], v[128:131], v[204:207], 0
	v_mfma_f32_16x16x32_bf16 v[88:91], v[136:139], v[204:207], 0
	v_mfma_f32_16x16x32_bf16 v[76:79], v[128:131], v[212:215], 0
	v_mfma_f32_16x16x32_bf16 v[72:75], v[136:139], v[212:215], 0
	v_mfma_f32_16x16x32_bf16 v[124:127], v[132:135], v[192:195], v[124:127]
	v_mfma_f32_16x16x32_bf16 v[120:123], v[140:143], v[192:195], v[120:123]
	v_mfma_f32_16x16x32_bf16 v[108:111], v[132:135], v[200:203], v[108:111]
	v_mfma_f32_16x16x32_bf16 v[104:107], v[140:143], v[200:203], v[104:107]
	v_mfma_f32_16x16x32_bf16 v[92:95], v[132:135], v[208:211], v[92:95]
	v_mfma_f32_16x16x32_bf16 v[88:91], v[140:143], v[208:211], v[88:91]
	v_mfma_f32_16x16x32_bf16 v[76:79], v[132:135], v[216:219], v[76:79]
	v_mfma_f32_16x16x32_bf16 v[72:75], v[140:143], v[216:219], v[72:75]
	s_setprio 0
	s_setprio 1
	v_mfma_f32_16x16x32_bf16 v[116:119], v[144:147], v[180:183], 0
	v_mfma_f32_16x16x32_bf16 v[112:115], v[172:175], v[180:183], 0
	v_mfma_f32_16x16x32_bf16 v[100:103], v[144:147], v[196:199], 0
	v_mfma_f32_16x16x32_bf16 v[96:99], v[172:175], v[196:199], 0
	v_mfma_f32_16x16x32_bf16 v[84:87], v[144:147], v[204:207], 0
	v_mfma_f32_16x16x32_bf16 v[80:83], v[172:175], v[204:207], 0
	v_mfma_f32_16x16x32_bf16 v[68:71], v[144:147], v[212:215], 0
	v_mfma_f32_16x16x32_bf16 v[64:67], v[172:175], v[212:215], 0
	v_mfma_f32_16x16x32_bf16 v[116:119], v[148:151], v[192:195], v[116:119]
	v_mfma_f32_16x16x32_bf16 v[112:115], v[176:179], v[192:195], v[112:115]
	v_mfma_f32_16x16x32_bf16 v[100:103], v[148:151], v[200:203], v[100:103]
	v_mfma_f32_16x16x32_bf16 v[96:99], v[176:179], v[200:203], v[96:99]
	v_mfma_f32_16x16x32_bf16 v[84:87], v[148:151], v[208:211], v[84:87]
	v_mfma_f32_16x16x32_bf16 v[80:83], v[176:179], v[208:211], v[80:83]
	v_mfma_f32_16x16x32_bf16 v[68:71], v[148:151], v[216:219], v[68:71]
	v_mfma_f32_16x16x32_bf16 v[64:67], v[176:179], v[216:219], v[64:67]
	s_barrier
	s_setprio 0
	s_add_i32 s48, s68, s58
	v_lshl_add_u64 v[220:221], s[52:53], 0, v[154:155]
	s_mov_b32 m0, s48
	ds_read_b128 v[180:183], v190 offset:16384
	v_xor_b32_e32 v253, 64, v190
	ds_read_b128 v[192:195], v253 offset:16384
	ds_read_b128 v[196:199], v190 offset:18432
	ds_read_b128 v[200:203], v253 offset:18432
	ds_read_b128 v[204:207], v190 offset:20480
	ds_read_b128 v[208:211], v253 offset:20480
	ds_read_b128 v[212:215], v190 offset:22528
	ds_read_b128 v[216:219], v253 offset:22528
	global_load_lds_dwordx4 v[220:221], off
	s_add_i32 m0, s48, 0x2000
	s_add_u32 s48, s52, 0xb0000
	v_lshl_add_u64 v[222:223], s[52:53], 0, v[162:163]
	s_addc_u32 s49, s53, 0
	s_add_i32 s75, s69, s58
	global_load_lds_dwordx4 v[222:223], off
	v_lshl_add_u64 v[224:225], s[48:49], 0, v[154:155]
	s_mov_b32 m0, s75
	v_lshl_add_u64 v[226:227], s[54:55], 0, v[160:161]
	global_load_lds_dwordx4 v[224:225], off
	v_lshl_add_u64 v[224:225], s[48:49], 0, v[162:163]
	s_add_i32 m0, s75, 0x2000
	s_nop 0
	global_load_lds_dwordx4 v[224:225], off
	v_lshl_add_u64 v[224:225], s[54:55], 0, v[152:153]
	s_mov_b32 m0, s59
	s_nop 0
	global_load_lds_dwordx4 v[224:225], off
	s_mov_b32 m0, s60
	s_nop 0
	global_load_lds_dwordx4 v[226:227], off
	s_waitcnt vmcnt(24)
	s_waitcnt lgkmcnt(0)
	.p2align 3
	s_setprio 1
	s_barrier
	v_mfma_f32_16x16x32_bf16 v[60:63], v[128:131], v[180:183], 0
	v_mfma_f32_16x16x32_bf16 v[56:59], v[136:139], v[180:183], 0
	v_mfma_f32_16x16x32_bf16 v[44:47], v[128:131], v[196:199], 0
	v_mfma_f32_16x16x32_bf16 v[40:43], v[136:139], v[196:199], 0
	v_mfma_f32_16x16x32_bf16 v[28:31], v[128:131], v[204:207], 0
	v_mfma_f32_16x16x32_bf16 v[24:27], v[136:139], v[204:207], 0
	v_mfma_f32_16x16x32_bf16 v[12:15], v[128:131], v[212:215], 0
	v_mfma_f32_16x16x32_bf16 v[8:11], v[136:139], v[212:215], 0
	v_mfma_f32_16x16x32_bf16 v[60:63], v[132:135], v[192:195], v[60:63]
	v_mfma_f32_16x16x32_bf16 v[56:59], v[140:143], v[192:195], v[56:59]
	v_mfma_f32_16x16x32_bf16 v[44:47], v[132:135], v[200:203], v[44:47]
	v_mfma_f32_16x16x32_bf16 v[40:43], v[140:143], v[200:203], v[40:43]
	v_mfma_f32_16x16x32_bf16 v[28:31], v[132:135], v[208:211], v[28:31]
	v_mfma_f32_16x16x32_bf16 v[24:27], v[140:143], v[208:211], v[24:27]
	v_mfma_f32_16x16x32_bf16 v[12:15], v[132:135], v[216:219], v[12:15]
	v_mfma_f32_16x16x32_bf16 v[8:11], v[140:143], v[216:219], v[8:11]
	s_setprio 0
	s_setprio 1
	v_mfma_f32_16x16x32_bf16 v[52:55], v[144:147], v[180:183], 0
	v_mfma_f32_16x16x32_bf16 v[48:51], v[172:175], v[180:183], 0
	v_mfma_f32_16x16x32_bf16 v[36:39], v[144:147], v[196:199], 0
	v_mfma_f32_16x16x32_bf16 v[32:35], v[172:175], v[196:199], 0
	v_mfma_f32_16x16x32_bf16 v[20:23], v[144:147], v[204:207], 0
	v_mfma_f32_16x16x32_bf16 v[16:19], v[172:175], v[204:207], 0
	v_mfma_f32_16x16x32_bf16 v[4:7], v[144:147], v[212:215], 0
	v_mfma_f32_16x16x32_bf16 v[0:3], v[172:175], v[212:215], 0
	v_mfma_f32_16x16x32_bf16 v[52:55], v[148:151], v[192:195], v[52:55]
	v_mfma_f32_16x16x32_bf16 v[48:51], v[176:179], v[192:195], v[48:51]
	v_mfma_f32_16x16x32_bf16 v[36:39], v[148:151], v[200:203], v[36:39]
	v_mfma_f32_16x16x32_bf16 v[32:35], v[176:179], v[200:203], v[32:35]
	v_mfma_f32_16x16x32_bf16 v[20:23], v[148:151], v[208:211], v[20:23]
	v_mfma_f32_16x16x32_bf16 v[16:19], v[176:179], v[208:211], v[16:19]
	v_mfma_f32_16x16x32_bf16 v[4:7], v[148:151], v[216:219], v[4:7]
	v_mfma_f32_16x16x32_bf16 v[0:3], v[176:179], v[216:219], v[0:3]
	s_barrier
	s_setprio 0
	s_add_i32 s75, 0, 0x18000
	s_add_i32 s76, 0, 0x1c000
	v_add_u32_e32 v140, s75, v185
	v_add_u32_e32 v176, s76, v185
	ds_read_b128 v[128:131], v140
	v_xor_b32_e32 v253, 64, v140
	ds_read_b128 v[132:135], v253
	ds_read_b128 v[136:139], v140 offset:2048
	ds_read_b128 v[140:143], v253 offset:2048
	ds_read_b128 v[144:147], v176
	v_xor_b32_e32 v253, 64, v176
	ds_read_b128 v[148:151], v253
	ds_read_b128 v[172:175], v176 offset:2048
	ds_read_b128 v[176:179], v253 offset:2048
	s_add_u32 s48, s54, 0xb0000
	s_addc_u32 s49, s55, 0
	s_mov_b32 m0, s61
	v_lshl_add_u64 v[228:229], s[48:49], 0, v[152:153]
	ds_read_b128 v[180:183], v190 offset:32768
	v_xor_b32_e32 v253, 64, v190
	ds_read_b128 v[192:195], v253 offset:32768
	ds_read_b128 v[196:199], v190 offset:34816
	ds_read_b128 v[200:203], v253 offset:34816
	ds_read_b128 v[204:207], v190 offset:36864
	ds_read_b128 v[208:211], v253 offset:36864
	ds_read_b128 v[212:215], v190 offset:38912
	ds_read_b128 v[216:219], v253 offset:38912
	global_load_lds_dwordx4 v[228:229], off
	v_lshl_add_u64 v[228:229], s[48:49], 0, v[160:161]
	s_mov_b32 m0, s62
	s_nop 0
	global_load_lds_dwordx4 v[228:229], off
	s_waitcnt vmcnt(8)
	s_waitcnt lgkmcnt(0)
	.p2align 3
	s_setprio 1
	s_barrier
	v_mfma_f32_16x16x32_bf16 v[124:127], v[128:131], v[180:183], v[124:127]
	v_mfma_f32_16x16x32_bf16 v[124:127], v[132:135], v[192:195], v[124:127]
	v_mfma_f32_16x16x32_bf16 v[120:123], v[140:143], v[192:195], v[120:123]
	v_mfma_f32_16x16x32_bf16 v[120:123], v[136:139], v[180:183], v[120:123]
	v_mfma_f32_16x16x32_bf16 v[104:107], v[136:139], v[196:199], v[104:107]
	v_mfma_f32_16x16x32_bf16 v[104:107], v[140:143], v[200:203], v[104:107]
	v_mfma_f32_16x16x32_bf16 v[108:111], v[132:135], v[200:203], v[108:111]
	v_mfma_f32_16x16x32_bf16 v[108:111], v[128:131], v[196:199], v[108:111]
	v_mfma_f32_16x16x32_bf16 v[92:95], v[128:131], v[204:207], v[92:95]
	v_mfma_f32_16x16x32_bf16 v[92:95], v[132:135], v[208:211], v[92:95]
	v_mfma_f32_16x16x32_bf16 v[88:91], v[140:143], v[208:211], v[88:91]
	v_mfma_f32_16x16x32_bf16 v[88:91], v[136:139], v[204:207], v[88:91]
	v_mfma_f32_16x16x32_bf16 v[72:75], v[136:139], v[212:215], v[72:75]
	v_mfma_f32_16x16x32_bf16 v[72:75], v[140:143], v[216:219], v[72:75]
	v_mfma_f32_16x16x32_bf16 v[76:79], v[132:135], v[216:219], v[76:79]
	v_mfma_f32_16x16x32_bf16 v[76:79], v[128:131], v[212:215], v[76:79]
	s_setprio 0
	s_setprio 1
	v_mfma_f32_16x16x32_bf16 v[116:119], v[144:147], v[180:183], v[116:119]
	v_mfma_f32_16x16x32_bf16 v[116:119], v[148:151], v[192:195], v[116:119]
	v_mfma_f32_16x16x32_bf16 v[112:115], v[176:179], v[192:195], v[112:115]
	v_mfma_f32_16x16x32_bf16 v[112:115], v[172:175], v[180:183], v[112:115]
	v_mfma_f32_16x16x32_bf16 v[96:99], v[172:175], v[196:199], v[96:99]
	v_mfma_f32_16x16x32_bf16 v[96:99], v[176:179], v[200:203], v[96:99]
	v_mfma_f32_16x16x32_bf16 v[100:103], v[148:151], v[200:203], v[100:103]
	v_mfma_f32_16x16x32_bf16 v[100:103], v[144:147], v[196:199], v[100:103]
	v_mfma_f32_16x16x32_bf16 v[84:87], v[144:147], v[204:207], v[84:87]
	v_mfma_f32_16x16x32_bf16 v[84:87], v[148:151], v[208:211], v[84:87]
	v_mfma_f32_16x16x32_bf16 v[80:83], v[176:179], v[208:211], v[80:83]
	v_mfma_f32_16x16x32_bf16 v[80:83], v[172:175], v[204:207], v[80:83]
	v_mfma_f32_16x16x32_bf16 v[64:67], v[172:175], v[212:215], v[64:67]
	v_mfma_f32_16x16x32_bf16 v[64:67], v[176:179], v[216:219], v[64:67]
	v_mfma_f32_16x16x32_bf16 v[68:71], v[148:151], v[216:219], v[68:71]
	v_mfma_f32_16x16x32_bf16 v[68:71], v[144:147], v[212:215], v[68:71]
	s_barrier
	s_setprio 0
	s_add_i32 s48, s75, s58
	v_lshl_add_u64 v[220:221], v[220:221], 0, s[22:23]
	s_mov_b32 m0, s48
	ds_read_b128 v[180:183], v190 offset:49152
	v_xor_b32_e32 v253, 64, v190
	ds_read_b128 v[192:195], v253 offset:49152
	ds_read_b128 v[196:199], v190 offset:51200
	ds_read_b128 v[200:203], v253 offset:51200
	ds_read_b128 v[204:207], v190 offset:53248
	ds_read_b128 v[208:211], v253 offset:53248
	ds_read_b128 v[212:215], v190 offset:55296
	ds_read_b128 v[216:219], v253 offset:55296
	global_load_lds_dwordx4 v[220:221], off
	s_add_i32 m0, s48, 0x2000
	s_add_u32 s48, s52, 0xb0080
	v_lshl_add_u64 v[220:221], v[222:223], 0, s[22:23]
	s_addc_u32 s49, s53, 0
	s_add_i32 s52, s76, s58
	global_load_lds_dwordx4 v[220:221], off
	v_lshl_add_u64 v[220:221], s[48:49], 0, v[154:155]
	s_mov_b32 m0, s52
	s_nop 0
	global_load_lds_dwordx4 v[220:221], off
	v_lshl_add_u64 v[220:221], s[48:49], 0, v[162:163]
	s_add_i32 m0, s52, 0x2000
	s_nop 0
	global_load_lds_dwordx4 v[220:221], off
	v_lshl_add_u64 v[220:221], v[224:225], 0, s[22:23]
	s_mov_b32 m0, s3
	s_nop 0
	global_load_lds_dwordx4 v[220:221], off
	v_lshl_add_u64 v[220:221], v[226:227], 0, s[22:23]
	s_mov_b32 m0, s64
	s_nop 0
	global_load_lds_dwordx4 v[220:221], off
	s_waitcnt vmcnt(8)
	s_waitcnt lgkmcnt(0)
	.p2align 3
	s_setprio 1
	s_barrier
	v_mfma_f32_16x16x32_bf16 v[60:63], v[128:131], v[180:183], v[60:63]
	v_mfma_f32_16x16x32_bf16 v[60:63], v[132:135], v[192:195], v[60:63]
	v_mfma_f32_16x16x32_bf16 v[56:59], v[140:143], v[192:195], v[56:59]
	v_mfma_f32_16x16x32_bf16 v[56:59], v[136:139], v[180:183], v[56:59]
	v_mfma_f32_16x16x32_bf16 v[40:43], v[136:139], v[196:199], v[40:43]
	v_mfma_f32_16x16x32_bf16 v[40:43], v[140:143], v[200:203], v[40:43]
	v_mfma_f32_16x16x32_bf16 v[44:47], v[132:135], v[200:203], v[44:47]
	v_mfma_f32_16x16x32_bf16 v[44:47], v[128:131], v[196:199], v[44:47]
	v_mfma_f32_16x16x32_bf16 v[28:31], v[128:131], v[204:207], v[28:31]
	v_mfma_f32_16x16x32_bf16 v[28:31], v[132:135], v[208:211], v[28:31]
	v_mfma_f32_16x16x32_bf16 v[24:27], v[140:143], v[208:211], v[24:27]
	v_mfma_f32_16x16x32_bf16 v[24:27], v[136:139], v[204:207], v[24:27]
	v_mfma_f32_16x16x32_bf16 v[8:11], v[136:139], v[212:215], v[8:11]
	v_mfma_f32_16x16x32_bf16 v[8:11], v[140:143], v[216:219], v[8:11]
	v_mfma_f32_16x16x32_bf16 v[12:15], v[132:135], v[216:219], v[12:15]
	v_mfma_f32_16x16x32_bf16 v[12:15], v[128:131], v[212:215], v[12:15]
	s_setprio 0
	s_setprio 1
	v_mfma_f32_16x16x32_bf16 v[52:55], v[144:147], v[180:183], v[52:55]
	v_mfma_f32_16x16x32_bf16 v[52:55], v[148:151], v[192:195], v[52:55]
	v_mfma_f32_16x16x32_bf16 v[48:51], v[176:179], v[192:195], v[48:51]
	v_mfma_f32_16x16x32_bf16 v[48:51], v[172:175], v[180:183], v[48:51]
	v_mfma_f32_16x16x32_bf16 v[32:35], v[172:175], v[196:199], v[32:35]
	v_mfma_f32_16x16x32_bf16 v[32:35], v[176:179], v[200:203], v[32:35]
	v_mfma_f32_16x16x32_bf16 v[36:39], v[148:151], v[200:203], v[36:39]
	v_mfma_f32_16x16x32_bf16 v[36:39], v[144:147], v[196:199], v[36:39]
	v_mfma_f32_16x16x32_bf16 v[20:23], v[144:147], v[204:207], v[20:23]
	v_mfma_f32_16x16x32_bf16 v[20:23], v[148:151], v[208:211], v[20:23]
	v_mfma_f32_16x16x32_bf16 v[16:19], v[176:179], v[208:211], v[16:19]
	v_mfma_f32_16x16x32_bf16 v[16:19], v[172:175], v[204:207], v[16:19]
	v_mfma_f32_16x16x32_bf16 v[0:3], v[172:175], v[212:215], v[0:3]
	v_mfma_f32_16x16x32_bf16 v[0:3], v[176:179], v[216:219], v[0:3]
	v_mfma_f32_16x16x32_bf16 v[4:7], v[148:151], v[216:219], v[4:7]
	v_mfma_f32_16x16x32_bf16 v[4:7], v[144:147], v[212:215], v[4:7]
	s_barrier
	s_setprio 0
	s_add_i32 s74, s74, 2
	s_add_u32 s72, s72, 0x100
	s_addc_u32 s73, s73, 0
	s_cmp_gt_u32 s74, 41
	s_mov_b64 s[48:49], s[50:51]
	s_branch .LBB0_1181
.Lfa_11:
	ds_read_b128 v[128:131], v188
	v_xor_b32_e32 v253, 64, v188
	ds_read_b128 v[132:135], v253
	ds_read_b128 v[136:139], v188 offset:2048
	ds_read_b128 v[140:143], v253 offset:2048
	ds_read_b128 v[144:147], v189
	v_xor_b32_e32 v253, 64, v189
	ds_read_b128 v[148:151], v253
	ds_read_b128 v[172:175], v189 offset:2048
	ds_read_b128 v[176:179], v253 offset:2048
	s_add_u32 s50, s48, 0x100
	s_addc_u32 s51, s49, 0
	s_cmp_eq_u32 s74, 40
	s_cselect_b32 s55, s11, s51
	s_cselect_b32 s54, s10, s50
	s_cselect_b32 s53, s47, s73
	s_cselect_b32 s52, s46, s72
	v_lshl_add_u64 v[220:221], s[48:49], 0, v[166:167]
	s_add_i32 m0, s59, 0xc000
	ds_read_b128 v[180:183], v190
	v_xor_b32_e32 v253, 64, v190
	ds_read_b128 v[192:195], v253
	ds_read_b128 v[196:199], v190 offset:2048
	ds_read_b128 v[200:203], v253 offset:2048
	ds_read_b128 v[204:207], v190 offset:4096
	ds_read_b128 v[208:211], v253 offset:4096
	ds_read_b128 v[212:215], v190 offset:6144
	ds_read_b128 v[216:219], v253 offset:6144
	global_load_lds_dwordx4 v[220:221], off
	v_lshl_add_u64 v[220:221], s[48:49], 0, v[164:165]
	s_add_i32 m0, s59, 0xe000
	s_nop 0
	global_load_lds_dwordx4 v[220:221], off
	s_waitcnt vmcnt(8)
	s_waitcnt lgkmcnt(0)
	.p2align 3
	s_setprio 1
	s_barrier
	v_mfma_f32_16x16x32_bf16 v[124:127], v[128:131], v[180:183], 0
	v_mfma_f32_16x16x32_bf16 v[120:123], v[136:139], v[180:183], 0
	v_mfma_f32_16x16x32_bf16 v[108:111], v[128:131], v[196:199], 0
	v_mfma_f32_16x16x32_bf16 v[104:107], v[136:139], v[196:199], 0
	v_mfma_f32_16x16x32_bf16 v[92:95], v[128:131], v[204:207], 0
	v_mfma_f32_16x16x32_bf16 v[88:91], v[136:139], v[204:207], 0
	v_mfma_f32_16x16x32_bf16 v[76:79], v[128:131], v[212:215], 0
	v_mfma_f32_16x16x32_bf16 v[72:75], v[136:139], v[212:215], 0
	v_mfma_f32_16x16x32_bf16 v[124:127], v[132:135], v[192:195], v[124:127]
	v_mfma_f32_16x16x32_bf16 v[120:123], v[140:143], v[192:195], v[120:123]
	v_mfma_f32_16x16x32_bf16 v[108:111], v[132:135], v[200:203], v[108:111]
	v_mfma_f32_16x16x32_bf16 v[104:107], v[140:143], v[200:203], v[104:107]
	v_mfma_f32_16x16x32_bf16 v[92:95], v[132:135], v[208:211], v[92:95]
	v_mfma_f32_16x16x32_bf16 v[88:91], v[140:143], v[208:211], v[88:91]
	v_mfma_f32_16x16x32_bf16 v[76:79], v[132:135], v[216:219], v[76:79]
	v_mfma_f32_16x16x32_bf16 v[72:75], v[140:143], v[216:219], v[72:75]
	s_setprio 0
	s_setprio 1
	v_mfma_f32_16x16x32_bf16 v[116:119], v[144:147], v[180:183], 0
	v_mfma_f32_16x16x32_bf16 v[112:115], v[172:175], v[180:183], 0
	v_mfma_f32_16x16x32_bf16 v[100:103], v[144:147], v[196:199], 0
	v_mfma_f32_16x16x32_bf16 v[96:99], v[172:175], v[196:199], 0
	v_mfma_f32_16x16x32_bf16 v[84:87], v[144:147], v[204:207], 0
	v_mfma_f32_16x16x32_bf16 v[80:83], v[172:175], v[204:207], 0
	v_mfma_f32_16x16x32_bf16 v[68:71], v[144:147], v[212:215], 0
	v_mfma_f32_16x16x32_bf16 v[64:67], v[172:175], v[212:215], 0
	v_mfma_f32_16x16x32_bf16 v[116:119], v[148:151], v[192:195], v[116:119]
	v_mfma_f32_16x16x32_bf16 v[112:115], v[176:179], v[192:195], v[112:115]
	v_mfma_f32_16x16x32_bf16 v[100:103], v[148:151], v[200:203], v[100:103]
	v_mfma_f32_16x16x32_bf16 v[96:99], v[176:179], v[200:203], v[96:99]
	v_mfma_f32_16x16x32_bf16 v[84:87], v[148:151], v[208:211], v[84:87]
	v_mfma_f32_16x16x32_bf16 v[80:83], v[176:179], v[208:211], v[80:83]
	v_mfma_f32_16x16x32_bf16 v[68:71], v[148:151], v[216:219], v[68:71]
	v_mfma_f32_16x16x32_bf16 v[64:67], v[176:179], v[216:219], v[64:67]
	s_barrier
	s_setprio 0
	s_add_i32 s48, s68, s58
	v_lshl_add_u64 v[220:221], s[52:53], 0, v[154:155]
	s_mov_b32 m0, s48
	ds_read_b128 v[180:183], v190 offset:16384
	v_xor_b32_e32 v253, 64, v190
	ds_read_b128 v[192:195], v253 offset:16384
	ds_read_b128 v[196:199], v190 offset:18432
	ds_read_b128 v[200:203], v253 offset:18432
	ds_read_b128 v[204:207], v190 offset:20480
	ds_read_b128 v[208:211], v253 offset:20480
	ds_read_b128 v[212:215], v190 offset:22528
	ds_read_b128 v[216:219], v253 offset:22528
	global_load_lds_dwordx4 v[220:221], off
	s_add_i32 m0, s48, 0x2000
	s_add_u32 s48, s52, 0xb0000
	v_lshl_add_u64 v[222:223], s[52:53], 0, v[162:163]
	s_addc_u32 s49, s53, 0
	s_add_i32 s75, s69, s58
	global_load_lds_dwordx4 v[222:223], off
	v_lshl_add_u64 v[224:225], s[48:49], 0, v[154:155]
	s_mov_b32 m0, s75
	v_lshl_add_u64 v[226:227], s[54:55], 0, v[160:161]
	global_load_lds_dwordx4 v[224:225], off
	v_lshl_add_u64 v[224:225], s[48:49], 0, v[162:163]
	s_add_i32 m0, s75, 0x2000
	s_nop 0
	global_load_lds_dwordx4 v[224:225], off
	v_lshl_add_u64 v[224:225], s[54:55], 0, v[152:153]
	s_mov_b32 m0, s59
	s_nop 0
	global_load_lds_dwordx4 v[224:225], off
	s_mov_b32 m0, s60
	s_nop 0
	global_load_lds_dwordx4 v[226:227], off
	s_waitcnt vmcnt(8)
	s_waitcnt lgkmcnt(0)
	.p2align 3
	s_setprio 1
	s_barrier
	v_mfma_f32_16x16x32_bf16 v[60:63], v[128:131], v[180:183], 0
	v_mfma_f32_16x16x32_bf16 v[56:59], v[136:139], v[180:183], 0
	v_mfma_f32_16x16x32_bf16 v[44:47], v[128:131], v[196:199], 0
	v_mfma_f32_16x16x32_bf16 v[40:43], v[136:139], v[196:199], 0
	v_mfma_f32_16x16x32_bf16 v[28:31], v[128:131], v[204:207], 0
	v_mfma_f32_16x16x32_bf16 v[24:27], v[136:139], v[204:207], 0
	v_mfma_f32_16x16x32_bf16 v[12:15], v[128:131], v[212:215], 0
	v_mfma_f32_16x16x32_bf16 v[8:11], v[136:139], v[212:215], 0
	v_mfma_f32_16x16x32_bf16 v[60:63], v[132:135], v[192:195], v[60:63]
	v_mfma_f32_16x16x32_bf16 v[56:59], v[140:143], v[192:195], v[56:59]
	v_mfma_f32_16x16x32_bf16 v[44:47], v[132:135], v[200:203], v[44:47]
	v_mfma_f32_16x16x32_bf16 v[40:43], v[140:143], v[200:203], v[40:43]
	v_mfma_f32_16x16x32_bf16 v[28:31], v[132:135], v[208:211], v[28:31]
	v_mfma_f32_16x16x32_bf16 v[24:27], v[140:143], v[208:211], v[24:27]
	v_mfma_f32_16x16x32_bf16 v[12:15], v[132:135], v[216:219], v[12:15]
	v_mfma_f32_16x16x32_bf16 v[8:11], v[140:143], v[216:219], v[8:11]
	s_setprio 0
	s_setprio 1
	v_mfma_f32_16x16x32_bf16 v[52:55], v[144:147], v[180:183], 0
	v_mfma_f32_16x16x32_bf16 v[48:51], v[172:175], v[180:183], 0
	v_mfma_f32_16x16x32_bf16 v[36:39], v[144:147], v[196:199], 0
	v_mfma_f32_16x16x32_bf16 v[32:35], v[172:175], v[196:199], 0
	v_mfma_f32_16x16x32_bf16 v[20:23], v[144:147], v[204:207], 0
	v_mfma_f32_16x16x32_bf16 v[16:19], v[172:175], v[204:207], 0
	v_mfma_f32_16x16x32_bf16 v[4:7], v[144:147], v[212:215], 0
	v_mfma_f32_16x16x32_bf16 v[0:3], v[172:175], v[212:215], 0
	v_mfma_f32_16x16x32_bf16 v[52:55], v[148:151], v[192:195], v[52:55]
	v_mfma_f32_16x16x32_bf16 v[48:51], v[176:179], v[192:195], v[48:51]
	v_mfma_f32_16x16x32_bf16 v[36:39], v[148:151], v[200:203], v[36:39]
	v_mfma_f32_16x16x32_bf16 v[32:35], v[176:179], v[200:203], v[32:35]
	v_mfma_f32_16x16x32_bf16 v[20:23], v[148:151], v[208:211], v[20:23]
	v_mfma_f32_16x16x32_bf16 v[16:19], v[176:179], v[208:211], v[16:19]
	v_mfma_f32_16x16x32_bf16 v[4:7], v[148:151], v[216:219], v[4:7]
	v_mfma_f32_16x16x32_bf16 v[0:3], v[176:179], v[216:219], v[0:3]
	s_barrier
	s_setprio 0
	s_add_i32 s75, 0, 0x18000
	s_add_i32 s76, 0, 0x1c000
	v_add_u32_e32 v140, s75, v185
	v_add_u32_e32 v176, s76, v185
	ds_read_b128 v[128:131], v140
	v_xor_b32_e32 v253, 64, v140
	ds_read_b128 v[132:135], v253
	ds_read_b128 v[136:139], v140 offset:2048
	ds_read_b128 v[140:143], v253 offset:2048
	ds_read_b128 v[144:147], v176
	v_xor_b32_e32 v253, 64, v176
	ds_read_b128 v[148:151], v253
	ds_read_b128 v[172:175], v176 offset:2048
	ds_read_b128 v[176:179], v253 offset:2048
	s_add_u32 s48, s54, 0xb0000
	s_addc_u32 s49, s55, 0
	s_mov_b32 m0, s61
	v_lshl_add_u64 v[228:229], s[48:49], 0, v[152:153]
	ds_read_b128 v[180:183], v190 offset:32768
	v_xor_b32_e32 v253, 64, v190
	ds_read_b128 v[192:195], v253 offset:32768
	ds_read_b128 v[196:199], v190 offset:34816
	ds_read_b128 v[200:203], v253 offset:34816
	ds_read_b128 v[204:207], v190 offset:36864
	ds_read_b128 v[208:211], v253 offset:36864
	ds_read_b128 v[212:215], v190 offset:38912
	ds_read_b128 v[216:219], v253 offset:38912
	global_load_lds_dwordx4 v[228:229], off
	v_lshl_add_u64 v[228:229], s[48:49], 0, v[160:161]
	s_mov_b32 m0, s62
	s_nop 0
	global_load_lds_dwordx4 v[228:229], off
	s_waitcnt vmcnt(8)
	s_waitcnt lgkmcnt(0)
	.p2align 3
	s_setprio 1
	s_barrier
	v_mfma_f32_16x16x32_bf16 v[124:127], v[128:131], v[180:183], v[124:127]
	v_mfma_f32_16x16x32_bf16 v[124:127], v[132:135], v[192:195], v[124:127]
	v_mfma_f32_16x16x32_bf16 v[120:123], v[140:143], v[192:195], v[120:123]
	v_mfma_f32_16x16x32_bf16 v[120:123], v[136:139], v[180:183], v[120:123]
	v_mfma_f32_16x16x32_bf16 v[104:107], v[136:139], v[196:199], v[104:107]
	v_mfma_f32_16x16x32_bf16 v[104:107], v[140:143], v[200:203], v[104:107]
	v_mfma_f32_16x16x32_bf16 v[108:111], v[132:135], v[200:203], v[108:111]
	v_mfma_f32_16x16x32_bf16 v[108:111], v[128:131], v[196:199], v[108:111]
	v_mfma_f32_16x16x32_bf16 v[92:95], v[128:131], v[204:207], v[92:95]
	v_mfma_f32_16x16x32_bf16 v[92:95], v[132:135], v[208:211], v[92:95]
	v_mfma_f32_16x16x32_bf16 v[88:91], v[140:143], v[208:211], v[88:91]
	v_mfma_f32_16x16x32_bf16 v[88:91], v[136:139], v[204:207], v[88:91]
	v_mfma_f32_16x16x32_bf16 v[72:75], v[136:139], v[212:215], v[72:75]
	v_mfma_f32_16x16x32_bf16 v[72:75], v[140:143], v[216:219], v[72:75]
	v_mfma_f32_16x16x32_bf16 v[76:79], v[132:135], v[216:219], v[76:79]
	v_mfma_f32_16x16x32_bf16 v[76:79], v[128:131], v[212:215], v[76:79]
	s_setprio 0
	s_setprio 1
	v_mfma_f32_16x16x32_bf16 v[116:119], v[144:147], v[180:183], v[116:119]
	v_mfma_f32_16x16x32_bf16 v[116:119], v[148:151], v[192:195], v[116:119]
	v_mfma_f32_16x16x32_bf16 v[112:115], v[176:179], v[192:195], v[112:115]
	v_mfma_f32_16x16x32_bf16 v[112:115], v[172:175], v[180:183], v[112:115]
	v_mfma_f32_16x16x32_bf16 v[96:99], v[172:175], v[196:199], v[96:99]
	v_mfma_f32_16x16x32_bf16 v[96:99], v[176:179], v[200:203], v[96:99]
	v_mfma_f32_16x16x32_bf16 v[100:103], v[148:151], v[200:203], v[100:103]
	v_mfma_f32_16x16x32_bf16 v[100:103], v[144:147], v[196:199], v[100:103]
	v_mfma_f32_16x16x32_bf16 v[84:87], v[144:147], v[204:207], v[84:87]
	v_mfma_f32_16x16x32_bf16 v[84:87], v[148:151], v[208:211], v[84:87]
	v_mfma_f32_16x16x32_bf16 v[80:83], v[176:179], v[208:211], v[80:83]
	v_mfma_f32_16x16x32_bf16 v[80:83], v[172:175], v[204:207], v[80:83]
	v_mfma_f32_16x16x32_bf16 v[64:67], v[172:175], v[212:215], v[64:67]
	v_mfma_f32_16x16x32_bf16 v[64:67], v[176:179], v[216:219], v[64:67]
	v_mfma_f32_16x16x32_bf16 v[68:71], v[148:151], v[216:219], v[68:71]
	v_mfma_f32_16x16x32_bf16 v[68:71], v[144:147], v[212:215], v[68:71]
	s_barrier
	s_setprio 0
	s_add_i32 s48, s75, s58
	v_lshl_add_u64 v[220:221], v[220:221], 0, s[22:23]
	s_mov_b32 m0, s48
	ds_read_b128 v[180:183], v190 offset:49152
	v_xor_b32_e32 v253, 64, v190
	ds_read_b128 v[192:195], v253 offset:49152
	ds_read_b128 v[196:199], v190 offset:51200
	ds_read_b128 v[200:203], v253 offset:51200
	ds_read_b128 v[204:207], v190 offset:53248
	ds_read_b128 v[208:211], v253 offset:53248
	ds_read_b128 v[212:215], v190 offset:55296
	ds_read_b128 v[216:219], v253 offset:55296
	global_load_lds_dwordx4 v[220:221], off
	s_add_i32 m0, s48, 0x2000
	s_add_u32 s48, s52, 0xb0080
	v_lshl_add_u64 v[220:221], v[222:223], 0, s[22:23]
	s_addc_u32 s49, s53, 0
	s_add_i32 s52, s76, s58
	global_load_lds_dwordx4 v[220:221], off
	v_lshl_add_u64 v[220:221], s[48:49], 0, v[154:155]
	s_mov_b32 m0, s52
	s_nop 0
	global_load_lds_dwordx4 v[220:221], off
	v_lshl_add_u64 v[220:221], s[48:49], 0, v[162:163]
	s_add_i32 m0, s52, 0x2000
	s_nop 0
	global_load_lds_dwordx4 v[220:221], off
	v_lshl_add_u64 v[220:221], v[224:225], 0, s[22:23]
	s_mov_b32 m0, s3
	s_nop 0
	global_load_lds_dwordx4 v[220:221], off
	v_lshl_add_u64 v[220:221], v[226:227], 0, s[22:23]
	s_mov_b32 m0, s64
	s_nop 0
	global_load_lds_dwordx4 v[220:221], off
	s_waitcnt vmcnt(8)
	s_waitcnt lgkmcnt(0)
	.p2align 3
	s_setprio 1
	s_barrier
	v_mfma_f32_16x16x32_bf16 v[60:63], v[128:131], v[180:183], v[60:63]
	v_mfma_f32_16x16x32_bf16 v[60:63], v[132:135], v[192:195], v[60:63]
	v_mfma_f32_16x16x32_bf16 v[56:59], v[140:143], v[192:195], v[56:59]
	v_mfma_f32_16x16x32_bf16 v[56:59], v[136:139], v[180:183], v[56:59]
	v_mfma_f32_16x16x32_bf16 v[40:43], v[136:139], v[196:199], v[40:43]
	v_mfma_f32_16x16x32_bf16 v[40:43], v[140:143], v[200:203], v[40:43]
	v_mfma_f32_16x16x32_bf16 v[44:47], v[132:135], v[200:203], v[44:47]
	v_mfma_f32_16x16x32_bf16 v[44:47], v[128:131], v[196:199], v[44:47]
	v_mfma_f32_16x16x32_bf16 v[28:31], v[128:131], v[204:207], v[28:31]
	v_mfma_f32_16x16x32_bf16 v[28:31], v[132:135], v[208:211], v[28:31]
	v_mfma_f32_16x16x32_bf16 v[24:27], v[140:143], v[208:211], v[24:27]
	v_mfma_f32_16x16x32_bf16 v[24:27], v[136:139], v[204:207], v[24:27]
	v_mfma_f32_16x16x32_bf16 v[8:11], v[136:139], v[212:215], v[8:11]
	v_mfma_f32_16x16x32_bf16 v[8:11], v[140:143], v[216:219], v[8:11]
	v_mfma_f32_16x16x32_bf16 v[12:15], v[132:135], v[216:219], v[12:15]
	v_mfma_f32_16x16x32_bf16 v[12:15], v[128:131], v[212:215], v[12:15]
	s_setprio 0
	s_setprio 1
	v_mfma_f32_16x16x32_bf16 v[52:55], v[144:147], v[180:183], v[52:55]
	v_mfma_f32_16x16x32_bf16 v[52:55], v[148:151], v[192:195], v[52:55]
	v_mfma_f32_16x16x32_bf16 v[48:51], v[176:179], v[192:195], v[48:51]
	v_mfma_f32_16x16x32_bf16 v[48:51], v[172:175], v[180:183], v[48:51]
	v_mfma_f32_16x16x32_bf16 v[32:35], v[172:175], v[196:199], v[32:35]
	v_mfma_f32_16x16x32_bf16 v[32:35], v[176:179], v[200:203], v[32:35]
	v_mfma_f32_16x16x32_bf16 v[36:39], v[148:151], v[200:203], v[36:39]
	v_mfma_f32_16x16x32_bf16 v[36:39], v[144:147], v[196:199], v[36:39]
	v_mfma_f32_16x16x32_bf16 v[20:23], v[144:147], v[204:207], v[20:23]
	v_mfma_f32_16x16x32_bf16 v[20:23], v[148:151], v[208:211], v[20:23]
	v_mfma_f32_16x16x32_bf16 v[16:19], v[176:179], v[208:211], v[16:19]
	v_mfma_f32_16x16x32_bf16 v[16:19], v[172:175], v[204:207], v[16:19]
	v_mfma_f32_16x16x32_bf16 v[0:3], v[172:175], v[212:215], v[0:3]
	v_mfma_f32_16x16x32_bf16 v[0:3], v[176:179], v[216:219], v[0:3]
	v_mfma_f32_16x16x32_bf16 v[4:7], v[148:151], v[216:219], v[4:7]
	v_mfma_f32_16x16x32_bf16 v[4:7], v[144:147], v[212:215], v[4:7]
	s_barrier
	s_setprio 0
	s_add_i32 s74, s74, 2
	s_add_u32 s72, s72, 0x100
	s_addc_u32 s73, s73, 0
	s_cmp_gt_u32 s74, 41
	s_mov_b64 s[48:49], s[50:51]
.LBB0_1181:
	ds_read_b128 v[128:131], v188
	v_xor_b32_e32 v253, 64, v188
	ds_read_b128 v[132:135], v253
	ds_read_b128 v[136:139], v188 offset:2048
	ds_read_b128 v[140:143], v253 offset:2048
	ds_read_b128 v[144:147], v189
	v_xor_b32_e32 v253, 64, v189
	ds_read_b128 v[148:151], v253
	ds_read_b128 v[172:175], v189 offset:2048
	ds_read_b128 v[176:179], v253 offset:2048
	s_add_u32 s50, s48, 0x100
	s_addc_u32 s51, s49, 0
	s_cmp_eq_u32 s74, 40
	s_cselect_b32 s55, s11, s51
	s_cselect_b32 s54, s10, s50
	s_cselect_b32 s53, s47, s73
	s_cselect_b32 s52, s46, s72
	v_lshl_add_u64 v[220:221], s[48:49], 0, v[166:167]
	s_add_i32 m0, s59, 0xc000
	ds_read_b128 v[180:183], v190
	v_xor_b32_e32 v253, 64, v190
	ds_read_b128 v[192:195], v253
	ds_read_b128 v[196:199], v190 offset:2048
	ds_read_b128 v[200:203], v253 offset:2048
	ds_read_b128 v[204:207], v190 offset:4096
	ds_read_b128 v[208:211], v253 offset:4096
	ds_read_b128 v[212:215], v190 offset:6144
	ds_read_b128 v[216:219], v253 offset:6144
	global_load_lds_dwordx4 v[220:221], off
	v_lshl_add_u64 v[220:221], s[48:49], 0, v[164:165]
	s_add_i32 m0, s59, 0xe000
	s_nop 0
	global_load_lds_dwordx4 v[220:221], off
	s_waitcnt vmcnt(8)
	s_waitcnt lgkmcnt(0)
	.p2align 3
	s_setprio 1
	s_barrier
	v_mfma_f32_16x16x32_bf16 v[124:127], v[128:131], v[180:183], v[124:127]
	v_mfma_f32_16x16x32_bf16 v[124:127], v[132:135], v[192:195], v[124:127]
	v_mfma_f32_16x16x32_bf16 v[120:123], v[140:143], v[192:195], v[120:123]
	v_mfma_f32_16x16x32_bf16 v[120:123], v[136:139], v[180:183], v[120:123]
	v_mfma_f32_16x16x32_bf16 v[104:107], v[136:139], v[196:199], v[104:107]
	v_mfma_f32_16x16x32_bf16 v[104:107], v[140:143], v[200:203], v[104:107]
	v_mfma_f32_16x16x32_bf16 v[108:111], v[132:135], v[200:203], v[108:111]
	v_mfma_f32_16x16x32_bf16 v[108:111], v[128:131], v[196:199], v[108:111]
	v_mfma_f32_16x16x32_bf16 v[92:95], v[128:131], v[204:207], v[92:95]
	v_mfma_f32_16x16x32_bf16 v[92:95], v[132:135], v[208:211], v[92:95]
	v_mfma_f32_16x16x32_bf16 v[88:91], v[140:143], v[208:211], v[88:91]
	v_mfma_f32_16x16x32_bf16 v[88:91], v[136:139], v[204:207], v[88:91]
	v_mfma_f32_16x16x32_bf16 v[72:75], v[136:139], v[212:215], v[72:75]
	v_mfma_f32_16x16x32_bf16 v[72:75], v[140:143], v[216:219], v[72:75]
	v_mfma_f32_16x16x32_bf16 v[76:79], v[132:135], v[216:219], v[76:79]
	v_mfma_f32_16x16x32_bf16 v[76:79], v[128:131], v[212:215], v[76:79]
	s_setprio 0
	s_setprio 1
	v_mfma_f32_16x16x32_bf16 v[116:119], v[144:147], v[180:183], v[116:119]
	v_mfma_f32_16x16x32_bf16 v[116:119], v[148:151], v[192:195], v[116:119]
	v_mfma_f32_16x16x32_bf16 v[112:115], v[176:179], v[192:195], v[112:115]
	v_mfma_f32_16x16x32_bf16 v[112:115], v[172:175], v[180:183], v[112:115]
	v_mfma_f32_16x16x32_bf16 v[96:99], v[172:175], v[196:199], v[96:99]
	v_mfma_f32_16x16x32_bf16 v[96:99], v[176:179], v[200:203], v[96:99]
	v_mfma_f32_16x16x32_bf16 v[100:103], v[148:151], v[200:203], v[100:103]
	v_mfma_f32_16x16x32_bf16 v[100:103], v[144:147], v[196:199], v[100:103]
	v_mfma_f32_16x16x32_bf16 v[84:87], v[144:147], v[204:207], v[84:87]
	v_mfma_f32_16x16x32_bf16 v[84:87], v[148:151], v[208:211], v[84:87]
	v_mfma_f32_16x16x32_bf16 v[80:83], v[176:179], v[208:211], v[80:83]
	v_mfma_f32_16x16x32_bf16 v[80:83], v[172:175], v[204:207], v[80:83]
	v_mfma_f32_16x16x32_bf16 v[64:67], v[172:175], v[212:215], v[64:67]
	v_mfma_f32_16x16x32_bf16 v[64:67], v[176:179], v[216:219], v[64:67]
	v_mfma_f32_16x16x32_bf16 v[68:71], v[148:151], v[216:219], v[68:71]
	v_mfma_f32_16x16x32_bf16 v[68:71], v[144:147], v[212:215], v[68:71]
	s_barrier
	s_setprio 0
	s_add_i32 s48, s68, s58
	v_lshl_add_u64 v[220:221], s[52:53], 0, v[154:155]
	s_mov_b32 m0, s48
	ds_read_b128 v[180:183], v190 offset:16384
	v_xor_b32_e32 v253, 64, v190
	ds_read_b128 v[192:195], v253 offset:16384
	ds_read_b128 v[196:199], v190 offset:18432
	ds_read_b128 v[200:203], v253 offset:18432
	ds_read_b128 v[204:207], v190 offset:20480
	ds_read_b128 v[208:211], v253 offset:20480
	ds_read_b128 v[212:215], v190 offset:22528
	ds_read_b128 v[216:219], v253 offset:22528
	global_load_lds_dwordx4 v[220:221], off
	s_add_i32 m0, s48, 0x2000
	s_add_u32 s48, s52, 0xb0000
	v_lshl_add_u64 v[222:223], s[52:53], 0, v[162:163]
	s_addc_u32 s49, s53, 0
	s_add_i32 s75, s69, s58
	global_load_lds_dwordx4 v[222:223], off
	v_lshl_add_u64 v[224:225], s[48:49], 0, v[154:155]
	s_mov_b32 m0, s75
	v_lshl_add_u64 v[226:227], s[54:55], 0, v[160:161]
	global_load_lds_dwordx4 v[224:225], off
	v_lshl_add_u64 v[224:225], s[48:49], 0, v[162:163]
	s_add_i32 m0, s75, 0x2000
	s_nop 0
	global_load_lds_dwordx4 v[224:225], off
	v_lshl_add_u64 v[224:225], s[54:55], 0, v[152:153]
	s_mov_b32 m0, s59
	s_nop 0
	global_load_lds_dwordx4 v[224:225], off
	s_mov_b32 m0, s60
	s_nop 0
	global_load_lds_dwordx4 v[226:227], off
	s_waitcnt vmcnt(8)
	s_waitcnt lgkmcnt(0)
	.p2align 3
	s_setprio 1
	s_barrier
	v_mfma_f32_16x16x32_bf16 v[60:63], v[128:131], v[180:183], v[60:63]
	v_mfma_f32_16x16x32_bf16 v[60:63], v[132:135], v[192:195], v[60:63]
	v_mfma_f32_16x16x32_bf16 v[56:59], v[140:143], v[192:195], v[56:59]
	v_mfma_f32_16x16x32_bf16 v[56:59], v[136:139], v[180:183], v[56:59]
	v_mfma_f32_16x16x32_bf16 v[40:43], v[136:139], v[196:199], v[40:43]
	v_mfma_f32_16x16x32_bf16 v[40:43], v[140:143], v[200:203], v[40:43]
	v_mfma_f32_16x16x32_bf16 v[44:47], v[132:135], v[200:203], v[44:47]
	v_mfma_f32_16x16x32_bf16 v[44:47], v[128:131], v[196:199], v[44:47]
	v_mfma_f32_16x16x32_bf16 v[28:31], v[128:131], v[204:207], v[28:31]
	v_mfma_f32_16x16x32_bf16 v[28:31], v[132:135], v[208:211], v[28:31]
	v_mfma_f32_16x16x32_bf16 v[24:27], v[140:143], v[208:211], v[24:27]
	v_mfma_f32_16x16x32_bf16 v[24:27], v[136:139], v[204:207], v[24:27]
	v_mfma_f32_16x16x32_bf16 v[8:11], v[136:139], v[212:215], v[8:11]
	v_mfma_f32_16x16x32_bf16 v[8:11], v[140:143], v[216:219], v[8:11]
	v_mfma_f32_16x16x32_bf16 v[12:15], v[132:135], v[216:219], v[12:15]
	v_mfma_f32_16x16x32_bf16 v[12:15], v[128:131], v[212:215], v[12:15]
	s_setprio 0
	s_setprio 1
	v_mfma_f32_16x16x32_bf16 v[52:55], v[144:147], v[180:183], v[52:55]
	v_mfma_f32_16x16x32_bf16 v[52:55], v[148:151], v[192:195], v[52:55]
	v_mfma_f32_16x16x32_bf16 v[48:51], v[176:179], v[192:195], v[48:51]
	v_mfma_f32_16x16x32_bf16 v[48:51], v[172:175], v[180:183], v[48:51]
	v_mfma_f32_16x16x32_bf16 v[32:35], v[172:175], v[196:199], v[32:35]
	v_mfma_f32_16x16x32_bf16 v[32:35], v[176:179], v[200:203], v[32:35]
	v_mfma_f32_16x16x32_bf16 v[36:39], v[148:151], v[200:203], v[36:39]
	v_mfma_f32_16x16x32_bf16 v[36:39], v[144:147], v[196:199], v[36:39]
	v_mfma_f32_16x16x32_bf16 v[20:23], v[144:147], v[204:207], v[20:23]
	v_mfma_f32_16x16x32_bf16 v[20:23], v[148:151], v[208:211], v[20:23]
	v_mfma_f32_16x16x32_bf16 v[16:19], v[176:179], v[208:211], v[16:19]
	v_mfma_f32_16x16x32_bf16 v[16:19], v[172:175], v[204:207], v[16:19]
	v_mfma_f32_16x16x32_bf16 v[0:3], v[172:175], v[212:215], v[0:3]
	v_mfma_f32_16x16x32_bf16 v[0:3], v[176:179], v[216:219], v[0:3]
	v_mfma_f32_16x16x32_bf16 v[4:7], v[148:151], v[216:219], v[4:7]
	v_mfma_f32_16x16x32_bf16 v[4:7], v[144:147], v[212:215], v[4:7]
	s_barrier
	s_setprio 0
	s_add_i32 s75, 0, 0x18000
	s_add_i32 s76, 0, 0x1c000
	v_add_u32_e32 v140, s75, v185
	v_add_u32_e32 v176, s76, v185
	ds_read_b128 v[128:131], v140
	v_xor_b32_e32 v253, 64, v140
	ds_read_b128 v[132:135], v253
	ds_read_b128 v[136:139], v140 offset:2048
	ds_read_b128 v[140:143], v253 offset:2048
	ds_read_b128 v[144:147], v176
	v_xor_b32_e32 v253, 64, v176
	ds_read_b128 v[148:151], v253
	ds_read_b128 v[172:175], v176 offset:2048
	ds_read_b128 v[176:179], v253 offset:2048
	s_add_u32 s48, s54, 0xb0000
	s_addc_u32 s49, s55, 0
	s_mov_b32 m0, s61
	v_lshl_add_u64 v[228:229], s[48:49], 0, v[152:153]
	ds_read_b128 v[180:183], v190 offset:32768
	v_xor_b32_e32 v253, 64, v190
	ds_read_b128 v[192:195], v253 offset:32768
	ds_read_b128 v[196:199], v190 offset:34816
	ds_read_b128 v[200:203], v253 offset:34816
	ds_read_b128 v[204:207], v190 offset:36864
	ds_read_b128 v[208:211], v253 offset:36864
	ds_read_b128 v[212:215], v190 offset:38912
	ds_read_b128 v[216:219], v253 offset:38912
	global_load_lds_dwordx4 v[228:229], off
	v_lshl_add_u64 v[228:229], s[48:49], 0, v[160:161]
	s_mov_b32 m0, s62
	s_nop 0
	global_load_lds_dwordx4 v[228:229], off
	s_waitcnt vmcnt(8)
	s_waitcnt lgkmcnt(0)
	.p2align 3
	s_setprio 1
	s_barrier
	v_mfma_f32_16x16x32_bf16 v[124:127], v[128:131], v[180:183], v[124:127]
	v_mfma_f32_16x16x32_bf16 v[124:127], v[132:135], v[192:195], v[124:127]
	v_mfma_f32_16x16x32_bf16 v[120:123], v[140:143], v[192:195], v[120:123]
	v_mfma_f32_16x16x32_bf16 v[120:123], v[136:139], v[180:183], v[120:123]
	v_mfma_f32_16x16x32_bf16 v[104:107], v[136:139], v[196:199], v[104:107]
	v_mfma_f32_16x16x32_bf16 v[104:107], v[140:143], v[200:203], v[104:107]
	v_mfma_f32_16x16x32_bf16 v[108:111], v[132:135], v[200:203], v[108:111]
	v_mfma_f32_16x16x32_bf16 v[108:111], v[128:131], v[196:199], v[108:111]
	v_mfma_f32_16x16x32_bf16 v[92:95], v[128:131], v[204:207], v[92:95]
	v_mfma_f32_16x16x32_bf16 v[92:95], v[132:135], v[208:211], v[92:95]
	v_mfma_f32_16x16x32_bf16 v[88:91], v[140:143], v[208:211], v[88:91]
	v_mfma_f32_16x16x32_bf16 v[88:91], v[136:139], v[204:207], v[88:91]
	v_mfma_f32_16x16x32_bf16 v[72:75], v[136:139], v[212:215], v[72:75]
	v_mfma_f32_16x16x32_bf16 v[72:75], v[140:143], v[216:219], v[72:75]
	v_mfma_f32_16x16x32_bf16 v[76:79], v[132:135], v[216:219], v[76:79]
	v_mfma_f32_16x16x32_bf16 v[76:79], v[128:131], v[212:215], v[76:79]
	s_setprio 0
	s_setprio 1
	v_mfma_f32_16x16x32_bf16 v[116:119], v[144:147], v[180:183], v[116:119]
	v_mfma_f32_16x16x32_bf16 v[116:119], v[148:151], v[192:195], v[116:119]
	v_mfma_f32_16x16x32_bf16 v[112:115], v[176:179], v[192:195], v[112:115]
	v_mfma_f32_16x16x32_bf16 v[112:115], v[172:175], v[180:183], v[112:115]
	v_mfma_f32_16x16x32_bf16 v[96:99], v[172:175], v[196:199], v[96:99]
	v_mfma_f32_16x16x32_bf16 v[96:99], v[176:179], v[200:203], v[96:99]
	v_mfma_f32_16x16x32_bf16 v[100:103], v[148:151], v[200:203], v[100:103]
	v_mfma_f32_16x16x32_bf16 v[100:103], v[144:147], v[196:199], v[100:103]
	v_mfma_f32_16x16x32_bf16 v[84:87], v[144:147], v[204:207], v[84:87]
	v_mfma_f32_16x16x32_bf16 v[84:87], v[148:151], v[208:211], v[84:87]
	v_mfma_f32_16x16x32_bf16 v[80:83], v[176:179], v[208:211], v[80:83]
	v_mfma_f32_16x16x32_bf16 v[80:83], v[172:175], v[204:207], v[80:83]
	v_mfma_f32_16x16x32_bf16 v[64:67], v[172:175], v[212:215], v[64:67]
	v_mfma_f32_16x16x32_bf16 v[64:67], v[176:179], v[216:219], v[64:67]
	v_mfma_f32_16x16x32_bf16 v[68:71], v[148:151], v[216:219], v[68:71]
	v_mfma_f32_16x16x32_bf16 v[68:71], v[144:147], v[212:215], v[68:71]
	s_barrier
	s_setprio 0
	s_add_i32 s48, s75, s58
	v_lshl_add_u64 v[220:221], v[220:221], 0, s[22:23]
	s_mov_b32 m0, s48
	ds_read_b128 v[180:183], v190 offset:49152
	v_xor_b32_e32 v253, 64, v190
	ds_read_b128 v[192:195], v253 offset:49152
	ds_read_b128 v[196:199], v190 offset:51200
	ds_read_b128 v[200:203], v253 offset:51200
	ds_read_b128 v[204:207], v190 offset:53248
	ds_read_b128 v[208:211], v253 offset:53248
	ds_read_b128 v[212:215], v190 offset:55296
	ds_read_b128 v[216:219], v253 offset:55296
	global_load_lds_dwordx4 v[220:221], off
	s_add_i32 m0, s48, 0x2000
	s_add_u32 s48, s52, 0xb0080
	v_lshl_add_u64 v[220:221], v[222:223], 0, s[22:23]
	s_addc_u32 s49, s53, 0
	s_add_i32 s52, s76, s58
	global_load_lds_dwordx4 v[220:221], off
	v_lshl_add_u64 v[220:221], s[48:49], 0, v[154:155]
	s_mov_b32 m0, s52
	s_nop 0
	global_load_lds_dwordx4 v[220:221], off
	v_lshl_add_u64 v[220:221], s[48:49], 0, v[162:163]
	s_add_i32 m0, s52, 0x2000
	s_nop 0
	global_load_lds_dwordx4 v[220:221], off
	v_lshl_add_u64 v[220:221], v[224:225], 0, s[22:23]
	s_mov_b32 m0, s3
	s_nop 0
	global_load_lds_dwordx4 v[220:221], off
	v_lshl_add_u64 v[220:221], v[226:227], 0, s[22:23]
	s_mov_b32 m0, s64
	s_nop 0
	global_load_lds_dwordx4 v[220:221], off
	s_waitcnt vmcnt(8)
	s_waitcnt lgkmcnt(0)
	.p2align 3
	s_setprio 1
	s_barrier
	v_mfma_f32_16x16x32_bf16 v[60:63], v[128:131], v[180:183], v[60:63]
	v_mfma_f32_16x16x32_bf16 v[60:63], v[132:135], v[192:195], v[60:63]
	v_mfma_f32_16x16x32_bf16 v[56:59], v[140:143], v[192:195], v[56:59]
	v_mfma_f32_16x16x32_bf16 v[56:59], v[136:139], v[180:183], v[56:59]
	v_mfma_f32_16x16x32_bf16 v[40:43], v[136:139], v[196:199], v[40:43]
	v_mfma_f32_16x16x32_bf16 v[40:43], v[140:143], v[200:203], v[40:43]
	v_mfma_f32_16x16x32_bf16 v[44:47], v[132:135], v[200:203], v[44:47]
	v_mfma_f32_16x16x32_bf16 v[44:47], v[128:131], v[196:199], v[44:47]
	v_mfma_f32_16x16x32_bf16 v[28:31], v[128:131], v[204:207], v[28:31]
	v_mfma_f32_16x16x32_bf16 v[28:31], v[132:135], v[208:211], v[28:31]
	v_mfma_f32_16x16x32_bf16 v[24:27], v[140:143], v[208:211], v[24:27]
	v_mfma_f32_16x16x32_bf16 v[24:27], v[136:139], v[204:207], v[24:27]
	v_mfma_f32_16x16x32_bf16 v[8:11], v[136:139], v[212:215], v[8:11]
	v_mfma_f32_16x16x32_bf16 v[8:11], v[140:143], v[216:219], v[8:11]
	v_mfma_f32_16x16x32_bf16 v[12:15], v[132:135], v[216:219], v[12:15]
	v_mfma_f32_16x16x32_bf16 v[12:15], v[128:131], v[212:215], v[12:15]
	s_setprio 0
	s_setprio 1
	v_mfma_f32_16x16x32_bf16 v[52:55], v[144:147], v[180:183], v[52:55]
	v_mfma_f32_16x16x32_bf16 v[52:55], v[148:151], v[192:195], v[52:55]
	v_mfma_f32_16x16x32_bf16 v[48:51], v[176:179], v[192:195], v[48:51]
	v_mfma_f32_16x16x32_bf16 v[48:51], v[172:175], v[180:183], v[48:51]
	v_mfma_f32_16x16x32_bf16 v[32:35], v[172:175], v[196:199], v[32:35]
	v_mfma_f32_16x16x32_bf16 v[32:35], v[176:179], v[200:203], v[32:35]
	v_mfma_f32_16x16x32_bf16 v[36:39], v[148:151], v[200:203], v[36:39]
	v_mfma_f32_16x16x32_bf16 v[36:39], v[144:147], v[196:199], v[36:39]
	v_mfma_f32_16x16x32_bf16 v[20:23], v[144:147], v[204:207], v[20:23]
	v_mfma_f32_16x16x32_bf16 v[20:23], v[148:151], v[208:211], v[20:23]
	v_mfma_f32_16x16x32_bf16 v[16:19], v[176:179], v[208:211], v[16:19]
	v_mfma_f32_16x16x32_bf16 v[16:19], v[172:175], v[204:207], v[16:19]
	v_mfma_f32_16x16x32_bf16 v[0:3], v[172:175], v[212:215], v[0:3]
	v_mfma_f32_16x16x32_bf16 v[0:3], v[176:179], v[216:219], v[0:3]
	v_mfma_f32_16x16x32_bf16 v[4:7], v[148:151], v[216:219], v[4:7]
	v_mfma_f32_16x16x32_bf16 v[4:7], v[144:147], v[212:215], v[4:7]
	s_barrier
	s_setprio 0
	s_add_i32 s74, s74, 2
	s_add_u32 s72, s72, 0x100
	s_addc_u32 s73, s73, 0
	s_cmp_gt_u32 s74, 41
	s_mov_b64 s[48:49], s[50:51]
	s_cbranch_scc0 .LBB0_1181
	s_and_b64 vcc, exec, s[24:25]
	s_cbranch_vccz .LBB0_1184
	s_barrier
